# v10: v9 plus nt policy on read-once activation streams (head-norm inputs, residual reads, LN1 rows, combine rows and expert outputs, conv input, MLA norm input)
# baseline (speedup 1.0000x reference)
.LBB0_426:
	s_lshl_b32 s0, s27, 8
	s_add_i32 s0, s0, s97
	s_ashr_i32 s1, s0, 31
	s_add_i32 s8, s0, 8
	s_lshl_b64 s[10:11], s[0:1], 11
	s_ashr_i32 s9, s8, 31
	v_lshl_add_u64 v[76:77], v[68:69], 0, s[10:11]
	v_lshl_add_u64 v[78:79], v[70:71], 0, s[10:11]
	v_mad_i64_i32 v[80:81], s[10:11], s0, v86, v[72:73]
	s_lshl_b64 s[10:11], s[8:9], 11
	global_load_dwordx4 v[2:5], v[66:67], off
	global_load_dwordx4 v[6:9], v[66:67], off offset:16
	global_load_dwordx4 v[10:13], v[66:67], off offset:2048
	global_load_dwordx4 v[14:17], v[66:67], off offset:2064
	v_lshl_add_u64 v[82:83], v[68:69], 0, s[10:11]
	v_lshl_add_u64 v[84:85], v[70:71], 0, s[10:11]
	v_mad_i64_i32 v[90:91], s[8:9], s8, v86, v[72:73]
	flat_load_dwordx4 v[58:61], v[76:77] nt
	flat_load_dwordx4 v[22:25], v[76:77] offset:1024 nt
	flat_load_dwordx4 v[54:57], v[78:79] nt
	flat_load_dwordx4 v[18:21], v[78:79] offset:1024 nt
	flat_load_dwordx4 v[62:65], v[80:81] nt
	flat_load_dwordx4 v[26:29], v[80:81] offset:1024 nt
	s_waitcnt vmcnt(0) lgkmcnt(0)
	flat_load_dwordx4 v[42:45], v[82:83] nt
	flat_load_dwordx4 v[38:41], v[82:83] offset:1024 nt
	flat_load_dwordx4 v[50:53], v[84:85] nt
	flat_load_dwordx4 v[46:49], v[84:85] offset:1024 nt
	flat_load_dwordx4 v[30:33], v[90:91] nt
	flat_load_dwordx4 v[34:37], v[90:91] offset:1024 nt
	s_add_i32 s28, s0, 16
	s_mov_b32 s14, s4
	s_mov_b32 s29, 0
.LBB0_427:
	s_min_u32 s8, s29, 29
	s_ashr_i32 s15, s14, 31
	s_waitcnt vmcnt(0) lgkmcnt(0)
	v_lshlrev_b32_e32 v89, 16, v62
	v_and_b32_e32 v98, 0xffff0000, v62
	v_lshlrev_b32_e32 v99, 16, v63
	v_and_b32_e32 v100, 0xffff0000, v63
	v_lshlrev_b32_e32 v101, 16, v64
	v_and_b32_e32 v102, 0xffff0000, v64
	v_lshlrev_b32_e32 v103, 16, v65
	v_and_b32_e32 v104, 0xffff0000, v65
	v_lshlrev_b32_e32 v76, 16, v61
	v_and_b32_e32 v77, 0xffff0000, v61
	v_lshlrev_b32_e32 v78, 16, v57
	v_and_b32_e32 v79, 0xffff0000, v57
	v_lshlrev_b32_e32 v80, 16, v60
	v_and_b32_e32 v81, 0xffff0000, v60
	v_lshlrev_b32_e32 v60, 16, v56
	v_and_b32_e32 v61, 0xffff0000, v56
	v_lshlrev_b32_e32 v56, 16, v59
	v_and_b32_e32 v57, 0xffff0000, v59
	v_lshlrev_b32_e32 v82, 16, v55
	v_and_b32_e32 v83, 0xffff0000, v55
	v_lshlrev_b32_e32 v84, 16, v58
	v_and_b32_e32 v85, 0xffff0000, v58
	v_lshlrev_b32_e32 v58, 16, v54
	v_and_b32_e32 v59, 0xffff0000, v54
	v_lshlrev_b32_e32 v105, 16, v26
	v_and_b32_e32 v106, 0xffff0000, v26
	v_lshlrev_b32_e32 v107, 16, v27
	v_and_b32_e32 v108, 0xffff0000, v27
	v_lshlrev_b32_e32 v109, 16, v28
	v_and_b32_e32 v110, 0xffff0000, v28
	v_lshlrev_b32_e32 v111, 16, v29
	v_and_b32_e32 v112, 0xffff0000, v29
	v_lshlrev_b32_e32 v54, 16, v25
	v_and_b32_e32 v55, 0xffff0000, v25
	v_lshlrev_b32_e32 v90, 16, v21
	v_and_b32_e32 v91, 0xffff0000, v21
	v_lshlrev_b32_e32 v92, 16, v24
	v_and_b32_e32 v93, 0xffff0000, v24
	v_lshlrev_b32_e32 v24, 16, v20
	v_and_b32_e32 v25, 0xffff0000, v20
	v_lshlrev_b32_e32 v20, 16, v23
	v_and_b32_e32 v21, 0xffff0000, v23
	v_lshlrev_b32_e32 v94, 16, v19
	v_and_b32_e32 v95, 0xffff0000, v19
	v_lshlrev_b32_e32 v96, 16, v22
	v_and_b32_e32 v97, 0xffff0000, v22
	v_lshlrev_b32_e32 v22, 16, v18
	v_and_b32_e32 v23, 0xffff0000, v18
	v_mov_b64_e32 v[26:27], v[34:35]
	v_mov_b64_e32 v[64:65], v[32:33]
	s_lshl_b32 s8, s8, 3
	v_mov_b64_e32 v[28:29], v[36:37]
	v_mov_b64_e32 v[62:63], v[30:31]
	s_lshl_b64 s[0:1], s[14:15], 11
	v_mul_f32_e32 v30, 0xbfb8aa3b, v89
	v_mul_f32_e32 v31, 0xbfb8aa3b, v98
	v_mul_f32_e32 v32, 0xbfb8aa3b, v99
	v_mul_f32_e32 v33, 0xbfb8aa3b, v100
	v_mul_f32_e32 v34, 0xbfb8aa3b, v101
	v_mul_f32_e32 v35, 0xbfb8aa3b, v102
	v_mul_f32_e32 v36, 0xbfb8aa3b, v103
	v_mul_f32_e32 v37, 0xbfb8aa3b, v104
	v_pk_add_f32 v[76:77], v[78:79], v[76:77]
	v_pk_add_f32 v[78:79], v[60:61], v[80:81]
	v_pk_add_f32 v[80:81], v[82:83], v[56:57]
	v_pk_add_f32 v[82:83], v[58:59], v[84:85]
	v_pk_add_f32 v[84:85], v[90:91], v[54:55]
	v_pk_add_f32 v[90:91], v[24:25], v[92:93]
	v_pk_add_f32 v[92:93], v[94:95], v[20:21]
	v_pk_add_f32 v[94:95], v[22:23], v[96:97]
	v_mov_b64_e32 v[18:19], v[46:47]
	v_mov_b64_e32 v[60:61], v[44:45]
	v_mov_b64_e32 v[22:23], v[38:39]
	s_add_i32 s8, s28, s8
	v_mul_f32_e32 v89, 0xbfb8aa3b, v105
	v_mul_f32_e32 v98, 0xbfb8aa3b, v106
	v_mul_f32_e32 v99, 0xbfb8aa3b, v107
	v_mul_f32_e32 v100, 0xbfb8aa3b, v108
	v_mul_f32_e32 v101, 0xbfb8aa3b, v109
	v_mul_f32_e32 v102, 0xbfb8aa3b, v110
	v_mul_f32_e32 v103, 0xbfb8aa3b, v111
	v_mul_f32_e32 v104, 0xbfb8aa3b, v112
	v_mov_b64_e32 v[56:57], v[52:53]
	v_mov_b64_e32 v[20:21], v[48:49]
	v_mov_b64_e32 v[58:59], v[42:43]
	v_mov_b64_e32 v[24:25], v[40:41]
	v_exp_f32_e32 v105, v30
	v_exp_f32_e32 v106, v31
	v_exp_f32_e32 v107, v32
	v_exp_f32_e32 v108, v33
	v_exp_f32_e32 v109, v34
	v_exp_f32_e32 v110, v35
	v_exp_f32_e32 v111, v36
	v_exp_f32_e32 v112, v37
	v_mov_b32_e32 v30, v80
	v_mov_b32_e32 v31, v76
	v_mov_b32_e32 v32, v81
	v_mov_b32_e32 v33, v77
	v_mov_b32_e32 v34, v82
	v_mov_b32_e32 v35, v78
	v_mov_b32_e32 v36, v83
	v_mov_b32_e32 v37, v79
	v_lshl_add_u64 v[96:97], v[74:75], 0, s[0:1]
	v_mov_b32_e32 v38, v92
	v_mov_b32_e32 v39, v84
	v_mov_b32_e32 v40, v93
	v_mov_b32_e32 v41, v85
	v_mov_b32_e32 v42, v94
	v_mov_b32_e32 v43, v90
	v_mov_b32_e32 v44, v95
	v_mov_b32_e32 v45, v91
	s_ashr_i32 s9, s8, 31
	v_mad_i64_i32 v[46:47], s[0:1], s8, v86, v[72:73]
	v_mov_b64_e32 v[54:55], v[50:51]
	v_pk_add_f32 v[48:49], v[30:31], v[32:33]
	v_pk_add_f32 v[50:51], v[34:35], v[36:37]
	v_pk_add_f32 v[38:39], v[38:39], v[40:41]
	v_pk_add_f32 v[40:41], v[42:43], v[44:45]
	s_lshl_b64 s[0:1], s[8:9], 11
	flat_load_dwordx4 v[30:33], v[46:47] nt
	flat_load_dwordx4 v[34:37], v[46:47] offset:1024 nt
	v_pk_add_f32 v[42:43], v[50:51], v[48:49]
	v_pk_add_f32 v[38:39], v[40:41], v[38:39]
	v_lshl_add_u64 v[40:41], v[68:69], 0, s[0:1]
	v_lshl_add_u64 v[46:47], v[70:71], 0, s[0:1]
	v_add_f32_e32 v113, v42, v43
	v_add_f32_e32 v114, v38, v39
	flat_load_dwordx4 v[42:45], v[40:41] nt
	s_nop 0
	flat_load_dwordx4 v[38:41], v[40:41] offset:1024 nt
	s_nop 0
	flat_load_dwordx4 v[50:53], v[46:47] nt
	s_nop 0
	flat_load_dwordx4 v[46:49], v[46:47] offset:1024 nt
	v_exp_f32_e32 v89, v89
	v_exp_f32_e32 v99, v99
	v_add_f32_dpp v113, v113, v113 quad_perm:[1,0,3,2] row_mask:0xf bank_mask:0xf bound_ctrl:1
	v_exp_f32_e32 v98, v98
	v_add_f32_e32 v106, 1.0, v106
	v_add_f32_e32 v89, 1.0, v89
	v_add_f32_dpp v114, v114, v114 quad_perm:[1,0,3,2] row_mask:0xf bank_mask:0xf bound_ctrl:1
	v_add_f32_dpp v122, v113, v113 quad_perm:[2,3,0,1] row_mask:0xf bank_mask:0xf bound_ctrl:1
	v_exp_f32_e32 v100, v100
	v_exp_f32_e32 v101, v101
	v_add_f32_e32 v116, 1.0, v99
	v_rcp_f32_e32 v99, v106
	v_rcp_f32_e32 v106, v89
	v_add_f32_dpp v89, v114, v114 quad_perm:[2,3,0,1] row_mask:0xf bank_mask:0xf bound_ctrl:1
	v_add_f32_dpp v114, v122, v122 row_half_mirror row_mask:0xf bank_mask:0xf bound_ctrl:1
	v_add_f32_e32 v107, 1.0, v107
	v_add_f32_dpp v89, v89, v89 row_half_mirror row_mask:0xf bank_mask:0xf bound_ctrl:1
	v_add_f32_dpp v114, v114, v114 row_mirror row_mask:0xf bank_mask:0xf bound_ctrl:1
	v_add_f32_e32 v108, 1.0, v108
	v_add_f32_dpp v89, v89, v89 row_mirror row_mask:0xf bank_mask:0xf bound_ctrl:1
	v_readlane_b32 s1, v114, 16
	v_readlane_b32 s9, v114, 48
	v_add_f32_e32 v115, 1.0, v98
	v_readlane_b32 s0, v114, 0
	v_readlane_b32 s8, v114, 32
	v_readlane_b32 s10, v89, 0
	v_readlane_b32 s11, v89, 16
	v_readlane_b32 s12, v89, 32
	v_readlane_b32 s13, v89, 48
	v_mov_b32_e32 v89, s1
	v_mov_b32_e32 v114, s9
	v_add_f32_e32 v117, 1.0, v100
	v_add_f32_e32 v118, 1.0, v101
	v_rcp_f32_e32 v100, v107
	v_rcp_f32_e32 v101, v108
	v_rcp_f32_e32 v107, v115
	v_rcp_f32_e32 v108, v116
	v_mov_b32_e32 v115, s11
	v_mov_b32_e32 v116, s13
	v_add_f32_e32 v89, s0, v89
	v_add_f32_e32 v114, s8, v114
	v_exp_f32_e32 v102, v102
	v_add_f32_e32 v115, s10, v115
	v_add_f32_e32 v116, s12, v116
	v_cndmask_b32_e64 v89, v89, v114, s[6:7]
	v_cndmask_b32_e64 v115, v115, v116, s[6:7]
	v_mul_f32_e32 v114, 0x3b800000, v89
	v_exp_f32_e32 v103, v103
	v_exp_f32_e32 v104, v104
	v_mul_f32_e32 v116, 0x3b800000, v115
	v_pk_add_f32 v[82:83], v[82:83], v[114:115] op_sel_hi:[1,0] neg_lo:[0,1] neg_hi:[0,1]
	v_add_f32_e32 v109, 1.0, v109
	v_pk_add_f32 v[80:81], v[80:81], v[114:115] op_sel_hi:[1,0] neg_lo:[0,1] neg_hi:[0,1]
	v_pk_add_f32 v[78:79], v[78:79], v[114:115] op_sel_hi:[1,0] neg_lo:[0,1] neg_hi:[0,1]
	v_pk_add_f32 v[76:77], v[76:77], v[114:115] op_sel_hi:[1,0] neg_lo:[0,1] neg_hi:[0,1]
	v_pk_add_f32 v[94:95], v[94:95], v[116:117] op_sel_hi:[1,0] neg_lo:[0,1] neg_hi:[0,1]
	v_pk_mul_f32 v[114:115], v[82:83], v[82:83]
	v_add_f32_e32 v119, 1.0, v102
	v_rcp_f32_e32 v102, v109
	v_rcp_f32_e32 v109, v117
	v_pk_add_f32 v[92:93], v[92:93], v[116:117] op_sel_hi:[1,0] neg_lo:[0,1] neg_hi:[0,1]
	v_pk_add_f32 v[90:91], v[90:91], v[116:117] op_sel_hi:[1,0] neg_lo:[0,1] neg_hi:[0,1]
	v_pk_add_f32 v[84:85], v[84:85], v[116:117] op_sel_hi:[1,0] neg_lo:[0,1] neg_hi:[0,1]
	v_pk_mul_f32 v[116:117], v[80:81], v[80:81]
	v_pk_mul_f32 v[122:123], v[94:95], v[94:95]
	v_add_f32_e32 v89, v114, v115
	v_add_f32_e32 v110, 1.0, v110
	v_add_f32_e32 v111, 1.0, v111
	v_pk_mul_f32 v[124:125], v[92:93], v[92:93]
	v_add_f32_e32 v114, v122, v123
	v_add_f32_e32 v89, v116, v89
	v_add_f32_e32 v120, 1.0, v103
	v_add_f32_e32 v121, 1.0, v104
	v_rcp_f32_e32 v103, v110
	v_rcp_f32_e32 v104, v111
	v_rcp_f32_e32 v110, v118
	v_rcp_f32_e32 v111, v119
	v_pk_mul_f32 v[118:119], v[78:79], v[78:79]
	v_add_f32_e32 v114, v124, v114
	v_add_f32_e32 v89, v117, v89
	v_add_f32_e32 v105, 1.0, v105
	v_add_f32_e32 v112, 1.0, v112
	v_pk_mul_f32 v[126:127], v[90:91], v[90:91]
	v_add_f32_e32 v114, v125, v114
	v_add_f32_e32 v89, v118, v89
	v_rcp_f32_e32 v98, v105
	v_rcp_f32_e32 v105, v112
	v_rcp_f32_e32 v112, v120
	v_rcp_f32_e32 v113, v121
	v_pk_mul_f32 v[120:121], v[76:77], v[76:77]
	v_add_f32_e32 v114, v126, v114
	v_add_f32_e32 v89, v119, v89
	v_pk_mul_f32 v[128:129], v[84:85], v[84:85]
	v_add_f32_e32 v114, v127, v114
	v_add_f32_e32 v89, v120, v89
	v_add_f32_e32 v114, v128, v114
	v_add_f32_e32 v89, v121, v89
	v_add_f32_e32 v114, v129, v114
	s_add_i32 s29, s29, 1
	v_add_f32_dpp v89, v89, v89 quad_perm:[1,0,3,2] row_mask:0xf bank_mask:0xf bound_ctrl:1
	v_add_f32_dpp v114, v114, v114 quad_perm:[1,0,3,2] row_mask:0xf bank_mask:0xf bound_ctrl:1
	s_add_i32 s14, s14, 8
	v_add_f32_dpp v89, v89, v89 quad_perm:[2,3,0,1] row_mask:0xf bank_mask:0xf bound_ctrl:1
	v_add_f32_dpp v114, v114, v114 quad_perm:[2,3,0,1] row_mask:0xf bank_mask:0xf bound_ctrl:1
	s_cmp_lg_u32 s29, 32
	v_add_f32_dpp v89, v89, v89 row_half_mirror row_mask:0xf bank_mask:0xf bound_ctrl:1
	v_add_f32_dpp v114, v114, v114 row_half_mirror row_mask:0xf bank_mask:0xf bound_ctrl:1
	s_nop 0
	v_add_f32_dpp v89, v89, v89 row_mirror row_mask:0xf bank_mask:0xf bound_ctrl:1
	v_add_f32_dpp v114, v114, v114 row_mirror row_mask:0xf bank_mask:0xf bound_ctrl:1
	v_readlane_b32 s1, v89, 16
	v_readlane_b32 s9, v89, 48
	v_readlane_b32 s0, v89, 0
	v_readlane_b32 s8, v89, 32
	v_readlane_b32 s10, v114, 0
	v_readlane_b32 s11, v114, 16
	v_readlane_b32 s12, v114, 32
	v_readlane_b32 s13, v114, 48
	v_mov_b32_e32 v89, s1
	v_mov_b32_e32 v114, s9
	v_mov_b32_e32 v115, s11
	v_mov_b32_e32 v116, s13
	v_add_f32_e32 v89, s0, v89
	v_add_f32_e32 v114, s8, v114
	v_add_f32_e32 v115, s10, v115
	v_add_f32_e32 v116, s12, v116
	v_cndmask_b32_e64 v89, v89, v114, s[6:7]
	v_cndmask_b32_e64 v114, v115, v116, s[6:7]
	v_fmamk_f32 v89, v89, 0x3b800000, v87
	v_fmamk_f32 v114, v114, 0x3b800000, v87
	v_mul_f32_e32 v115, 0x4f800000, v89
	v_cmp_gt_f32_e64 s[8:9], s26, v89
	v_mul_f32_e32 v116, 0x4f800000, v114
	v_cmp_gt_f32_e32 vcc, s26, v114
	v_cndmask_b32_e64 v89, v89, v115, s[8:9]
	v_sqrt_f32_e32 v115, v89
	v_cndmask_b32_e32 v114, v114, v116, vcc
	v_sqrt_f32_e32 v116, v114
	v_add_u32_e32 v117, -1, v115
	v_add_u32_e32 v118, 1, v115
	v_add_u32_e32 v119, -1, v116
	v_fma_f32 v121, -v117, v115, v89
	v_add_u32_e32 v120, 1, v116
	v_fma_f32 v122, -v118, v115, v89
	v_fma_f32 v123, -v119, v116, v114
	v_cmp_ge_f32_e64 s[10:11], 0, v121
	v_fma_f32 v124, -v120, v116, v114
	v_cmp_lt_f32_e64 s[12:13], 0, v122
	v_cndmask_b32_e64 v115, v115, v117, s[10:11]
	v_cmp_ge_f32_e64 s[10:11], 0, v123
	v_cndmask_b32_e64 v115, v115, v118, s[12:13]
	v_mul_f32_e32 v117, 0x37800000, v115
	v_cndmask_b32_e64 v116, v116, v119, s[10:11]
	v_cmp_lt_f32_e64 s[10:11], 0, v124
	v_cndmask_b32_e64 v115, v115, v117, s[8:9]
	v_cmp_class_f32_e64 s[8:9], v89, v88
	v_cndmask_b32_e64 v116, v116, v120, s[10:11]
	v_mul_f32_e32 v118, 0x37800000, v116
	v_cndmask_b32_e32 v116, v116, v118, vcc
	v_cmp_class_f32_e32 vcc, v114, v88
	v_cndmask_b32_e64 v89, v115, v89, s[8:9]
	s_nop 0
	v_cndmask_b32_e32 v115, v116, v114, vcc
	v_div_scale_f32 v114, s[0:1], v89, v89, 1.0
	v_div_scale_f32 v117, s[0:1], v115, v115, 1.0
	v_rcp_f32_e32 v119, v114
	v_rcp_f32_e32 v120, v117
	v_div_scale_f32 v116, vcc, 1.0, v89, 1.0
	v_fma_f32 v121, -v114, v119, 1.0
	v_fma_f32 v122, -v117, v120, 1.0
	v_fmac_f32_e32 v119, v121, v119
	v_div_scale_f32 v118, s[8:9], 1.0, v115, 1.0
	v_fmac_f32_e32 v120, v122, v120
	v_mul_f32_e32 v121, v116, v119
	v_mul_f32_e32 v122, v118, v120
	v_fma_f32 v123, -v114, v121, v116
	v_fma_f32 v124, -v117, v122, v118
	v_fmac_f32_e32 v121, v123, v119
	v_fmac_f32_e32 v122, v124, v120
	v_fma_f32 v114, -v114, v121, v116
	v_fma_f32 v116, -v117, v122, v118
	v_div_fmas_f32 v114, v114, v119, v121
	s_mov_b64 vcc, s[8:9]
	v_div_fixup_f32 v114, v114, v89, 1.0
	v_div_fmas_f32 v89, v116, v120, v122
	v_pk_mul_f32 v[82:83], v[82:83], v[114:115] op_sel_hi:[1,0]
	v_pk_mul_f32 v[80:81], v[80:81], v[114:115] op_sel_hi:[1,0]
	v_pk_mul_f32 v[78:79], v[78:79], v[114:115] op_sel_hi:[1,0]
	v_pk_mul_f32 v[76:77], v[76:77], v[114:115] op_sel_hi:[1,0]
	v_div_fixup_f32 v114, v89, v115, 1.0
	v_pk_mul_f32 v[82:83], v[2:3], v[82:83]
	v_pk_mul_f32 v[80:81], v[4:5], v[80:81]
	v_pk_mul_f32 v[78:79], v[6:7], v[78:79]
	v_pk_mul_f32 v[76:77], v[8:9], v[76:77]
	v_pk_mul_f32 v[94:95], v[94:95], v[114:115] op_sel_hi:[1,0]
	v_pk_mul_f32 v[92:93], v[92:93], v[114:115] op_sel_hi:[1,0]
	v_pk_mul_f32 v[90:91], v[90:91], v[114:115] op_sel_hi:[1,0]
	v_pk_mul_f32 v[84:85], v[84:85], v[114:115] op_sel_hi:[1,0]
	v_pk_mul_f32 v[82:83], v[98:99], v[82:83]
	v_pk_mul_f32 v[80:81], v[100:101], v[80:81]
	v_pk_mul_f32 v[78:79], v[102:103], v[78:79]
	v_pk_mul_f32 v[98:99], v[104:105], v[76:77]
	v_pk_mul_f32 v[94:95], v[10:11], v[94:95]
	v_pk_mul_f32 v[92:93], v[12:13], v[92:93]
	v_pk_mul_f32 v[90:91], v[14:15], v[90:91]
	v_pk_mul_f32 v[84:85], v[16:17], v[84:85]
	v_cvt_pk_bf16_f32 v76, v82, v83
	v_cvt_pk_bf16_f32 v77, v80, v81
	v_cvt_pk_bf16_f32 v78, v78, v79
	v_cvt_pk_bf16_f32 v79, v98, v99
	v_pk_mul_f32 v[80:81], v[106:107], v[94:95]
	v_pk_mul_f32 v[82:83], v[108:109], v[92:93]
	v_pk_mul_f32 v[90:91], v[110:111], v[90:91]
	v_pk_mul_f32 v[84:85], v[112:113], v[84:85]
	flat_store_dwordx4 v[96:97], v[76:79]
	s_nop 1
	v_cvt_pk_bf16_f32 v76, v80, v81
	v_cvt_pk_bf16_f32 v77, v82, v83
	v_cvt_pk_bf16_f32 v78, v90, v91
	v_cvt_pk_bf16_f32 v79, v84, v85
	flat_store_dwordx4 v[96:97], v[76:79] offset:1024
	s_cbranch_scc1 .LBB0_427
	s_add_i32 s27, s27, s74
	s_add_i32 s4, s4, s5
	s_cmpk_gt_i32 s27, 0xff
	s_cbranch_scc0 .LBB0_426

.LBB0_434:
	ds_read_b128 v[146:149], v152
	ds_read_b128 v[156:159], v152 offset:1024
	ds_read_b128 v[160:163], v152 offset:2048
	ds_read_b128 v[164:167], v152 offset:3072
	s_add_u32 s0, s36, 0xfffc0080
	s_addc_u32 s1, s37, -1
	s_cmp_eq_u32 s69, 12
	s_cselect_b32 s41, s60, s1
	s_cselect_b32 s40, s61, s0
	s_cselect_b32 s39, s62, s67
	s_cselect_b32 s38, s63, s66
	s_mov_b32 m0, s50
	v_lshl_add_u64 v[200:201], s[36:37], 0, v[144:145]
	ds_read_b128 v[168:171], v153
	ds_read_b128 v[172:175], v153 offset:1024
	ds_read_b128 v[176:179], v153 offset:2048
	ds_read_b128 v[180:183], v153 offset:3072
	ds_read_b128 v[184:187], v153 offset:4096
	ds_read_b128 v[188:191], v153 offset:5120
	ds_read_b128 v[192:195], v153 offset:6144
	ds_read_b128 v[196:199], v153 offset:7168
	global_load_lds_dwordx4 v[200:201], off
	v_lshl_add_u64 v[200:201], s[36:37], 0, v[142:143]
	s_mov_b32 m0, s51
	s_nop 0
	global_load_lds_dwordx4 v[200:201], off
	s_waitcnt lgkmcnt(8)
	s_waitcnt vmcnt(10)
	s_barrier
	s_waitcnt lgkmcnt(0)
	s_setprio 1
	s_waitcnt lgkmcnt(0)
	v_mfma_f32_16x16x32_bf16 v[126:129], v[146:149], v[168:171], v[126:129]
	v_mfma_f32_16x16x32_bf16 v[122:125], v[160:163], v[168:171], v[122:125]
	v_mfma_f32_16x16x32_bf16 v[114:117], v[146:149], v[176:179], v[114:117]
	v_mfma_f32_16x16x32_bf16 v[106:109], v[160:163], v[176:179], v[106:109]
	v_mfma_f32_16x16x32_bf16 v[98:101], v[146:149], v[184:187], v[98:101]
	v_mfma_f32_16x16x32_bf16 v[90:93], v[160:163], v[184:187], v[90:93]
	v_mfma_f32_16x16x32_bf16 v[82:85], v[146:149], v[192:195], v[82:85]
	v_mfma_f32_16x16x32_bf16 v[74:77], v[160:163], v[192:195], v[74:77]
	v_mfma_f32_16x16x32_bf16 v[126:129], v[156:159], v[172:175], v[126:129]
	v_mfma_f32_16x16x32_bf16 v[122:125], v[164:167], v[172:175], v[122:125]
	v_mfma_f32_16x16x32_bf16 v[114:117], v[156:159], v[180:183], v[114:117]
	v_mfma_f32_16x16x32_bf16 v[106:109], v[164:167], v[180:183], v[106:109]
	v_mfma_f32_16x16x32_bf16 v[98:101], v[156:159], v[188:191], v[98:101]
	v_mfma_f32_16x16x32_bf16 v[90:93], v[164:167], v[188:191], v[90:93]
	v_mfma_f32_16x16x32_bf16 v[82:85], v[156:159], v[196:199], v[82:85]
	v_mfma_f32_16x16x32_bf16 v[74:77], v[164:167], v[196:199], v[74:77]
	s_setprio 0
	s_barrier
	s_mov_b32 m0, s52
	v_lshl_add_u64 v[216:217], s[38:39], 0, v[138:139]
	ds_read_b128 v[200:203], v154
	ds_read_b128 v[204:207], v154 offset:1024
	ds_read_b128 v[208:211], v154 offset:2048
	ds_read_b128 v[212:215], v154 offset:3072
	global_load_lds_dwordx4 v[216:217], off
	v_lshl_add_u64 v[218:219], s[38:39], 0, v[134:135]
	s_mov_b32 m0, s53
	s_nop 0
	global_load_lds_dwordx4 v[218:219], off
	s_waitcnt vmcnt(10)
	s_barrier
	s_waitcnt lgkmcnt(0)
	s_setprio 1
	s_waitcnt lgkmcnt(0)
	v_mfma_f32_16x16x32_bf16 v[118:121], v[200:203], v[168:171], v[118:121]
	v_mfma_f32_16x16x32_bf16 v[110:113], v[208:211], v[168:171], v[110:113]
	v_mfma_f32_16x16x32_bf16 v[102:105], v[200:203], v[176:179], v[102:105]
	v_mfma_f32_16x16x32_bf16 v[94:97], v[208:211], v[176:179], v[94:97]
	v_mfma_f32_16x16x32_bf16 v[86:89], v[200:203], v[184:187], v[86:89]
	v_mfma_f32_16x16x32_bf16 v[78:81], v[208:211], v[184:187], v[78:81]
	v_mfma_f32_16x16x32_bf16 v[70:73], v[200:203], v[192:195], v[70:73]
	v_mfma_f32_16x16x32_bf16 v[66:69], v[208:211], v[192:195], v[66:69]
	v_mfma_f32_16x16x32_bf16 v[118:121], v[204:207], v[172:175], v[118:121]
	v_mfma_f32_16x16x32_bf16 v[110:113], v[212:215], v[172:175], v[110:113]
	v_mfma_f32_16x16x32_bf16 v[102:105], v[204:207], v[180:183], v[102:105]
	v_mfma_f32_16x16x32_bf16 v[94:97], v[212:215], v[180:183], v[94:97]
	v_mfma_f32_16x16x32_bf16 v[86:89], v[204:207], v[188:191], v[86:89]
	v_mfma_f32_16x16x32_bf16 v[78:81], v[212:215], v[188:191], v[78:81]
	v_mfma_f32_16x16x32_bf16 v[70:73], v[204:207], v[196:199], v[70:73]
	v_mfma_f32_16x16x32_bf16 v[66:69], v[212:215], v[196:199], v[66:69]
	s_setprio 0
	s_mov_b32 m0, s6
	v_lshl_add_u64 v[220:221], s[40:41], 0, v[140:141]
	s_barrier
	ds_read_b128 v[168:171], v153 offset:16384
	ds_read_b128 v[172:175], v153 offset:17408
	ds_read_b128 v[176:179], v153 offset:18432
	ds_read_b128 v[180:183], v153 offset:19456
	ds_read_b128 v[184:187], v153 offset:20480
	ds_read_b128 v[188:191], v153 offset:21504
	ds_read_b128 v[192:195], v153 offset:22528
	ds_read_b128 v[196:199], v153 offset:23552
	global_load_lds_dwordx4 v[220:221], off
	v_lshl_add_u64 v[222:223], s[40:41], 0, v[136:137]
	s_mov_b32 m0, s7
	s_nop 0
	global_load_lds_dwordx4 v[222:223], off
	s_waitcnt vmcnt(10)
	s_barrier
	s_waitcnt lgkmcnt(0)
	s_setprio 1
	s_waitcnt lgkmcnt(0)
	v_mfma_f32_16x16x32_bf16 v[62:65], v[146:149], v[168:171], v[62:65]
	v_mfma_f32_16x16x32_bf16 v[58:61], v[160:163], v[168:171], v[58:61]
	v_mfma_f32_16x16x32_bf16 v[50:53], v[146:149], v[176:179], v[50:53]
	v_mfma_f32_16x16x32_bf16 v[42:45], v[160:163], v[176:179], v[42:45]
	v_mfma_f32_16x16x32_bf16 v[34:37], v[146:149], v[184:187], v[34:37]
	v_mfma_f32_16x16x32_bf16 v[26:29], v[160:163], v[184:187], v[26:29]
	v_mfma_f32_16x16x32_bf16 v[18:21], v[146:149], v[192:195], v[18:21]
	v_mfma_f32_16x16x32_bf16 v[10:13], v[160:163], v[192:195], v[10:13]
	v_mfma_f32_16x16x32_bf16 v[62:65], v[156:159], v[172:175], v[62:65]
	v_mfma_f32_16x16x32_bf16 v[58:61], v[164:167], v[172:175], v[58:61]
	v_mfma_f32_16x16x32_bf16 v[50:53], v[156:159], v[180:183], v[50:53]
	v_mfma_f32_16x16x32_bf16 v[42:45], v[164:167], v[180:183], v[42:45]
	v_mfma_f32_16x16x32_bf16 v[34:37], v[156:159], v[188:191], v[34:37]
	v_mfma_f32_16x16x32_bf16 v[26:29], v[164:167], v[188:191], v[26:29]
	v_mfma_f32_16x16x32_bf16 v[18:21], v[156:159], v[196:199], v[18:21]
	v_mfma_f32_16x16x32_bf16 v[10:13], v[164:167], v[196:199], v[10:13]
	s_setprio 0
	s_barrier
	s_add_u32 s0, s38, 0x40000
	s_addc_u32 s1, s39, 0
	s_mov_b32 m0, s54
	v_lshl_add_u64 v[146:147], s[0:1], 0, v[138:139]
	global_load_lds_dwordx4 v[146:147], off
	v_lshl_add_u64 v[146:147], s[0:1], 0, v[134:135]
	s_add_i32 m0, s54, 0x2000
	s_nop 0
	global_load_lds_dwordx4 v[146:147], off
	s_waitcnt vmcnt(10)
	s_barrier
	s_setprio 1
	v_mfma_f32_16x16x32_bf16 v[54:57], v[200:203], v[168:171], v[54:57]
	v_mfma_f32_16x16x32_bf16 v[46:49], v[208:211], v[168:171], v[46:49]
	v_mfma_f32_16x16x32_bf16 v[38:41], v[200:203], v[176:179], v[38:41]
	v_mfma_f32_16x16x32_bf16 v[30:33], v[208:211], v[176:179], v[30:33]
	v_mfma_f32_16x16x32_bf16 v[22:25], v[200:203], v[184:187], v[22:25]
	v_mfma_f32_16x16x32_bf16 v[14:17], v[208:211], v[184:187], v[14:17]
	v_mfma_f32_16x16x32_bf16 v[6:9], v[200:203], v[192:195], v[6:9]
	v_mfma_f32_16x16x32_bf16 v[2:5], v[208:211], v[192:195], v[2:5]
	v_mfma_f32_16x16x32_bf16 v[54:57], v[204:207], v[172:175], v[54:57]
	v_mfma_f32_16x16x32_bf16 v[46:49], v[212:215], v[172:175], v[46:49]
	v_mfma_f32_16x16x32_bf16 v[38:41], v[204:207], v[180:183], v[38:41]
	v_mfma_f32_16x16x32_bf16 v[30:33], v[212:215], v[180:183], v[30:33]
	v_mfma_f32_16x16x32_bf16 v[22:25], v[204:207], v[188:191], v[22:25]
	v_mfma_f32_16x16x32_bf16 v[14:17], v[212:215], v[188:191], v[14:17]
	v_mfma_f32_16x16x32_bf16 v[6:9], v[204:207], v[196:199], v[6:9]
	v_mfma_f32_16x16x32_bf16 v[2:5], v[212:215], v[196:199], v[2:5]
	s_setprio 0
	s_add_i32 s70, 0, 0x18000
	v_add_u32_e32 v155, s70, v151
	s_barrier
	ds_read_b128 v[146:149], v155
	ds_read_b128 v[156:159], v155 offset:1024
	ds_read_b128 v[160:163], v155 offset:2048
	ds_read_b128 v[164:167], v155 offset:3072
	s_add_u32 s0, s40, 0x40000
	s_addc_u32 s1, s41, 0
	s_mov_b32 m0, s29
	v_lshl_add_u64 v[200:201], s[0:1], 0, v[140:141]
	ds_read_b128 v[168:171], v153 offset:32768
	ds_read_b128 v[172:175], v153 offset:33792
	ds_read_b128 v[176:179], v153 offset:34816
	ds_read_b128 v[180:183], v153 offset:35840
	ds_read_b128 v[184:187], v153 offset:36864
	ds_read_b128 v[188:191], v153 offset:37888
	ds_read_b128 v[192:195], v153 offset:38912
	ds_read_b128 v[196:199], v153 offset:39936
	global_load_lds_dwordx4 v[200:201], off
	v_lshl_add_u64 v[200:201], s[0:1], 0, v[136:137]
	s_mov_b32 m0, s42
	s_nop 0
	global_load_lds_dwordx4 v[200:201], off
	s_waitcnt lgkmcnt(8)
	s_waitcnt vmcnt(10)
	s_barrier
	s_waitcnt lgkmcnt(0)
	s_setprio 1
	s_waitcnt lgkmcnt(0)
	v_mfma_f32_16x16x32_bf16 v[126:129], v[146:149], v[168:171], v[126:129]
	v_mfma_f32_16x16x32_bf16 v[122:125], v[160:163], v[168:171], v[122:125]
	v_mfma_f32_16x16x32_bf16 v[114:117], v[146:149], v[176:179], v[114:117]
	v_mfma_f32_16x16x32_bf16 v[106:109], v[160:163], v[176:179], v[106:109]
	v_mfma_f32_16x16x32_bf16 v[98:101], v[146:149], v[184:187], v[98:101]
	v_mfma_f32_16x16x32_bf16 v[90:93], v[160:163], v[184:187], v[90:93]
	v_mfma_f32_16x16x32_bf16 v[82:85], v[146:149], v[192:195], v[82:85]
	v_mfma_f32_16x16x32_bf16 v[74:77], v[160:163], v[192:195], v[74:77]
	v_mfma_f32_16x16x32_bf16 v[126:129], v[156:159], v[172:175], v[126:129]
	v_mfma_f32_16x16x32_bf16 v[122:125], v[164:167], v[172:175], v[122:125]
	v_mfma_f32_16x16x32_bf16 v[114:117], v[156:159], v[180:183], v[114:117]
	v_mfma_f32_16x16x32_bf16 v[106:109], v[164:167], v[180:183], v[106:109]
	v_mfma_f32_16x16x32_bf16 v[98:101], v[156:159], v[188:191], v[98:101]
	v_mfma_f32_16x16x32_bf16 v[90:93], v[164:167], v[188:191], v[90:93]
	v_mfma_f32_16x16x32_bf16 v[82:85], v[156:159], v[196:199], v[82:85]
	v_mfma_f32_16x16x32_bf16 v[74:77], v[164:167], v[196:199], v[74:77]
	s_setprio 0
	s_barrier
	s_add_i32 s40, 0, 0x1c000
	s_add_i32 s0, s70, s5
	v_add_u32_e32 v155, s40, v151
	v_lshl_add_u64 v[216:217], v[216:217], 0, s[26:27]
	s_mov_b32 m0, s0
	ds_read_b128 v[200:203], v155
	ds_read_b128 v[204:207], v155 offset:1024
	ds_read_b128 v[208:211], v155 offset:2048
	ds_read_b128 v[212:215], v155 offset:3072
	global_load_lds_dwordx4 v[216:217], off
	v_lshl_add_u64 v[216:217], v[218:219], 0, s[26:27]
	s_add_i32 m0, s0, 0x2000
	s_nop 0
	global_load_lds_dwordx4 v[216:217], off
	s_waitcnt vmcnt(10)
	s_barrier
	s_waitcnt lgkmcnt(0)
	s_setprio 1
	s_waitcnt lgkmcnt(0)
	v_mfma_f32_16x16x32_bf16 v[118:121], v[200:203], v[168:171], v[118:121]
	v_mfma_f32_16x16x32_bf16 v[110:113], v[208:211], v[168:171], v[110:113]
	v_mfma_f32_16x16x32_bf16 v[102:105], v[200:203], v[176:179], v[102:105]
	v_mfma_f32_16x16x32_bf16 v[94:97], v[208:211], v[176:179], v[94:97]
	v_mfma_f32_16x16x32_bf16 v[86:89], v[200:203], v[184:187], v[86:89]
	v_mfma_f32_16x16x32_bf16 v[78:81], v[208:211], v[184:187], v[78:81]
	v_mfma_f32_16x16x32_bf16 v[70:73], v[200:203], v[192:195], v[70:73]
	v_mfma_f32_16x16x32_bf16 v[66:69], v[208:211], v[192:195], v[66:69]
	v_mfma_f32_16x16x32_bf16 v[118:121], v[204:207], v[172:175], v[118:121]
	v_mfma_f32_16x16x32_bf16 v[110:113], v[212:215], v[172:175], v[110:113]
	v_mfma_f32_16x16x32_bf16 v[102:105], v[204:207], v[180:183], v[102:105]
	v_mfma_f32_16x16x32_bf16 v[94:97], v[212:215], v[180:183], v[94:97]
	v_mfma_f32_16x16x32_bf16 v[86:89], v[204:207], v[188:191], v[86:89]
	v_mfma_f32_16x16x32_bf16 v[78:81], v[212:215], v[188:191], v[78:81]
	v_mfma_f32_16x16x32_bf16 v[70:73], v[204:207], v[196:199], v[70:73]
	v_mfma_f32_16x16x32_bf16 v[66:69], v[212:215], v[196:199], v[66:69]
	s_setprio 0
	s_mov_b32 m0, s46
	v_lshl_add_u64 v[216:217], v[220:221], 0, s[26:27]
	s_barrier
	ds_read_b128 v[168:171], v153 offset:49152
	ds_read_b128 v[172:175], v153 offset:50176
	ds_read_b128 v[176:179], v153 offset:51200
	ds_read_b128 v[180:183], v153 offset:52224
	ds_read_b128 v[184:187], v153 offset:53248
	ds_read_b128 v[188:191], v153 offset:54272
	ds_read_b128 v[192:195], v153 offset:55296
	ds_read_b128 v[196:199], v153 offset:56320
	global_load_lds_dwordx4 v[216:217], off
	v_lshl_add_u64 v[216:217], v[222:223], 0, s[26:27]
	s_mov_b32 m0, s47
	s_nop 0
	global_load_lds_dwordx4 v[216:217], off
	s_waitcnt vmcnt(10)
	s_barrier
	s_waitcnt lgkmcnt(0)
	s_setprio 1
	s_waitcnt lgkmcnt(0)
	v_mfma_f32_16x16x32_bf16 v[62:65], v[146:149], v[168:171], v[62:65]
	v_mfma_f32_16x16x32_bf16 v[58:61], v[160:163], v[168:171], v[58:61]
	v_mfma_f32_16x16x32_bf16 v[50:53], v[146:149], v[176:179], v[50:53]
	v_mfma_f32_16x16x32_bf16 v[42:45], v[160:163], v[176:179], v[42:45]
	v_mfma_f32_16x16x32_bf16 v[34:37], v[146:149], v[184:187], v[34:37]
	v_mfma_f32_16x16x32_bf16 v[26:29], v[160:163], v[184:187], v[26:29]
	v_mfma_f32_16x16x32_bf16 v[18:21], v[146:149], v[192:195], v[18:21]
	v_mfma_f32_16x16x32_bf16 v[10:13], v[160:163], v[192:195], v[10:13]
	v_mfma_f32_16x16x32_bf16 v[62:65], v[156:159], v[172:175], v[62:65]
	v_mfma_f32_16x16x32_bf16 v[58:61], v[164:167], v[172:175], v[58:61]
	v_mfma_f32_16x16x32_bf16 v[50:53], v[156:159], v[180:183], v[50:53]
	v_mfma_f32_16x16x32_bf16 v[42:45], v[164:167], v[180:183], v[42:45]
	v_mfma_f32_16x16x32_bf16 v[34:37], v[156:159], v[188:191], v[34:37]
	v_mfma_f32_16x16x32_bf16 v[26:29], v[164:167], v[188:191], v[26:29]
	v_mfma_f32_16x16x32_bf16 v[18:21], v[156:159], v[196:199], v[18:21]
	v_mfma_f32_16x16x32_bf16 v[10:13], v[164:167], v[196:199], v[10:13]
	s_setprio 0
	s_barrier
	s_add_u32 s0, s38, 0x40080
	s_addc_u32 s1, s39, 0
	s_add_i32 s38, s40, s5
	v_lshl_add_u64 v[146:147], s[0:1], 0, v[138:139]
	s_mov_b32 m0, s38
	s_nop 0
	global_load_lds_dwordx4 v[146:147], off
	v_lshl_add_u64 v[146:147], s[0:1], 0, v[134:135]
	s_add_i32 m0, s38, 0x2000
	s_nop 0
	global_load_lds_dwordx4 v[146:147], off
	s_waitcnt vmcnt(10)
	s_barrier
	s_setprio 1
	v_mfma_f32_16x16x32_bf16 v[54:57], v[200:203], v[168:171], v[54:57]
	v_mfma_f32_16x16x32_bf16 v[46:49], v[208:211], v[168:171], v[46:49]
	v_mfma_f32_16x16x32_bf16 v[38:41], v[200:203], v[176:179], v[38:41]
	v_mfma_f32_16x16x32_bf16 v[30:33], v[208:211], v[176:179], v[30:33]
	v_mfma_f32_16x16x32_bf16 v[22:25], v[200:203], v[184:187], v[22:25]
	v_mfma_f32_16x16x32_bf16 v[14:17], v[208:211], v[184:187], v[14:17]
	v_mfma_f32_16x16x32_bf16 v[6:9], v[200:203], v[192:195], v[6:9]
	v_mfma_f32_16x16x32_bf16 v[2:5], v[208:211], v[192:195], v[2:5]
	v_mfma_f32_16x16x32_bf16 v[54:57], v[204:207], v[172:175], v[54:57]
	v_mfma_f32_16x16x32_bf16 v[46:49], v[212:215], v[172:175], v[46:49]
	v_mfma_f32_16x16x32_bf16 v[38:41], v[204:207], v[180:183], v[38:41]
	v_mfma_f32_16x16x32_bf16 v[30:33], v[212:215], v[180:183], v[30:33]
	v_mfma_f32_16x16x32_bf16 v[22:25], v[204:207], v[188:191], v[22:25]
	v_mfma_f32_16x16x32_bf16 v[14:17], v[212:215], v[188:191], v[14:17]
	v_mfma_f32_16x16x32_bf16 v[6:9], v[204:207], v[196:199], v[6:9]
	v_mfma_f32_16x16x32_bf16 v[2:5], v[212:215], v[196:199], v[2:5]
	s_setprio 0
	s_add_i32 s69, s69, 2
	s_add_u32 s66, s66, 0x100
	s_addc_u32 s67, s67, 0
	s_add_u32 s36, s36, 0x100
	s_addc_u32 s37, s37, 0
	s_cmp_gt_u32 s69, 13
	s_barrier
	s_cbranch_scc0 .LBB0_434
	v_mov_b32_e32 v147, v131
	v_mov_b32_e32 v146, v133
	s_lshl_b32 s0, s58, 8
	s_or_b32 s0, s0, s45
	v_lshl_add_u32 v146, v146, 3, s0
	s_lshl_b32 s0, s59, 8
	s_add_i32 s0, s0, s44
	v_add_u32_e32 v155, s0, v147
	v_mov_b32_e32 v148, v155
	v_ashrrev_i32_e32 v147, 31, v146
	v_ashrrev_i32_e32 v149, 31, v148
	v_lshlrev_b64 v[148:149], 10, v[148:149]
	v_lshl_add_u64 v[148:149], v[148:149], 0, v[146:147]
	v_lshlrev_b64 v[148:149], 1, v[148:149]
	v_lshl_add_u64 v[176:177], s[10:11], 0, v[148:149]
	flat_load_dwordx4 v[156:159], v[176:177] nt
	flat_load_dwordx4 v[160:163], v[176:177] offset:256 nt
	v_add_co_u32_e32 v168, vcc, s49, v176
	v_lshl_add_u64 v[148:149], s[12:13], 0, v[148:149]
	s_nop 0
	v_addc_co_u32_e32 v169, vcc, 0, v177, vcc
	flat_load_dwordx4 v[164:167], v[168:169] nt
	s_nop 0
	flat_load_dwordx4 v[168:171], v[168:169] offset:256 nt
	v_add_co_u32_e32 v178, vcc, s43, v176
	s_mov_b32 s58, s57
	s_nop 0
	v_addc_co_u32_e32 v179, vcc, 0, v177, vcc
	flat_load_dwordx4 v[172:175], v[178:179] nt
	v_add_co_u32_e32 v184, vcc, s48, v176
	s_mov_b32 s59, s56
	s_nop 0
	v_addc_co_u32_e32 v185, vcc, 0, v177, vcc
	flat_load_dwordx4 v[176:179], v[178:179] offset:256 nt
	s_nop 0
	flat_load_dwordx4 v[180:183], v[184:185] nt
	s_nop 0
	flat_load_dwordx4 v[184:187], v[184:185] offset:256 nt
	v_add_co_u32_e32 v188, vcc, s49, v148
	s_waitcnt vmcnt(0) lgkmcnt(0)
	v_lshlrev_b32_e32 v190, 16, v156
	v_and_b32_e32 v191, 0xffff0000, v156
	v_lshlrev_b32_e32 v156, 16, v157
	v_and_b32_e32 v157, 0xffff0000, v157
	v_lshlrev_b32_e32 v192, 16, v158
	v_and_b32_e32 v193, 0xffff0000, v158
	v_lshlrev_b32_e32 v194, 16, v160
	v_and_b32_e32 v195, 0xffff0000, v160
	v_lshlrev_b32_e32 v160, 16, v161
	v_and_b32_e32 v161, 0xffff0000, v161
	v_lshlrev_b32_e32 v196, 16, v162
	v_and_b32_e32 v197, 0xffff0000, v162
	v_lshlrev_b32_e32 v162, 16, v163
	v_and_b32_e32 v163, 0xffff0000, v163
	v_lshlrev_b32_e32 v158, 16, v159
	v_and_b32_e32 v159, 0xffff0000, v159
	v_pk_fma_f32 v[128:129], v[156:157], s[28:29], v[128:129] op_sel_hi:[1,0,1]
	v_pk_fma_f32 v[122:123], v[192:193], s[28:29], v[122:123] op_sel_hi:[1,0,1]
	v_pk_fma_f32 v[120:121], v[160:161], s[28:29], v[120:121] op_sel_hi:[1,0,1]
	v_pk_fma_f32 v[156:157], v[162:163], s[28:29], v[112:113] op_sel_hi:[1,0,1]
	v_lshlrev_b32_e32 v160, 16, v164
	v_and_b32_e32 v161, 0xffff0000, v164
	v_lshlrev_b32_e32 v162, 16, v165
	v_and_b32_e32 v163, 0xffff0000, v165
	v_lshlrev_b32_e32 v164, 16, v166
	v_and_b32_e32 v165, 0xffff0000, v166
	v_lshlrev_b32_e32 v166, 16, v167
	v_and_b32_e32 v167, 0xffff0000, v167
	v_pk_fma_f32 v[126:127], v[190:191], s[28:29], v[126:127] op_sel_hi:[1,0,1]
	v_pk_fma_f32 v[124:125], v[158:159], s[28:29], v[124:125] op_sel_hi:[1,0,1]
	v_cvt_pk_bf16_f32 v112, v122, v123
	v_pk_fma_f32 v[116:117], v[162:163], s[28:29], v[116:117] op_sel_hi:[1,0,1]
	v_pk_fma_f32 v[114:115], v[160:161], s[28:29], v[114:115] op_sel_hi:[1,0,1]
	v_pk_fma_f32 v[122:123], v[166:167], s[28:29], v[108:109] op_sel_hi:[1,0,1]
	v_pk_fma_f32 v[108:109], v[164:165], s[28:29], v[106:107] op_sel_hi:[1,0,1]
	v_addc_co_u32_e32 v189, vcc, 0, v149, vcc
	v_pk_fma_f32 v[118:119], v[194:195], s[28:29], v[118:119] op_sel_hi:[1,0,1]
	v_pk_fma_f32 v[158:159], v[196:197], s[28:29], v[110:111] op_sel_hi:[1,0,1]
	v_cvt_pk_bf16_f32 v110, v126, v127
	v_cvt_pk_bf16_f32 v111, v128, v129
	v_cvt_pk_bf16_f32 v113, v124, v125
	v_cvt_pk_bf16_f32 v106, v114, v115
	v_cvt_pk_bf16_f32 v107, v116, v117
	v_cvt_pk_bf16_f32 v108, v108, v109
	v_cvt_pk_bf16_f32 v109, v122, v123
	v_lshlrev_b32_e32 v190, 16, v168
	v_cvt_pk_bf16_f32 v118, v118, v119
	v_cvt_pk_bf16_f32 v119, v120, v121
	v_cvt_pk_bf16_f32 v120, v158, v159
	v_cvt_pk_bf16_f32 v121, v156, v157
	flat_store_dwordx4 v[148:149], v[110:113]
	flat_store_dwordx4 v[148:149], v[118:121] offset:256
	flat_store_dwordx4 v[188:189], v[106:109]
	v_and_b32_e32 v191, 0xffff0000, v168
	v_lshlrev_b32_e32 v110, 16, v171
	v_lshlrev_b32_e32 v106, 16, v169
	v_and_b32_e32 v107, 0xffff0000, v169
	v_lshlrev_b32_e32 v108, 16, v170
	v_and_b32_e32 v109, 0xffff0000, v170
	v_and_b32_e32 v111, 0xffff0000, v171
	v_pk_fma_f32 v[104:105], v[106:107], s[28:29], v[104:105] op_sel_hi:[1,0,1]
	v_pk_fma_f32 v[102:103], v[190:191], s[28:29], v[102:103] op_sel_hi:[1,0,1]
	v_pk_fma_f32 v[106:107], v[110:111], s[28:29], v[96:97] op_sel_hi:[1,0,1]
	v_pk_fma_f32 v[96:97], v[108:109], s[28:29], v[94:95] op_sel_hi:[1,0,1]
	v_cvt_pk_bf16_f32 v94, v102, v103
	v_cvt_pk_bf16_f32 v95, v104, v105
	v_cvt_pk_bf16_f32 v96, v96, v97
	v_cvt_pk_bf16_f32 v97, v106, v107
	flat_store_dwordx4 v[188:189], v[94:97] offset:256
	v_lshlrev_b32_e32 v102, 16, v174
	v_and_b32_e32 v103, 0xffff0000, v174
	v_lshlrev_b32_e32 v94, 16, v172
	v_and_b32_e32 v95, 0xffff0000, v172
	v_lshlrev_b32_e32 v96, 16, v173
	v_and_b32_e32 v97, 0xffff0000, v173
	v_lshlrev_b32_e32 v104, 16, v175
	v_and_b32_e32 v105, 0xffff0000, v175
	v_pk_fma_f32 v[94:95], v[94:95], s[28:29], v[98:99] op_sel_hi:[1,0,1]
	v_pk_fma_f32 v[96:97], v[96:97], s[28:29], v[100:101] op_sel_hi:[1,0,1]
	v_pk_fma_f32 v[98:99], v[104:105], s[28:29], v[92:93] op_sel_hi:[1,0,1]
	v_pk_fma_f32 v[92:93], v[102:103], s[28:29], v[90:91] op_sel_hi:[1,0,1]
	v_cvt_pk_bf16_f32 v90, v94, v95
	v_add_co_u32_e32 v94, vcc, s43, v148
	v_cvt_pk_bf16_f32 v91, v96, v97
	v_cvt_pk_bf16_f32 v92, v92, v93
	v_cvt_pk_bf16_f32 v93, v98, v99
	v_addc_co_u32_e32 v95, vcc, 0, v149, vcc
	flat_store_dwordx4 v[94:95], v[90:93]
	v_lshlrev_b32_e32 v96, 16, v178
	v_and_b32_e32 v97, 0xffff0000, v178
	v_lshlrev_b32_e32 v90, 16, v176
	v_and_b32_e32 v91, 0xffff0000, v176
	v_lshlrev_b32_e32 v92, 16, v177
	v_and_b32_e32 v93, 0xffff0000, v177
	v_lshlrev_b32_e32 v98, 16, v179
	v_and_b32_e32 v99, 0xffff0000, v179
	v_pk_fma_f32 v[88:89], v[92:93], s[28:29], v[88:89] op_sel_hi:[1,0,1]
	v_pk_fma_f32 v[86:87], v[90:91], s[28:29], v[86:87] op_sel_hi:[1,0,1]
	v_pk_fma_f32 v[90:91], v[98:99], s[28:29], v[80:81] op_sel_hi:[1,0,1]
	v_pk_fma_f32 v[80:81], v[96:97], s[28:29], v[78:79] op_sel_hi:[1,0,1]
	v_cvt_pk_bf16_f32 v78, v86, v87
	v_cvt_pk_bf16_f32 v79, v88, v89
	v_cvt_pk_bf16_f32 v80, v80, v81
	v_cvt_pk_bf16_f32 v81, v90, v91
	flat_store_dwordx4 v[94:95], v[78:81] offset:256
	v_lshlrev_b32_e32 v86, 16, v182
	v_and_b32_e32 v87, 0xffff0000, v182
	v_lshlrev_b32_e32 v78, 16, v180
	v_and_b32_e32 v79, 0xffff0000, v180
	v_lshlrev_b32_e32 v80, 16, v181
	v_and_b32_e32 v81, 0xffff0000, v181
	v_lshlrev_b32_e32 v88, 16, v183
	v_and_b32_e32 v89, 0xffff0000, v183
	v_pk_fma_f32 v[78:79], v[78:79], s[28:29], v[82:83] op_sel_hi:[1,0,1]
	v_pk_fma_f32 v[80:81], v[80:81], s[28:29], v[84:85] op_sel_hi:[1,0,1]
	v_pk_fma_f32 v[82:83], v[88:89], s[28:29], v[76:77] op_sel_hi:[1,0,1]
	v_pk_fma_f32 v[76:77], v[86:87], s[28:29], v[74:75] op_sel_hi:[1,0,1]
	v_cvt_pk_bf16_f32 v74, v78, v79
	v_add_co_u32_e32 v78, vcc, s48, v148
	v_cvt_pk_bf16_f32 v75, v80, v81
	v_cvt_pk_bf16_f32 v76, v76, v77
	v_cvt_pk_bf16_f32 v77, v82, v83
	v_addc_co_u32_e32 v79, vcc, 0, v149, vcc
	flat_store_dwordx4 v[78:79], v[74:77]
	v_lshlrev_b32_e32 v80, 16, v186
	v_and_b32_e32 v81, 0xffff0000, v186
	v_lshlrev_b32_e32 v74, 16, v184
	v_and_b32_e32 v75, 0xffff0000, v184
	v_lshlrev_b32_e32 v76, 16, v185
	v_and_b32_e32 v77, 0xffff0000, v185
	v_lshlrev_b32_e32 v82, 16, v187
	v_and_b32_e32 v83, 0xffff0000, v187
	v_pk_fma_f32 v[72:73], v[76:77], s[28:29], v[72:73] op_sel_hi:[1,0,1]
	v_pk_fma_f32 v[70:71], v[74:75], s[28:29], v[70:71] op_sel_hi:[1,0,1]
	v_pk_fma_f32 v[74:75], v[82:83], s[28:29], v[68:69] op_sel_hi:[1,0,1]
	v_pk_fma_f32 v[68:69], v[80:81], s[28:29], v[66:67] op_sel_hi:[1,0,1]
	v_cvt_pk_bf16_f32 v66, v70, v71
	v_cvt_pk_bf16_f32 v67, v72, v73
	v_cvt_pk_bf16_f32 v68, v68, v69
	v_cvt_pk_bf16_f32 v69, v74, v75
	flat_store_dwordx4 v[78:79], v[66:69] offset:256
	s_nop 1
	v_add_u32_e32 v66, 0x80, v155
	s_nop 0
	v_ashrrev_i32_e32 v67, 31, v66
	v_lshlrev_b64 v[66:67], 10, v[66:67]
	v_lshl_add_u64 v[66:67], v[66:67], 0, v[146:147]
	v_lshlrev_b64 v[98:99], 1, v[66:67]
	v_lshl_add_u64 v[90:91], s[10:11], 0, v[98:99]
	flat_load_dwordx4 v[66:69], v[90:91] nt
	flat_load_dwordx4 v[70:73], v[90:91] offset:256 nt
	v_add_co_u32_e32 v78, vcc, s49, v90
	s_waitcnt vmcnt(0) lgkmcnt(0)
	v_lshlrev_b32_e32 v100, 16, v66
	v_addc_co_u32_e32 v79, vcc, 0, v91, vcc
	flat_load_dwordx4 v[74:77], v[78:79] nt
	s_nop 0
	flat_load_dwordx4 v[78:81], v[78:79] offset:256 nt
	v_add_co_u32_e32 v86, vcc, s43, v90
	v_and_b32_e32 v101, 0xffff0000, v66
	s_nop 0
	v_addc_co_u32_e32 v87, vcc, 0, v91, vcc
	flat_load_dwordx4 v[82:85], v[86:87] nt
	s_nop 0
	flat_load_dwordx4 v[86:89], v[86:87] offset:256 nt
	v_add_co_u32_e32 v94, vcc, s48, v90
	v_lshlrev_b32_e32 v66, 16, v67
	s_nop 0
	v_addc_co_u32_e32 v95, vcc, 0, v91, vcc
	flat_load_dwordx4 v[90:93], v[94:95] nt
	s_nop 0
	flat_load_dwordx4 v[94:97], v[94:95] offset:256 nt
	v_and_b32_e32 v67, 0xffff0000, v67
	v_lshlrev_b32_e32 v102, 16, v68
	v_and_b32_e32 v103, 0xffff0000, v68
	v_lshlrev_b32_e32 v68, 16, v69
	v_and_b32_e32 v69, 0xffff0000, v69
	v_pk_fma_f32 v[64:65], v[66:67], s[28:29], v[64:65] op_sel_hi:[1,0,1]
	v_pk_fma_f32 v[62:63], v[100:101], s[28:29], v[62:63] op_sel_hi:[1,0,1]
	v_pk_fma_f32 v[66:67], v[68:69], s[28:29], v[60:61] op_sel_hi:[1,0,1]
	v_pk_fma_f32 v[60:61], v[102:103], s[28:29], v[58:59] op_sel_hi:[1,0,1]
	v_cvt_pk_bf16_f32 v58, v62, v63
	v_cvt_pk_bf16_f32 v59, v64, v65
	v_cvt_pk_bf16_f32 v60, v60, v61
	v_cvt_pk_bf16_f32 v61, v66, v67
	v_lshl_add_u64 v[62:63], s[12:13], 0, v[98:99]
	flat_store_dwordx4 v[62:63], v[58:61]
	v_lshlrev_b32_e32 v64, 16, v72
	v_and_b32_e32 v65, 0xffff0000, v72
	v_lshlrev_b32_e32 v58, 16, v70
	v_and_b32_e32 v59, 0xffff0000, v70
	v_lshlrev_b32_e32 v60, 16, v71
	v_and_b32_e32 v61, 0xffff0000, v71
	v_lshlrev_b32_e32 v66, 16, v73
	v_and_b32_e32 v67, 0xffff0000, v73
	v_pk_fma_f32 v[56:57], v[60:61], s[28:29], v[56:57] op_sel_hi:[1,0,1]
	v_pk_fma_f32 v[54:55], v[58:59], s[28:29], v[54:55] op_sel_hi:[1,0,1]
	v_pk_fma_f32 v[58:59], v[66:67], s[28:29], v[48:49] op_sel_hi:[1,0,1]
	v_pk_fma_f32 v[48:49], v[64:65], s[28:29], v[46:47] op_sel_hi:[1,0,1]
	v_cvt_pk_bf16_f32 v46, v54, v55
	v_cvt_pk_bf16_f32 v47, v56, v57
	v_cvt_pk_bf16_f32 v48, v48, v49
	v_cvt_pk_bf16_f32 v49, v58, v59
	flat_store_dwordx4 v[62:63], v[46:49] offset:256
	s_waitcnt vmcnt(0) lgkmcnt(0)
	v_lshlrev_b32_e32 v54, 16, v76
	v_lshlrev_b32_e32 v46, 16, v74
	v_and_b32_e32 v47, 0xffff0000, v74
	v_lshlrev_b32_e32 v48, 16, v75
	v_and_b32_e32 v49, 0xffff0000, v75
	v_and_b32_e32 v55, 0xffff0000, v76
	v_lshlrev_b32_e32 v56, 16, v77
	v_and_b32_e32 v57, 0xffff0000, v77
	v_pk_fma_f32 v[46:47], v[46:47], s[28:29], v[50:51] op_sel_hi:[1,0,1]
	v_pk_fma_f32 v[48:49], v[48:49], s[28:29], v[52:53] op_sel_hi:[1,0,1]
	v_pk_fma_f32 v[50:51], v[56:57], s[28:29], v[44:45] op_sel_hi:[1,0,1]
	v_pk_fma_f32 v[44:45], v[54:55], s[28:29], v[42:43] op_sel_hi:[1,0,1]
	v_cvt_pk_bf16_f32 v42, v46, v47
	v_add_co_u32_e32 v46, vcc, s49, v62
	v_cvt_pk_bf16_f32 v43, v48, v49
	v_cvt_pk_bf16_f32 v44, v44, v45
	v_cvt_pk_bf16_f32 v45, v50, v51
	v_addc_co_u32_e32 v47, vcc, 0, v63, vcc
	flat_store_dwordx4 v[46:47], v[42:45]
	v_lshlrev_b32_e32 v48, 16, v80
	v_and_b32_e32 v49, 0xffff0000, v80
	v_lshlrev_b32_e32 v42, 16, v78
	v_and_b32_e32 v43, 0xffff0000, v78
	v_lshlrev_b32_e32 v44, 16, v79
	v_and_b32_e32 v45, 0xffff0000, v79
	v_lshlrev_b32_e32 v50, 16, v81
	v_and_b32_e32 v51, 0xffff0000, v81
	v_pk_fma_f32 v[40:41], v[44:45], s[28:29], v[40:41] op_sel_hi:[1,0,1]
	v_pk_fma_f32 v[38:39], v[42:43], s[28:29], v[38:39] op_sel_hi:[1,0,1]
	v_pk_fma_f32 v[42:43], v[50:51], s[28:29], v[32:33] op_sel_hi:[1,0,1]
	v_pk_fma_f32 v[32:33], v[48:49], s[28:29], v[30:31] op_sel_hi:[1,0,1]
	v_cvt_pk_bf16_f32 v30, v38, v39
	v_cvt_pk_bf16_f32 v31, v40, v41
	v_cvt_pk_bf16_f32 v32, v32, v33
	v_cvt_pk_bf16_f32 v33, v42, v43
	flat_store_dwordx4 v[46:47], v[30:33] offset:256
	v_lshlrev_b32_e32 v38, 16, v84
	v_and_b32_e32 v39, 0xffff0000, v84
	v_lshlrev_b32_e32 v30, 16, v82
	v_and_b32_e32 v31, 0xffff0000, v82
	v_lshlrev_b32_e32 v32, 16, v83
	v_and_b32_e32 v33, 0xffff0000, v83
	v_lshlrev_b32_e32 v40, 16, v85
	v_and_b32_e32 v41, 0xffff0000, v85
	v_pk_fma_f32 v[30:31], v[30:31], s[28:29], v[34:35] op_sel_hi:[1,0,1]
	v_pk_fma_f32 v[32:33], v[32:33], s[28:29], v[36:37] op_sel_hi:[1,0,1]
	v_pk_fma_f32 v[34:35], v[40:41], s[28:29], v[28:29] op_sel_hi:[1,0,1]
	v_pk_fma_f32 v[28:29], v[38:39], s[28:29], v[26:27] op_sel_hi:[1,0,1]
	v_cvt_pk_bf16_f32 v26, v30, v31
	v_add_co_u32_e32 v30, vcc, s43, v62
	v_cvt_pk_bf16_f32 v27, v32, v33
	v_cvt_pk_bf16_f32 v28, v28, v29
	v_cvt_pk_bf16_f32 v29, v34, v35
	v_addc_co_u32_e32 v31, vcc, 0, v63, vcc
	flat_store_dwordx4 v[30:31], v[26:29]
	v_lshlrev_b32_e32 v32, 16, v88
	v_and_b32_e32 v33, 0xffff0000, v88
	v_lshlrev_b32_e32 v26, 16, v86
	v_and_b32_e32 v27, 0xffff0000, v86
	v_lshlrev_b32_e32 v28, 16, v87
	v_and_b32_e32 v29, 0xffff0000, v87
	v_lshlrev_b32_e32 v34, 16, v89
	v_and_b32_e32 v35, 0xffff0000, v89
	v_pk_fma_f32 v[24:25], v[28:29], s[28:29], v[24:25] op_sel_hi:[1,0,1]
	v_pk_fma_f32 v[22:23], v[26:27], s[28:29], v[22:23] op_sel_hi:[1,0,1]
	v_pk_fma_f32 v[26:27], v[34:35], s[28:29], v[16:17] op_sel_hi:[1,0,1]
	v_pk_fma_f32 v[16:17], v[32:33], s[28:29], v[14:15] op_sel_hi:[1,0,1]
	v_cvt_pk_bf16_f32 v14, v22, v23
	v_cvt_pk_bf16_f32 v15, v24, v25
	v_cvt_pk_bf16_f32 v16, v16, v17
	v_cvt_pk_bf16_f32 v17, v26, v27
	flat_store_dwordx4 v[30:31], v[14:17] offset:256
	v_lshlrev_b32_e32 v22, 16, v92
	v_and_b32_e32 v23, 0xffff0000, v92
	v_lshlrev_b32_e32 v14, 16, v90
	v_and_b32_e32 v15, 0xffff0000, v90
	v_lshlrev_b32_e32 v16, 16, v91
	v_and_b32_e32 v17, 0xffff0000, v91
	v_lshlrev_b32_e32 v24, 16, v93
	v_and_b32_e32 v25, 0xffff0000, v93
	v_pk_fma_f32 v[14:15], v[14:15], s[28:29], v[18:19] op_sel_hi:[1,0,1]
	v_pk_fma_f32 v[16:17], v[16:17], s[28:29], v[20:21] op_sel_hi:[1,0,1]
	v_pk_fma_f32 v[18:19], v[24:25], s[28:29], v[12:13] op_sel_hi:[1,0,1]
	v_pk_fma_f32 v[12:13], v[22:23], s[28:29], v[10:11] op_sel_hi:[1,0,1]
	v_cvt_pk_bf16_f32 v10, v14, v15
	v_add_co_u32_e32 v14, vcc, s48, v62
	v_cvt_pk_bf16_f32 v11, v16, v17
	v_cvt_pk_bf16_f32 v12, v12, v13
	v_cvt_pk_bf16_f32 v13, v18, v19
	v_addc_co_u32_e32 v15, vcc, 0, v63, vcc
	flat_store_dwordx4 v[14:15], v[10:13]
	v_lshlrev_b32_e32 v16, 16, v96
	v_and_b32_e32 v17, 0xffff0000, v96
	v_lshlrev_b32_e32 v10, 16, v94
	v_and_b32_e32 v11, 0xffff0000, v94
	v_lshlrev_b32_e32 v12, 16, v95
	v_and_b32_e32 v13, 0xffff0000, v95
	v_lshlrev_b32_e32 v18, 16, v97
	v_and_b32_e32 v19, 0xffff0000, v97
	v_pk_fma_f32 v[8:9], v[12:13], s[28:29], v[8:9] op_sel_hi:[1,0,1]
	v_pk_fma_f32 v[6:7], v[10:11], s[28:29], v[6:7] op_sel_hi:[1,0,1]
	v_pk_fma_f32 v[10:11], v[18:19], s[28:29], v[4:5] op_sel_hi:[1,0,1]
	v_pk_fma_f32 v[4:5], v[16:17], s[28:29], v[2:3] op_sel_hi:[1,0,1]
	v_cvt_pk_bf16_f32 v2, v6, v7
	v_cvt_pk_bf16_f32 v3, v8, v9
	v_cvt_pk_bf16_f32 v4, v4, v5
	v_cvt_pk_bf16_f32 v5, v10, v11
	s_and_b64 vcc, exec, s[30:31]
	flat_store_dwordx4 v[14:15], v[2:5] offset:256
	s_cbranch_vccz .LBB0_433
	s_waitcnt vmcnt(0)
	s_cmpk_gt_u32 s4, 0xff
	s_cbranch_scc1 .LBB0_438
	s_barrier

.LBB0_455:
	s_or_b64 exec, exec, s[18:19]
	s_lshl_b32 s0, s39, 8
	s_add_i32 s0, s0, s97
	s_ashr_i32 s1, s0, 31
	s_lshl_b64 s[18:19], s[0:1], 11
	v_lshl_add_u64 v[38:39], v[54:55], 0, s[18:19]
	v_add_co_u32_e32 v44, vcc, 0x4000, v38
	s_waitcnt lgkmcnt(0)
	s_barrier
	global_load_dwordx4 v[2:5], v[50:51], off
	global_load_dwordx4 v[6:9], v[50:51], off offset:1024
	global_load_dwordx4 v[10:13], v[52:53], off
	global_load_dwordx4 v[14:17], v[52:53], off offset:1024
	global_load_dwordx4 v[18:21], v[50:51], off offset:2048
	global_load_dwordx4 v[22:25], v[50:51], off offset:3072
	global_load_dwordx4 v[26:29], v[52:53], off offset:2048
	global_load_dwordx4 v[30:33], v[52:53], off offset:3072
	v_lshl_add_u64 v[42:43], v[38:39], 0, s[28:29]
	v_addc_co_u32_e32 v45, vcc, 0, v39, vcc
	flat_load_dwordx2 v[36:37], v[38:39] nt
	flat_load_dwordx2 v[34:35], v[38:39] offset:512 nt
	flat_load_dwordx2 v[40:41], v[38:39] offset:1024 nt
	s_nop 0
	flat_load_dwordx2 v[38:39], v[38:39] offset:1536 nt
	s_nop 0
	flat_load_dwordx2 v[60:61], v[44:45] nt
	flat_load_dwordx2 v[62:63], v[42:43] offset:512 nt
	flat_load_dwordx2 v[64:65], v[42:43] offset:1024 nt
	flat_load_dwordx2 v[66:67], v[42:43] offset:1536 nt
	s_mov_b32 s34, 0
	s_add_i32 s35, s0, 16
	s_mov_b32 s36, 0
	s_branch .LBB0_458

.LBB0_458:
	s_waitcnt vmcnt(0) lgkmcnt(0)
	v_lshlrev_b32_e32 v85, 16, v37
	v_lshlrev_b32_e32 v84, 16, v36
	v_and_b32_e32 v37, 0xffff0000, v37
	v_and_b32_e32 v36, 0xffff0000, v36
	v_pk_add_f32 v[68:69], v[84:85], v[36:37]
	v_lshlrev_b32_e32 v87, 16, v35
	v_lshlrev_b32_e32 v86, 16, v34
	v_and_b32_e32 v35, 0xffff0000, v35
	v_and_b32_e32 v34, 0xffff0000, v34
	v_lshlrev_b32_e32 v46, 16, v39
	v_and_b32_e32 v48, 0xffff0000, v39
	v_add_f32_e32 v39, v68, v69
	v_pk_add_f32 v[68:69], v[86:87], v[34:35]
	v_lshlrev_b32_e32 v42, 16, v40
	v_and_b32_e32 v43, 0xffff0000, v40
	v_lshlrev_b32_e32 v40, 16, v41
	v_and_b32_e32 v41, 0xffff0000, v41
	v_pk_add_f32 v[68:69], v[68:69], v[68:69] op_sel_hi:[0,1]
	v_lshlrev_b32_e32 v44, 16, v38
	v_and_b32_e32 v38, 0xffff0000, v38
	v_add_f32_e32 v49, 0, v39
	v_add_f32_e32 v45, v42, v43
	v_add_f32_e32 v39, v40, v41
	v_mov_b32_e32 v47, v69
	v_pk_add_f32 v[70:71], v[44:45], v[38:39]
	v_pk_add_f32 v[68:69], v[46:47], v[48:49]
	s_min_u32 s0, s36, 29
	v_pk_add_f32 v[68:69], v[70:71], v[68:69]
	s_lshl_b32 s0, s0, 3
	v_add_f32_e32 v39, v68, v69
	s_add_i32 s18, s35, s0
	s_nop 0
	v_add_f32_dpp v39, v39, v39 quad_perm:[1,0,3,2] row_mask:0xf bank_mask:0xf bound_ctrl:1
	s_nop 1
	v_add_f32_dpp v39, v39, v39 quad_perm:[2,3,0,1] row_mask:0xf bank_mask:0xf bound_ctrl:1
	s_nop 1
	v_add_f32_dpp v39, v39, v39 row_half_mirror row_mask:0xf bank_mask:0xf bound_ctrl:1
	s_nop 1
	v_add_f32_dpp v39, v39, v39 row_mirror row_mask:0xf bank_mask:0xf bound_ctrl:1
	s_nop 0
	v_readlane_b32 s19, v39, 16
	v_readlane_b32 s20, v39, 48
	v_readlane_b32 s0, v39, 0
	v_readlane_b32 s1, v39, 32
	v_mov_b32_e32 v68, s19
	v_mov_b32_e32 v69, s20
	v_pk_add_f32 v[68:69], s[0:1], v[68:69]
	s_nop 0
	v_add_f32_e32 v39, v68, v69
	v_fmac_f32_e32 v36, 0xba800000, v39
	v_fmac_f32_e32 v37, 0xba800000, v39
	v_fmac_f32_e32 v85, 0xba800000, v39
	v_fmac_f32_e32 v84, 0xba800000, v39
	v_mov_b32_e32 v88, v85
	v_mov_b32_e32 v89, v37
	v_mov_b32_e32 v85, v36
	v_fmac_f32_e32 v34, 0xba800000, v39
	v_fmac_f32_e32 v35, 0xba800000, v39
	v_fmac_f32_e32 v87, 0xba800000, v39
	v_pk_mul_f32 v[68:69], v[88:89], v[88:89]
	v_pk_mul_f32 v[36:37], v[84:85], v[84:85]
	v_fmac_f32_e32 v86, 0xba800000, v39
	v_mov_b32_e32 v90, v87
	v_mov_b32_e32 v91, v35
	v_mov_b32_e32 v87, v34
	v_pk_mov_b32 v[70:71], v[36:37], v[68:69] op_sel:[1,0]
	v_mov_b32_e32 v37, v69
	v_pk_mul_f32 v[68:69], v[90:91], v[90:91]
	v_pk_mul_f32 v[34:35], v[86:87], v[86:87]
	v_pk_add_f32 v[36:37], v[70:71], v[36:37]
	v_pk_mov_b32 v[70:71], v[34:35], v[68:69] op_sel:[1,0]
	v_mov_b32_e32 v35, v69
	v_pk_add_f32 v[34:35], v[70:71], v[34:35]
	v_fmac_f32_e32 v42, 0xba800000, v39
	v_pk_add_f32 v[34:35], v[34:35], v[34:35] op_sel_hi:[0,1]
	v_fmac_f32_e32 v43, 0xba800000, v39
	v_fmac_f32_e32 v40, 0xba800000, v39
	v_mul_f32_e32 v34, v42, v42
	v_fmac_f32_e32 v41, 0xba800000, v39
	v_pk_fma_f32 v[68:69], v[42:43], v[42:43], v[34:35] op_sel_hi:[1,1,0]
	v_mul_f32_e32 v34, v40, v40
	v_pk_add_f32 v[36:37], v[36:37], v[36:37] op_sel_hi:[0,1]
	v_pk_fma_f32 v[70:71], v[40:41], v[40:41], v[34:35] op_sel_hi:[1,1,0]
	v_fmac_f32_e32 v48, 0xba800000, v39
	v_fmac_f32_e32 v46, 0xba800000, v39
	v_fmac_f32_e32 v38, 0xba800000, v39
	v_fmac_f32_e32 v44, 0xba800000, v39
	v_mul_f32_e32 v68, v44, v44
	v_mul_f32_e32 v70, v38, v38
	v_mul_f32_e32 v36, v46, v46
	v_mul_f32_e32 v34, v48, v48
	v_pk_add_f32 v[68:69], v[68:69], v[70:71]
	v_pk_add_f32 v[34:35], v[36:37], v[34:35]
	v_mov_b32_e32 v47, v48
	v_pk_add_f32 v[34:35], v[68:69], v[34:35]
	s_nop 0
	v_add_f32_e32 v34, v34, v35
	s_nop 1
	v_add_f32_dpp v34, v34, v34 quad_perm:[1,0,3,2] row_mask:0xf bank_mask:0xf bound_ctrl:1
	s_nop 1
	v_add_f32_dpp v34, v34, v34 quad_perm:[2,3,0,1] row_mask:0xf bank_mask:0xf bound_ctrl:1
	s_nop 1
	v_add_f32_dpp v34, v34, v34 row_half_mirror row_mask:0xf bank_mask:0xf bound_ctrl:1
	s_nop 1
	v_add_f32_dpp v34, v34, v34 row_mirror row_mask:0xf bank_mask:0xf bound_ctrl:1
	s_nop 0
	v_readlane_b32 s19, v34, 16
	v_readlane_b32 s20, v34, 48
	v_readlane_b32 s0, v34, 0
	v_readlane_b32 s1, v34, 32
	v_mov_b32_e32 v34, s19
	v_mov_b32_e32 v35, s20
	v_pk_add_f32 v[34:35], s[0:1], v[34:35]
	s_ashr_i32 s19, s18, 31
	v_add_f32_e32 v34, v34, v35
	v_fmamk_f32 v34, v34, 0x3a800000, v80
	v_mul_f32_e32 v35, 0x4f800000, v34
	v_cmp_gt_f32_e32 vcc, s7, v34
	s_lshl_b64 s[0:1], s[18:19], 11
	s_and_b32 s20, s36, 3
	v_cndmask_b32_e32 v36, v34, v35, vcc
	v_lshl_add_u64 v[34:35], v[54:55], 0, s[0:1]
	flat_load_dwordx2 v[68:69], v[34:35] nt
	flat_load_dwordx2 v[70:71], v[34:35] offset:512 nt
	flat_load_dwordx2 v[72:73], v[34:35] offset:1024 nt
	flat_load_dwordx2 v[74:75], v[34:35] offset:1536 nt
	v_sqrt_f32_e32 v37, v36
	s_mul_i32 s30, s20, 0x810
	s_add_i32 s30, s87, s30
	v_add_u32_e32 v39, -1, v37
	v_fma_f32 v45, -v39, v37, v36
	v_cmp_ge_f32_e64 s[18:19], 0, v45
	v_add_u32_e32 v45, 1, v37
	s_nop 0
	v_cndmask_b32_e64 v39, v37, v39, s[18:19]
	v_fma_f32 v37, -v45, v37, v36
	v_cmp_lt_f32_e64 s[18:19], 0, v37
	s_nop 1
	v_cndmask_b32_e64 v37, v39, v45, s[18:19]
	v_mul_f32_e32 v39, 0x37800000, v37
	v_cndmask_b32_e32 v37, v37, v39, vcc
	v_cmp_class_f32_e32 vcc, v36, v81
	s_add_i32 s18, s4, s34
	s_ashr_i32 s19, s18, 31
	v_cndmask_b32_e32 v36, v37, v36, vcc
	v_div_scale_f32 v37, s[0:1], v36, v36, 1.0
	v_rcp_f32_e32 v39, v37
	s_lshl_b64 s[0:1], s[18:19], 11
	v_fma_f32 v34, -v37, v39, 1.0
	v_fmac_f32_e32 v39, v34, v39
	v_div_scale_f32 v34, vcc, 1.0, v36, 1.0
	v_mul_f32_e32 v35, v34, v39
	v_fma_f32 v45, -v37, v35, v34
	v_fmac_f32_e32 v35, v45, v39
	v_fma_f32 v34, -v37, v35, v34
	v_div_fmas_f32 v34, v34, v39, v35
	v_div_fixup_f32 v34, v34, v36, 1.0
	v_mov_b32_e32 v45, v38
	v_pk_mul_f32 v[36:37], v[84:85], v[34:35] op_sel_hi:[1,0]
	v_pk_mul_f32 v[84:85], v[88:89], v[34:35] op_sel_hi:[1,0]
	v_pk_mul_f32 v[38:39], v[44:45], v[34:35] op_sel_hi:[1,0]
	v_mov_b32_e32 v44, v150
	v_pk_fma_f32 v[84:85], v[4:5], v[84:85], v[12:13]
	v_pk_fma_f32 v[36:37], v[2:3], v[36:37], v[10:11]
	v_pk_mul_f32 v[86:87], v[86:87], v[34:35] op_sel_hi:[1,0]
	v_pk_mul_f32 v[88:89], v[90:91], v[34:35] op_sel_hi:[1,0]
	v_pk_fma_f32 v[86:87], v[6:7], v[86:87], v[14:15]
	v_pk_fma_f32 v[88:89], v[8:9], v[88:89], v[16:17]
	v_pk_mul_f32 v[42:43], v[42:43], v[34:35] op_sel_hi:[1,0]
	v_pk_mul_f32 v[40:41], v[40:41], v[34:35] op_sel_hi:[1,0]
	v_pk_mul_f32 v[34:35], v[46:47], v[34:35] op_sel_hi:[1,0]
	v_lshl_add_u32 v48, v44, 3, s30
	v_cvt_pk_bf16_f32 v44, v36, v37
	v_cvt_pk_bf16_f32 v45, v84, v85
	v_lshl_add_u64 v[46:47], v[56:57], 0, s[0:1]
	v_pk_fma_f32 v[40:41], v[20:21], v[40:41], v[28:29]
	v_pk_fma_f32 v[42:43], v[18:19], v[42:43], v[26:27]
	flat_store_dwordx2 v[46:47], v[44:45]
	ds_write_b64 v48, v[44:45] offset:33024
	v_cvt_pk_bf16_f32 v44, v86, v87
	v_cvt_pk_bf16_f32 v45, v88, v89
	v_pk_fma_f32 v[34:35], v[24:25], v[34:35], v[32:33]
	v_pk_fma_f32 v[38:39], v[22:23], v[38:39], v[30:31]
	flat_store_dwordx2 v[46:47], v[44:45] offset:512
	ds_write_b64 v48, v[44:45] offset:33536
	v_cvt_pk_bf16_f32 v44, v42, v43
	v_cvt_pk_bf16_f32 v45, v40, v41
	flat_store_dwordx2 v[46:47], v[44:45] offset:1024
	ds_write_b64 v48, v[44:45] offset:34048
	v_cvt_pk_bf16_f32 v44, v38, v39
	v_cvt_pk_bf16_f32 v45, v34, v35
	flat_store_dwordx2 v[46:47], v[44:45] offset:1536
	ds_write_b64 v48, v[44:45] offset:34560
	v_med3_f32 v36, v36, s38, v82
	v_med3_f32 v37, v37, s38, v82
	v_mov_b32_e32 v44, 0
	v_cvt_pk_fp8_f32 v44, v36, v37
	v_med3_f32 v36, v84, s38, v82
	v_med3_f32 v37, v85, s38, v82
	v_med3_f32 v45, v86, s38, v82
	v_cvt_pk_fp8_f32 v44, v36, v37 op_sel:[0,0,1]
	v_med3_f32 v46, v87, s38, v82
	v_mov_b32_e32 v47, 0
	v_cvt_pk_fp8_f32 v47, v45, v46
	s_lshl_b64 s[0:1], s[18:19], 10
	v_lshl_add_u64 v[36:37], v[58:59], 0, s[0:1]
	flat_store_dword v[36:37], v44
	v_med3_f32 v44, v88, s38, v82
	v_med3_f32 v45, v89, s38, v82
	v_cvt_pk_fp8_f32 v47, v44, v45 op_sel:[0,0,1]
	v_med3_f32 v42, v42, s38, v82
	v_med3_f32 v43, v43, s38, v82
	v_mov_b32_e32 v44, 0
	v_cvt_pk_fp8_f32 v44, v42, v43
	v_med3_f32 v38, v38, s38, v82
	v_med3_f32 v39, v39, s38, v82
	v_mov_b32_e32 v42, 0
	v_cvt_pk_fp8_f32 v42, v38, v39
	v_med3_f32 v34, v34, s38, v82
	v_med3_f32 v35, v35, s38, v82
	v_med3_f32 v40, v40, s38, v82
	v_med3_f32 v41, v41, s38, v82
	v_cvt_pk_fp8_f32 v42, v34, v35 op_sel:[0,0,1]
	v_cvt_pk_fp8_f32 v44, v40, v41 op_sel:[0,0,1]
	s_cmp_lg_u32 s20, 3
	flat_store_dword v[36:37], v47 offset:256
	flat_store_dword v[36:37], v44 offset:512
	flat_store_dword v[36:37], v42 offset:768
	s_cbranch_scc1 .LBB0_457
	v_mov_b32_e32 v100, v150
	s_nop 0
	v_and_b32_e32 v34, 3, v100
	v_mul_u32_u24_e32 v34, 0x810, v34
	v_and_b32_e32 v38, -16, v100
	v_add3_u32 v83, s87, v34, v38
	ds_read_b128 v[34:37], v83 offset:33024
	v_and_b32_e32 v39, 15, v100
	v_mul_u32_u24_e32 v39, 0x810, v39
	v_add3_u32 v101, 0, v39, v38
	ds_read_b128 v[38:41], v83 offset:33088
	ds_read_b128 v[42:45], v101
	ds_read_b128 v[46:49], v101 offset:64
	s_waitcnt lgkmcnt(0)
	v_mfma_f32_16x16x32_bf16 v[38:41], v[38:41], v[46:49], 0
	v_cmp_gt_i32_e32 vcc, 16, v100
	v_mfma_f32_16x16x32_bf16 v[34:37], v[34:37], v[42:45], 0
	ds_read_b128 v[42:45], v83 offset:33152
	ds_read_b128 v[46:49], v83 offset:33216
	ds_read_b128 v[84:87], v101 offset:128
	ds_read_b128 v[88:91], v101 offset:192
	s_waitcnt lgkmcnt(0)
	v_mfma_f32_16x16x32_bf16 v[42:45], v[42:45], v[84:87], 0
	ds_read_b128 v[84:87], v83 offset:33280
	v_mfma_f32_16x16x32_bf16 v[46:49], v[46:49], v[88:91], 0
	ds_read_b128 v[88:91], v83 offset:33344
	ds_read_b128 v[92:95], v101 offset:256
	ds_read_b128 v[96:99], v101 offset:320
	s_waitcnt lgkmcnt(0)
	v_mfma_f32_16x16x32_bf16 v[34:37], v[84:87], v[92:95], v[34:37]
	ds_read_b128 v[84:87], v83 offset:33408
	v_mfma_f32_16x16x32_bf16 v[38:41], v[88:91], v[96:99], v[38:41]
	ds_read_b128 v[88:91], v83 offset:33472
	ds_read_b128 v[92:95], v101 offset:384
	ds_read_b128 v[96:99], v101 offset:448
	s_waitcnt lgkmcnt(0)
	v_mfma_f32_16x16x32_bf16 v[42:45], v[84:87], v[92:95], v[42:45]
	ds_read_b128 v[84:87], v83 offset:33536
	v_mfma_f32_16x16x32_bf16 v[46:49], v[88:91], v[96:99], v[46:49]
	ds_read_b128 v[88:91], v83 offset:33600
	ds_read_b128 v[92:95], v101 offset:512
	ds_read_b128 v[96:99], v101 offset:576
	s_waitcnt lgkmcnt(0)
	v_mfma_f32_16x16x32_bf16 v[34:37], v[84:87], v[92:95], v[34:37]
	ds_read_b128 v[84:87], v83 offset:33664
	v_mfma_f32_16x16x32_bf16 v[38:41], v[88:91], v[96:99], v[38:41]
	ds_read_b128 v[88:91], v83 offset:33728
	ds_read_b128 v[92:95], v101 offset:640
	ds_read_b128 v[96:99], v101 offset:704
	s_waitcnt lgkmcnt(0)
	v_mfma_f32_16x16x32_bf16 v[42:45], v[84:87], v[92:95], v[42:45]
	ds_read_b128 v[84:87], v83 offset:33792
	ds_read_b128 v[92:95], v83 offset:33856
	v_mfma_f32_16x16x32_bf16 v[46:49], v[88:91], v[96:99], v[46:49]
	ds_read_b128 v[88:91], v101 offset:768
	ds_read_b128 v[96:99], v101 offset:832
	s_waitcnt lgkmcnt(0)
	v_mfma_f32_16x16x32_bf16 v[34:37], v[84:87], v[88:91], v[34:37]
	ds_read_b128 v[84:87], v83 offset:33920
	ds_read_b128 v[88:91], v83 offset:33984
	v_mfma_f32_16x16x32_bf16 v[38:41], v[92:95], v[96:99], v[38:41]
	ds_read_b128 v[92:95], v101 offset:896
	ds_read_b128 v[96:99], v101 offset:960
	s_waitcnt lgkmcnt(0)
	v_mfma_f32_16x16x32_bf16 v[42:45], v[84:87], v[92:95], v[42:45]
	ds_read_b128 v[84:87], v83 offset:34048
	ds_read_b128 v[92:95], v83 offset:34112
	v_mfma_f32_16x16x32_bf16 v[46:49], v[88:91], v[96:99], v[46:49]
	ds_read_b128 v[88:91], v101 offset:1024
	ds_read_b128 v[96:99], v101 offset:1088
	s_waitcnt lgkmcnt(0)
	v_mfma_f32_16x16x32_bf16 v[34:37], v[84:87], v[88:91], v[34:37]
	ds_read_b128 v[84:87], v83 offset:34176
	ds_read_b128 v[88:91], v83 offset:34240
	v_mfma_f32_16x16x32_bf16 v[38:41], v[92:95], v[96:99], v[38:41]
	ds_read_b128 v[92:95], v101 offset:1152
	ds_read_b128 v[96:99], v101 offset:1216
	s_waitcnt lgkmcnt(0)
	v_mfma_f32_16x16x32_bf16 v[42:45], v[84:87], v[92:95], v[42:45]
	ds_read_b128 v[84:87], v83 offset:34304
	ds_read_b128 v[92:95], v83 offset:34368
	v_mfma_f32_16x16x32_bf16 v[46:49], v[88:91], v[96:99], v[46:49]
	ds_read_b128 v[88:91], v101 offset:1280
	ds_read_b128 v[96:99], v101 offset:1344
	s_waitcnt lgkmcnt(0)
	v_mfma_f32_16x16x32_bf16 v[34:37], v[84:87], v[88:91], v[34:37]
	ds_read_b128 v[84:87], v83 offset:34432
	ds_read_b128 v[88:91], v83 offset:34496
	v_mfma_f32_16x16x32_bf16 v[38:41], v[92:95], v[96:99], v[38:41]
	ds_read_b128 v[92:95], v101 offset:1408
	ds_read_b128 v[96:99], v101 offset:1472
	s_waitcnt lgkmcnt(0)
	v_mfma_f32_16x16x32_bf16 v[42:45], v[84:87], v[92:95], v[42:45]
	ds_read_b128 v[84:87], v83 offset:34560
	ds_read_b128 v[92:95], v83 offset:34624
	v_mfma_f32_16x16x32_bf16 v[46:49], v[88:91], v[96:99], v[46:49]
	ds_read_b128 v[88:91], v101 offset:1536
	ds_read_b128 v[96:99], v101 offset:1600
	s_waitcnt lgkmcnt(0)
	v_mfma_f32_16x16x32_bf16 v[34:37], v[84:87], v[88:91], v[34:37]
	ds_read_b128 v[84:87], v83 offset:34688
	ds_read_b128 v[88:91], v83 offset:34752
	v_mfma_f32_16x16x32_bf16 v[38:41], v[92:95], v[96:99], v[38:41]
	ds_read_b128 v[92:95], v101 offset:1664
	ds_read_b128 v[96:99], v101 offset:1728
	s_waitcnt lgkmcnt(0)
	v_mfma_f32_16x16x32_bf16 v[42:45], v[84:87], v[92:95], v[42:45]
	ds_read_b128 v[84:87], v83 offset:34816
	ds_read_b128 v[92:95], v83 offset:34880
	v_mfma_f32_16x16x32_bf16 v[46:49], v[88:91], v[96:99], v[46:49]
	ds_read_b128 v[88:91], v101 offset:1792
	ds_read_b128 v[96:99], v101 offset:1856
	s_waitcnt lgkmcnt(0)
	v_mfma_f32_16x16x32_bf16 v[34:37], v[84:87], v[88:91], v[34:37]
	ds_read_b128 v[84:87], v83 offset:34944
	ds_read_b128 v[88:91], v83 offset:35008
	v_mfma_f32_16x16x32_bf16 v[38:41], v[92:95], v[96:99], v[38:41]
	ds_read_b128 v[92:95], v101 offset:1920
	ds_read_b128 v[96:99], v101 offset:1984
	v_ashrrev_i32_e32 v101, 31, v100
	s_waitcnt lgkmcnt(0)
	v_mfma_f32_16x16x32_bf16 v[42:45], v[84:87], v[92:95], v[42:45]
	s_nop 2
	v_add_f32_e64 v34, v34, v38
	v_add_f32_e64 v35, v35, v39
	v_mfma_f32_16x16x32_bf16 v[46:49], v[88:91], v[96:99], v[46:49]
	s_nop 7
	v_pk_add_f32 v[38:39], v[42:43], v[46:47]
	s_nop 0
	v_pk_add_f32 v[38:39], v[34:35], v[38:39]
	s_nop 1
	v_mov_b32_dpp v34, v38 quad_perm:[1,0,3,2] row_mask:0xf bank_mask:0xf bound_ctrl:1
	v_max_f32_e32 v34, v34, v34
	v_max_f32_e32 v34, v38, v34
	s_nop 1
	v_mov_b32_dpp v35, v34 quad_perm:[2,3,0,1] row_mask:0xf bank_mask:0xf bound_ctrl:1
	v_max_f32_e32 v35, v35, v35
	v_max_f32_e32 v34, v34, v35
	s_nop 1
	v_mov_b32_dpp v35, v34 row_half_mirror row_mask:0xf bank_mask:0xf bound_ctrl:1
	v_max_f32_e32 v35, v35, v35
	v_max_f32_e32 v34, v34, v35
	s_nop 1
	v_mov_b32_dpp v35, v34 row_mirror row_mask:0xf bank_mask:0xf bound_ctrl:1
	v_max_f32_e32 v35, v35, v35
	v_max_f32_e32 v34, v34, v35
	v_sub_f32_e32 v34, v38, v34
	v_mul_f32_e32 v34, 0x3fb8aa3b, v34
	v_exp_f32_e32 v38, v34
	v_lshlrev_b64 v[34:35], 13, v[100:101]
	v_lshl_add_u64 v[34:35], s[26:27], 0, v[34:35]
	v_add_f32_dpp v42, v38, v38 quad_perm:[1,0,3,2] row_mask:0xf bank_mask:0xf bound_ctrl:1
	s_nop 1
	v_add_f32_dpp v42, v42, v42 quad_perm:[2,3,0,1] row_mask:0xf bank_mask:0xf bound_ctrl:1
	s_nop 1
	v_add_f32_dpp v42, v42, v42 row_half_mirror row_mask:0xf bank_mask:0xf bound_ctrl:1
	s_nop 1
	v_mov_b32_dpp v43, v42 row_mirror row_mask:0xf bank_mask:0xf bound_ctrl:1
	s_and_saveexec_b64 s[30:31], vcc
	s_cbranch_execz .LBB0_461
	v_add_f32_e32 v42, v42, v43
	v_rcp_f32_e32 v42, v42
	s_sub_i32 s19, s18, 24
	s_ashr_i32 s0, s19, 11
	s_ashr_i32 s1, s0, 31
	s_and_b32 s19, s19, 0x7ff
	s_lshl_b64 s[0:1], s[0:1], 17
	v_mul_f32_e32 v38, v38, v42
	v_lshl_add_u64 v[42:43], v[34:35], 0, s[0:1]
	s_lshl_b32 s20, s19, 2
	v_lshl_add_u64 v[42:43], v[42:43], 0, s[20:21]
	flat_store_dword v[42:43], v38

.LBB0_813:
	s_or_b64 exec, exec, s[8:9]
	s_waitcnt lgkmcnt(0)
	s_barrier
	s_load_dwordx8 s[12:19], s[84:85], 0xd8
	s_load_dwordx4 s[4:7], s[84:85], 0xf8
	s_load_dwordx2 s[20:21], s[84:85], 0x108
	s_add_i32 s8, s33, s68
	s_ashr_i32 s69, s68, 31
	s_ashr_i32 s9, s8, 31
	s_mov_b32 s0, s8
	s_lshl_b64 s[24:25], s[68:69], 11
	v_writelane_b32 v253, s0, 34
	s_lshl_b64 s[26:27], s[8:9], 11
	v_mov_b32_e32 v39, v0
	s_waitcnt lgkmcnt(0)
	s_mov_b32 s8, s21
	v_writelane_b32 v253, s1, 35
	s_mov_b32 s0, s7
	v_and_b32_e32 v74, 63, v39
	s_add_u32 s22, s20, 0x3e00000
	s_addc_u32 s23, s8, 0
	v_lshlrev_b32_e32 v34, 4, v74
	v_mov_b32_e32 v35, 0
	v_lshl_add_u64 v[2:3], s[18:19], 0, v[34:35]
	s_mov_b64 s[0:1], 0x1000
	v_lshl_add_u64 v[6:7], s[4:5], 0, v[34:35]
	s_add_u32 s18, s20, 0x3900000
	v_lshl_add_u64 v[26:27], v[2:3], 0, s[0:1]
	v_lshl_add_u64 v[30:31], v[6:7], 0, s[0:1]
	s_movk_i32 s0, 0x1000
	s_addc_u32 s19, s8, 0
	v_add_co_u32_e32 v2, vcc, s0, v2
	s_add_u32 s10, s20, 0xa100000
	s_nop 0
	v_addc_co_u32_e32 v3, vcc, 0, v3, vcc
	s_addc_u32 s11, s8, 0
	v_add_co_u32_e32 v6, vcc, s0, v6
	s_add_u32 s0, s10, s24
	v_writelane_b32 v253, s24, 36
	s_addc_u32 s1, s11, s25
	s_add_u32 s4, s10, s26
	v_writelane_b32 v253, s25, 37
	v_lshlrev_b32_e32 v34, 3, v74
	v_addc_co_u32_e32 v7, vcc, 0, v7, vcc
	v_writelane_b32 v253, s26, 38
	s_addc_u32 s5, s11, s27
	v_lshl_add_u64 v[36:37], s[0:1], 0, v[34:35]
	global_load_dwordx4 v[2:5], v[2:3], off nt
	s_nop 0
	global_load_dwordx4 v[6:9], v[6:7], off nt
	s_nop 0
	global_load_dwordx4 v[10:13], v[26:27], off offset:1024
	global_load_dwordx4 v[14:17], v[26:27], off offset:2048
	global_load_dwordx4 v[18:21], v[30:31], off offset:1024
	global_load_dwordx4 v[22:25], v[30:31], off offset:2048
	s_nop 0
	global_load_dwordx4 v[26:29], v[26:27], off offset:3072
	s_nop 0
	global_load_dwordx4 v[30:33], v[30:31], off offset:3072
	v_lshl_add_u64 v[46:47], s[4:5], 0, v[34:35]
	flat_load_dwordx2 v[64:65], v[36:37] nt
	flat_load_dwordx2 v[62:63], v[36:37] offset:512 nt
	flat_load_dwordx2 v[60:61], v[36:37] offset:1024 nt
	flat_load_dwordx2 v[58:59], v[36:37] offset:1536 nt
	flat_load_dwordx2 v[44:45], v[46:47] nt
	flat_load_dwordx2 v[42:43], v[46:47] offset:512 nt
	flat_load_dwordx2 v[40:41], v[46:47] offset:1024 nt
	s_nop 0
	flat_load_dwordx2 v[36:37], v[46:47] offset:1536 nt
	s_mov_b32 s7, s8
	v_cmp_gt_u32_e64 s[8:9], 16, v74
	v_mov_b32_e32 v75, -1
	v_lshlrev_b32_e32 v38, 11, v74
	v_mov_b32_e32 v82, v35
	v_mov_b32_e32 v81, -1
	v_writelane_b32 v253, s27, 39
	s_and_saveexec_b64 s[24:25], s[8:9]
	s_cbranch_execz .LBB0_815
	v_readlane_b32 s0, v253, 34
	v_readlane_b32 s1, v253, 35
	s_mov_b32 s4, s0
	s_ashr_i32 s0, s0, 11
	s_ashr_i32 s1, s0, 31
	s_lshl_b64 s[0:1], s[0:1], 15
	s_and_b32 s4, s4, 0x7ff
	s_or_b32 s0, s0, s4
	s_ashr_i32 s4, s68, 11
	s_ashr_i32 s5, s4, 31
	s_lshl_b64 s[4:5], s[4:5], 15
	s_and_b32 s6, s68, 0x7ff
	s_or_b32 s4, s4, s6
	v_or_b32_e32 v46, s4, v38
	v_mov_b32_e32 v47, s5
	v_lshl_add_u64 v[48:49], v[46:47], 1, s[22:23]
	v_lshl_add_u64 v[46:47], v[46:47], 2, s[18:19]
	flat_load_sshort v81, v[48:49]
	flat_load_dword v82, v[46:47] nt
	v_or_b32_e32 v46, s0, v38
	v_mov_b32_e32 v47, s1
	v_lshl_add_u64 v[48:49], v[46:47], 1, s[22:23]
	v_lshl_add_u64 v[46:47], v[46:47], 2, s[18:19]
	flat_load_sshort v75, v[48:49]
	flat_load_dword v35, v[46:47] nt

.LBB0_818:
	s_add_i32 s26, s28, s94
	s_cmp_gt_i32 s26, 0xffff
	v_mov_b32_e32 v80, v35
	s_cbranch_scc1 .LBB0_822
	s_ashr_i32 s27, s26, 31
	s_lshl_b64 s[0:1], s[26:27], 11
	v_lshl_add_u64 v[50:51], v[48:49], 0, s[0:1]
	flat_load_dwordx2 v[56:57], v[50:51] nt
	flat_load_dwordx2 v[54:55], v[50:51] offset:512 nt
	flat_load_dwordx2 v[52:53], v[50:51] offset:1024 nt
	s_nop 0
	flat_load_dwordx2 v[50:51], v[50:51] offset:1536 nt
	v_mov_b32_e32 v79, v75
	v_mov_b32_e32 v80, v35
	s_and_saveexec_b64 s[10:11], s[8:9]
	s_cbranch_execz .LBB0_821
	s_ashr_i32 s0, s26, 11
	s_ashr_i32 s1, s0, 31
	s_lshl_b64 s[0:1], s[0:1], 15
	v_or_b32_e32 v34, s0, v38
	s_and_b32 s0, s26, 0x7ff
	v_mov_b32_e32 v67, s1
	v_or_b32_e32 v66, s0, v34
	v_lshl_add_u64 v[68:69], v[66:67], 1, s[22:23]
	v_lshl_add_u64 v[66:67], v[66:67], 2, s[18:19]
	flat_load_sshort v79, v[68:69]
	flat_load_dword v80, v[66:67] nt

.LBB0_824:
	s_add_u32 s36, s34, -1
	s_addc_u32 s37, s35, -1
	s_lshl_b32 s11, s11, 5
	s_and_b64 vcc, s[36:37], s[34:35]
	s_add_i32 s34, s11, s6
	s_ashr_i32 s35, s34, 31
	s_ashr_i32 s31, s30, 31
	s_lshl_b64 s[34:35], s[34:35], 18
	s_lshl_b64 s[30:31], s[30:31], 10
	s_add_u32 s11, s4, s34
	s_addc_u32 s21, s5, s35
	s_add_u32 s30, s11, s30
	s_addc_u32 s31, s21, s31
	s_lshl_b32 s1, s1, 5
	s_add_i32 s34, s1, s6
	s_ashr_i32 s35, s34, 31
	s_ashr_i32 s11, s10, 31
	v_lshlrev_b32_e32 v46, 2, v74
	s_lshl_b64 s[34:35], s[34:35], 18
	s_lshl_b64 s[10:11], s[10:11], 10
	v_lshl_add_u64 v[84:85], s[30:31], 0, v[46:47]
	s_add_u32 s1, s4, s34
	flat_load_dword v83, v[84:85] nt
	s_addc_u32 s21, s5, s35
	s_add_u32 s10, s1, s10
	s_addc_u32 s11, s21, s11
	v_lshl_add_u64 v[86:87], s[10:11], 0, v[46:47]
	flat_load_dword v90, v[86:87] nt
	flat_load_dword v92, v[84:85] offset:256 nt
	flat_load_dword v93, v[86:87] offset:256 nt
	flat_load_dword v94, v[84:85] offset:512 nt
	flat_load_dword v95, v[86:87] offset:512 nt
	flat_load_dword v96, v[84:85] offset:768 nt
	flat_load_dword v97, v[86:87] offset:768 nt
	v_mul_f32_e32 v46, s0, v78
	s_cmp_eq_u64 vcc, 0
	s_waitcnt vmcnt(0) lgkmcnt(0)
	v_cvt_pk_f32_fp8_e32 v[88:89], v90
	v_cvt_pk_f32_fp8_sdwa v[90:91], v90 src0_sel:WORD_1
	v_cvt_pk_f32_fp8_e32 v[84:85], v83
	v_cvt_pk_f32_fp8_sdwa v[86:87], v83 src0_sel:WORD_1
	v_pk_mul_f32 v[88:89], v[34:35], v[88:89] op_sel_hi:[0,1]
	v_pk_mul_f32 v[90:91], v[34:35], v[90:91] op_sel_hi:[0,1]
	v_pk_fma_f32 v[84:85], v[46:47], v[84:85], v[88:89] op_sel_hi:[0,1,1]
	v_pk_fma_f32 v[86:87], v[46:47], v[86:87], v[90:91] op_sel_hi:[0,1,1]
	v_cvt_pk_f32_fp8_e32 v[88:89], v93
	v_cvt_pk_f32_fp8_sdwa v[90:91], v93 src0_sel:WORD_1
	v_pk_add_f32 v[68:69], v[68:69], v[86:87]
	v_pk_add_f32 v[70:71], v[70:71], v[84:85]
	v_cvt_pk_f32_fp8_e32 v[84:85], v92
	v_cvt_pk_f32_fp8_sdwa v[86:87], v92 src0_sel:WORD_1
	v_pk_mul_f32 v[90:91], v[34:35], v[90:91] op_sel_hi:[0,1]
	v_pk_mul_f32 v[88:89], v[34:35], v[88:89] op_sel_hi:[0,1]
	v_pk_fma_f32 v[84:85], v[46:47], v[84:85], v[88:89] op_sel_hi:[0,1,1]
	v_pk_fma_f32 v[86:87], v[46:47], v[86:87], v[90:91] op_sel_hi:[0,1,1]
	v_cvt_pk_f32_fp8_e32 v[88:89], v95
	v_cvt_pk_f32_fp8_sdwa v[90:91], v95 src0_sel:WORD_1
	v_pk_add_f32 v[62:63], v[62:63], v[86:87]
	v_pk_add_f32 v[66:67], v[66:67], v[84:85]
	v_cvt_pk_f32_fp8_e32 v[84:85], v94
	v_cvt_pk_f32_fp8_sdwa v[86:87], v94 src0_sel:WORD_1
	v_pk_mul_f32 v[90:91], v[34:35], v[90:91] op_sel_hi:[0,1]
	v_pk_mul_f32 v[88:89], v[34:35], v[88:89] op_sel_hi:[0,1]
	v_pk_fma_f32 v[84:85], v[46:47], v[84:85], v[88:89] op_sel_hi:[0,1,1]
	v_pk_fma_f32 v[86:87], v[46:47], v[86:87], v[90:91] op_sel_hi:[0,1,1]
	v_cvt_pk_f32_fp8_e32 v[88:89], v97
	v_cvt_pk_f32_fp8_sdwa v[90:91], v97 src0_sel:WORD_1
	v_pk_add_f32 v[60:61], v[60:61], v[86:87]
	v_pk_add_f32 v[64:65], v[64:65], v[84:85]
	v_cvt_pk_f32_fp8_e32 v[84:85], v96
	v_cvt_pk_f32_fp8_sdwa v[86:87], v96 src0_sel:WORD_1
	v_pk_mul_f32 v[90:91], v[34:35], v[90:91] op_sel_hi:[0,1]
	v_pk_mul_f32 v[88:89], v[34:35], v[88:89] op_sel_hi:[0,1]
	v_pk_fma_f32 v[84:85], v[46:47], v[84:85], v[88:89] op_sel_hi:[0,1,1]
	v_pk_fma_f32 v[86:87], v[46:47], v[86:87], v[90:91] op_sel_hi:[0,1,1]
	v_pk_add_f32 v[72:73], v[72:73], v[86:87]
	v_pk_add_f32 v[58:59], v[58:59], v[84:85]
	s_cbranch_scc1 .LBB0_817

.LBB0_1039:
	s_lshl_b32 s0, s7, 8
	s_add_i32 s0, s0, s97
	s_ashr_i32 s1, s0, 31
	s_add_i32 s10, s0, 8
	s_lshl_b64 s[12:13], s[0:1], 11
	s_ashr_i32 s11, s10, 31
	v_lshl_add_u64 v[18:19], v[92:93], 0, s[12:13]
	v_lshl_add_u64 v[20:21], v[94:95], 0, s[12:13]
	v_mad_i64_i32 v[22:23], s[12:13], s0, v102, v[96:97]
	s_lshl_b64 s[12:13], s[10:11], 11
	s_nop 0
	v_lshl_add_u64 v[24:25], v[92:93], 0, s[12:13]
	v_lshl_add_u64 v[38:39], v[94:95], 0, s[12:13]
	global_load_dwordx4 v[2:5], v[90:91], off
	global_load_dwordx4 v[6:9], v[90:91], off offset:16
	global_load_dwordx4 v[10:13], v[90:91], off offset:2048
	global_load_dwordx4 v[14:17], v[90:91], off offset:2064
	v_mad_i64_i32 v[54:55], s[10:11], s10, v102, v[96:97]
	flat_load_dwordx4 v[86:89], v[18:19] nt
	flat_load_dwordx4 v[50:53], v[18:19] offset:1024 nt
	flat_load_dwordx4 v[82:85], v[20:21] nt
	flat_load_dwordx4 v[46:49], v[20:21] offset:1024 nt
	flat_load_dwordx4 v[78:81], v[22:23] nt
	flat_load_dwordx4 v[42:45], v[22:23] offset:1024 nt
	flat_load_dwordx4 v[26:29], v[24:25] nt
	flat_load_dwordx4 v[30:33], v[24:25] offset:1024 nt
	flat_load_dwordx4 v[34:37], v[38:39] nt
	s_nop 0
	flat_load_dwordx4 v[38:41], v[38:39] offset:1024 nt
	s_nop 0
	flat_load_dwordx4 v[18:21], v[54:55] nt
	flat_load_dwordx4 v[22:25], v[54:55] offset:1024 nt
	s_add_i32 s10, s0, 16
	s_mov_b32 s24, s4
	s_mov_b32 s11, 0
.LBB0_1040:
	s_waitcnt vmcnt(0) lgkmcnt(0)
	v_lshlrev_b32_e32 v100, 16, v89
	v_and_b32_e32 v101, 0xffff0000, v89
	v_lshlrev_b32_e32 v106, 16, v85
	v_and_b32_e32 v107, 0xffff0000, v85
	v_pk_add_f32 v[106:107], v[106:107], v[100:101]
	v_lshlrev_b32_e32 v100, 16, v81
	v_and_b32_e32 v101, 0xffff0000, v81
	v_mul_f32_e32 v81, 0xbfb8aa3b, v100
	v_exp_f32_e32 v81, v81
	v_and_b32_e32 v89, 0xffff0000, v84
	s_min_u32 s0, s11, 29
	s_lshl_b32 s0, s0, 3
	v_add_f32_e32 v81, 1.0, v81
	v_rcp_f32_e32 v108, v81
	v_mul_f32_e32 v81, 0xbfb8aa3b, v101
	v_exp_f32_e32 v81, v81
	s_add_i32 s0, s10, s0
	s_ashr_i32 s1, s0, 31
	s_lshl_b64 s[12:13], s[0:1], 11
	v_add_f32_e32 v81, 1.0, v81
	v_rcp_f32_e32 v109, v81
	v_mad_i64_i32 v[74:75], s[0:1], s0, v102, v[96:97]
	v_mov_b64_e32 v[64:65], v[40:41]
	v_pk_mul_f32 v[100:101], v[108:109], v[100:101]
	v_lshlrev_b32_e32 v108, 16, v88
	v_and_b32_e32 v109, 0xffff0000, v88
	v_lshlrev_b32_e32 v88, 16, v84
	v_pk_add_f32 v[84:85], v[88:89], v[108:109]
	v_lshlrev_b32_e32 v88, 16, v80
	v_and_b32_e32 v89, 0xffff0000, v80
	v_mul_f32_e32 v80, 0xbfb8aa3b, v88
	v_mul_f32_e32 v81, 0xbfb8aa3b, v89
	v_exp_f32_e32 v80, v80
	v_exp_f32_e32 v81, v81
	v_lshlrev_b32_e32 v108, 16, v83
	v_and_b32_e32 v109, 0xffff0000, v83
	v_add_f32_e32 v80, 1.0, v80
	v_add_f32_e32 v81, 1.0, v81
	v_rcp_f32_e32 v80, v80
	v_rcp_f32_e32 v81, v81
	v_mov_b32_e32 v113, v85
	v_mov_b64_e32 v[56:57], v[32:33]
	v_mov_b64_e32 v[62:63], v[38:39]
	v_pk_mul_f32 v[80:81], v[80:81], v[88:89]
	v_lshlrev_b32_e32 v88, 16, v87
	v_and_b32_e32 v89, 0xffff0000, v87
	v_pk_add_f32 v[88:89], v[108:109], v[88:89]
	v_lshlrev_b32_e32 v108, 16, v79
	v_and_b32_e32 v109, 0xffff0000, v79
	v_mul_f32_e32 v79, 0xbfb8aa3b, v108
	v_exp_f32_e32 v79, v79
	v_and_b32_e32 v87, 0xffff0000, v82
	v_mov_b64_e32 v[54:55], v[30:31]
	v_lshl_add_u64 v[30:31], v[92:93], 0, s[12:13]
	v_add_f32_e32 v79, 1.0, v79
	v_rcp_f32_e32 v110, v79
	v_mul_f32_e32 v79, 0xbfb8aa3b, v109
	v_exp_f32_e32 v79, v79
	v_lshl_add_u64 v[38:39], v[94:95], 0, s[12:13]
	s_ashr_i32 s25, s24, 31
	s_lshl_b64 s[26:27], s[24:25], 11
	v_add_f32_e32 v79, 1.0, v79
	v_rcp_f32_e32 v111, v79
	v_mov_b64_e32 v[68:69], v[36:37]
	v_mov_b64_e32 v[60:61], v[28:29]
	v_mov_b64_e32 v[66:67], v[34:35]
	v_pk_mul_f32 v[108:109], v[110:111], v[108:109]
	v_lshlrev_b32_e32 v110, 16, v86
	v_and_b32_e32 v111, 0xffff0000, v86
	v_lshlrev_b32_e32 v86, 16, v82
	v_pk_add_f32 v[82:83], v[86:87], v[110:111]
	v_lshlrev_b32_e32 v86, 16, v78
	v_and_b32_e32 v87, 0xffff0000, v78
	v_mul_f32_e32 v78, 0xbfb8aa3b, v86
	v_mul_f32_e32 v79, 0xbfb8aa3b, v87
	v_exp_f32_e32 v78, v78
	v_exp_f32_e32 v79, v79
	v_mov_b32_e32 v110, v89
	v_mov_b32_e32 v111, v107
	v_add_f32_e32 v78, 1.0, v78
	v_add_f32_e32 v79, 1.0, v79
	v_rcp_f32_e32 v78, v78
	v_rcp_f32_e32 v79, v79
	v_mov_b32_e32 v112, v83
	v_mov_b64_e32 v[58:59], v[26:27]
	flat_load_dwordx4 v[26:29], v[30:31] nt
	flat_load_dwordx4 v[34:37], v[38:39] nt
	v_pk_mul_f32 v[78:79], v[78:79], v[86:87]
	v_mov_b32_e32 v86, v88
	v_mov_b32_e32 v87, v106
	v_pk_add_f32 v[86:87], v[86:87], v[110:111]
	v_mov_b32_e32 v110, v82
	v_mov_b32_e32 v111, v84
	v_pk_add_f32 v[110:111], v[110:111], v[112:113]
	flat_load_dwordx4 v[70:73], v[74:75] nt
	s_nop 0
	flat_load_dwordx4 v[30:33], v[30:31] offset:1024 nt
	s_nop 0
	flat_load_dwordx4 v[38:41], v[38:39] offset:1024 nt
	s_nop 0
	flat_load_dwordx4 v[74:77], v[74:75] offset:1024 nt
	v_pk_add_f32 v[86:87], v[110:111], v[86:87]
	s_add_i32 s11, s11, 1
	v_add_f32_e32 v86, v86, v87
	s_add_i32 s24, s24, 8
	s_cmp_lg_u32 s11, 32
	v_add_f32_dpp v86, v86, v86 quad_perm:[1,0,3,2] row_mask:0xf bank_mask:0xf bound_ctrl:1
	s_nop 1
	v_add_f32_dpp v86, v86, v86 quad_perm:[2,3,0,1] row_mask:0xf bank_mask:0xf bound_ctrl:1
	s_nop 1
	v_add_f32_dpp v86, v86, v86 row_half_mirror row_mask:0xf bank_mask:0xf bound_ctrl:1
	s_nop 1
	v_add_f32_dpp v86, v86, v86 row_mirror row_mask:0xf bank_mask:0xf bound_ctrl:1
	s_nop 0
	v_readlane_b32 s1, v86, 16
	v_readlane_b32 s0, v86, 0
	s_nop 0
	v_mov_b32_e32 v87, s1
	v_readlane_b32 s1, v86, 48
	v_add_f32_e32 v87, s0, v87
	v_readlane_b32 s0, v86, 32
	v_mov_b32_e32 v86, s1
	s_nop 0
	v_add_f32_e32 v86, s0, v86
	v_cndmask_b32_e64 v86, v87, v86, s[8:9]
	v_mul_f32_e32 v86, 0x3b800000, v86
	v_pk_add_f32 v[82:83], v[82:83], v[86:87] op_sel_hi:[1,0] neg_lo:[0,1] neg_hi:[0,1]
	v_pk_add_f32 v[88:89], v[88:89], v[86:87] op_sel_hi:[1,0] neg_lo:[0,1] neg_hi:[0,1]
	v_pk_mul_f32 v[110:111], v[82:83], v[82:83]
	v_pk_mul_f32 v[112:113], v[88:89], v[88:89]
	v_add_f32_e32 v105, v110, v111
	v_pk_add_f32 v[84:85], v[84:85], v[86:87] op_sel_hi:[1,0] neg_lo:[0,1] neg_hi:[0,1]
	v_add_f32_e32 v105, v112, v105
	v_pk_mul_f32 v[114:115], v[84:85], v[84:85]
	v_add_f32_e32 v105, v113, v105
	v_pk_add_f32 v[86:87], v[106:107], v[86:87] op_sel_hi:[1,0] neg_lo:[0,1] neg_hi:[0,1]
	v_add_f32_e32 v105, v114, v105
	v_pk_mul_f32 v[106:107], v[86:87], v[86:87]
	v_add_f32_e32 v105, v115, v105
	v_add_f32_e32 v105, v106, v105
	v_add_f32_e32 v105, v107, v105
	s_nop 1
	v_add_f32_dpp v105, v105, v105 quad_perm:[1,0,3,2] row_mask:0xf bank_mask:0xf bound_ctrl:1
	s_nop 1
	v_add_f32_dpp v105, v105, v105 quad_perm:[2,3,0,1] row_mask:0xf bank_mask:0xf bound_ctrl:1
	s_nop 1
	v_add_f32_dpp v105, v105, v105 row_half_mirror row_mask:0xf bank_mask:0xf bound_ctrl:1
	s_nop 1
	v_add_f32_dpp v105, v105, v105 row_mirror row_mask:0xf bank_mask:0xf bound_ctrl:1
	s_nop 0
	v_readlane_b32 s1, v105, 16
	v_readlane_b32 s0, v105, 0
	s_nop 0
	v_mov_b32_e32 v106, s1
	v_readlane_b32 s1, v105, 48
	v_add_f32_e32 v106, s0, v106
	v_readlane_b32 s0, v105, 32
	v_mov_b32_e32 v105, s1
	s_nop 0
	v_add_f32_e32 v105, s0, v105
	v_cndmask_b32_e64 v105, v106, v105, s[8:9]
	v_fmamk_f32 v105, v105, 0x3b800000, v103
	v_cmp_gt_f32_e32 vcc, s6, v105
	v_mul_f32_e32 v106, 0x4f800000, v105
	s_nop 0
	v_cndmask_b32_e32 v105, v105, v106, vcc
	v_sqrt_f32_e32 v106, v105
	s_nop 0
	v_add_u32_e32 v107, -1, v106
	v_fma_f32 v110, -v107, v106, v105
	v_cmp_ge_f32_e64 s[12:13], 0, v110
	v_add_u32_e32 v110, 1, v106
	s_nop 0
	v_cndmask_b32_e64 v107, v106, v107, s[12:13]
	v_fma_f32 v106, -v110, v106, v105
	v_cmp_lt_f32_e64 s[12:13], 0, v106
	s_nop 1
	v_cndmask_b32_e64 v106, v107, v110, s[12:13]
	v_mul_f32_e32 v107, 0x37800000, v106
	v_cndmask_b32_e32 v106, v106, v107, vcc
	v_cmp_class_f32_e32 vcc, v105, v104
	s_nop 1
	v_cndmask_b32_e32 v105, v106, v105, vcc
	v_div_scale_f32 v106, s[0:1], v105, v105, 1.0
	v_rcp_f32_e32 v107, v106
	s_nop 0
	v_fma_f32 v110, -v106, v107, 1.0
	v_fmac_f32_e32 v107, v110, v107
	v_div_scale_f32 v110, vcc, 1.0, v105, 1.0
	v_mul_f32_e32 v111, v110, v107
	v_fma_f32 v112, -v106, v111, v110
	v_fmac_f32_e32 v111, v112, v107
	v_fma_f32 v106, -v106, v111, v110
	v_div_fmas_f32 v106, v106, v107, v111
	v_div_fixup_f32 v106, v106, v105, 1.0
	v_pk_mul_f32 v[82:83], v[82:83], v[106:107] op_sel_hi:[1,0]
	v_pk_mul_f32 v[84:85], v[84:85], v[106:107] op_sel_hi:[1,0]
	v_pk_mul_f32 v[82:83], v[2:3], v[82:83]
	v_pk_mul_f32 v[84:85], v[6:7], v[84:85]
	v_pk_mul_f32 v[78:79], v[78:79], v[82:83]
	v_pk_mul_f32 v[82:83], v[88:89], v[106:107] op_sel_hi:[1,0]
	v_pk_mul_f32 v[84:85], v[80:81], v[84:85]
	v_pk_mul_f32 v[80:81], v[86:87], v[106:107] op_sel_hi:[1,0]
	v_pk_mul_f32 v[82:83], v[4:5], v[82:83]
	v_pk_mul_f32 v[80:81], v[8:9], v[80:81]
	v_pk_mul_f32 v[82:83], v[108:109], v[82:83]
	v_pk_mul_f32 v[86:87], v[100:101], v[80:81]
	v_cvt_pk_bf16_f32 v80, v78, v79
	v_cvt_pk_bf16_f32 v81, v82, v83
	v_cvt_pk_bf16_f32 v82, v84, v85
	v_cvt_pk_bf16_f32 v83, v86, v87
	v_lshl_add_u64 v[78:79], v[98:99], 0, s[26:27]
	flat_store_dwordx4 v[78:79], v[80:83]
	s_nop 1
	v_lshlrev_b32_e32 v80, 16, v53
	v_and_b32_e32 v81, 0xffff0000, v53
	v_lshlrev_b32_e32 v82, 16, v49
	v_and_b32_e32 v83, 0xffff0000, v49
	v_pk_add_f32 v[82:83], v[82:83], v[80:81]
	v_lshlrev_b32_e32 v80, 16, v45
	v_and_b32_e32 v81, 0xffff0000, v45
	v_mul_f32_e32 v45, 0xbfb8aa3b, v80
	v_exp_f32_e32 v45, v45
	v_and_b32_e32 v53, 0xffff0000, v48
	v_add_f32_e32 v45, 1.0, v45
	v_rcp_f32_e32 v84, v45
	v_mul_f32_e32 v45, 0xbfb8aa3b, v81
	v_exp_f32_e32 v45, v45
	s_nop 0
	v_add_f32_e32 v45, 1.0, v45
	v_rcp_f32_e32 v85, v45
	s_nop 0
	v_pk_mul_f32 v[80:81], v[84:85], v[80:81]
	v_lshlrev_b32_e32 v84, 16, v52
	v_and_b32_e32 v85, 0xffff0000, v52
	v_lshlrev_b32_e32 v52, 16, v48
	v_pk_add_f32 v[48:49], v[52:53], v[84:85]
	v_lshlrev_b32_e32 v52, 16, v44
	v_and_b32_e32 v53, 0xffff0000, v44
	v_mul_f32_e32 v44, 0xbfb8aa3b, v52
	v_mul_f32_e32 v45, 0xbfb8aa3b, v53
	v_exp_f32_e32 v44, v44
	v_exp_f32_e32 v45, v45
	v_lshlrev_b32_e32 v84, 16, v47
	v_and_b32_e32 v85, 0xffff0000, v47
	v_add_f32_e32 v44, 1.0, v44
	v_add_f32_e32 v45, 1.0, v45
	v_rcp_f32_e32 v44, v44
	v_rcp_f32_e32 v45, v45
	v_mov_b32_e32 v89, v49
	v_pk_mul_f32 v[44:45], v[44:45], v[52:53]
	v_lshlrev_b32_e32 v52, 16, v51
	v_and_b32_e32 v53, 0xffff0000, v51
	v_pk_add_f32 v[52:53], v[84:85], v[52:53]
	v_lshlrev_b32_e32 v84, 16, v43
	v_and_b32_e32 v85, 0xffff0000, v43
	v_mul_f32_e32 v43, 0xbfb8aa3b, v84
	v_exp_f32_e32 v43, v43
	v_and_b32_e32 v51, 0xffff0000, v46
	v_add_f32_e32 v43, 1.0, v43
	v_rcp_f32_e32 v86, v43
	v_mul_f32_e32 v43, 0xbfb8aa3b, v85
	v_exp_f32_e32 v43, v43
	s_nop 0
	v_add_f32_e32 v43, 1.0, v43
	v_rcp_f32_e32 v87, v43
	s_nop 0
	v_pk_mul_f32 v[84:85], v[86:87], v[84:85]
	v_lshlrev_b32_e32 v86, 16, v50
	v_and_b32_e32 v87, 0xffff0000, v50
	v_lshlrev_b32_e32 v50, 16, v46
	v_pk_add_f32 v[46:47], v[50:51], v[86:87]
	v_lshlrev_b32_e32 v50, 16, v42
	v_and_b32_e32 v51, 0xffff0000, v42
	v_mul_f32_e32 v42, 0xbfb8aa3b, v50
	v_mul_f32_e32 v43, 0xbfb8aa3b, v51
	v_exp_f32_e32 v42, v42
	v_exp_f32_e32 v43, v43
	v_mov_b32_e32 v86, v53
	v_mov_b32_e32 v87, v83
	v_add_f32_e32 v42, 1.0, v42
	v_add_f32_e32 v43, 1.0, v43
	v_rcp_f32_e32 v42, v42
	v_rcp_f32_e32 v43, v43
	v_mov_b32_e32 v88, v47
	v_pk_mul_f32 v[42:43], v[42:43], v[50:51]
	v_mov_b32_e32 v50, v52
	v_mov_b32_e32 v51, v82
	v_pk_add_f32 v[50:51], v[50:51], v[86:87]
	v_mov_b32_e32 v86, v46
	v_mov_b32_e32 v87, v48
	v_pk_add_f32 v[86:87], v[86:87], v[88:89]
	s_nop 0
	v_pk_add_f32 v[50:51], v[86:87], v[50:51]
	s_nop 0
	v_add_f32_e32 v50, v50, v51
	s_nop 1
	v_add_f32_dpp v50, v50, v50 quad_perm:[1,0,3,2] row_mask:0xf bank_mask:0xf bound_ctrl:1
	s_nop 1
	v_add_f32_dpp v50, v50, v50 quad_perm:[2,3,0,1] row_mask:0xf bank_mask:0xf bound_ctrl:1
	s_nop 1
	v_add_f32_dpp v50, v50, v50 row_half_mirror row_mask:0xf bank_mask:0xf bound_ctrl:1
	s_nop 1
	v_add_f32_dpp v50, v50, v50 row_mirror row_mask:0xf bank_mask:0xf bound_ctrl:1
	s_nop 0
	v_readlane_b32 s1, v50, 16
	v_readlane_b32 s0, v50, 0
	s_nop 0
	v_mov_b32_e32 v51, s1
	v_readlane_b32 s1, v50, 48
	v_add_f32_e32 v51, s0, v51
	v_readlane_b32 s0, v50, 32
	v_mov_b32_e32 v50, s1
	s_nop 0
	v_add_f32_e32 v50, s0, v50
	v_cndmask_b32_e64 v50, v51, v50, s[8:9]
	v_mul_f32_e32 v50, 0x3b800000, v50
	v_pk_add_f32 v[46:47], v[46:47], v[50:51] op_sel_hi:[1,0] neg_lo:[0,1] neg_hi:[0,1]
	v_pk_add_f32 v[52:53], v[52:53], v[50:51] op_sel_hi:[1,0] neg_lo:[0,1] neg_hi:[0,1]
	v_pk_mul_f32 v[86:87], v[46:47], v[46:47]
	v_pk_mul_f32 v[88:89], v[52:53], v[52:53]
	v_add_f32_e32 v86, v86, v87
	v_pk_add_f32 v[48:49], v[48:49], v[50:51] op_sel_hi:[1,0] neg_lo:[0,1] neg_hi:[0,1]
	v_add_f32_e32 v86, v88, v86
	v_pk_mul_f32 v[100:101], v[48:49], v[48:49]
	v_add_f32_e32 v86, v89, v86
	v_pk_add_f32 v[50:51], v[82:83], v[50:51] op_sel_hi:[1,0] neg_lo:[0,1] neg_hi:[0,1]
	v_add_f32_e32 v86, v100, v86
	v_pk_mul_f32 v[82:83], v[50:51], v[50:51]
	v_add_f32_e32 v86, v101, v86
	v_add_f32_e32 v82, v82, v86
	v_add_f32_e32 v82, v83, v82
	s_nop 1
	v_add_f32_dpp v82, v82, v82 quad_perm:[1,0,3,2] row_mask:0xf bank_mask:0xf bound_ctrl:1
	s_nop 1
	v_add_f32_dpp v82, v82, v82 quad_perm:[2,3,0,1] row_mask:0xf bank_mask:0xf bound_ctrl:1
	s_nop 1
	v_add_f32_dpp v82, v82, v82 row_half_mirror row_mask:0xf bank_mask:0xf bound_ctrl:1
	s_nop 1
	v_add_f32_dpp v82, v82, v82 row_mirror row_mask:0xf bank_mask:0xf bound_ctrl:1
	s_nop 0
	v_readlane_b32 s1, v82, 16
	v_readlane_b32 s0, v82, 0
	s_nop 0
	v_mov_b32_e32 v83, s1
	v_readlane_b32 s1, v82, 48
	v_add_f32_e32 v83, s0, v83
	v_readlane_b32 s0, v82, 32
	v_mov_b32_e32 v82, s1
	s_nop 0
	v_add_f32_e32 v82, s0, v82
	v_cndmask_b32_e64 v82, v83, v82, s[8:9]
	v_fmamk_f32 v82, v82, 0x3b800000, v103
	v_cmp_gt_f32_e32 vcc, s6, v82
	v_mul_f32_e32 v83, 0x4f800000, v82
	s_nop 0
	v_cndmask_b32_e32 v82, v82, v83, vcc
	v_sqrt_f32_e32 v83, v82
	s_nop 0
	v_add_u32_e32 v86, -1, v83
	v_fma_f32 v87, -v86, v83, v82
	v_cmp_ge_f32_e64 s[12:13], 0, v87
	v_add_u32_e32 v87, 1, v83
	s_nop 0
	v_cndmask_b32_e64 v86, v83, v86, s[12:13]
	v_fma_f32 v83, -v87, v83, v82
	v_cmp_lt_f32_e64 s[12:13], 0, v83
	s_nop 1
	v_cndmask_b32_e64 v83, v86, v87, s[12:13]
	v_mul_f32_e32 v86, 0x37800000, v83
	v_cndmask_b32_e32 v83, v83, v86, vcc
	v_cmp_class_f32_e32 vcc, v82, v104
	s_nop 1
	v_cndmask_b32_e32 v82, v83, v82, vcc
	v_div_scale_f32 v83, s[0:1], v82, v82, 1.0
	v_rcp_f32_e32 v86, v83
	s_nop 0
	v_fma_f32 v87, -v83, v86, 1.0
	v_fmac_f32_e32 v86, v87, v86
	v_div_scale_f32 v87, vcc, 1.0, v82, 1.0
	v_mul_f32_e32 v88, v87, v86
	v_fma_f32 v89, -v83, v88, v87
	v_fmac_f32_e32 v88, v89, v86
	v_fma_f32 v83, -v83, v88, v87
	v_div_fmas_f32 v83, v83, v86, v88
	v_div_fixup_f32 v82, v83, v82, 1.0
	v_pk_mul_f32 v[46:47], v[46:47], v[82:83] op_sel_hi:[1,0]
	v_pk_mul_f32 v[48:49], v[48:49], v[82:83] op_sel_hi:[1,0]
	v_pk_mul_f32 v[46:47], v[10:11], v[46:47]
	v_pk_mul_f32 v[48:49], v[14:15], v[48:49]
	v_pk_mul_f32 v[42:43], v[42:43], v[46:47]
	v_pk_mul_f32 v[46:47], v[52:53], v[82:83] op_sel_hi:[1,0]
	v_pk_mul_f32 v[44:45], v[44:45], v[48:49]
	v_pk_mul_f32 v[48:49], v[50:51], v[82:83] op_sel_hi:[1,0]
	v_pk_mul_f32 v[46:47], v[12:13], v[46:47]
	v_pk_mul_f32 v[48:49], v[16:17], v[48:49]
	v_pk_mul_f32 v[46:47], v[84:85], v[46:47]
	v_pk_mul_f32 v[48:49], v[80:81], v[48:49]
	v_cvt_pk_bf16_f32 v42, v42, v43
	v_cvt_pk_bf16_f32 v43, v46, v47
	v_cvt_pk_bf16_f32 v44, v44, v45
	v_cvt_pk_bf16_f32 v45, v48, v49
	flat_store_dwordx4 v[78:79], v[42:45] offset:1024
	v_mov_b64_e32 v[80:81], v[20:21]
	v_mov_b64_e32 v[78:79], v[18:19]
	v_mov_b64_e32 v[44:45], v[24:25]
	v_mov_b64_e32 v[42:43], v[22:23]
	s_waitcnt vmcnt(0) lgkmcnt(0)
	v_mov_b64_e32 v[22:23], v[74:75]
	v_mov_b64_e32 v[18:19], v[70:71]
	v_mov_b64_e32 v[84:85], v[68:69]
	v_mov_b64_e32 v[46:47], v[62:63]
	v_mov_b64_e32 v[88:89], v[60:61]
	v_mov_b64_e32 v[50:51], v[54:55]
	v_mov_b64_e32 v[24:25], v[76:77]
	v_mov_b64_e32 v[20:21], v[72:73]
	v_mov_b64_e32 v[82:83], v[66:67]
	v_mov_b64_e32 v[48:49], v[64:65]
	v_mov_b64_e32 v[86:87], v[58:59]
	v_mov_b64_e32 v[52:53], v[56:57]
	s_cbranch_scc1 .LBB0_1040
	s_add_i32 s7, s7, s74
	s_add_i32 s4, s4, s5
	s_cmpk_gt_i32 s7, 0xff
	s_cbranch_scc0 .LBB0_1039

.LBB0_1047:
	ds_read_b128 v[130:133], v170
	ds_read_b128 v[134:137], v170 offset:1024
	ds_read_b128 v[138:141], v170 offset:2048
	ds_read_b128 v[142:145], v170 offset:3072
	s_add_u32 s0, s38, 0xfffc0080
	s_addc_u32 s1, s39, -1
	s_cmp_eq_u32 s69, 12
	s_cselect_b32 s43, s60, s1
	s_cselect_b32 s42, s61, s0
	s_cselect_b32 s41, s62, s65
	s_cselect_b32 s40, s63, s64
	s_mov_b32 m0, s50
	v_lshl_add_u64 v[166:167], s[38:39], 0, v[164:165]
	ds_read_b128 v[146:149], v171
	ds_read_b128 v[174:177], v171 offset:1024
	ds_read_b128 v[178:181], v171 offset:2048
	ds_read_b128 v[182:185], v171 offset:3072
	ds_read_b128 v[186:189], v171 offset:4096
	ds_read_b128 v[190:193], v171 offset:5120
	ds_read_b128 v[194:197], v171 offset:6144
	ds_read_b128 v[198:201], v171 offset:7168
	global_load_lds_dwordx4 v[166:167], off
	v_lshl_add_u64 v[166:167], s[38:39], 0, v[162:163]
	s_mov_b32 m0, s51
	s_nop 0
	global_load_lds_dwordx4 v[166:167], off
	s_waitcnt lgkmcnt(8)
	s_waitcnt vmcnt(10)
	s_barrier
	s_waitcnt lgkmcnt(0)
	s_setprio 1
	s_waitcnt lgkmcnt(0)
	v_mfma_f32_16x16x32_bf16 v[126:129], v[130:133], v[146:149], v[126:129]
	v_mfma_f32_16x16x32_bf16 v[122:125], v[138:141], v[146:149], v[122:125]
	v_mfma_f32_16x16x32_bf16 v[118:121], v[130:133], v[178:181], v[118:121]
	v_mfma_f32_16x16x32_bf16 v[110:113], v[138:141], v[178:181], v[110:113]
	v_mfma_f32_16x16x32_bf16 v[98:101], v[130:133], v[186:189], v[98:101]
	v_mfma_f32_16x16x32_bf16 v[90:93], v[138:141], v[186:189], v[90:93]
	v_mfma_f32_16x16x32_bf16 v[82:85], v[130:133], v[194:197], v[82:85]
	v_mfma_f32_16x16x32_bf16 v[74:77], v[138:141], v[194:197], v[74:77]
	v_mfma_f32_16x16x32_bf16 v[126:129], v[134:137], v[174:177], v[126:129]
	v_mfma_f32_16x16x32_bf16 v[122:125], v[142:145], v[174:177], v[122:125]
	v_mfma_f32_16x16x32_bf16 v[118:121], v[134:137], v[182:185], v[118:121]
	v_mfma_f32_16x16x32_bf16 v[110:113], v[142:145], v[182:185], v[110:113]
	v_mfma_f32_16x16x32_bf16 v[98:101], v[134:137], v[190:193], v[98:101]
	v_mfma_f32_16x16x32_bf16 v[90:93], v[142:145], v[190:193], v[90:93]
	v_mfma_f32_16x16x32_bf16 v[82:85], v[134:137], v[198:201], v[82:85]
	v_mfma_f32_16x16x32_bf16 v[74:77], v[142:145], v[198:201], v[74:77]
	s_setprio 0
	s_barrier
	s_mov_b32 m0, s52
	v_lshl_add_u64 v[166:167], s[40:41], 0, v[158:159]
	ds_read_b128 v[202:205], v172
	ds_read_b128 v[206:209], v172 offset:1024
	ds_read_b128 v[210:213], v172 offset:2048
	ds_read_b128 v[214:217], v172 offset:3072
	global_load_lds_dwordx4 v[166:167], off
	v_lshl_add_u64 v[218:219], s[40:41], 0, v[154:155]
	s_mov_b32 m0, s53
	s_nop 0
	global_load_lds_dwordx4 v[218:219], off
	s_waitcnt vmcnt(10)
	s_barrier
	s_waitcnt lgkmcnt(0)
	s_setprio 1
	s_waitcnt lgkmcnt(0)
	v_mfma_f32_16x16x32_bf16 v[114:117], v[202:205], v[146:149], v[114:117]
	v_mfma_f32_16x16x32_bf16 v[106:109], v[210:213], v[146:149], v[106:109]
	v_mfma_f32_16x16x32_bf16 v[102:105], v[202:205], v[178:181], v[102:105]
	v_mfma_f32_16x16x32_bf16 v[94:97], v[210:213], v[178:181], v[94:97]
	v_mfma_f32_16x16x32_bf16 v[86:89], v[202:205], v[186:189], v[86:89]
	v_mfma_f32_16x16x32_bf16 v[78:81], v[210:213], v[186:189], v[78:81]
	v_mfma_f32_16x16x32_bf16 v[70:73], v[202:205], v[194:197], v[70:73]
	v_mfma_f32_16x16x32_bf16 v[66:69], v[210:213], v[194:197], v[66:69]
	v_mfma_f32_16x16x32_bf16 v[114:117], v[206:209], v[174:177], v[114:117]
	v_mfma_f32_16x16x32_bf16 v[106:109], v[214:217], v[174:177], v[106:109]
	v_mfma_f32_16x16x32_bf16 v[102:105], v[206:209], v[182:185], v[102:105]
	v_mfma_f32_16x16x32_bf16 v[94:97], v[214:217], v[182:185], v[94:97]
	v_mfma_f32_16x16x32_bf16 v[86:89], v[206:209], v[190:193], v[86:89]
	v_mfma_f32_16x16x32_bf16 v[78:81], v[214:217], v[190:193], v[78:81]
	v_mfma_f32_16x16x32_bf16 v[70:73], v[206:209], v[198:201], v[70:73]
	v_mfma_f32_16x16x32_bf16 v[66:69], v[214:217], v[198:201], v[66:69]
	s_setprio 0
	s_mov_b32 m0, s6
	v_lshl_add_u64 v[220:221], s[42:43], 0, v[160:161]
	s_barrier
	ds_read_b128 v[146:149], v171 offset:16384
	ds_read_b128 v[174:177], v171 offset:17408
	ds_read_b128 v[178:181], v171 offset:18432
	ds_read_b128 v[182:185], v171 offset:19456
	ds_read_b128 v[186:189], v171 offset:20480
	ds_read_b128 v[190:193], v171 offset:21504
	ds_read_b128 v[194:197], v171 offset:22528
	ds_read_b128 v[198:201], v171 offset:23552
	global_load_lds_dwordx4 v[220:221], off
	v_lshl_add_u64 v[222:223], s[42:43], 0, v[156:157]
	s_mov_b32 m0, s7
	s_nop 0
	global_load_lds_dwordx4 v[222:223], off
	s_waitcnt vmcnt(10)
	s_barrier
	s_waitcnt lgkmcnt(0)
	s_setprio 1
	s_waitcnt lgkmcnt(0)
	v_mfma_f32_16x16x32_bf16 v[62:65], v[130:133], v[146:149], v[62:65]
	v_mfma_f32_16x16x32_bf16 v[58:61], v[138:141], v[146:149], v[58:61]
	v_mfma_f32_16x16x32_bf16 v[50:53], v[130:133], v[178:181], v[50:53]
	v_mfma_f32_16x16x32_bf16 v[42:45], v[138:141], v[178:181], v[42:45]
	v_mfma_f32_16x16x32_bf16 v[34:37], v[130:133], v[186:189], v[34:37]
	v_mfma_f32_16x16x32_bf16 v[26:29], v[138:141], v[186:189], v[26:29]
	v_mfma_f32_16x16x32_bf16 v[18:21], v[130:133], v[194:197], v[18:21]
	v_mfma_f32_16x16x32_bf16 v[10:13], v[138:141], v[194:197], v[10:13]
	v_mfma_f32_16x16x32_bf16 v[62:65], v[134:137], v[174:177], v[62:65]
	v_mfma_f32_16x16x32_bf16 v[58:61], v[142:145], v[174:177], v[58:61]
	v_mfma_f32_16x16x32_bf16 v[50:53], v[134:137], v[182:185], v[50:53]
	v_mfma_f32_16x16x32_bf16 v[42:45], v[142:145], v[182:185], v[42:45]
	v_mfma_f32_16x16x32_bf16 v[34:37], v[134:137], v[190:193], v[34:37]
	v_mfma_f32_16x16x32_bf16 v[26:29], v[142:145], v[190:193], v[26:29]
	v_mfma_f32_16x16x32_bf16 v[18:21], v[134:137], v[198:201], v[18:21]
	v_mfma_f32_16x16x32_bf16 v[10:13], v[142:145], v[198:201], v[10:13]
	s_setprio 0
	s_barrier
	s_add_u32 s0, s40, 0x40000
	s_addc_u32 s1, s41, 0
	s_mov_b32 m0, s54
	v_lshl_add_u64 v[130:131], s[0:1], 0, v[158:159]
	global_load_lds_dwordx4 v[130:131], off
	v_lshl_add_u64 v[130:131], s[0:1], 0, v[154:155]
	s_add_i32 m0, s54, 0x2000
	s_nop 0
	global_load_lds_dwordx4 v[130:131], off
	s_waitcnt vmcnt(10)
	s_barrier
	s_setprio 1
	v_mfma_f32_16x16x32_bf16 v[54:57], v[202:205], v[146:149], v[54:57]
	v_mfma_f32_16x16x32_bf16 v[46:49], v[210:213], v[146:149], v[46:49]
	v_mfma_f32_16x16x32_bf16 v[38:41], v[202:205], v[178:181], v[38:41]
	v_mfma_f32_16x16x32_bf16 v[30:33], v[210:213], v[178:181], v[30:33]
	v_mfma_f32_16x16x32_bf16 v[22:25], v[202:205], v[186:189], v[22:25]
	v_mfma_f32_16x16x32_bf16 v[14:17], v[210:213], v[186:189], v[14:17]
	v_mfma_f32_16x16x32_bf16 v[6:9], v[202:205], v[194:197], v[6:9]
	v_mfma_f32_16x16x32_bf16 v[2:5], v[210:213], v[194:197], v[2:5]
	v_mfma_f32_16x16x32_bf16 v[54:57], v[206:209], v[174:177], v[54:57]
	v_mfma_f32_16x16x32_bf16 v[46:49], v[214:217], v[174:177], v[46:49]
	v_mfma_f32_16x16x32_bf16 v[38:41], v[206:209], v[182:185], v[38:41]
	v_mfma_f32_16x16x32_bf16 v[30:33], v[214:217], v[182:185], v[30:33]
	v_mfma_f32_16x16x32_bf16 v[22:25], v[206:209], v[190:193], v[22:25]
	v_mfma_f32_16x16x32_bf16 v[14:17], v[214:217], v[190:193], v[14:17]
	v_mfma_f32_16x16x32_bf16 v[6:9], v[206:209], v[198:201], v[6:9]
	v_mfma_f32_16x16x32_bf16 v[2:5], v[214:217], v[198:201], v[2:5]
	s_setprio 0
	s_add_i32 s70, 0, 0x18000
	v_add_u32_e32 v142, s70, v169
	s_barrier
	ds_read_b128 v[130:133], v142
	ds_read_b128 v[134:137], v142 offset:1024
	ds_read_b128 v[138:141], v142 offset:2048
	ds_read_b128 v[142:145], v142 offset:3072
	s_add_u32 s0, s42, 0x40000
	s_addc_u32 s1, s43, 0
	s_mov_b32 m0, s10
	v_lshl_add_u64 v[202:203], s[0:1], 0, v[160:161]
	ds_read_b128 v[146:149], v171 offset:32768
	ds_read_b128 v[174:177], v171 offset:33792
	ds_read_b128 v[178:181], v171 offset:34816
	ds_read_b128 v[182:185], v171 offset:35840
	ds_read_b128 v[186:189], v171 offset:36864
	ds_read_b128 v[190:193], v171 offset:37888
	ds_read_b128 v[194:197], v171 offset:38912
	ds_read_b128 v[198:201], v171 offset:39936
	global_load_lds_dwordx4 v[202:203], off
	v_lshl_add_u64 v[202:203], s[0:1], 0, v[156:157]
	s_mov_b32 m0, s11
	s_nop 0
	global_load_lds_dwordx4 v[202:203], off
	s_waitcnt lgkmcnt(8)
	s_waitcnt vmcnt(10)
	s_barrier
	s_waitcnt lgkmcnt(0)
	s_setprio 1
	s_waitcnt lgkmcnt(0)
	v_mfma_f32_16x16x32_bf16 v[126:129], v[130:133], v[146:149], v[126:129]
	v_mfma_f32_16x16x32_bf16 v[122:125], v[138:141], v[146:149], v[122:125]
	v_mfma_f32_16x16x32_bf16 v[118:121], v[130:133], v[178:181], v[118:121]
	v_mfma_f32_16x16x32_bf16 v[110:113], v[138:141], v[178:181], v[110:113]
	v_mfma_f32_16x16x32_bf16 v[98:101], v[130:133], v[186:189], v[98:101]
	v_mfma_f32_16x16x32_bf16 v[90:93], v[138:141], v[186:189], v[90:93]
	v_mfma_f32_16x16x32_bf16 v[82:85], v[130:133], v[194:197], v[82:85]
	v_mfma_f32_16x16x32_bf16 v[74:77], v[138:141], v[194:197], v[74:77]
	v_mfma_f32_16x16x32_bf16 v[126:129], v[134:137], v[174:177], v[126:129]
	v_mfma_f32_16x16x32_bf16 v[122:125], v[142:145], v[174:177], v[122:125]
	v_mfma_f32_16x16x32_bf16 v[118:121], v[134:137], v[182:185], v[118:121]
	v_mfma_f32_16x16x32_bf16 v[110:113], v[142:145], v[182:185], v[110:113]
	v_mfma_f32_16x16x32_bf16 v[98:101], v[134:137], v[190:193], v[98:101]
	v_mfma_f32_16x16x32_bf16 v[90:93], v[142:145], v[190:193], v[90:93]
	v_mfma_f32_16x16x32_bf16 v[82:85], v[134:137], v[198:201], v[82:85]
	v_mfma_f32_16x16x32_bf16 v[74:77], v[142:145], v[198:201], v[74:77]
	s_setprio 0
	s_barrier
	s_add_i32 s42, 0, 0x1c000
	s_add_i32 s0, s70, s5
	v_add_u32_e32 v173, s42, v169
	v_lshl_add_u64 v[166:167], v[166:167], 0, s[28:29]
	s_mov_b32 m0, s0
	ds_read_b128 v[202:205], v173
	ds_read_b128 v[206:209], v173 offset:1024
	ds_read_b128 v[210:213], v173 offset:2048
	ds_read_b128 v[214:217], v173 offset:3072
	global_load_lds_dwordx4 v[166:167], off
	v_lshl_add_u64 v[166:167], v[218:219], 0, s[28:29]
	s_add_i32 m0, s0, 0x2000
	s_nop 0
	global_load_lds_dwordx4 v[166:167], off
	s_waitcnt vmcnt(10)
	s_barrier
	s_waitcnt lgkmcnt(0)
	s_setprio 1
	s_waitcnt lgkmcnt(0)
	v_mfma_f32_16x16x32_bf16 v[114:117], v[202:205], v[146:149], v[114:117]
	v_mfma_f32_16x16x32_bf16 v[106:109], v[210:213], v[146:149], v[106:109]
	v_mfma_f32_16x16x32_bf16 v[102:105], v[202:205], v[178:181], v[102:105]
	v_mfma_f32_16x16x32_bf16 v[94:97], v[210:213], v[178:181], v[94:97]
	v_mfma_f32_16x16x32_bf16 v[86:89], v[202:205], v[186:189], v[86:89]
	v_mfma_f32_16x16x32_bf16 v[78:81], v[210:213], v[186:189], v[78:81]
	v_mfma_f32_16x16x32_bf16 v[70:73], v[202:205], v[194:197], v[70:73]
	v_mfma_f32_16x16x32_bf16 v[66:69], v[210:213], v[194:197], v[66:69]
	v_mfma_f32_16x16x32_bf16 v[114:117], v[206:209], v[174:177], v[114:117]
	v_mfma_f32_16x16x32_bf16 v[106:109], v[214:217], v[174:177], v[106:109]
	v_mfma_f32_16x16x32_bf16 v[102:105], v[206:209], v[182:185], v[102:105]
	v_mfma_f32_16x16x32_bf16 v[94:97], v[214:217], v[182:185], v[94:97]
	v_mfma_f32_16x16x32_bf16 v[86:89], v[206:209], v[190:193], v[86:89]
	v_mfma_f32_16x16x32_bf16 v[78:81], v[214:217], v[190:193], v[78:81]
	v_mfma_f32_16x16x32_bf16 v[70:73], v[206:209], v[198:201], v[70:73]
	v_mfma_f32_16x16x32_bf16 v[66:69], v[214:217], v[198:201], v[66:69]
	s_setprio 0
	s_mov_b32 m0, s48
	v_lshl_add_u64 v[166:167], v[220:221], 0, s[28:29]
	s_barrier
	ds_read_b128 v[146:149], v171 offset:49152
	ds_read_b128 v[174:177], v171 offset:50176
	ds_read_b128 v[178:181], v171 offset:51200
	ds_read_b128 v[182:185], v171 offset:52224
	ds_read_b128 v[186:189], v171 offset:53248
	ds_read_b128 v[190:193], v171 offset:54272
	ds_read_b128 v[194:197], v171 offset:55296
	ds_read_b128 v[198:201], v171 offset:56320
	global_load_lds_dwordx4 v[166:167], off
	v_lshl_add_u64 v[166:167], v[222:223], 0, s[28:29]
	s_mov_b32 m0, s49
	s_nop 0
	global_load_lds_dwordx4 v[166:167], off
	s_waitcnt vmcnt(10)
	s_barrier
	s_waitcnt lgkmcnt(0)
	s_setprio 1
	s_waitcnt lgkmcnt(0)
	v_mfma_f32_16x16x32_bf16 v[62:65], v[130:133], v[146:149], v[62:65]
	v_mfma_f32_16x16x32_bf16 v[58:61], v[138:141], v[146:149], v[58:61]
	v_mfma_f32_16x16x32_bf16 v[50:53], v[130:133], v[178:181], v[50:53]
	v_mfma_f32_16x16x32_bf16 v[42:45], v[138:141], v[178:181], v[42:45]
	v_mfma_f32_16x16x32_bf16 v[34:37], v[130:133], v[186:189], v[34:37]
	v_mfma_f32_16x16x32_bf16 v[26:29], v[138:141], v[186:189], v[26:29]
	v_mfma_f32_16x16x32_bf16 v[18:21], v[130:133], v[194:197], v[18:21]
	v_mfma_f32_16x16x32_bf16 v[10:13], v[138:141], v[194:197], v[10:13]
	v_mfma_f32_16x16x32_bf16 v[62:65], v[134:137], v[174:177], v[62:65]
	v_mfma_f32_16x16x32_bf16 v[58:61], v[142:145], v[174:177], v[58:61]
	v_mfma_f32_16x16x32_bf16 v[50:53], v[134:137], v[182:185], v[50:53]
	v_mfma_f32_16x16x32_bf16 v[42:45], v[142:145], v[182:185], v[42:45]
	v_mfma_f32_16x16x32_bf16 v[34:37], v[134:137], v[190:193], v[34:37]
	v_mfma_f32_16x16x32_bf16 v[26:29], v[142:145], v[190:193], v[26:29]
	v_mfma_f32_16x16x32_bf16 v[18:21], v[134:137], v[198:201], v[18:21]
	v_mfma_f32_16x16x32_bf16 v[10:13], v[142:145], v[198:201], v[10:13]
	s_setprio 0
	s_barrier
	s_add_u32 s0, s40, 0x40080
	s_addc_u32 s1, s41, 0
	s_add_i32 s40, s42, s5
	v_lshl_add_u64 v[130:131], s[0:1], 0, v[158:159]
	s_mov_b32 m0, s40
	s_nop 0
	global_load_lds_dwordx4 v[130:131], off
	v_lshl_add_u64 v[130:131], s[0:1], 0, v[154:155]
	s_add_i32 m0, s40, 0x2000
	s_nop 0
	global_load_lds_dwordx4 v[130:131], off
	s_waitcnt vmcnt(10)
	s_barrier
	s_setprio 1
	v_mfma_f32_16x16x32_bf16 v[54:57], v[202:205], v[146:149], v[54:57]
	v_mfma_f32_16x16x32_bf16 v[46:49], v[210:213], v[146:149], v[46:49]
	v_mfma_f32_16x16x32_bf16 v[38:41], v[202:205], v[178:181], v[38:41]
	v_mfma_f32_16x16x32_bf16 v[30:33], v[210:213], v[178:181], v[30:33]
	v_mfma_f32_16x16x32_bf16 v[22:25], v[202:205], v[186:189], v[22:25]
	v_mfma_f32_16x16x32_bf16 v[14:17], v[210:213], v[186:189], v[14:17]
	v_mfma_f32_16x16x32_bf16 v[6:9], v[202:205], v[194:197], v[6:9]
	v_mfma_f32_16x16x32_bf16 v[2:5], v[210:213], v[194:197], v[2:5]
	v_mfma_f32_16x16x32_bf16 v[54:57], v[206:209], v[174:177], v[54:57]
	v_mfma_f32_16x16x32_bf16 v[46:49], v[214:217], v[174:177], v[46:49]
	v_mfma_f32_16x16x32_bf16 v[38:41], v[206:209], v[182:185], v[38:41]
	v_mfma_f32_16x16x32_bf16 v[30:33], v[214:217], v[182:185], v[30:33]
	v_mfma_f32_16x16x32_bf16 v[22:25], v[206:209], v[190:193], v[22:25]
	v_mfma_f32_16x16x32_bf16 v[14:17], v[214:217], v[190:193], v[14:17]
	v_mfma_f32_16x16x32_bf16 v[6:9], v[206:209], v[198:201], v[6:9]
	v_mfma_f32_16x16x32_bf16 v[2:5], v[214:217], v[198:201], v[2:5]
	s_setprio 0
	s_add_i32 s69, s69, 2
	s_add_u32 s64, s64, 0x100
	s_addc_u32 s65, s65, 0
	s_add_u32 s38, s38, 0x100
	s_addc_u32 s39, s39, 0
	s_cmp_gt_u32 s69, 13
	s_barrier
	s_cbranch_scc0 .LBB0_1047
	s_lshl_b32 s0, s58, 8
	v_mov_b32_e32 v130, v151
	v_mov_b32_e32 v131, v153
	s_or_b32 s0, s0, s45
	s_mov_b32 s58, s57
	v_lshl_add_u32 v166, v131, 3, s0
	s_lshl_b32 s0, s59, 8
	s_add_i32 s0, s0, s44
	v_add_u32_e32 v173, s0, v130
	v_mov_b32_e32 v130, v173
	v_ashrrev_i32_e32 v167, 31, v166
	v_ashrrev_i32_e32 v131, 31, v130
	v_lshlrev_b64 v[130:131], 10, v[130:131]
	v_lshl_add_u64 v[130:131], v[130:131], 0, v[166:167]
	v_lshlrev_b64 v[186:187], 1, v[130:131]
	v_lshl_add_u64 v[130:131], s[12:13], 0, v[186:187]
	flat_load_dwordx4 v[174:177], v[130:131] nt
	flat_load_dwordx4 v[178:181], v[130:131] offset:256 nt
	v_add_co_u32_e32 v132, vcc, s47, v130
	s_mov_b32 s59, s56
	s_nop 0
	v_addc_co_u32_e32 v133, vcc, 0, v131, vcc
	flat_load_dwordx4 v[182:185], v[132:133] nt
	flat_load_dwordx4 v[146:149], v[132:133] offset:256 nt
	v_add_co_u32_e32 v132, vcc, s31, v130
	s_waitcnt vmcnt(0) lgkmcnt(0)
	v_lshlrev_b32_e32 v188, 16, v174
	v_addc_co_u32_e32 v133, vcc, 0, v131, vcc
	flat_load_dwordx4 v[142:145], v[132:133] nt
	flat_load_dwordx4 v[138:141], v[132:133] offset:256 nt
	v_add_co_u32_e32 v130, vcc, s46, v130
	v_and_b32_e32 v189, 0xffff0000, v174
	s_nop 0
	v_addc_co_u32_e32 v131, vcc, 0, v131, vcc
	flat_load_dwordx4 v[134:137], v[130:131] nt
	s_nop 0
	flat_load_dwordx4 v[130:133], v[130:131] offset:256 nt
	v_lshlrev_b32_e32 v174, 16, v175
	v_and_b32_e32 v175, 0xffff0000, v175
	v_lshlrev_b32_e32 v190, 16, v176
	v_and_b32_e32 v191, 0xffff0000, v176
	v_lshlrev_b32_e32 v176, 16, v177
	v_and_b32_e32 v177, 0xffff0000, v177
	v_pk_fma_f32 v[128:129], v[174:175], s[30:31], v[128:129] op_sel_hi:[1,0,1]
	v_pk_fma_f32 v[126:127], v[188:189], s[30:31], v[126:127] op_sel_hi:[1,0,1]
	v_pk_fma_f32 v[174:175], v[176:177], s[30:31], v[124:125] op_sel_hi:[1,0,1]
	v_pk_fma_f32 v[122:123], v[190:191], s[30:31], v[122:123] op_sel_hi:[1,0,1]
	v_cvt_pk_bf16_f32 v124, v126, v127
	v_cvt_pk_bf16_f32 v125, v128, v129
	v_cvt_pk_bf16_f32 v126, v122, v123
	v_cvt_pk_bf16_f32 v127, v174, v175
	v_lshl_add_u64 v[122:123], s[24:25], 0, v[186:187]
	flat_store_dwordx4 v[122:123], v[124:127]
	v_lshlrev_b32_e32 v128, 16, v180
	v_and_b32_e32 v129, 0xffff0000, v180
	v_lshlrev_b32_e32 v124, 16, v178
	v_and_b32_e32 v125, 0xffff0000, v178
	v_lshlrev_b32_e32 v126, 16, v179
	v_and_b32_e32 v127, 0xffff0000, v179
	v_lshlrev_b32_e32 v174, 16, v181
	v_and_b32_e32 v175, 0xffff0000, v181
	v_pk_fma_f32 v[116:117], v[126:127], s[30:31], v[116:117] op_sel_hi:[1,0,1]
	v_pk_fma_f32 v[114:115], v[124:125], s[30:31], v[114:115] op_sel_hi:[1,0,1]
	v_pk_fma_f32 v[124:125], v[174:175], s[30:31], v[108:109] op_sel_hi:[1,0,1]
	v_pk_fma_f32 v[108:109], v[128:129], s[30:31], v[106:107] op_sel_hi:[1,0,1]
	v_cvt_pk_bf16_f32 v106, v114, v115
	v_cvt_pk_bf16_f32 v107, v116, v117
	v_cvt_pk_bf16_f32 v108, v108, v109
	v_cvt_pk_bf16_f32 v109, v124, v125
	flat_store_dwordx4 v[122:123], v[106:109] offset:256
	v_lshlrev_b32_e32 v114, 16, v184
	v_and_b32_e32 v115, 0xffff0000, v184
	v_lshlrev_b32_e32 v106, 16, v182
	v_and_b32_e32 v107, 0xffff0000, v182
	v_lshlrev_b32_e32 v108, 16, v183
	v_and_b32_e32 v109, 0xffff0000, v183
	v_lshlrev_b32_e32 v116, 16, v185
	v_and_b32_e32 v117, 0xffff0000, v185
	v_pk_fma_f32 v[108:109], v[108:109], s[30:31], v[120:121] op_sel_hi:[1,0,1]
	v_pk_fma_f32 v[106:107], v[106:107], s[30:31], v[118:119] op_sel_hi:[1,0,1]
	v_pk_fma_f32 v[110:111], v[114:115], s[30:31], v[110:111] op_sel_hi:[1,0,1]
	v_pk_fma_f32 v[112:113], v[116:117], s[30:31], v[112:113] op_sel_hi:[1,0,1]
	v_cvt_pk_bf16_f32 v106, v106, v107
	v_cvt_pk_bf16_f32 v107, v108, v109
	v_cvt_pk_bf16_f32 v108, v110, v111
	v_add_co_u32_e32 v110, vcc, s47, v122
	v_cvt_pk_bf16_f32 v109, v112, v113
	s_nop 0
	v_addc_co_u32_e32 v111, vcc, 0, v123, vcc
	flat_store_dwordx4 v[110:111], v[106:109]
	v_lshlrev_b32_e32 v112, 16, v148
	v_and_b32_e32 v113, 0xffff0000, v148
	v_lshlrev_b32_e32 v106, 16, v146
	v_and_b32_e32 v107, 0xffff0000, v146
	v_lshlrev_b32_e32 v108, 16, v147
	v_and_b32_e32 v109, 0xffff0000, v147
	v_lshlrev_b32_e32 v114, 16, v149
	v_and_b32_e32 v115, 0xffff0000, v149
	v_pk_fma_f32 v[104:105], v[108:109], s[30:31], v[104:105] op_sel_hi:[1,0,1]
	v_pk_fma_f32 v[102:103], v[106:107], s[30:31], v[102:103] op_sel_hi:[1,0,1]
	v_pk_fma_f32 v[106:107], v[114:115], s[30:31], v[96:97] op_sel_hi:[1,0,1]
	v_pk_fma_f32 v[96:97], v[112:113], s[30:31], v[94:95] op_sel_hi:[1,0,1]
	v_cvt_pk_bf16_f32 v94, v102, v103
	v_cvt_pk_bf16_f32 v95, v104, v105
	v_cvt_pk_bf16_f32 v96, v96, v97
	v_cvt_pk_bf16_f32 v97, v106, v107
	flat_store_dwordx4 v[110:111], v[94:97] offset:256
	s_waitcnt vmcnt(0) lgkmcnt(0)
	v_lshlrev_b32_e32 v102, 16, v144
	v_lshlrev_b32_e32 v94, 16, v142
	v_and_b32_e32 v95, 0xffff0000, v142
	v_lshlrev_b32_e32 v96, 16, v143
	v_and_b32_e32 v97, 0xffff0000, v143
	v_and_b32_e32 v103, 0xffff0000, v144
	v_lshlrev_b32_e32 v104, 16, v145
	v_and_b32_e32 v105, 0xffff0000, v145
	v_pk_fma_f32 v[94:95], v[94:95], s[30:31], v[98:99] op_sel_hi:[1,0,1]
	v_pk_fma_f32 v[96:97], v[96:97], s[30:31], v[100:101] op_sel_hi:[1,0,1]
	v_pk_fma_f32 v[98:99], v[104:105], s[30:31], v[92:93] op_sel_hi:[1,0,1]
	v_pk_fma_f32 v[92:93], v[102:103], s[30:31], v[90:91] op_sel_hi:[1,0,1]
	v_cvt_pk_bf16_f32 v90, v94, v95
	v_add_co_u32_e32 v94, vcc, s31, v122
	v_cvt_pk_bf16_f32 v91, v96, v97
	v_cvt_pk_bf16_f32 v92, v92, v93
	v_cvt_pk_bf16_f32 v93, v98, v99
	v_addc_co_u32_e32 v95, vcc, 0, v123, vcc
	flat_store_dwordx4 v[94:95], v[90:93]
	v_lshlrev_b32_e32 v96, 16, v140
	v_and_b32_e32 v97, 0xffff0000, v140
	v_lshlrev_b32_e32 v90, 16, v138
	v_and_b32_e32 v91, 0xffff0000, v138
	v_lshlrev_b32_e32 v92, 16, v139
	v_and_b32_e32 v93, 0xffff0000, v139
	v_lshlrev_b32_e32 v98, 16, v141
	v_and_b32_e32 v99, 0xffff0000, v141
	v_pk_fma_f32 v[88:89], v[92:93], s[30:31], v[88:89] op_sel_hi:[1,0,1]
	v_pk_fma_f32 v[86:87], v[90:91], s[30:31], v[86:87] op_sel_hi:[1,0,1]
	v_pk_fma_f32 v[90:91], v[98:99], s[30:31], v[80:81] op_sel_hi:[1,0,1]
	v_pk_fma_f32 v[80:81], v[96:97], s[30:31], v[78:79] op_sel_hi:[1,0,1]
	v_cvt_pk_bf16_f32 v78, v86, v87
	v_cvt_pk_bf16_f32 v79, v88, v89
	v_cvt_pk_bf16_f32 v80, v80, v81
	v_cvt_pk_bf16_f32 v81, v90, v91
	flat_store_dwordx4 v[94:95], v[78:81] offset:256
	v_lshlrev_b32_e32 v86, 16, v136
	v_and_b32_e32 v87, 0xffff0000, v136
	v_lshlrev_b32_e32 v78, 16, v134
	v_and_b32_e32 v79, 0xffff0000, v134
	v_lshlrev_b32_e32 v80, 16, v135
	v_and_b32_e32 v81, 0xffff0000, v135
	v_lshlrev_b32_e32 v88, 16, v137
	v_and_b32_e32 v89, 0xffff0000, v137
	v_pk_fma_f32 v[78:79], v[78:79], s[30:31], v[82:83] op_sel_hi:[1,0,1]
	v_pk_fma_f32 v[80:81], v[80:81], s[30:31], v[84:85] op_sel_hi:[1,0,1]
	v_pk_fma_f32 v[82:83], v[88:89], s[30:31], v[76:77] op_sel_hi:[1,0,1]
	v_pk_fma_f32 v[76:77], v[86:87], s[30:31], v[74:75] op_sel_hi:[1,0,1]
	v_cvt_pk_bf16_f32 v74, v78, v79
	v_add_co_u32_e32 v78, vcc, s46, v122
	v_cvt_pk_bf16_f32 v75, v80, v81
	v_cvt_pk_bf16_f32 v76, v76, v77
	v_cvt_pk_bf16_f32 v77, v82, v83
	v_addc_co_u32_e32 v79, vcc, 0, v123, vcc
	flat_store_dwordx4 v[78:79], v[74:77]
	v_lshlrev_b32_e32 v80, 16, v132
	v_and_b32_e32 v81, 0xffff0000, v132
	v_lshlrev_b32_e32 v74, 16, v130
	v_and_b32_e32 v75, 0xffff0000, v130
	v_lshlrev_b32_e32 v76, 16, v131
	v_and_b32_e32 v77, 0xffff0000, v131
	v_lshlrev_b32_e32 v82, 16, v133
	v_and_b32_e32 v83, 0xffff0000, v133
	v_pk_fma_f32 v[72:73], v[76:77], s[30:31], v[72:73] op_sel_hi:[1,0,1]
	v_pk_fma_f32 v[70:71], v[74:75], s[30:31], v[70:71] op_sel_hi:[1,0,1]
	v_pk_fma_f32 v[74:75], v[82:83], s[30:31], v[68:69] op_sel_hi:[1,0,1]
	v_pk_fma_f32 v[68:69], v[80:81], s[30:31], v[66:67] op_sel_hi:[1,0,1]
	v_cvt_pk_bf16_f32 v66, v70, v71
	v_cvt_pk_bf16_f32 v67, v72, v73
	v_cvt_pk_bf16_f32 v68, v68, v69
	v_cvt_pk_bf16_f32 v69, v74, v75
	flat_store_dwordx4 v[78:79], v[66:69] offset:256
	s_nop 1
	v_add_u32_e32 v66, 0x80, v173
	s_nop 0
	v_ashrrev_i32_e32 v67, 31, v66
	v_lshlrev_b64 v[66:67], 10, v[66:67]
	v_lshl_add_u64 v[66:67], v[66:67], 0, v[166:167]
	v_lshlrev_b64 v[98:99], 1, v[66:67]
	v_lshl_add_u64 v[90:91], s[12:13], 0, v[98:99]
	flat_load_dwordx4 v[66:69], v[90:91] nt
	flat_load_dwordx4 v[70:73], v[90:91] offset:256 nt
	v_add_co_u32_e32 v78, vcc, s47, v90
	s_waitcnt vmcnt(0) lgkmcnt(0)
	v_lshlrev_b32_e32 v100, 16, v66
	v_addc_co_u32_e32 v79, vcc, 0, v91, vcc
	flat_load_dwordx4 v[74:77], v[78:79] nt
	s_nop 0
	flat_load_dwordx4 v[78:81], v[78:79] offset:256 nt
	v_add_co_u32_e32 v86, vcc, s31, v90
	v_and_b32_e32 v101, 0xffff0000, v66
	s_nop 0
	v_addc_co_u32_e32 v87, vcc, 0, v91, vcc
	flat_load_dwordx4 v[82:85], v[86:87] nt
	s_nop 0
	flat_load_dwordx4 v[86:89], v[86:87] offset:256 nt
	v_add_co_u32_e32 v94, vcc, s46, v90
	v_lshlrev_b32_e32 v66, 16, v67
	s_nop 0
	v_addc_co_u32_e32 v95, vcc, 0, v91, vcc
	flat_load_dwordx4 v[90:93], v[94:95] nt
	s_nop 0
	flat_load_dwordx4 v[94:97], v[94:95] offset:256 nt
	v_and_b32_e32 v67, 0xffff0000, v67
	v_lshlrev_b32_e32 v102, 16, v68
	v_and_b32_e32 v103, 0xffff0000, v68
	v_lshlrev_b32_e32 v68, 16, v69
	v_and_b32_e32 v69, 0xffff0000, v69
	v_pk_fma_f32 v[64:65], v[66:67], s[30:31], v[64:65] op_sel_hi:[1,0,1]
	v_pk_fma_f32 v[62:63], v[100:101], s[30:31], v[62:63] op_sel_hi:[1,0,1]
	v_pk_fma_f32 v[66:67], v[68:69], s[30:31], v[60:61] op_sel_hi:[1,0,1]
	v_pk_fma_f32 v[60:61], v[102:103], s[30:31], v[58:59] op_sel_hi:[1,0,1]
	v_cvt_pk_bf16_f32 v58, v62, v63
	v_cvt_pk_bf16_f32 v59, v64, v65
	v_cvt_pk_bf16_f32 v60, v60, v61
	v_cvt_pk_bf16_f32 v61, v66, v67
	v_lshl_add_u64 v[62:63], s[24:25], 0, v[98:99]
	flat_store_dwordx4 v[62:63], v[58:61]
	v_lshlrev_b32_e32 v64, 16, v72
	v_and_b32_e32 v65, 0xffff0000, v72
	v_lshlrev_b32_e32 v58, 16, v70
	v_and_b32_e32 v59, 0xffff0000, v70
	v_lshlrev_b32_e32 v60, 16, v71
	v_and_b32_e32 v61, 0xffff0000, v71
	v_lshlrev_b32_e32 v66, 16, v73
	v_and_b32_e32 v67, 0xffff0000, v73
	v_pk_fma_f32 v[56:57], v[60:61], s[30:31], v[56:57] op_sel_hi:[1,0,1]
	v_pk_fma_f32 v[54:55], v[58:59], s[30:31], v[54:55] op_sel_hi:[1,0,1]
	v_pk_fma_f32 v[58:59], v[66:67], s[30:31], v[48:49] op_sel_hi:[1,0,1]
	v_pk_fma_f32 v[48:49], v[64:65], s[30:31], v[46:47] op_sel_hi:[1,0,1]
	v_cvt_pk_bf16_f32 v46, v54, v55
	v_cvt_pk_bf16_f32 v47, v56, v57
	v_cvt_pk_bf16_f32 v48, v48, v49
	v_cvt_pk_bf16_f32 v49, v58, v59
	flat_store_dwordx4 v[62:63], v[46:49] offset:256
	s_waitcnt vmcnt(0) lgkmcnt(0)
	v_lshlrev_b32_e32 v54, 16, v76
	v_lshlrev_b32_e32 v46, 16, v74
	v_and_b32_e32 v47, 0xffff0000, v74
	v_lshlrev_b32_e32 v48, 16, v75
	v_and_b32_e32 v49, 0xffff0000, v75
	v_and_b32_e32 v55, 0xffff0000, v76
	v_lshlrev_b32_e32 v56, 16, v77
	v_and_b32_e32 v57, 0xffff0000, v77
	v_pk_fma_f32 v[46:47], v[46:47], s[30:31], v[50:51] op_sel_hi:[1,0,1]
	v_pk_fma_f32 v[48:49], v[48:49], s[30:31], v[52:53] op_sel_hi:[1,0,1]
	v_pk_fma_f32 v[50:51], v[56:57], s[30:31], v[44:45] op_sel_hi:[1,0,1]
	v_pk_fma_f32 v[44:45], v[54:55], s[30:31], v[42:43] op_sel_hi:[1,0,1]
	v_cvt_pk_bf16_f32 v42, v46, v47
	v_add_co_u32_e32 v46, vcc, s47, v62
	v_cvt_pk_bf16_f32 v43, v48, v49
	v_cvt_pk_bf16_f32 v44, v44, v45
	v_cvt_pk_bf16_f32 v45, v50, v51
	v_addc_co_u32_e32 v47, vcc, 0, v63, vcc
	flat_store_dwordx4 v[46:47], v[42:45]
	v_lshlrev_b32_e32 v48, 16, v80
	v_and_b32_e32 v49, 0xffff0000, v80
	v_lshlrev_b32_e32 v42, 16, v78
	v_and_b32_e32 v43, 0xffff0000, v78
	v_lshlrev_b32_e32 v44, 16, v79
	v_and_b32_e32 v45, 0xffff0000, v79
	v_lshlrev_b32_e32 v50, 16, v81
	v_and_b32_e32 v51, 0xffff0000, v81
	v_pk_fma_f32 v[40:41], v[44:45], s[30:31], v[40:41] op_sel_hi:[1,0,1]
	v_pk_fma_f32 v[38:39], v[42:43], s[30:31], v[38:39] op_sel_hi:[1,0,1]
	v_pk_fma_f32 v[42:43], v[50:51], s[30:31], v[32:33] op_sel_hi:[1,0,1]
	v_pk_fma_f32 v[32:33], v[48:49], s[30:31], v[30:31] op_sel_hi:[1,0,1]
	v_cvt_pk_bf16_f32 v30, v38, v39
	v_cvt_pk_bf16_f32 v31, v40, v41
	v_cvt_pk_bf16_f32 v32, v32, v33
	v_cvt_pk_bf16_f32 v33, v42, v43
	flat_store_dwordx4 v[46:47], v[30:33] offset:256
	v_lshlrev_b32_e32 v38, 16, v84
	v_and_b32_e32 v39, 0xffff0000, v84
	v_lshlrev_b32_e32 v30, 16, v82
	v_and_b32_e32 v31, 0xffff0000, v82
	v_lshlrev_b32_e32 v32, 16, v83
	v_and_b32_e32 v33, 0xffff0000, v83
	v_lshlrev_b32_e32 v40, 16, v85
	v_and_b32_e32 v41, 0xffff0000, v85
	v_pk_fma_f32 v[30:31], v[30:31], s[30:31], v[34:35] op_sel_hi:[1,0,1]
	v_pk_fma_f32 v[32:33], v[32:33], s[30:31], v[36:37] op_sel_hi:[1,0,1]
	v_pk_fma_f32 v[34:35], v[40:41], s[30:31], v[28:29] op_sel_hi:[1,0,1]
	v_pk_fma_f32 v[28:29], v[38:39], s[30:31], v[26:27] op_sel_hi:[1,0,1]
	v_cvt_pk_bf16_f32 v26, v30, v31
	v_add_co_u32_e32 v30, vcc, s31, v62
	v_cvt_pk_bf16_f32 v27, v32, v33
	v_cvt_pk_bf16_f32 v28, v28, v29
	v_cvt_pk_bf16_f32 v29, v34, v35
	v_addc_co_u32_e32 v31, vcc, 0, v63, vcc
	flat_store_dwordx4 v[30:31], v[26:29]
	v_lshlrev_b32_e32 v32, 16, v88
	v_and_b32_e32 v33, 0xffff0000, v88
	v_lshlrev_b32_e32 v26, 16, v86
	v_and_b32_e32 v27, 0xffff0000, v86
	v_lshlrev_b32_e32 v28, 16, v87
	v_and_b32_e32 v29, 0xffff0000, v87
	v_lshlrev_b32_e32 v34, 16, v89
	v_and_b32_e32 v35, 0xffff0000, v89
	v_pk_fma_f32 v[24:25], v[28:29], s[30:31], v[24:25] op_sel_hi:[1,0,1]
	v_pk_fma_f32 v[22:23], v[26:27], s[30:31], v[22:23] op_sel_hi:[1,0,1]
	v_pk_fma_f32 v[26:27], v[34:35], s[30:31], v[16:17] op_sel_hi:[1,0,1]
	v_pk_fma_f32 v[16:17], v[32:33], s[30:31], v[14:15] op_sel_hi:[1,0,1]
	v_cvt_pk_bf16_f32 v14, v22, v23
	v_cvt_pk_bf16_f32 v15, v24, v25
	v_cvt_pk_bf16_f32 v16, v16, v17
	v_cvt_pk_bf16_f32 v17, v26, v27
	flat_store_dwordx4 v[30:31], v[14:17] offset:256
	v_lshlrev_b32_e32 v22, 16, v92
	v_and_b32_e32 v23, 0xffff0000, v92
	v_lshlrev_b32_e32 v14, 16, v90
	v_and_b32_e32 v15, 0xffff0000, v90
	v_lshlrev_b32_e32 v16, 16, v91
	v_and_b32_e32 v17, 0xffff0000, v91
	v_lshlrev_b32_e32 v24, 16, v93
	v_and_b32_e32 v25, 0xffff0000, v93
	v_pk_fma_f32 v[14:15], v[14:15], s[30:31], v[18:19] op_sel_hi:[1,0,1]
	v_pk_fma_f32 v[16:17], v[16:17], s[30:31], v[20:21] op_sel_hi:[1,0,1]
	v_pk_fma_f32 v[18:19], v[24:25], s[30:31], v[12:13] op_sel_hi:[1,0,1]
	v_pk_fma_f32 v[12:13], v[22:23], s[30:31], v[10:11] op_sel_hi:[1,0,1]
	v_cvt_pk_bf16_f32 v10, v14, v15
	v_add_co_u32_e32 v14, vcc, s46, v62
	v_cvt_pk_bf16_f32 v11, v16, v17
	v_cvt_pk_bf16_f32 v12, v12, v13
	v_cvt_pk_bf16_f32 v13, v18, v19
	v_addc_co_u32_e32 v15, vcc, 0, v63, vcc
	flat_store_dwordx4 v[14:15], v[10:13]
	v_lshlrev_b32_e32 v16, 16, v96
	v_and_b32_e32 v17, 0xffff0000, v96
	v_lshlrev_b32_e32 v10, 16, v94
	v_and_b32_e32 v11, 0xffff0000, v94
	v_lshlrev_b32_e32 v12, 16, v95
	v_and_b32_e32 v13, 0xffff0000, v95
	v_lshlrev_b32_e32 v18, 16, v97
	v_and_b32_e32 v19, 0xffff0000, v97
	v_pk_fma_f32 v[8:9], v[12:13], s[30:31], v[8:9] op_sel_hi:[1,0,1]
	v_pk_fma_f32 v[6:7], v[10:11], s[30:31], v[6:7] op_sel_hi:[1,0,1]
	v_pk_fma_f32 v[10:11], v[18:19], s[30:31], v[4:5] op_sel_hi:[1,0,1]
	v_pk_fma_f32 v[4:5], v[16:17], s[30:31], v[2:3] op_sel_hi:[1,0,1]
	v_cvt_pk_bf16_f32 v2, v6, v7
	v_cvt_pk_bf16_f32 v3, v8, v9
	v_cvt_pk_bf16_f32 v4, v4, v5
	v_cvt_pk_bf16_f32 v5, v10, v11
	s_and_b64 vcc, exec, s[34:35]
	flat_store_dwordx4 v[14:15], v[2:5] offset:256
	s_cbranch_vccz .LBB0_1046
	s_waitcnt vmcnt(0)
	s_cmpk_gt_u32 s4, 0xff
	s_cbranch_scc1 .LBB0_1051
	s_barrier

.LBB0_1068:
	s_or_b64 exec, exec, s[20:21]
	s_lshl_b32 s0, s7, 8
	s_add_i32 s0, s0, s97
	s_ashr_i32 s1, s0, 31
	s_lshl_b64 s[10:11], s[0:1], 11
	v_lshl_add_u64 v[38:39], v[54:55], 0, s[10:11]
	s_mov_b64 s[10:11], 0x4000
	v_add_co_u32_e32 v44, vcc, 0x4000, v38
	s_waitcnt lgkmcnt(0)
	s_barrier
	global_load_dwordx4 v[2:5], v[50:51], off
	global_load_dwordx4 v[6:9], v[50:51], off offset:1024
	global_load_dwordx4 v[10:13], v[52:53], off
	global_load_dwordx4 v[14:17], v[52:53], off offset:1024
	global_load_dwordx4 v[18:21], v[50:51], off offset:2048
	global_load_dwordx4 v[22:25], v[50:51], off offset:3072
	global_load_dwordx4 v[26:29], v[52:53], off offset:2048
	global_load_dwordx4 v[30:33], v[52:53], off offset:3072
	v_lshl_add_u64 v[42:43], v[38:39], 0, s[10:11]
	v_addc_co_u32_e32 v45, vcc, 0, v39, vcc
	flat_load_dwordx2 v[36:37], v[38:39] nt
	flat_load_dwordx2 v[34:35], v[38:39] offset:512 nt
	flat_load_dwordx2 v[40:41], v[38:39] offset:1024 nt
	s_nop 0
	flat_load_dwordx2 v[38:39], v[38:39] offset:1536 nt
	s_nop 0
	flat_load_dwordx2 v[60:61], v[44:45] nt
	flat_load_dwordx2 v[62:63], v[42:43] offset:512 nt
	flat_load_dwordx2 v[64:65], v[42:43] offset:1024 nt
	flat_load_dwordx2 v[66:67], v[42:43] offset:1536 nt
	s_mov_b32 s10, 0
	s_add_i32 s11, s0, 16
	s_mov_b32 s24, 0
	s_branch .LBB0_1071

.LBB0_1071:
	s_waitcnt vmcnt(0) lgkmcnt(0)
	v_lshlrev_b32_e32 v77, 16, v37
	v_lshlrev_b32_e32 v76, 16, v36
	v_and_b32_e32 v37, 0xffff0000, v37
	v_and_b32_e32 v36, 0xffff0000, v36
	v_pk_add_f32 v[68:69], v[76:77], v[36:37]
	v_lshlrev_b32_e32 v87, 16, v35
	v_lshlrev_b32_e32 v86, 16, v34
	v_and_b32_e32 v35, 0xffff0000, v35
	v_and_b32_e32 v34, 0xffff0000, v34
	v_lshlrev_b32_e32 v46, 16, v39
	v_and_b32_e32 v48, 0xffff0000, v39
	v_add_f32_e32 v39, v68, v69
	v_pk_add_f32 v[68:69], v[86:87], v[34:35]
	v_lshlrev_b32_e32 v42, 16, v40
	v_and_b32_e32 v43, 0xffff0000, v40
	v_lshlrev_b32_e32 v40, 16, v41
	v_and_b32_e32 v41, 0xffff0000, v41
	v_pk_add_f32 v[68:69], v[68:69], v[68:69] op_sel_hi:[0,1]
	v_lshlrev_b32_e32 v44, 16, v38
	v_and_b32_e32 v38, 0xffff0000, v38
	v_add_f32_e32 v49, 0, v39
	v_add_f32_e32 v45, v42, v43
	v_add_f32_e32 v39, v40, v41
	v_mov_b32_e32 v47, v69
	v_pk_add_f32 v[70:71], v[44:45], v[38:39]
	v_pk_add_f32 v[68:69], v[46:47], v[48:49]
	s_min_u32 s0, s24, 29
	v_pk_add_f32 v[68:69], v[70:71], v[68:69]
	s_lshl_b32 s0, s0, 3
	v_add_f32_e32 v39, v68, v69
	s_add_i32 s20, s11, s0
	s_nop 0
	v_add_f32_dpp v39, v39, v39 quad_perm:[1,0,3,2] row_mask:0xf bank_mask:0xf bound_ctrl:1
	s_nop 1
	v_add_f32_dpp v39, v39, v39 quad_perm:[2,3,0,1] row_mask:0xf bank_mask:0xf bound_ctrl:1
	s_nop 1
	v_add_f32_dpp v39, v39, v39 row_half_mirror row_mask:0xf bank_mask:0xf bound_ctrl:1
	s_nop 1
	v_add_f32_dpp v39, v39, v39 row_mirror row_mask:0xf bank_mask:0xf bound_ctrl:1
	s_nop 0
	v_readlane_b32 s21, v39, 16
	v_readlane_b32 s22, v39, 48
	v_readlane_b32 s0, v39, 0
	v_readlane_b32 s1, v39, 32
	v_mov_b32_e32 v68, s21
	v_mov_b32_e32 v69, s22
	v_pk_add_f32 v[68:69], s[0:1], v[68:69]
	s_nop 0
	v_add_f32_e32 v39, v68, v69
	v_fmac_f32_e32 v36, 0xba800000, v39
	v_fmac_f32_e32 v37, 0xba800000, v39
	v_fmac_f32_e32 v77, 0xba800000, v39
	v_fmac_f32_e32 v76, 0xba800000, v39
	v_mov_b32_e32 v88, v77
	v_mov_b32_e32 v89, v37
	v_mov_b32_e32 v77, v36
	v_fmac_f32_e32 v34, 0xba800000, v39
	v_fmac_f32_e32 v35, 0xba800000, v39
	v_fmac_f32_e32 v87, 0xba800000, v39
	v_pk_mul_f32 v[68:69], v[88:89], v[88:89]
	v_pk_mul_f32 v[36:37], v[76:77], v[76:77]
	v_fmac_f32_e32 v86, 0xba800000, v39
	v_mov_b32_e32 v90, v87
	v_mov_b32_e32 v91, v35
	v_mov_b32_e32 v87, v34
	v_pk_mov_b32 v[70:71], v[36:37], v[68:69] op_sel:[1,0]
	v_mov_b32_e32 v37, v69
	v_pk_mul_f32 v[68:69], v[90:91], v[90:91]
	v_pk_mul_f32 v[34:35], v[86:87], v[86:87]
	v_pk_add_f32 v[36:37], v[70:71], v[36:37]
	v_pk_mov_b32 v[70:71], v[34:35], v[68:69] op_sel:[1,0]
	v_mov_b32_e32 v35, v69
	v_pk_add_f32 v[34:35], v[70:71], v[34:35]
	v_fmac_f32_e32 v42, 0xba800000, v39
	v_pk_add_f32 v[34:35], v[34:35], v[34:35] op_sel_hi:[0,1]
	v_fmac_f32_e32 v43, 0xba800000, v39
	v_fmac_f32_e32 v40, 0xba800000, v39
	v_mul_f32_e32 v34, v42, v42
	v_fmac_f32_e32 v41, 0xba800000, v39
	v_pk_fma_f32 v[68:69], v[42:43], v[42:43], v[34:35] op_sel_hi:[1,1,0]
	v_mul_f32_e32 v34, v40, v40
	v_pk_add_f32 v[36:37], v[36:37], v[36:37] op_sel_hi:[0,1]
	v_pk_fma_f32 v[70:71], v[40:41], v[40:41], v[34:35] op_sel_hi:[1,1,0]
	v_fmac_f32_e32 v48, 0xba800000, v39
	v_fmac_f32_e32 v46, 0xba800000, v39
	v_fmac_f32_e32 v38, 0xba800000, v39
	v_fmac_f32_e32 v44, 0xba800000, v39
	v_mul_f32_e32 v68, v44, v44
	v_mul_f32_e32 v70, v38, v38
	v_mul_f32_e32 v36, v46, v46
	v_mul_f32_e32 v34, v48, v48
	v_pk_add_f32 v[68:69], v[68:69], v[70:71]
	v_pk_add_f32 v[34:35], v[36:37], v[34:35]
	v_mov_b32_e32 v47, v48
	v_pk_add_f32 v[34:35], v[68:69], v[34:35]
	s_nop 0
	v_add_f32_e32 v34, v34, v35
	s_nop 1
	v_add_f32_dpp v34, v34, v34 quad_perm:[1,0,3,2] row_mask:0xf bank_mask:0xf bound_ctrl:1
	s_nop 1
	v_add_f32_dpp v34, v34, v34 quad_perm:[2,3,0,1] row_mask:0xf bank_mask:0xf bound_ctrl:1
	s_nop 1
	v_add_f32_dpp v34, v34, v34 row_half_mirror row_mask:0xf bank_mask:0xf bound_ctrl:1
	s_nop 1
	v_add_f32_dpp v34, v34, v34 row_mirror row_mask:0xf bank_mask:0xf bound_ctrl:1
	s_nop 0
	v_readlane_b32 s21, v34, 16
	v_readlane_b32 s22, v34, 48
	v_readlane_b32 s0, v34, 0
	v_readlane_b32 s1, v34, 32
	v_mov_b32_e32 v34, s21
	v_mov_b32_e32 v35, s22
	v_pk_add_f32 v[34:35], s[0:1], v[34:35]
	s_mov_b32 s0, 0xf800000
	v_add_f32_e32 v34, v34, v35
	v_fmamk_f32 v34, v34, 0x3a800000, v82
	s_ashr_i32 s21, s20, 31
	v_mul_f32_e32 v35, 0x4f800000, v34
	v_cmp_gt_f32_e32 vcc, s0, v34
	s_lshl_b64 s[0:1], s[20:21], 11
	s_and_b32 s22, s24, 3
	v_cndmask_b32_e32 v36, v34, v35, vcc
	v_lshl_add_u64 v[34:35], v[54:55], 0, s[0:1]
	flat_load_dwordx2 v[68:69], v[34:35] nt
	flat_load_dwordx2 v[70:71], v[34:35] offset:512 nt
	flat_load_dwordx2 v[72:73], v[34:35] offset:1024 nt
	flat_load_dwordx2 v[74:75], v[34:35] offset:1536 nt
	v_sqrt_f32_e32 v37, v36
	s_mul_i32 s23, s22, 0x810
	s_add_i32 s23, s87, s23
	v_add_u32_e32 v39, -1, v37
	v_fma_f32 v45, -v39, v37, v36
	v_cmp_ge_f32_e64 s[20:21], 0, v45
	v_add_u32_e32 v45, 1, v37
	s_nop 0
	v_cndmask_b32_e64 v39, v37, v39, s[20:21]
	v_fma_f32 v37, -v45, v37, v36
	v_cmp_lt_f32_e64 s[20:21], 0, v37
	s_nop 1
	v_cndmask_b32_e64 v37, v39, v45, s[20:21]
	v_mul_f32_e32 v39, 0x37800000, v37
	v_cndmask_b32_e32 v37, v37, v39, vcc
	v_cmp_class_f32_e32 vcc, v36, v83
	s_add_i32 s20, s4, s10
	s_ashr_i32 s21, s20, 31
	v_cndmask_b32_e32 v36, v37, v36, vcc
	v_div_scale_f32 v37, s[0:1], v36, v36, 1.0
	v_rcp_f32_e32 v39, v37
	s_lshl_b64 s[0:1], s[20:21], 11
	v_fma_f32 v34, -v37, v39, 1.0
	v_fmac_f32_e32 v39, v34, v39
	v_div_scale_f32 v34, vcc, 1.0, v36, 1.0
	v_mul_f32_e32 v35, v34, v39
	v_fma_f32 v45, -v37, v35, v34
	v_fmac_f32_e32 v35, v45, v39
	v_fma_f32 v34, -v37, v35, v34
	v_div_fmas_f32 v34, v34, v39, v35
	v_div_fixup_f32 v34, v34, v36, 1.0
	v_mov_b32_e32 v45, v38
	v_pk_mul_f32 v[36:37], v[76:77], v[34:35] op_sel_hi:[1,0]
	v_pk_mul_f32 v[76:77], v[88:89], v[34:35] op_sel_hi:[1,0]
	v_pk_mul_f32 v[38:39], v[44:45], v[34:35] op_sel_hi:[1,0]
	v_mov_b32_e32 v44, v168
	v_pk_fma_f32 v[76:77], v[4:5], v[76:77], v[12:13]
	v_pk_fma_f32 v[36:37], v[2:3], v[36:37], v[10:11]
	v_pk_mul_f32 v[86:87], v[86:87], v[34:35] op_sel_hi:[1,0]
	v_pk_mul_f32 v[88:89], v[90:91], v[34:35] op_sel_hi:[1,0]
	v_pk_fma_f32 v[86:87], v[6:7], v[86:87], v[14:15]
	v_pk_fma_f32 v[88:89], v[8:9], v[88:89], v[16:17]
	v_pk_mul_f32 v[42:43], v[42:43], v[34:35] op_sel_hi:[1,0]
	v_pk_mul_f32 v[40:41], v[40:41], v[34:35] op_sel_hi:[1,0]
	v_pk_mul_f32 v[34:35], v[46:47], v[34:35] op_sel_hi:[1,0]
	v_lshl_add_u32 v48, v44, 3, s23
	v_cvt_pk_bf16_f32 v44, v36, v37
	v_cvt_pk_bf16_f32 v45, v76, v77
	v_lshl_add_u64 v[46:47], v[56:57], 0, s[0:1]
	v_pk_fma_f32 v[40:41], v[20:21], v[40:41], v[28:29]
	v_pk_fma_f32 v[42:43], v[18:19], v[42:43], v[26:27]
	flat_store_dwordx2 v[46:47], v[44:45]
	ds_write_b64 v48, v[44:45] offset:33024
	v_cvt_pk_bf16_f32 v44, v86, v87
	v_cvt_pk_bf16_f32 v45, v88, v89
	v_pk_fma_f32 v[34:35], v[24:25], v[34:35], v[32:33]
	v_pk_fma_f32 v[38:39], v[22:23], v[38:39], v[30:31]
	flat_store_dwordx2 v[46:47], v[44:45] offset:512
	ds_write_b64 v48, v[44:45] offset:33536
	v_cvt_pk_bf16_f32 v44, v42, v43
	v_cvt_pk_bf16_f32 v45, v40, v41
	flat_store_dwordx2 v[46:47], v[44:45] offset:1024
	ds_write_b64 v48, v[44:45] offset:34048
	v_cvt_pk_bf16_f32 v44, v38, v39
	v_cvt_pk_bf16_f32 v45, v34, v35
	flat_store_dwordx2 v[46:47], v[44:45] offset:1536
	ds_write_b64 v48, v[44:45] offset:34560
	v_med3_f32 v36, v36, s6, v84
	v_med3_f32 v37, v37, s6, v84
	v_mov_b32_e32 v44, 0
	v_cvt_pk_fp8_f32 v44, v36, v37
	v_med3_f32 v36, v76, s6, v84
	v_med3_f32 v37, v77, s6, v84
	v_med3_f32 v45, v86, s6, v84
	v_cvt_pk_fp8_f32 v44, v36, v37 op_sel:[0,0,1]
	v_med3_f32 v46, v87, s6, v84
	v_mov_b32_e32 v47, 0
	v_cvt_pk_fp8_f32 v47, v45, v46
	s_lshl_b64 s[0:1], s[20:21], 10
	v_lshl_add_u64 v[36:37], v[58:59], 0, s[0:1]
	flat_store_dword v[36:37], v44
	v_med3_f32 v44, v88, s6, v84
	v_med3_f32 v45, v89, s6, v84
	v_cvt_pk_fp8_f32 v47, v44, v45 op_sel:[0,0,1]
	v_med3_f32 v42, v42, s6, v84
	v_med3_f32 v43, v43, s6, v84
	v_mov_b32_e32 v44, 0
	v_cvt_pk_fp8_f32 v44, v42, v43
	v_med3_f32 v38, v38, s6, v84
	v_med3_f32 v39, v39, s6, v84
	v_mov_b32_e32 v42, 0
	v_cvt_pk_fp8_f32 v42, v38, v39
	v_med3_f32 v34, v34, s6, v84
	v_med3_f32 v35, v35, s6, v84
	v_med3_f32 v40, v40, s6, v84
	v_med3_f32 v41, v41, s6, v84
	v_cvt_pk_fp8_f32 v42, v34, v35 op_sel:[0,0,1]
	v_cvt_pk_fp8_f32 v44, v40, v41 op_sel:[0,0,1]
	s_cmp_lg_u32 s22, 3
	flat_store_dword v[36:37], v47 offset:256
	flat_store_dword v[36:37], v44 offset:512
	flat_store_dword v[36:37], v42 offset:768
	s_cbranch_scc1 .LBB0_1070
	v_mov_b32_e32 v76, v168
	s_nop 0
	v_and_b32_e32 v34, 3, v76
	v_mul_u32_u24_e32 v34, 0x810, v34
	v_and_b32_e32 v35, -16, v76
	v_add3_u32 v77, s87, v34, v35
	v_and_b32_e32 v34, 15, v76
	v_mul_u32_u24_e32 v34, 0x810, v34
	v_add3_u32 v85, 0, v34, v35
	ds_read_b128 v[34:37], v77 offset:33024
	ds_read_b128 v[38:41], v85
	s_waitcnt lgkmcnt(0)
	v_mfma_f32_16x16x32_bf16 v[34:37], v[34:37], v[38:41], 0
	ds_read_b128 v[38:41], v77 offset:33088
	ds_read_b128 v[42:45], v85 offset:64
	v_cmp_gt_i32_e32 vcc, 16, v76
	s_waitcnt lgkmcnt(0)
	v_mfma_f32_16x16x32_bf16 v[38:41], v[38:41], v[42:45], 0
	ds_read_b128 v[42:45], v77 offset:33152
	ds_read_b128 v[46:49], v85 offset:128
	s_waitcnt lgkmcnt(0)
	v_mfma_f32_16x16x32_bf16 v[42:45], v[42:45], v[46:49], 0
	ds_read_b128 v[46:49], v77 offset:33216
	ds_read_b128 v[86:89], v85 offset:192
	s_waitcnt lgkmcnt(0)
	v_mfma_f32_16x16x32_bf16 v[46:49], v[46:49], v[86:89], 0
	ds_read_b128 v[86:89], v77 offset:33280
	ds_read_b128 v[90:93], v85 offset:256
	s_waitcnt lgkmcnt(0)
	v_mfma_f32_16x16x32_bf16 v[34:37], v[86:89], v[90:93], v[34:37]
	ds_read_b128 v[86:89], v77 offset:33344
	ds_read_b128 v[90:93], v85 offset:320
	s_waitcnt lgkmcnt(0)
	v_mfma_f32_16x16x32_bf16 v[38:41], v[86:89], v[90:93], v[38:41]
	ds_read_b128 v[86:89], v77 offset:33408
	ds_read_b128 v[90:93], v85 offset:384
	s_waitcnt lgkmcnt(0)
	v_mfma_f32_16x16x32_bf16 v[42:45], v[86:89], v[90:93], v[42:45]
	ds_read_b128 v[86:89], v77 offset:33472
	ds_read_b128 v[90:93], v85 offset:448
	s_waitcnt lgkmcnt(0)
	v_mfma_f32_16x16x32_bf16 v[46:49], v[86:89], v[90:93], v[46:49]
	ds_read_b128 v[86:89], v77 offset:33536
	ds_read_b128 v[90:93], v85 offset:512
	s_waitcnt lgkmcnt(0)
	v_mfma_f32_16x16x32_bf16 v[34:37], v[86:89], v[90:93], v[34:37]
	ds_read_b128 v[86:89], v77 offset:33600
	ds_read_b128 v[90:93], v85 offset:576
	s_waitcnt lgkmcnt(0)
	v_mfma_f32_16x16x32_bf16 v[38:41], v[86:89], v[90:93], v[38:41]
	ds_read_b128 v[86:89], v77 offset:33664
	ds_read_b128 v[90:93], v85 offset:640
	s_waitcnt lgkmcnt(0)
	v_mfma_f32_16x16x32_bf16 v[42:45], v[86:89], v[90:93], v[42:45]
	ds_read_b128 v[86:89], v77 offset:33728
	ds_read_b128 v[90:93], v85 offset:704
	s_waitcnt lgkmcnt(0)
	v_mfma_f32_16x16x32_bf16 v[46:49], v[86:89], v[90:93], v[46:49]
	ds_read_b128 v[86:89], v77 offset:33792
	ds_read_b128 v[90:93], v85 offset:768
	s_waitcnt lgkmcnt(0)
	v_mfma_f32_16x16x32_bf16 v[34:37], v[86:89], v[90:93], v[34:37]
	ds_read_b128 v[86:89], v77 offset:33856
	ds_read_b128 v[90:93], v85 offset:832
	s_waitcnt lgkmcnt(0)
	v_mfma_f32_16x16x32_bf16 v[38:41], v[86:89], v[90:93], v[38:41]
	ds_read_b128 v[86:89], v77 offset:33920
	ds_read_b128 v[90:93], v85 offset:896
	s_waitcnt lgkmcnt(0)
	v_mfma_f32_16x16x32_bf16 v[42:45], v[86:89], v[90:93], v[42:45]
	ds_read_b128 v[86:89], v77 offset:33984
	ds_read_b128 v[90:93], v85 offset:960
	s_waitcnt lgkmcnt(0)
	v_mfma_f32_16x16x32_bf16 v[46:49], v[86:89], v[90:93], v[46:49]
	ds_read_b128 v[86:89], v77 offset:34048
	ds_read_b128 v[90:93], v85 offset:1024
	s_waitcnt lgkmcnt(0)
	v_mfma_f32_16x16x32_bf16 v[34:37], v[86:89], v[90:93], v[34:37]
	ds_read_b128 v[86:89], v77 offset:34112
	ds_read_b128 v[90:93], v85 offset:1088
	s_waitcnt lgkmcnt(0)
	v_mfma_f32_16x16x32_bf16 v[38:41], v[86:89], v[90:93], v[38:41]
	ds_read_b128 v[86:89], v77 offset:34176
	ds_read_b128 v[90:93], v85 offset:1152
	s_waitcnt lgkmcnt(0)
	v_mfma_f32_16x16x32_bf16 v[42:45], v[86:89], v[90:93], v[42:45]
	ds_read_b128 v[86:89], v77 offset:34240
	ds_read_b128 v[90:93], v85 offset:1216
	s_waitcnt lgkmcnt(0)
	v_mfma_f32_16x16x32_bf16 v[46:49], v[86:89], v[90:93], v[46:49]
	ds_read_b128 v[86:89], v77 offset:34304
	ds_read_b128 v[90:93], v85 offset:1280
	s_waitcnt lgkmcnt(0)
	v_mfma_f32_16x16x32_bf16 v[34:37], v[86:89], v[90:93], v[34:37]
	ds_read_b128 v[86:89], v77 offset:34368
	ds_read_b128 v[90:93], v85 offset:1344
	s_waitcnt lgkmcnt(0)
	v_mfma_f32_16x16x32_bf16 v[38:41], v[86:89], v[90:93], v[38:41]
	ds_read_b128 v[86:89], v77 offset:34432
	ds_read_b128 v[90:93], v85 offset:1408
	s_waitcnt lgkmcnt(0)
	v_mfma_f32_16x16x32_bf16 v[42:45], v[86:89], v[90:93], v[42:45]
	ds_read_b128 v[86:89], v77 offset:34496
	ds_read_b128 v[90:93], v85 offset:1472
	s_waitcnt lgkmcnt(0)
	v_mfma_f32_16x16x32_bf16 v[46:49], v[86:89], v[90:93], v[46:49]
	ds_read_b128 v[86:89], v77 offset:34560
	ds_read_b128 v[90:93], v85 offset:1536
	s_waitcnt lgkmcnt(0)
	v_mfma_f32_16x16x32_bf16 v[34:37], v[86:89], v[90:93], v[34:37]
	ds_read_b128 v[86:89], v77 offset:34624
	ds_read_b128 v[90:93], v85 offset:1600
	s_waitcnt lgkmcnt(0)
	v_mfma_f32_16x16x32_bf16 v[38:41], v[86:89], v[90:93], v[38:41]
	ds_read_b128 v[86:89], v77 offset:34688
	ds_read_b128 v[90:93], v85 offset:1664
	s_waitcnt lgkmcnt(0)
	v_mfma_f32_16x16x32_bf16 v[42:45], v[86:89], v[90:93], v[42:45]
	ds_read_b128 v[86:89], v77 offset:34752
	ds_read_b128 v[90:93], v85 offset:1728
	s_waitcnt lgkmcnt(0)
	v_mfma_f32_16x16x32_bf16 v[46:49], v[86:89], v[90:93], v[46:49]
	ds_read_b128 v[86:89], v77 offset:34816
	ds_read_b128 v[90:93], v85 offset:1792
	s_waitcnt lgkmcnt(0)
	v_mfma_f32_16x16x32_bf16 v[34:37], v[86:89], v[90:93], v[34:37]
	ds_read_b128 v[86:89], v77 offset:34880
	ds_read_b128 v[90:93], v85 offset:1856
	s_waitcnt lgkmcnt(0)
	v_mfma_f32_16x16x32_bf16 v[38:41], v[86:89], v[90:93], v[38:41]
	ds_read_b128 v[86:89], v77 offset:34944
	ds_read_b128 v[90:93], v85 offset:1920
	s_waitcnt lgkmcnt(0)
	v_mfma_f32_16x16x32_bf16 v[42:45], v[86:89], v[90:93], v[42:45]
	ds_read_b128 v[86:89], v77 offset:35008
	ds_read_b128 v[90:93], v85 offset:1984
	s_nop 1
	v_pk_add_f32 v[34:35], v[34:35], v[38:39]
	v_ashrrev_i32_e32 v77, 31, v76
	s_waitcnt lgkmcnt(0)
	v_mfma_f32_16x16x32_bf16 v[46:49], v[86:89], v[90:93], v[46:49]
	s_nop 7
	v_pk_add_f32 v[38:39], v[42:43], v[46:47]
	s_nop 0
	v_pk_add_f32 v[38:39], v[34:35], v[38:39]
	v_lshlrev_b64 v[34:35], 13, v[76:77]
	v_lshl_add_u64 v[34:35], s[30:31], 0, v[34:35]
	v_mov_b32_dpp v42, v38 quad_perm:[1,0,3,2] row_mask:0xf bank_mask:0xf bound_ctrl:1
	v_max_f32_e32 v42, v42, v42
	v_max_f32_e32 v42, v38, v42
	s_nop 1
	v_mov_b32_dpp v43, v42 quad_perm:[2,3,0,1] row_mask:0xf bank_mask:0xf bound_ctrl:1
	v_max_f32_e32 v43, v43, v43
	v_max_f32_e32 v42, v42, v43
	s_nop 1
	v_mov_b32_dpp v43, v42 row_half_mirror row_mask:0xf bank_mask:0xf bound_ctrl:1
	v_max_f32_e32 v43, v43, v43
	v_max_f32_e32 v42, v42, v43
	s_nop 1
	v_mov_b32_dpp v43, v42 row_mirror row_mask:0xf bank_mask:0xf bound_ctrl:1
	v_max_f32_e32 v43, v43, v43
	v_max_f32_e32 v42, v42, v43
	v_sub_f32_e32 v38, v38, v42
	v_mul_f32_e32 v38, 0x3fb8aa3b, v38
	v_exp_f32_e32 v38, v38
	s_nop 1
	v_add_f32_dpp v42, v38, v38 quad_perm:[1,0,3,2] row_mask:0xf bank_mask:0xf bound_ctrl:1
	s_nop 1
	v_add_f32_dpp v42, v42, v42 quad_perm:[2,3,0,1] row_mask:0xf bank_mask:0xf bound_ctrl:1
	s_nop 1
	v_add_f32_dpp v42, v42, v42 row_half_mirror row_mask:0xf bank_mask:0xf bound_ctrl:1
	s_nop 1
	v_mov_b32_dpp v43, v42 row_mirror row_mask:0xf bank_mask:0xf bound_ctrl:1
	s_and_saveexec_b64 s[22:23], vcc
	s_cbranch_execz .LBB0_1074
	v_add_f32_e32 v42, v42, v43
	v_rcp_f32_e32 v42, v42
	s_sub_i32 s21, s20, 24
	s_ashr_i32 s0, s21, 11
	s_ashr_i32 s1, s0, 31
	s_and_b32 s21, s21, 0x7ff
	s_lshl_b64 s[0:1], s[0:1], 17
	v_mul_f32_e32 v38, v38, v42
	v_lshl_add_u64 v[42:43], v[34:35], 0, s[0:1]
	s_lshl_b32 s28, s21, 2
	v_lshl_add_u64 v[42:43], v[42:43], 0, s[28:29]
	flat_store_dword v[42:43], v38

.LBB0_1427:
	s_or_b64 exec, exec, s[8:9]
	s_waitcnt lgkmcnt(0)
	s_barrier
	s_load_dwordx4 s[4:7], s[84:85], 0xf8
	s_load_dwordx2 s[24:25], s[84:85], 0x108
	s_load_dwordx8 s[16:23], s[84:85], 0xd8
	v_mov_b32_e32 v39, v0
	s_waitcnt lgkmcnt(0)
	s_mov_b32 s0, s7
	v_and_b32_e32 v74, 63, v39
	s_mov_b32 s8, s25
	s_add_u32 s26, s24, 0x3e00000
	v_lshlrev_b32_e32 v34, 4, v74
	v_mov_b32_e32 v35, 0
	s_addc_u32 s27, s8, 0
	v_lshl_add_u64 v[2:3], s[22:23], 0, v[34:35]
	s_mov_b64 s[0:1], 0x3000
	v_lshl_add_u64 v[6:7], s[4:5], 0, v[34:35]
	v_lshl_add_u64 v[26:27], v[2:3], 0, s[0:1]
	v_lshl_add_u64 v[30:31], v[6:7], 0, s[0:1]
	s_movk_i32 s0, 0x3000
	s_add_u32 s22, s24, 0x3900000
	v_add_co_u32_e32 v2, vcc, s0, v2
	s_addc_u32 s23, s8, 0
	s_nop 0
	v_addc_co_u32_e32 v3, vcc, 0, v3, vcc
	s_add_u32 s14, s24, 0xa100000
	v_add_co_u32_e32 v6, vcc, s0, v6
	s_addc_u32 s15, s8, 0
	v_readlane_b32 s0, v253, 36
	v_readlane_b32 s1, v253, 37
	s_add_u32 s0, s14, s0
	s_addc_u32 s1, s15, s1
	v_readlane_b32 s4, v253, 38
	v_readlane_b32 s5, v253, 39
	s_add_u32 s4, s14, s4
	v_lshlrev_b32_e32 v34, 3, v74
	v_addc_co_u32_e32 v7, vcc, 0, v7, vcc
	s_addc_u32 s5, s15, s5
	v_lshl_add_u64 v[36:37], s[0:1], 0, v[34:35]
	global_load_dwordx4 v[2:5], v[2:3], off nt
	s_nop 0
	global_load_dwordx4 v[6:9], v[6:7], off nt
	s_nop 0
	global_load_dwordx4 v[10:13], v[26:27], off offset:1024
	global_load_dwordx4 v[14:17], v[26:27], off offset:2048
	global_load_dwordx4 v[18:21], v[30:31], off offset:1024
	global_load_dwordx4 v[22:25], v[30:31], off offset:2048
	s_nop 0
	global_load_dwordx4 v[26:29], v[26:27], off offset:3072
	s_nop 0
	global_load_dwordx4 v[30:33], v[30:31], off offset:3072
	v_lshl_add_u64 v[46:47], s[4:5], 0, v[34:35]
	flat_load_dwordx2 v[64:65], v[36:37] nt
	flat_load_dwordx2 v[62:63], v[36:37] offset:512 nt
	flat_load_dwordx2 v[60:61], v[36:37] offset:1024 nt
	flat_load_dwordx2 v[58:59], v[36:37] offset:1536 nt
	flat_load_dwordx2 v[44:45], v[46:47] nt
	flat_load_dwordx2 v[42:43], v[46:47] offset:512 nt
	flat_load_dwordx2 v[40:41], v[46:47] offset:1024 nt
	s_nop 0
	flat_load_dwordx2 v[36:37], v[46:47] offset:1536 nt
	s_mov_b32 s7, s8
	v_cmp_gt_u32_e64 s[12:13], 16, v74
	v_mov_b32_e32 v75, -1
	v_lshlrev_b32_e32 v38, 11, v74
	v_mov_b32_e32 v82, v35
	v_mov_b32_e32 v81, -1
	s_and_saveexec_b64 s[8:9], s[12:13]
	s_cbranch_execz .LBB0_1429
	v_readlane_b32 s0, v253, 34
	v_readlane_b32 s1, v253, 35
	s_mov_b32 s4, s0
	s_ashr_i32 s0, s0, 11
	s_ashr_i32 s1, s0, 31
	s_lshl_b64 s[0:1], s[0:1], 15
	s_and_b32 s4, s4, 0x7ff
	s_or_b32 s0, s0, s4
	s_ashr_i32 s4, s68, 11
	s_ashr_i32 s5, s4, 31
	s_lshl_b64 s[4:5], s[4:5], 15
	s_and_b32 s6, s68, 0x7ff
	s_or_b32 s4, s4, s6
	v_or_b32_e32 v46, s4, v38
	v_mov_b32_e32 v47, s5
	v_lshl_add_u64 v[48:49], v[46:47], 1, s[26:27]
	v_lshl_add_u64 v[46:47], v[46:47], 2, s[22:23]
	flat_load_sshort v81, v[48:49]
	flat_load_dword v82, v[46:47] nt
	v_or_b32_e32 v46, s0, v38
	v_mov_b32_e32 v47, s1
	v_lshl_add_u64 v[48:49], v[46:47], 1, s[26:27]
	v_lshl_add_u64 v[46:47], v[46:47], 2, s[22:23]
	flat_load_sshort v75, v[48:49]
	flat_load_dword v35, v[46:47] nt

.LBB0_1432:
	s_add_i32 s30, s34, s94
	s_cmp_gt_i32 s30, 0xffff
	v_mov_b32_e32 v80, v35
	s_cbranch_scc1 .LBB0_1436
	s_ashr_i32 s31, s30, 31
	s_lshl_b64 s[0:1], s[30:31], 11
	v_lshl_add_u64 v[50:51], v[48:49], 0, s[0:1]
	flat_load_dwordx2 v[56:57], v[50:51] nt
	flat_load_dwordx2 v[54:55], v[50:51] offset:512 nt
	flat_load_dwordx2 v[52:53], v[50:51] offset:1024 nt
	s_nop 0
	flat_load_dwordx2 v[50:51], v[50:51] offset:1536 nt
	v_mov_b32_e32 v79, v75
	v_mov_b32_e32 v80, v35
	s_and_saveexec_b64 s[14:15], s[12:13]
	s_cbranch_execz .LBB0_1435
	s_ashr_i32 s0, s30, 11
	s_ashr_i32 s1, s0, 31
	s_lshl_b64 s[0:1], s[0:1], 15
	v_or_b32_e32 v34, s0, v38
	s_and_b32 s0, s30, 0x7ff
	v_mov_b32_e32 v67, s1
	v_or_b32_e32 v66, s0, v34
	v_lshl_add_u64 v[68:69], v[66:67], 1, s[26:27]
	v_lshl_add_u64 v[66:67], v[66:67], 2, s[22:23]
	flat_load_sshort v79, v[68:69]
	flat_load_dword v80, v[66:67] nt

.LBB0_1438:
	s_add_u32 s10, s38, -1
	s_addc_u32 s11, s39, -1
	s_lshl_b32 s8, s8, 5
	s_add_i32 s8, s8, s6
	s_ashr_i32 s9, s8, 31
	s_ashr_i32 s37, s36, 31
	s_and_b64 vcc, s[10:11], s[38:39]
	s_lshl_b64 s[8:9], s[8:9], 18
	s_lshl_b64 s[10:11], s[36:37], 10
	s_add_u32 s8, s4, s8
	s_addc_u32 s9, s5, s9
	s_add_u32 s8, s8, s10
	s_addc_u32 s9, s9, s11
	s_lshl_b32 s1, s1, 5
	s_add_i32 s10, s1, s6
	s_ashr_i32 s11, s10, 31
	s_ashr_i32 s15, s14, 31
	v_lshlrev_b32_e32 v46, 2, v74
	s_lshl_b64 s[10:11], s[10:11], 18
	s_lshl_b64 s[14:15], s[14:15], 10
	v_lshl_add_u64 v[84:85], s[8:9], 0, v[46:47]
	s_add_u32 s1, s4, s10
	flat_load_dword v83, v[84:85] nt
	s_addc_u32 s11, s5, s11
	s_add_u32 s10, s1, s14
	s_addc_u32 s11, s11, s15
	v_lshl_add_u64 v[86:87], s[10:11], 0, v[46:47]
	flat_load_dword v90, v[86:87] nt
	flat_load_dword v92, v[84:85] offset:256 nt
	flat_load_dword v93, v[86:87] offset:256 nt
	flat_load_dword v94, v[84:85] offset:512 nt
	flat_load_dword v95, v[86:87] offset:512 nt
	flat_load_dword v96, v[84:85] offset:768 nt
	flat_load_dword v97, v[86:87] offset:768 nt
	v_mul_f32_e32 v46, s0, v78
	s_cmp_eq_u64 vcc, 0
	s_waitcnt vmcnt(0) lgkmcnt(0)
	v_cvt_pk_f32_fp8_e32 v[88:89], v90
	v_cvt_pk_f32_fp8_sdwa v[90:91], v90 src0_sel:WORD_1
	v_cvt_pk_f32_fp8_e32 v[84:85], v83
	v_cvt_pk_f32_fp8_sdwa v[86:87], v83 src0_sel:WORD_1
	v_pk_mul_f32 v[88:89], v[34:35], v[88:89] op_sel_hi:[0,1]
	v_pk_mul_f32 v[90:91], v[34:35], v[90:91] op_sel_hi:[0,1]
	v_pk_fma_f32 v[84:85], v[46:47], v[84:85], v[88:89] op_sel_hi:[0,1,1]
	v_pk_fma_f32 v[86:87], v[46:47], v[86:87], v[90:91] op_sel_hi:[0,1,1]
	v_cvt_pk_f32_fp8_e32 v[88:89], v93
	v_cvt_pk_f32_fp8_sdwa v[90:91], v93 src0_sel:WORD_1
	v_pk_add_f32 v[68:69], v[68:69], v[86:87]
	v_pk_add_f32 v[70:71], v[70:71], v[84:85]
	v_cvt_pk_f32_fp8_e32 v[84:85], v92
	v_cvt_pk_f32_fp8_sdwa v[86:87], v92 src0_sel:WORD_1
	v_pk_mul_f32 v[90:91], v[34:35], v[90:91] op_sel_hi:[0,1]
	v_pk_mul_f32 v[88:89], v[34:35], v[88:89] op_sel_hi:[0,1]
	v_pk_fma_f32 v[84:85], v[46:47], v[84:85], v[88:89] op_sel_hi:[0,1,1]
	v_pk_fma_f32 v[86:87], v[46:47], v[86:87], v[90:91] op_sel_hi:[0,1,1]
	v_cvt_pk_f32_fp8_e32 v[88:89], v95
	v_cvt_pk_f32_fp8_sdwa v[90:91], v95 src0_sel:WORD_1
	v_pk_add_f32 v[62:63], v[62:63], v[86:87]
	v_pk_add_f32 v[66:67], v[66:67], v[84:85]
	v_cvt_pk_f32_fp8_e32 v[84:85], v94
	v_cvt_pk_f32_fp8_sdwa v[86:87], v94 src0_sel:WORD_1
	v_pk_mul_f32 v[90:91], v[34:35], v[90:91] op_sel_hi:[0,1]
	v_pk_mul_f32 v[88:89], v[34:35], v[88:89] op_sel_hi:[0,1]
	v_pk_fma_f32 v[84:85], v[46:47], v[84:85], v[88:89] op_sel_hi:[0,1,1]
	v_pk_fma_f32 v[86:87], v[46:47], v[86:87], v[90:91] op_sel_hi:[0,1,1]
	v_cvt_pk_f32_fp8_e32 v[88:89], v97
	v_cvt_pk_f32_fp8_sdwa v[90:91], v97 src0_sel:WORD_1
	v_pk_add_f32 v[60:61], v[60:61], v[86:87]
	v_pk_add_f32 v[64:65], v[64:65], v[84:85]
	v_cvt_pk_f32_fp8_e32 v[84:85], v96
	v_cvt_pk_f32_fp8_sdwa v[86:87], v96 src0_sel:WORD_1
	v_pk_mul_f32 v[90:91], v[34:35], v[90:91] op_sel_hi:[0,1]
	v_pk_mul_f32 v[88:89], v[34:35], v[88:89] op_sel_hi:[0,1]
	v_pk_fma_f32 v[84:85], v[46:47], v[84:85], v[88:89] op_sel_hi:[0,1,1]
	v_pk_fma_f32 v[86:87], v[46:47], v[86:87], v[90:91] op_sel_hi:[0,1,1]
	v_pk_add_f32 v[72:73], v[72:73], v[86:87]
	v_pk_add_f32 v[58:59], v[58:59], v[84:85]
	s_cbranch_scc1 .LBB0_1431

.LBB0_1576:
	v_max_i32_e32 v42, 2, v124
	v_lshlrev_b32_e32 v118, 11, v42
	v_lshl_add_u64 v[42:43], v[120:121], 0, v[118:119]
	v_max_i32_e32 v44, 1, v124
	v_add_co_u32_e32 v42, vcc, 0xfffff000, v42
	v_lshlrev_b32_e32 v118, 11, v44
	s_nop 0
	v_addc_co_u32_e32 v43, vcc, -1, v43, vcc
	v_lshl_add_u64 v[44:45], v[120:121], 0, v[118:119]
	v_add_co_u32_e32 v44, vcc, 0xfffff800, v44
	v_add_u32_e32 v154, 1, v124
	s_nop 0
	v_addc_co_u32_e32 v45, vcc, -1, v45, vcc
	flat_load_dwordx4 v[114:117], v[42:43] nt
	flat_load_dwordx4 v[110:113], v[44:45] nt
	v_max_i32_e32 v42, 0, v124
	v_lshlrev_b32_e32 v118, 11, v42
	v_med3_i32 v44, v154, 0, v157
	v_lshl_add_u64 v[42:43], v[120:121], 0, v[118:119]
	v_lshlrev_b32_e32 v118, 11, v44
	v_add_u32_e32 v152, 2, v124
	v_lshl_add_u64 v[44:45], v[120:121], 0, v[118:119]
	flat_load_dwordx4 v[106:109], v[42:43] nt
	flat_load_dwordx4 v[102:105], v[44:45] nt
	v_med3_i32 v42, v152, 0, v157
	v_add_u32_e32 v150, 3, v124
	v_lshlrev_b32_e32 v118, 11, v42
	v_med3_i32 v44, v150, 0, v157
	v_lshl_add_u64 v[42:43], v[120:121], 0, v[118:119]
	v_lshlrev_b32_e32 v118, 11, v44
	v_add_u32_e32 v148, 4, v124
	v_lshl_add_u64 v[44:45], v[120:121], 0, v[118:119]
	flat_load_dwordx4 v[98:101], v[42:43] nt
	flat_load_dwordx4 v[94:97], v[44:45] nt
	v_med3_i32 v42, v148, 0, v157
	v_add_u32_e32 v146, 5, v124
	v_lshlrev_b32_e32 v118, 11, v42
	v_med3_i32 v44, v146, 0, v157
	v_lshl_add_u64 v[42:43], v[120:121], 0, v[118:119]
	v_lshlrev_b32_e32 v118, 11, v44
	v_add_u32_e32 v144, 6, v124
	v_lshl_add_u64 v[44:45], v[120:121], 0, v[118:119]
	flat_load_dwordx4 v[90:93], v[42:43] nt
	flat_load_dwordx4 v[86:89], v[44:45] nt
	v_med3_i32 v42, v144, 0, v157
	v_add_u32_e32 v142, 7, v124
	v_lshlrev_b32_e32 v118, 11, v42
	v_med3_i32 v44, v142, 0, v157
	v_lshl_add_u64 v[42:43], v[120:121], 0, v[118:119]
	v_lshlrev_b32_e32 v118, 11, v44
	v_add_u32_e32 v140, 8, v124
	v_lshl_add_u64 v[44:45], v[120:121], 0, v[118:119]
	flat_load_dwordx4 v[82:85], v[42:43] nt
	flat_load_dwordx4 v[78:81], v[44:45] nt
	v_med3_i32 v42, v140, 0, v157
	v_add_u32_e32 v138, 9, v124
	v_lshlrev_b32_e32 v118, 11, v42
	v_med3_i32 v44, v138, 0, v157
	v_lshl_add_u64 v[42:43], v[120:121], 0, v[118:119]
	v_lshlrev_b32_e32 v118, 11, v44
	v_add_u32_e32 v136, 10, v124
	v_lshl_add_u64 v[44:45], v[120:121], 0, v[118:119]
	flat_load_dwordx4 v[74:77], v[42:43] nt
	flat_load_dwordx4 v[70:73], v[44:45] nt
	v_med3_i32 v42, v136, 0, v157
	v_add_u32_e32 v134, 11, v124
	v_lshlrev_b32_e32 v118, 11, v42
	v_med3_i32 v44, v134, 0, v157
	v_lshl_add_u64 v[42:43], v[120:121], 0, v[118:119]
	v_lshlrev_b32_e32 v118, 11, v44
	v_add_u32_e32 v132, 12, v124
	v_lshl_add_u64 v[44:45], v[120:121], 0, v[118:119]
	flat_load_dwordx4 v[66:69], v[42:43] nt
	flat_load_dwordx4 v[62:65], v[44:45] nt
	v_med3_i32 v42, v132, 0, v157
	v_add_u32_e32 v130, 13, v124
	v_lshlrev_b32_e32 v118, 11, v42
	v_med3_i32 v44, v130, 0, v157
	v_lshl_add_u64 v[42:43], v[120:121], 0, v[118:119]
	v_lshlrev_b32_e32 v118, 11, v44
	v_add_u32_e32 v128, 14, v124
	v_lshl_add_u64 v[44:45], v[120:121], 0, v[118:119]
	flat_load_dwordx4 v[58:61], v[42:43] nt
	flat_load_dwordx4 v[54:57], v[44:45] nt
	v_med3_i32 v42, v128, 0, v157
	v_add_u32_e32 v126, 15, v124
	v_lshlrev_b32_e32 v118, 11, v42
	v_med3_i32 v44, v126, 0, v157
	v_lshl_add_u64 v[42:43], v[120:121], 0, v[118:119]
	v_lshlrev_b32_e32 v118, 11, v44
	v_lshl_add_u64 v[44:45], v[120:121], 0, v[118:119]
	flat_load_dwordx4 v[50:53], v[42:43] nt
	flat_load_dwordx4 v[46:49], v[44:45] nt
	v_and_b32_e32 v125, 0x7f0, v124
	s_movk_i32 s0, 0x7ef
	v_cmp_lt_i32_e32 vcc, s0, v125
	s_and_saveexec_b64 s[0:1], vcc
	s_xor_b64 s[16:17], exec, s[0:1]
	s_or_saveexec_b64 s[16:17], s[16:17]
	v_mov_b32_e32 v42, 0
	v_mov_b32_e32 v43, 0
	v_mov_b32_e32 v44, 0
	v_mov_b32_e32 v45, 0
	s_xor_b64 exec, exec, s[16:17]
	s_cbranch_execz .LBB0_1575
	v_max_i32_e32 v42, -16, v124
	v_add_u32_e32 v42, 16, v42
	v_min_u32_e32 v42, 0xffff, v42
	v_lshlrev_b32_e32 v118, 11, v42
	v_lshl_add_u64 v[42:43], v[120:121], 0, v[118:119]
	flat_load_dwordx4 v[42:45], v[42:43] nt
	v_cmp_eq_u32_e32 vcc, 0, v125
	s_and_saveexec_b64 s[18:19], vcc
	s_cbranch_execz .LBB0_1574
	s_waitcnt vmcnt(0) lgkmcnt(0)
	v_mov_b32_e32 v117, 0
	v_mov_b32_e32 v116, v117
	v_mov_b32_e32 v115, v117
	v_mov_b32_e32 v114, v117
	v_mov_b32_e32 v113, v117
	v_mov_b32_e32 v112, v117
	v_mov_b32_e32 v111, v117
	v_mov_b32_e32 v110, v117
	s_branch .LBB0_1574

.LBB0_1786:
	ds_read_b128 v[130:133], v168
	ds_read_b128 v[134:137], v168 offset:1024
	ds_read_b128 v[138:141], v168 offset:2048
	ds_read_b128 v[142:145], v168 offset:3072
	s_add_u32 s0, s38, 0xfffc0080
	s_addc_u32 s1, s39, -1
	s_cmp_eq_u32 s66, 12
	s_cselect_b32 s43, s60, s1
	s_cselect_b32 s42, s61, s0
	s_cselect_b32 s41, s62, s65
	s_cselect_b32 s40, s63, s64
	s_mov_b32 m0, s50
	v_lshl_add_u64 v[164:165], s[38:39], 0, v[162:163]
	ds_read_b128 v[146:149], v169
	ds_read_b128 v[172:175], v169 offset:1024
	ds_read_b128 v[176:179], v169 offset:2048
	ds_read_b128 v[180:183], v169 offset:3072
	ds_read_b128 v[184:187], v169 offset:4096
	ds_read_b128 v[188:191], v169 offset:5120
	ds_read_b128 v[192:195], v169 offset:6144
	ds_read_b128 v[196:199], v169 offset:7168
	global_load_lds_dwordx4 v[164:165], off
	v_lshl_add_u64 v[164:165], s[38:39], 0, v[160:161]
	s_mov_b32 m0, s51
	s_nop 0
	global_load_lds_dwordx4 v[164:165], off
	s_waitcnt lgkmcnt(8)
	s_waitcnt vmcnt(10)
	s_barrier
	s_waitcnt lgkmcnt(0)
	s_setprio 1
	s_waitcnt lgkmcnt(0)
	v_mfma_f32_16x16x32_bf16 v[126:129], v[130:133], v[146:149], v[126:129]
	v_mfma_f32_16x16x32_bf16 v[122:125], v[138:141], v[146:149], v[122:125]
	v_mfma_f32_16x16x32_bf16 v[118:121], v[130:133], v[176:179], v[118:121]
	v_mfma_f32_16x16x32_bf16 v[110:113], v[138:141], v[176:179], v[110:113]
	v_mfma_f32_16x16x32_bf16 v[98:101], v[130:133], v[184:187], v[98:101]
	v_mfma_f32_16x16x32_bf16 v[90:93], v[138:141], v[184:187], v[90:93]
	v_mfma_f32_16x16x32_bf16 v[82:85], v[130:133], v[192:195], v[82:85]
	v_mfma_f32_16x16x32_bf16 v[74:77], v[138:141], v[192:195], v[74:77]
	v_mfma_f32_16x16x32_bf16 v[126:129], v[134:137], v[172:175], v[126:129]
	v_mfma_f32_16x16x32_bf16 v[122:125], v[142:145], v[172:175], v[122:125]
	v_mfma_f32_16x16x32_bf16 v[118:121], v[134:137], v[180:183], v[118:121]
	v_mfma_f32_16x16x32_bf16 v[110:113], v[142:145], v[180:183], v[110:113]
	v_mfma_f32_16x16x32_bf16 v[98:101], v[134:137], v[188:191], v[98:101]
	v_mfma_f32_16x16x32_bf16 v[90:93], v[142:145], v[188:191], v[90:93]
	v_mfma_f32_16x16x32_bf16 v[82:85], v[134:137], v[196:199], v[82:85]
	v_mfma_f32_16x16x32_bf16 v[74:77], v[142:145], v[196:199], v[74:77]
	s_setprio 0
	s_barrier
	s_mov_b32 m0, s52
	v_lshl_add_u64 v[164:165], s[40:41], 0, v[156:157]
	ds_read_b128 v[200:203], v170
	ds_read_b128 v[204:207], v170 offset:1024
	ds_read_b128 v[208:211], v170 offset:2048
	ds_read_b128 v[212:215], v170 offset:3072
	global_load_lds_dwordx4 v[164:165], off
	v_lshl_add_u64 v[216:217], s[40:41], 0, v[152:153]
	s_mov_b32 m0, s53
	s_nop 0
	global_load_lds_dwordx4 v[216:217], off
	s_waitcnt vmcnt(10)
	s_barrier
	s_waitcnt lgkmcnt(0)
	s_setprio 1
	s_waitcnt lgkmcnt(0)
	v_mfma_f32_16x16x32_bf16 v[114:117], v[200:203], v[146:149], v[114:117]
	v_mfma_f32_16x16x32_bf16 v[106:109], v[208:211], v[146:149], v[106:109]
	v_mfma_f32_16x16x32_bf16 v[102:105], v[200:203], v[176:179], v[102:105]
	v_mfma_f32_16x16x32_bf16 v[94:97], v[208:211], v[176:179], v[94:97]
	v_mfma_f32_16x16x32_bf16 v[86:89], v[200:203], v[184:187], v[86:89]
	v_mfma_f32_16x16x32_bf16 v[78:81], v[208:211], v[184:187], v[78:81]
	v_mfma_f32_16x16x32_bf16 v[70:73], v[200:203], v[192:195], v[70:73]
	v_mfma_f32_16x16x32_bf16 v[66:69], v[208:211], v[192:195], v[66:69]
	v_mfma_f32_16x16x32_bf16 v[114:117], v[204:207], v[172:175], v[114:117]
	v_mfma_f32_16x16x32_bf16 v[106:109], v[212:215], v[172:175], v[106:109]
	v_mfma_f32_16x16x32_bf16 v[102:105], v[204:207], v[180:183], v[102:105]
	v_mfma_f32_16x16x32_bf16 v[94:97], v[212:215], v[180:183], v[94:97]
	v_mfma_f32_16x16x32_bf16 v[86:89], v[204:207], v[188:191], v[86:89]
	v_mfma_f32_16x16x32_bf16 v[78:81], v[212:215], v[188:191], v[78:81]
	v_mfma_f32_16x16x32_bf16 v[70:73], v[204:207], v[196:199], v[70:73]
	v_mfma_f32_16x16x32_bf16 v[66:69], v[212:215], v[196:199], v[66:69]
	s_setprio 0
	s_mov_b32 m0, s8
	v_lshl_add_u64 v[218:219], s[42:43], 0, v[158:159]
	s_barrier
	ds_read_b128 v[146:149], v169 offset:16384
	ds_read_b128 v[172:175], v169 offset:17408
	ds_read_b128 v[176:179], v169 offset:18432
	ds_read_b128 v[180:183], v169 offset:19456
	ds_read_b128 v[184:187], v169 offset:20480
	ds_read_b128 v[188:191], v169 offset:21504
	ds_read_b128 v[192:195], v169 offset:22528
	ds_read_b128 v[196:199], v169 offset:23552
	global_load_lds_dwordx4 v[218:219], off
	v_lshl_add_u64 v[220:221], s[42:43], 0, v[154:155]
	s_mov_b32 m0, s9
	s_nop 0
	global_load_lds_dwordx4 v[220:221], off
	s_waitcnt vmcnt(10)
	s_barrier
	s_waitcnt lgkmcnt(0)
	s_setprio 1
	s_waitcnt lgkmcnt(0)
	v_mfma_f32_16x16x32_bf16 v[62:65], v[130:133], v[146:149], v[62:65]
	v_mfma_f32_16x16x32_bf16 v[58:61], v[138:141], v[146:149], v[58:61]
	v_mfma_f32_16x16x32_bf16 v[50:53], v[130:133], v[176:179], v[50:53]
	v_mfma_f32_16x16x32_bf16 v[42:45], v[138:141], v[176:179], v[42:45]
	v_mfma_f32_16x16x32_bf16 v[34:37], v[130:133], v[184:187], v[34:37]
	v_mfma_f32_16x16x32_bf16 v[26:29], v[138:141], v[184:187], v[26:29]
	v_mfma_f32_16x16x32_bf16 v[18:21], v[130:133], v[192:195], v[18:21]
	v_mfma_f32_16x16x32_bf16 v[10:13], v[138:141], v[192:195], v[10:13]
	v_mfma_f32_16x16x32_bf16 v[62:65], v[134:137], v[172:175], v[62:65]
	v_mfma_f32_16x16x32_bf16 v[58:61], v[142:145], v[172:175], v[58:61]
	v_mfma_f32_16x16x32_bf16 v[50:53], v[134:137], v[180:183], v[50:53]
	v_mfma_f32_16x16x32_bf16 v[42:45], v[142:145], v[180:183], v[42:45]
	v_mfma_f32_16x16x32_bf16 v[34:37], v[134:137], v[188:191], v[34:37]
	v_mfma_f32_16x16x32_bf16 v[26:29], v[142:145], v[188:191], v[26:29]
	v_mfma_f32_16x16x32_bf16 v[18:21], v[134:137], v[196:199], v[18:21]
	v_mfma_f32_16x16x32_bf16 v[10:13], v[142:145], v[196:199], v[10:13]
	s_setprio 0
	s_barrier
	s_add_u32 s0, s40, 0x40000
	s_addc_u32 s1, s41, 0
	s_mov_b32 m0, s54
	v_lshl_add_u64 v[130:131], s[0:1], 0, v[156:157]
	global_load_lds_dwordx4 v[130:131], off
	v_lshl_add_u64 v[130:131], s[0:1], 0, v[152:153]
	s_add_i32 m0, s54, 0x2000
	s_nop 0
	global_load_lds_dwordx4 v[130:131], off
	s_waitcnt vmcnt(10)
	s_barrier
	s_setprio 1
	v_mfma_f32_16x16x32_bf16 v[54:57], v[200:203], v[146:149], v[54:57]
	v_mfma_f32_16x16x32_bf16 v[46:49], v[208:211], v[146:149], v[46:49]
	v_mfma_f32_16x16x32_bf16 v[38:41], v[200:203], v[176:179], v[38:41]
	v_mfma_f32_16x16x32_bf16 v[30:33], v[208:211], v[176:179], v[30:33]
	v_mfma_f32_16x16x32_bf16 v[22:25], v[200:203], v[184:187], v[22:25]
	v_mfma_f32_16x16x32_bf16 v[14:17], v[208:211], v[184:187], v[14:17]
	v_mfma_f32_16x16x32_bf16 v[6:9], v[200:203], v[192:195], v[6:9]
	v_mfma_f32_16x16x32_bf16 v[2:5], v[208:211], v[192:195], v[2:5]
	v_mfma_f32_16x16x32_bf16 v[54:57], v[204:207], v[172:175], v[54:57]
	v_mfma_f32_16x16x32_bf16 v[46:49], v[212:215], v[172:175], v[46:49]
	v_mfma_f32_16x16x32_bf16 v[38:41], v[204:207], v[180:183], v[38:41]
	v_mfma_f32_16x16x32_bf16 v[30:33], v[212:215], v[180:183], v[30:33]
	v_mfma_f32_16x16x32_bf16 v[22:25], v[204:207], v[188:191], v[22:25]
	v_mfma_f32_16x16x32_bf16 v[14:17], v[212:215], v[188:191], v[14:17]
	v_mfma_f32_16x16x32_bf16 v[6:9], v[204:207], v[196:199], v[6:9]
	v_mfma_f32_16x16x32_bf16 v[2:5], v[212:215], v[196:199], v[2:5]
	s_setprio 0
	s_add_i32 s67, 0, 0x18000
	v_add_u32_e32 v142, s67, v167
	s_barrier
	ds_read_b128 v[130:133], v142
	ds_read_b128 v[134:137], v142 offset:1024
	ds_read_b128 v[138:141], v142 offset:2048
	ds_read_b128 v[142:145], v142 offset:3072
	s_add_u32 s0, s42, 0x40000
	s_addc_u32 s1, s43, 0
	s_mov_b32 m0, s10
	v_lshl_add_u64 v[200:201], s[0:1], 0, v[158:159]
	ds_read_b128 v[146:149], v169 offset:32768
	ds_read_b128 v[172:175], v169 offset:33792
	ds_read_b128 v[176:179], v169 offset:34816
	ds_read_b128 v[180:183], v169 offset:35840
	ds_read_b128 v[184:187], v169 offset:36864
	ds_read_b128 v[188:191], v169 offset:37888
	ds_read_b128 v[192:195], v169 offset:38912
	ds_read_b128 v[196:199], v169 offset:39936
	global_load_lds_dwordx4 v[200:201], off
	v_lshl_add_u64 v[200:201], s[0:1], 0, v[154:155]
	s_mov_b32 m0, s11
	s_nop 0
	global_load_lds_dwordx4 v[200:201], off
	s_waitcnt lgkmcnt(8)
	s_waitcnt vmcnt(10)
	s_barrier
	s_waitcnt lgkmcnt(0)
	s_setprio 1
	s_waitcnt lgkmcnt(0)
	v_mfma_f32_16x16x32_bf16 v[126:129], v[130:133], v[146:149], v[126:129]
	v_mfma_f32_16x16x32_bf16 v[122:125], v[138:141], v[146:149], v[122:125]
	v_mfma_f32_16x16x32_bf16 v[118:121], v[130:133], v[176:179], v[118:121]
	v_mfma_f32_16x16x32_bf16 v[110:113], v[138:141], v[176:179], v[110:113]
	v_mfma_f32_16x16x32_bf16 v[98:101], v[130:133], v[184:187], v[98:101]
	v_mfma_f32_16x16x32_bf16 v[90:93], v[138:141], v[184:187], v[90:93]
	v_mfma_f32_16x16x32_bf16 v[82:85], v[130:133], v[192:195], v[82:85]
	v_mfma_f32_16x16x32_bf16 v[74:77], v[138:141], v[192:195], v[74:77]
	v_mfma_f32_16x16x32_bf16 v[126:129], v[134:137], v[172:175], v[126:129]
	v_mfma_f32_16x16x32_bf16 v[122:125], v[142:145], v[172:175], v[122:125]
	v_mfma_f32_16x16x32_bf16 v[118:121], v[134:137], v[180:183], v[118:121]
	v_mfma_f32_16x16x32_bf16 v[110:113], v[142:145], v[180:183], v[110:113]
	v_mfma_f32_16x16x32_bf16 v[98:101], v[134:137], v[188:191], v[98:101]
	v_mfma_f32_16x16x32_bf16 v[90:93], v[142:145], v[188:191], v[90:93]
	v_mfma_f32_16x16x32_bf16 v[82:85], v[134:137], v[196:199], v[82:85]
	v_mfma_f32_16x16x32_bf16 v[74:77], v[142:145], v[196:199], v[74:77]
	s_setprio 0
	s_barrier
	s_add_i32 s42, 0, 0x1c000
	s_add_i32 s0, s67, s7
	v_add_u32_e32 v171, s42, v167
	v_lshl_add_u64 v[164:165], v[164:165], 0, s[28:29]
	s_mov_b32 m0, s0
	ds_read_b128 v[200:203], v171
	ds_read_b128 v[204:207], v171 offset:1024
	ds_read_b128 v[208:211], v171 offset:2048
	ds_read_b128 v[212:215], v171 offset:3072
	global_load_lds_dwordx4 v[164:165], off
	v_lshl_add_u64 v[164:165], v[216:217], 0, s[28:29]
	s_add_i32 m0, s0, 0x2000
	s_nop 0
	global_load_lds_dwordx4 v[164:165], off
	s_waitcnt vmcnt(10)
	s_barrier
	s_waitcnt lgkmcnt(0)
	s_setprio 1
	s_waitcnt lgkmcnt(0)
	v_mfma_f32_16x16x32_bf16 v[114:117], v[200:203], v[146:149], v[114:117]
	v_mfma_f32_16x16x32_bf16 v[106:109], v[208:211], v[146:149], v[106:109]
	v_mfma_f32_16x16x32_bf16 v[102:105], v[200:203], v[176:179], v[102:105]
	v_mfma_f32_16x16x32_bf16 v[94:97], v[208:211], v[176:179], v[94:97]
	v_mfma_f32_16x16x32_bf16 v[86:89], v[200:203], v[184:187], v[86:89]
	v_mfma_f32_16x16x32_bf16 v[78:81], v[208:211], v[184:187], v[78:81]
	v_mfma_f32_16x16x32_bf16 v[70:73], v[200:203], v[192:195], v[70:73]
	v_mfma_f32_16x16x32_bf16 v[66:69], v[208:211], v[192:195], v[66:69]
	v_mfma_f32_16x16x32_bf16 v[114:117], v[204:207], v[172:175], v[114:117]
	v_mfma_f32_16x16x32_bf16 v[106:109], v[212:215], v[172:175], v[106:109]
	v_mfma_f32_16x16x32_bf16 v[102:105], v[204:207], v[180:183], v[102:105]
	v_mfma_f32_16x16x32_bf16 v[94:97], v[212:215], v[180:183], v[94:97]
	v_mfma_f32_16x16x32_bf16 v[86:89], v[204:207], v[188:191], v[86:89]
	v_mfma_f32_16x16x32_bf16 v[78:81], v[212:215], v[188:191], v[78:81]
	v_mfma_f32_16x16x32_bf16 v[70:73], v[204:207], v[196:199], v[70:73]
	v_mfma_f32_16x16x32_bf16 v[66:69], v[212:215], v[196:199], v[66:69]
	s_setprio 0
	s_mov_b32 m0, s48
	v_lshl_add_u64 v[164:165], v[218:219], 0, s[28:29]
	s_barrier
	ds_read_b128 v[146:149], v169 offset:49152
	ds_read_b128 v[172:175], v169 offset:50176
	ds_read_b128 v[176:179], v169 offset:51200
	ds_read_b128 v[180:183], v169 offset:52224
	ds_read_b128 v[184:187], v169 offset:53248
	ds_read_b128 v[188:191], v169 offset:54272
	ds_read_b128 v[192:195], v169 offset:55296
	ds_read_b128 v[196:199], v169 offset:56320
	global_load_lds_dwordx4 v[164:165], off
	v_lshl_add_u64 v[164:165], v[220:221], 0, s[28:29]
	s_mov_b32 m0, s49
	s_nop 0
	global_load_lds_dwordx4 v[164:165], off
	s_waitcnt vmcnt(10)
	s_barrier
	s_waitcnt lgkmcnt(0)
	s_setprio 1
	s_waitcnt lgkmcnt(0)
	v_mfma_f32_16x16x32_bf16 v[62:65], v[130:133], v[146:149], v[62:65]
	v_mfma_f32_16x16x32_bf16 v[58:61], v[138:141], v[146:149], v[58:61]
	v_mfma_f32_16x16x32_bf16 v[50:53], v[130:133], v[176:179], v[50:53]
	v_mfma_f32_16x16x32_bf16 v[42:45], v[138:141], v[176:179], v[42:45]
	v_mfma_f32_16x16x32_bf16 v[34:37], v[130:133], v[184:187], v[34:37]
	v_mfma_f32_16x16x32_bf16 v[26:29], v[138:141], v[184:187], v[26:29]
	v_mfma_f32_16x16x32_bf16 v[18:21], v[130:133], v[192:195], v[18:21]
	v_mfma_f32_16x16x32_bf16 v[10:13], v[138:141], v[192:195], v[10:13]
	v_mfma_f32_16x16x32_bf16 v[62:65], v[134:137], v[172:175], v[62:65]
	v_mfma_f32_16x16x32_bf16 v[58:61], v[142:145], v[172:175], v[58:61]
	v_mfma_f32_16x16x32_bf16 v[50:53], v[134:137], v[180:183], v[50:53]
	v_mfma_f32_16x16x32_bf16 v[42:45], v[142:145], v[180:183], v[42:45]
	v_mfma_f32_16x16x32_bf16 v[34:37], v[134:137], v[188:191], v[34:37]
	v_mfma_f32_16x16x32_bf16 v[26:29], v[142:145], v[188:191], v[26:29]
	v_mfma_f32_16x16x32_bf16 v[18:21], v[134:137], v[196:199], v[18:21]
	v_mfma_f32_16x16x32_bf16 v[10:13], v[142:145], v[196:199], v[10:13]
	s_setprio 0
	s_barrier
	s_add_u32 s0, s40, 0x40080
	s_addc_u32 s1, s41, 0
	s_add_i32 s40, s42, s7
	v_lshl_add_u64 v[130:131], s[0:1], 0, v[156:157]
	s_mov_b32 m0, s40
	s_nop 0
	global_load_lds_dwordx4 v[130:131], off
	v_lshl_add_u64 v[130:131], s[0:1], 0, v[152:153]
	s_add_i32 m0, s40, 0x2000
	s_nop 0
	global_load_lds_dwordx4 v[130:131], off
	s_waitcnt vmcnt(10)
	s_barrier
	s_setprio 1
	v_mfma_f32_16x16x32_bf16 v[54:57], v[200:203], v[146:149], v[54:57]
	v_mfma_f32_16x16x32_bf16 v[46:49], v[208:211], v[146:149], v[46:49]
	v_mfma_f32_16x16x32_bf16 v[38:41], v[200:203], v[176:179], v[38:41]
	v_mfma_f32_16x16x32_bf16 v[30:33], v[208:211], v[176:179], v[30:33]
	v_mfma_f32_16x16x32_bf16 v[22:25], v[200:203], v[184:187], v[22:25]
	v_mfma_f32_16x16x32_bf16 v[14:17], v[208:211], v[184:187], v[14:17]
	v_mfma_f32_16x16x32_bf16 v[6:9], v[200:203], v[192:195], v[6:9]
	v_mfma_f32_16x16x32_bf16 v[2:5], v[208:211], v[192:195], v[2:5]
	v_mfma_f32_16x16x32_bf16 v[54:57], v[204:207], v[172:175], v[54:57]
	v_mfma_f32_16x16x32_bf16 v[46:49], v[212:215], v[172:175], v[46:49]
	v_mfma_f32_16x16x32_bf16 v[38:41], v[204:207], v[180:183], v[38:41]
	v_mfma_f32_16x16x32_bf16 v[30:33], v[212:215], v[180:183], v[30:33]
	v_mfma_f32_16x16x32_bf16 v[22:25], v[204:207], v[188:191], v[22:25]
	v_mfma_f32_16x16x32_bf16 v[14:17], v[212:215], v[188:191], v[14:17]
	v_mfma_f32_16x16x32_bf16 v[6:9], v[204:207], v[196:199], v[6:9]
	v_mfma_f32_16x16x32_bf16 v[2:5], v[212:215], v[196:199], v[2:5]
	s_setprio 0
	s_add_i32 s66, s66, 2
	s_add_u32 s64, s64, 0x100
	s_addc_u32 s65, s65, 0
	s_add_u32 s38, s38, 0x100
	s_addc_u32 s39, s39, 0
	s_cmp_gt_u32 s66, 13
	s_barrier
	s_cbranch_scc0 .LBB0_1786
	s_lshl_b32 s0, s58, 8
	v_mov_b32_e32 v130, v151
	v_mov_b32_e32 v131, v166
	s_or_b32 s0, s0, s45
	s_mov_b32 s58, s57
	v_lshl_add_u32 v164, v131, 3, s0
	s_lshl_b32 s0, s59, 8
	s_add_i32 s0, s0, s44
	v_add_u32_e32 v171, s0, v130
	v_mov_b32_e32 v130, v171
	v_ashrrev_i32_e32 v165, 31, v164
	v_ashrrev_i32_e32 v131, 31, v130
	v_lshlrev_b64 v[130:131], 10, v[130:131]
	v_lshl_add_u64 v[130:131], v[130:131], 0, v[164:165]
	v_lshlrev_b64 v[184:185], 1, v[130:131]
	v_lshl_add_u64 v[130:131], s[14:15], 0, v[184:185]
	flat_load_dwordx4 v[172:175], v[130:131] nt
	flat_load_dwordx4 v[176:179], v[130:131] offset:256 nt
	v_add_co_u32_e32 v132, vcc, s47, v130
	s_mov_b32 s59, s56
	s_nop 0
	v_addc_co_u32_e32 v133, vcc, 0, v131, vcc
	flat_load_dwordx4 v[180:183], v[132:133] nt
	flat_load_dwordx4 v[146:149], v[132:133] offset:256 nt
	v_add_co_u32_e32 v132, vcc, s31, v130
	s_waitcnt vmcnt(0) lgkmcnt(0)
	v_lshlrev_b32_e32 v186, 16, v172
	v_addc_co_u32_e32 v133, vcc, 0, v131, vcc
	flat_load_dwordx4 v[142:145], v[132:133] nt
	flat_load_dwordx4 v[138:141], v[132:133] offset:256 nt
	v_add_co_u32_e32 v130, vcc, s46, v130
	v_and_b32_e32 v187, 0xffff0000, v172
	s_nop 0
	v_addc_co_u32_e32 v131, vcc, 0, v131, vcc
	flat_load_dwordx4 v[134:137], v[130:131] nt
	s_nop 0
	flat_load_dwordx4 v[130:133], v[130:131] offset:256 nt
	v_lshlrev_b32_e32 v172, 16, v173
	v_and_b32_e32 v173, 0xffff0000, v173
	v_lshlrev_b32_e32 v188, 16, v174
	v_and_b32_e32 v189, 0xffff0000, v174
	v_lshlrev_b32_e32 v174, 16, v175
	v_and_b32_e32 v175, 0xffff0000, v175
	v_pk_fma_f32 v[128:129], v[172:173], s[30:31], v[128:129] op_sel_hi:[1,0,1]
	v_pk_fma_f32 v[126:127], v[186:187], s[30:31], v[126:127] op_sel_hi:[1,0,1]
	v_pk_fma_f32 v[172:173], v[174:175], s[30:31], v[124:125] op_sel_hi:[1,0,1]
	v_pk_fma_f32 v[122:123], v[188:189], s[30:31], v[122:123] op_sel_hi:[1,0,1]
	v_cvt_pk_bf16_f32 v124, v126, v127
	v_cvt_pk_bf16_f32 v125, v128, v129
	v_cvt_pk_bf16_f32 v126, v122, v123
	v_cvt_pk_bf16_f32 v127, v172, v173
	v_lshl_add_u64 v[122:123], s[20:21], 0, v[184:185]
	flat_store_dwordx4 v[122:123], v[124:127]
	v_lshlrev_b32_e32 v128, 16, v178
	v_and_b32_e32 v129, 0xffff0000, v178
	v_lshlrev_b32_e32 v124, 16, v176
	v_and_b32_e32 v125, 0xffff0000, v176
	v_lshlrev_b32_e32 v126, 16, v177
	v_and_b32_e32 v127, 0xffff0000, v177
	v_lshlrev_b32_e32 v172, 16, v179
	v_and_b32_e32 v173, 0xffff0000, v179
	v_pk_fma_f32 v[116:117], v[126:127], s[30:31], v[116:117] op_sel_hi:[1,0,1]
	v_pk_fma_f32 v[114:115], v[124:125], s[30:31], v[114:115] op_sel_hi:[1,0,1]
	v_pk_fma_f32 v[124:125], v[172:173], s[30:31], v[108:109] op_sel_hi:[1,0,1]
	v_pk_fma_f32 v[108:109], v[128:129], s[30:31], v[106:107] op_sel_hi:[1,0,1]
	v_cvt_pk_bf16_f32 v106, v114, v115
	v_cvt_pk_bf16_f32 v107, v116, v117
	v_cvt_pk_bf16_f32 v108, v108, v109
	v_cvt_pk_bf16_f32 v109, v124, v125
	flat_store_dwordx4 v[122:123], v[106:109] offset:256
	v_lshlrev_b32_e32 v114, 16, v182
	v_and_b32_e32 v115, 0xffff0000, v182
	v_lshlrev_b32_e32 v106, 16, v180
	v_and_b32_e32 v107, 0xffff0000, v180
	v_lshlrev_b32_e32 v108, 16, v181
	v_and_b32_e32 v109, 0xffff0000, v181
	v_lshlrev_b32_e32 v116, 16, v183
	v_and_b32_e32 v117, 0xffff0000, v183
	v_pk_fma_f32 v[108:109], v[108:109], s[30:31], v[120:121] op_sel_hi:[1,0,1]
	v_pk_fma_f32 v[106:107], v[106:107], s[30:31], v[118:119] op_sel_hi:[1,0,1]
	v_pk_fma_f32 v[110:111], v[114:115], s[30:31], v[110:111] op_sel_hi:[1,0,1]
	v_pk_fma_f32 v[112:113], v[116:117], s[30:31], v[112:113] op_sel_hi:[1,0,1]
	v_cvt_pk_bf16_f32 v106, v106, v107
	v_cvt_pk_bf16_f32 v107, v108, v109
	v_cvt_pk_bf16_f32 v108, v110, v111
	v_add_co_u32_e32 v110, vcc, s47, v122
	v_cvt_pk_bf16_f32 v109, v112, v113
	s_nop 0
	v_addc_co_u32_e32 v111, vcc, 0, v123, vcc
	flat_store_dwordx4 v[110:111], v[106:109]
	v_lshlrev_b32_e32 v112, 16, v148
	v_and_b32_e32 v113, 0xffff0000, v148
	v_lshlrev_b32_e32 v106, 16, v146
	v_and_b32_e32 v107, 0xffff0000, v146
	v_lshlrev_b32_e32 v108, 16, v147
	v_and_b32_e32 v109, 0xffff0000, v147
	v_lshlrev_b32_e32 v114, 16, v149
	v_and_b32_e32 v115, 0xffff0000, v149
	v_pk_fma_f32 v[104:105], v[108:109], s[30:31], v[104:105] op_sel_hi:[1,0,1]
	v_pk_fma_f32 v[102:103], v[106:107], s[30:31], v[102:103] op_sel_hi:[1,0,1]
	v_pk_fma_f32 v[106:107], v[114:115], s[30:31], v[96:97] op_sel_hi:[1,0,1]
	v_pk_fma_f32 v[96:97], v[112:113], s[30:31], v[94:95] op_sel_hi:[1,0,1]
	v_cvt_pk_bf16_f32 v94, v102, v103
	v_cvt_pk_bf16_f32 v95, v104, v105
	v_cvt_pk_bf16_f32 v96, v96, v97
	v_cvt_pk_bf16_f32 v97, v106, v107
	flat_store_dwordx4 v[110:111], v[94:97] offset:256
	s_waitcnt vmcnt(0) lgkmcnt(0)
	v_lshlrev_b32_e32 v102, 16, v144
	v_lshlrev_b32_e32 v94, 16, v142
	v_and_b32_e32 v95, 0xffff0000, v142
	v_lshlrev_b32_e32 v96, 16, v143
	v_and_b32_e32 v97, 0xffff0000, v143
	v_and_b32_e32 v103, 0xffff0000, v144
	v_lshlrev_b32_e32 v104, 16, v145
	v_and_b32_e32 v105, 0xffff0000, v145
	v_pk_fma_f32 v[94:95], v[94:95], s[30:31], v[98:99] op_sel_hi:[1,0,1]
	v_pk_fma_f32 v[96:97], v[96:97], s[30:31], v[100:101] op_sel_hi:[1,0,1]
	v_pk_fma_f32 v[98:99], v[104:105], s[30:31], v[92:93] op_sel_hi:[1,0,1]
	v_pk_fma_f32 v[92:93], v[102:103], s[30:31], v[90:91] op_sel_hi:[1,0,1]
	v_cvt_pk_bf16_f32 v90, v94, v95
	v_add_co_u32_e32 v94, vcc, s31, v122
	v_cvt_pk_bf16_f32 v91, v96, v97
	v_cvt_pk_bf16_f32 v92, v92, v93
	v_cvt_pk_bf16_f32 v93, v98, v99
	v_addc_co_u32_e32 v95, vcc, 0, v123, vcc
	flat_store_dwordx4 v[94:95], v[90:93]
	v_lshlrev_b32_e32 v96, 16, v140
	v_and_b32_e32 v97, 0xffff0000, v140
	v_lshlrev_b32_e32 v90, 16, v138
	v_and_b32_e32 v91, 0xffff0000, v138
	v_lshlrev_b32_e32 v92, 16, v139
	v_and_b32_e32 v93, 0xffff0000, v139
	v_lshlrev_b32_e32 v98, 16, v141
	v_and_b32_e32 v99, 0xffff0000, v141
	v_pk_fma_f32 v[88:89], v[92:93], s[30:31], v[88:89] op_sel_hi:[1,0,1]
	v_pk_fma_f32 v[86:87], v[90:91], s[30:31], v[86:87] op_sel_hi:[1,0,1]
	v_pk_fma_f32 v[90:91], v[98:99], s[30:31], v[80:81] op_sel_hi:[1,0,1]
	v_pk_fma_f32 v[80:81], v[96:97], s[30:31], v[78:79] op_sel_hi:[1,0,1]
	v_cvt_pk_bf16_f32 v78, v86, v87
	v_cvt_pk_bf16_f32 v79, v88, v89
	v_cvt_pk_bf16_f32 v80, v80, v81
	v_cvt_pk_bf16_f32 v81, v90, v91
	flat_store_dwordx4 v[94:95], v[78:81] offset:256
	v_lshlrev_b32_e32 v86, 16, v136
	v_and_b32_e32 v87, 0xffff0000, v136
	v_lshlrev_b32_e32 v78, 16, v134
	v_and_b32_e32 v79, 0xffff0000, v134
	v_lshlrev_b32_e32 v80, 16, v135
	v_and_b32_e32 v81, 0xffff0000, v135
	v_lshlrev_b32_e32 v88, 16, v137
	v_and_b32_e32 v89, 0xffff0000, v137
	v_pk_fma_f32 v[78:79], v[78:79], s[30:31], v[82:83] op_sel_hi:[1,0,1]
	v_pk_fma_f32 v[80:81], v[80:81], s[30:31], v[84:85] op_sel_hi:[1,0,1]
	v_pk_fma_f32 v[82:83], v[88:89], s[30:31], v[76:77] op_sel_hi:[1,0,1]
	v_pk_fma_f32 v[76:77], v[86:87], s[30:31], v[74:75] op_sel_hi:[1,0,1]
	v_cvt_pk_bf16_f32 v74, v78, v79
	v_add_co_u32_e32 v78, vcc, s46, v122
	v_cvt_pk_bf16_f32 v75, v80, v81
	v_cvt_pk_bf16_f32 v76, v76, v77
	v_cvt_pk_bf16_f32 v77, v82, v83
	v_addc_co_u32_e32 v79, vcc, 0, v123, vcc
	flat_store_dwordx4 v[78:79], v[74:77]
	v_lshlrev_b32_e32 v80, 16, v132
	v_and_b32_e32 v81, 0xffff0000, v132
	v_lshlrev_b32_e32 v74, 16, v130
	v_and_b32_e32 v75, 0xffff0000, v130
	v_lshlrev_b32_e32 v76, 16, v131
	v_and_b32_e32 v77, 0xffff0000, v131
	v_lshlrev_b32_e32 v82, 16, v133
	v_and_b32_e32 v83, 0xffff0000, v133
	v_pk_fma_f32 v[72:73], v[76:77], s[30:31], v[72:73] op_sel_hi:[1,0,1]
	v_pk_fma_f32 v[70:71], v[74:75], s[30:31], v[70:71] op_sel_hi:[1,0,1]
	v_pk_fma_f32 v[74:75], v[82:83], s[30:31], v[68:69] op_sel_hi:[1,0,1]
	v_pk_fma_f32 v[68:69], v[80:81], s[30:31], v[66:67] op_sel_hi:[1,0,1]
	v_cvt_pk_bf16_f32 v66, v70, v71
	v_cvt_pk_bf16_f32 v67, v72, v73
	v_cvt_pk_bf16_f32 v68, v68, v69
	v_cvt_pk_bf16_f32 v69, v74, v75
	flat_store_dwordx4 v[78:79], v[66:69] offset:256
	s_nop 1
	v_add_u32_e32 v66, 0x80, v171
	s_nop 0
	v_ashrrev_i32_e32 v67, 31, v66
	v_lshlrev_b64 v[66:67], 10, v[66:67]
	v_lshl_add_u64 v[66:67], v[66:67], 0, v[164:165]
	v_lshlrev_b64 v[98:99], 1, v[66:67]
	v_lshl_add_u64 v[90:91], s[14:15], 0, v[98:99]
	flat_load_dwordx4 v[66:69], v[90:91] nt
	flat_load_dwordx4 v[70:73], v[90:91] offset:256 nt
	v_add_co_u32_e32 v78, vcc, s47, v90
	s_waitcnt vmcnt(0) lgkmcnt(0)
	v_lshlrev_b32_e32 v100, 16, v66
	v_addc_co_u32_e32 v79, vcc, 0, v91, vcc
	flat_load_dwordx4 v[74:77], v[78:79] nt
	s_nop 0
	flat_load_dwordx4 v[78:81], v[78:79] offset:256 nt
	v_add_co_u32_e32 v86, vcc, s31, v90
	v_and_b32_e32 v101, 0xffff0000, v66
	s_nop 0
	v_addc_co_u32_e32 v87, vcc, 0, v91, vcc
	flat_load_dwordx4 v[82:85], v[86:87] nt
	s_nop 0
	flat_load_dwordx4 v[86:89], v[86:87] offset:256 nt
	v_add_co_u32_e32 v94, vcc, s46, v90
	v_lshlrev_b32_e32 v66, 16, v67
	s_nop 0
	v_addc_co_u32_e32 v95, vcc, 0, v91, vcc
	flat_load_dwordx4 v[90:93], v[94:95] nt
	s_nop 0
	flat_load_dwordx4 v[94:97], v[94:95] offset:256 nt
	v_and_b32_e32 v67, 0xffff0000, v67
	v_lshlrev_b32_e32 v102, 16, v68
	v_and_b32_e32 v103, 0xffff0000, v68
	v_lshlrev_b32_e32 v68, 16, v69
	v_and_b32_e32 v69, 0xffff0000, v69
	v_pk_fma_f32 v[64:65], v[66:67], s[30:31], v[64:65] op_sel_hi:[1,0,1]
	v_pk_fma_f32 v[62:63], v[100:101], s[30:31], v[62:63] op_sel_hi:[1,0,1]
	v_pk_fma_f32 v[66:67], v[68:69], s[30:31], v[60:61] op_sel_hi:[1,0,1]
	v_pk_fma_f32 v[60:61], v[102:103], s[30:31], v[58:59] op_sel_hi:[1,0,1]
	v_cvt_pk_bf16_f32 v58, v62, v63
	v_cvt_pk_bf16_f32 v59, v64, v65
	v_cvt_pk_bf16_f32 v60, v60, v61
	v_cvt_pk_bf16_f32 v61, v66, v67
	v_lshl_add_u64 v[62:63], s[20:21], 0, v[98:99]
	flat_store_dwordx4 v[62:63], v[58:61]
	v_lshlrev_b32_e32 v64, 16, v72
	v_and_b32_e32 v65, 0xffff0000, v72
	v_lshlrev_b32_e32 v58, 16, v70
	v_and_b32_e32 v59, 0xffff0000, v70
	v_lshlrev_b32_e32 v60, 16, v71
	v_and_b32_e32 v61, 0xffff0000, v71
	v_lshlrev_b32_e32 v66, 16, v73
	v_and_b32_e32 v67, 0xffff0000, v73
	v_pk_fma_f32 v[56:57], v[60:61], s[30:31], v[56:57] op_sel_hi:[1,0,1]
	v_pk_fma_f32 v[54:55], v[58:59], s[30:31], v[54:55] op_sel_hi:[1,0,1]
	v_pk_fma_f32 v[58:59], v[66:67], s[30:31], v[48:49] op_sel_hi:[1,0,1]
	v_pk_fma_f32 v[48:49], v[64:65], s[30:31], v[46:47] op_sel_hi:[1,0,1]
	v_cvt_pk_bf16_f32 v46, v54, v55
	v_cvt_pk_bf16_f32 v47, v56, v57
	v_cvt_pk_bf16_f32 v48, v48, v49
	v_cvt_pk_bf16_f32 v49, v58, v59
	flat_store_dwordx4 v[62:63], v[46:49] offset:256
	s_waitcnt vmcnt(0) lgkmcnt(0)
	v_lshlrev_b32_e32 v54, 16, v76
	v_lshlrev_b32_e32 v46, 16, v74
	v_and_b32_e32 v47, 0xffff0000, v74
	v_lshlrev_b32_e32 v48, 16, v75
	v_and_b32_e32 v49, 0xffff0000, v75
	v_and_b32_e32 v55, 0xffff0000, v76
	v_lshlrev_b32_e32 v56, 16, v77
	v_and_b32_e32 v57, 0xffff0000, v77
	v_pk_fma_f32 v[46:47], v[46:47], s[30:31], v[50:51] op_sel_hi:[1,0,1]
	v_pk_fma_f32 v[48:49], v[48:49], s[30:31], v[52:53] op_sel_hi:[1,0,1]
	v_pk_fma_f32 v[50:51], v[56:57], s[30:31], v[44:45] op_sel_hi:[1,0,1]
	v_pk_fma_f32 v[44:45], v[54:55], s[30:31], v[42:43] op_sel_hi:[1,0,1]
	v_cvt_pk_bf16_f32 v42, v46, v47
	v_add_co_u32_e32 v46, vcc, s47, v62
	v_cvt_pk_bf16_f32 v43, v48, v49
	v_cvt_pk_bf16_f32 v44, v44, v45
	v_cvt_pk_bf16_f32 v45, v50, v51
	v_addc_co_u32_e32 v47, vcc, 0, v63, vcc
	flat_store_dwordx4 v[46:47], v[42:45]
	v_lshlrev_b32_e32 v48, 16, v80
	v_and_b32_e32 v49, 0xffff0000, v80
	v_lshlrev_b32_e32 v42, 16, v78
	v_and_b32_e32 v43, 0xffff0000, v78
	v_lshlrev_b32_e32 v44, 16, v79
	v_and_b32_e32 v45, 0xffff0000, v79
	v_lshlrev_b32_e32 v50, 16, v81
	v_and_b32_e32 v51, 0xffff0000, v81
	v_pk_fma_f32 v[40:41], v[44:45], s[30:31], v[40:41] op_sel_hi:[1,0,1]
	v_pk_fma_f32 v[38:39], v[42:43], s[30:31], v[38:39] op_sel_hi:[1,0,1]
	v_pk_fma_f32 v[42:43], v[50:51], s[30:31], v[32:33] op_sel_hi:[1,0,1]
	v_pk_fma_f32 v[32:33], v[48:49], s[30:31], v[30:31] op_sel_hi:[1,0,1]
	v_cvt_pk_bf16_f32 v30, v38, v39
	v_cvt_pk_bf16_f32 v31, v40, v41
	v_cvt_pk_bf16_f32 v32, v32, v33
	v_cvt_pk_bf16_f32 v33, v42, v43
	flat_store_dwordx4 v[46:47], v[30:33] offset:256
	v_lshlrev_b32_e32 v38, 16, v84
	v_and_b32_e32 v39, 0xffff0000, v84
	v_lshlrev_b32_e32 v30, 16, v82
	v_and_b32_e32 v31, 0xffff0000, v82
	v_lshlrev_b32_e32 v32, 16, v83
	v_and_b32_e32 v33, 0xffff0000, v83
	v_lshlrev_b32_e32 v40, 16, v85
	v_and_b32_e32 v41, 0xffff0000, v85
	v_pk_fma_f32 v[30:31], v[30:31], s[30:31], v[34:35] op_sel_hi:[1,0,1]
	v_pk_fma_f32 v[32:33], v[32:33], s[30:31], v[36:37] op_sel_hi:[1,0,1]
	v_pk_fma_f32 v[34:35], v[40:41], s[30:31], v[28:29] op_sel_hi:[1,0,1]
	v_pk_fma_f32 v[28:29], v[38:39], s[30:31], v[26:27] op_sel_hi:[1,0,1]
	v_cvt_pk_bf16_f32 v26, v30, v31
	v_add_co_u32_e32 v30, vcc, s31, v62
	v_cvt_pk_bf16_f32 v27, v32, v33
	v_cvt_pk_bf16_f32 v28, v28, v29
	v_cvt_pk_bf16_f32 v29, v34, v35
	v_addc_co_u32_e32 v31, vcc, 0, v63, vcc
	flat_store_dwordx4 v[30:31], v[26:29]
	v_lshlrev_b32_e32 v32, 16, v88
	v_and_b32_e32 v33, 0xffff0000, v88
	v_lshlrev_b32_e32 v26, 16, v86
	v_and_b32_e32 v27, 0xffff0000, v86
	v_lshlrev_b32_e32 v28, 16, v87
	v_and_b32_e32 v29, 0xffff0000, v87
	v_lshlrev_b32_e32 v34, 16, v89
	v_and_b32_e32 v35, 0xffff0000, v89
	v_pk_fma_f32 v[24:25], v[28:29], s[30:31], v[24:25] op_sel_hi:[1,0,1]
	v_pk_fma_f32 v[22:23], v[26:27], s[30:31], v[22:23] op_sel_hi:[1,0,1]
	v_pk_fma_f32 v[26:27], v[34:35], s[30:31], v[16:17] op_sel_hi:[1,0,1]
	v_pk_fma_f32 v[16:17], v[32:33], s[30:31], v[14:15] op_sel_hi:[1,0,1]
	v_cvt_pk_bf16_f32 v14, v22, v23
	v_cvt_pk_bf16_f32 v15, v24, v25
	v_cvt_pk_bf16_f32 v16, v16, v17
	v_cvt_pk_bf16_f32 v17, v26, v27
	flat_store_dwordx4 v[30:31], v[14:17] offset:256
	v_lshlrev_b32_e32 v22, 16, v92
	v_and_b32_e32 v23, 0xffff0000, v92
	v_lshlrev_b32_e32 v14, 16, v90
	v_and_b32_e32 v15, 0xffff0000, v90
	v_lshlrev_b32_e32 v16, 16, v91
	v_and_b32_e32 v17, 0xffff0000, v91
	v_lshlrev_b32_e32 v24, 16, v93
	v_and_b32_e32 v25, 0xffff0000, v93
	v_pk_fma_f32 v[14:15], v[14:15], s[30:31], v[18:19] op_sel_hi:[1,0,1]
	v_pk_fma_f32 v[16:17], v[16:17], s[30:31], v[20:21] op_sel_hi:[1,0,1]
	v_pk_fma_f32 v[18:19], v[24:25], s[30:31], v[12:13] op_sel_hi:[1,0,1]
	v_pk_fma_f32 v[12:13], v[22:23], s[30:31], v[10:11] op_sel_hi:[1,0,1]
	v_cvt_pk_bf16_f32 v10, v14, v15
	v_add_co_u32_e32 v14, vcc, s46, v62
	v_cvt_pk_bf16_f32 v11, v16, v17
	v_cvt_pk_bf16_f32 v12, v12, v13
	v_cvt_pk_bf16_f32 v13, v18, v19
	v_addc_co_u32_e32 v15, vcc, 0, v63, vcc
	flat_store_dwordx4 v[14:15], v[10:13]
	v_lshlrev_b32_e32 v16, 16, v96
	v_and_b32_e32 v17, 0xffff0000, v96
	v_lshlrev_b32_e32 v10, 16, v94
	v_and_b32_e32 v11, 0xffff0000, v94
	v_lshlrev_b32_e32 v12, 16, v95
	v_and_b32_e32 v13, 0xffff0000, v95
	v_lshlrev_b32_e32 v18, 16, v97
	v_and_b32_e32 v19, 0xffff0000, v97
	v_pk_fma_f32 v[8:9], v[12:13], s[30:31], v[8:9] op_sel_hi:[1,0,1]
	v_pk_fma_f32 v[6:7], v[10:11], s[30:31], v[6:7] op_sel_hi:[1,0,1]
	v_pk_fma_f32 v[10:11], v[18:19], s[30:31], v[4:5] op_sel_hi:[1,0,1]
	v_pk_fma_f32 v[4:5], v[16:17], s[30:31], v[2:3] op_sel_hi:[1,0,1]
	v_cvt_pk_bf16_f32 v2, v6, v7
	v_cvt_pk_bf16_f32 v3, v8, v9
	v_cvt_pk_bf16_f32 v4, v4, v5
	v_cvt_pk_bf16_f32 v5, v10, v11
	s_and_b64 vcc, exec, s[34:35]
	flat_store_dwordx4 v[14:15], v[2:5] offset:256
	s_cbranch_vccz .LBB0_1785
	s_waitcnt vmcnt(0)
	s_cmpk_gt_u32 s4, 0xff
	s_cbranch_scc1 .LBB0_1790
	s_barrier

.LBB0_1807:
	s_or_b64 exec, exec, s[22:23]
	s_lshl_b32 s0, s7, 8
	s_add_i32 s0, s0, s97
	s_ashr_i32 s1, s0, 31
	s_lshl_b64 s[8:9], s[0:1], 11
	v_lshl_add_u64 v[38:39], v[54:55], 0, s[8:9]
	v_add_co_u32_e32 v44, vcc, 0x4000, v38
	s_waitcnt lgkmcnt(0)
	s_barrier
	global_load_dwordx4 v[2:5], v[50:51], off
	global_load_dwordx4 v[6:9], v[50:51], off offset:1024
	global_load_dwordx4 v[10:13], v[52:53], off
	global_load_dwordx4 v[14:17], v[52:53], off offset:1024
	global_load_dwordx4 v[18:21], v[50:51], off offset:2048
	global_load_dwordx4 v[22:25], v[50:51], off offset:3072
	global_load_dwordx4 v[26:29], v[52:53], off offset:2048
	global_load_dwordx4 v[30:33], v[52:53], off offset:3072
	v_lshl_add_u64 v[42:43], v[38:39], 0, s[28:29]
	v_addc_co_u32_e32 v45, vcc, 0, v39, vcc
	flat_load_dwordx2 v[36:37], v[38:39] nt
	flat_load_dwordx2 v[34:35], v[38:39] offset:512 nt
	flat_load_dwordx2 v[40:41], v[38:39] offset:1024 nt
	s_nop 0
	flat_load_dwordx2 v[38:39], v[38:39] offset:1536 nt
	s_nop 0
	flat_load_dwordx2 v[60:61], v[44:45] nt
	flat_load_dwordx2 v[62:63], v[42:43] offset:512 nt
	flat_load_dwordx2 v[64:65], v[42:43] offset:1024 nt
	flat_load_dwordx2 v[66:67], v[42:43] offset:1536 nt
	s_mov_b32 s8, 0
	s_add_i32 s9, s0, 16
	s_mov_b32 s10, 0
	s_branch .LBB0_1810

.LBB0_1810:
	s_waitcnt vmcnt(0) lgkmcnt(0)
	v_lshlrev_b32_e32 v77, 16, v37
	v_lshlrev_b32_e32 v76, 16, v36
	v_and_b32_e32 v37, 0xffff0000, v37
	v_and_b32_e32 v36, 0xffff0000, v36
	v_pk_add_f32 v[68:69], v[76:77], v[36:37]
	v_lshlrev_b32_e32 v87, 16, v35
	v_lshlrev_b32_e32 v86, 16, v34
	v_and_b32_e32 v35, 0xffff0000, v35
	v_and_b32_e32 v34, 0xffff0000, v34
	v_lshlrev_b32_e32 v46, 16, v39
	v_and_b32_e32 v48, 0xffff0000, v39
	v_add_f32_e32 v39, v68, v69
	v_pk_add_f32 v[68:69], v[86:87], v[34:35]
	v_lshlrev_b32_e32 v42, 16, v40
	v_and_b32_e32 v43, 0xffff0000, v40
	v_lshlrev_b32_e32 v40, 16, v41
	v_and_b32_e32 v41, 0xffff0000, v41
	v_pk_add_f32 v[68:69], v[68:69], v[68:69] op_sel_hi:[0,1]
	v_lshlrev_b32_e32 v44, 16, v38
	v_and_b32_e32 v38, 0xffff0000, v38
	v_add_f32_e32 v49, 0, v39
	v_add_f32_e32 v45, v42, v43
	v_add_f32_e32 v39, v40, v41
	v_mov_b32_e32 v47, v69
	v_pk_add_f32 v[70:71], v[44:45], v[38:39]
	v_pk_add_f32 v[68:69], v[46:47], v[48:49]
	s_min_u32 s0, s10, 29
	v_pk_add_f32 v[68:69], v[70:71], v[68:69]
	s_lshl_b32 s0, s0, 3
	v_add_f32_e32 v39, v68, v69
	s_add_i32 s22, s9, s0
	s_nop 0
	v_add_f32_dpp v39, v39, v39 quad_perm:[1,0,3,2] row_mask:0xf bank_mask:0xf bound_ctrl:1
	s_nop 1
	v_add_f32_dpp v39, v39, v39 quad_perm:[2,3,0,1] row_mask:0xf bank_mask:0xf bound_ctrl:1
	s_nop 1
	v_add_f32_dpp v39, v39, v39 row_half_mirror row_mask:0xf bank_mask:0xf bound_ctrl:1
	s_nop 1
	v_add_f32_dpp v39, v39, v39 row_mirror row_mask:0xf bank_mask:0xf bound_ctrl:1
	s_nop 0
	v_readlane_b32 s11, v39, 16
	v_readlane_b32 s23, v39, 48
	v_readlane_b32 s0, v39, 0
	v_readlane_b32 s1, v39, 32
	v_mov_b32_e32 v68, s11
	v_mov_b32_e32 v69, s23
	v_pk_add_f32 v[68:69], s[0:1], v[68:69]
	s_nop 0
	v_add_f32_e32 v39, v68, v69
	v_fmac_f32_e32 v36, 0xba800000, v39
	v_fmac_f32_e32 v37, 0xba800000, v39
	v_fmac_f32_e32 v77, 0xba800000, v39
	v_fmac_f32_e32 v76, 0xba800000, v39
	v_mov_b32_e32 v88, v77
	v_mov_b32_e32 v89, v37
	v_mov_b32_e32 v77, v36
	v_fmac_f32_e32 v34, 0xba800000, v39
	v_fmac_f32_e32 v35, 0xba800000, v39
	v_fmac_f32_e32 v87, 0xba800000, v39
	v_pk_mul_f32 v[68:69], v[88:89], v[88:89]
	v_pk_mul_f32 v[36:37], v[76:77], v[76:77]
	v_fmac_f32_e32 v86, 0xba800000, v39
	v_mov_b32_e32 v90, v87
	v_mov_b32_e32 v91, v35
	v_mov_b32_e32 v87, v34
	v_pk_mov_b32 v[70:71], v[36:37], v[68:69] op_sel:[1,0]
	v_mov_b32_e32 v37, v69
	v_pk_mul_f32 v[68:69], v[90:91], v[90:91]
	v_pk_mul_f32 v[34:35], v[86:87], v[86:87]
	v_pk_add_f32 v[36:37], v[70:71], v[36:37]
	v_pk_mov_b32 v[70:71], v[34:35], v[68:69] op_sel:[1,0]
	v_mov_b32_e32 v35, v69
	v_pk_add_f32 v[34:35], v[70:71], v[34:35]
	v_fmac_f32_e32 v42, 0xba800000, v39
	v_pk_add_f32 v[34:35], v[34:35], v[34:35] op_sel_hi:[0,1]
	v_fmac_f32_e32 v43, 0xba800000, v39
	v_fmac_f32_e32 v40, 0xba800000, v39
	v_mul_f32_e32 v34, v42, v42
	v_fmac_f32_e32 v41, 0xba800000, v39
	v_pk_fma_f32 v[68:69], v[42:43], v[42:43], v[34:35] op_sel_hi:[1,1,0]
	v_mul_f32_e32 v34, v40, v40
	v_pk_add_f32 v[36:37], v[36:37], v[36:37] op_sel_hi:[0,1]
	v_pk_fma_f32 v[70:71], v[40:41], v[40:41], v[34:35] op_sel_hi:[1,1,0]
	v_fmac_f32_e32 v48, 0xba800000, v39
	v_fmac_f32_e32 v46, 0xba800000, v39
	v_fmac_f32_e32 v38, 0xba800000, v39
	v_fmac_f32_e32 v44, 0xba800000, v39
	v_mul_f32_e32 v68, v44, v44
	v_mul_f32_e32 v70, v38, v38
	v_mul_f32_e32 v36, v46, v46
	v_mul_f32_e32 v34, v48, v48
	v_pk_add_f32 v[68:69], v[68:69], v[70:71]
	v_pk_add_f32 v[34:35], v[36:37], v[34:35]
	v_mov_b32_e32 v47, v48
	v_pk_add_f32 v[34:35], v[68:69], v[34:35]
	s_nop 0
	v_add_f32_e32 v34, v34, v35
	s_nop 1
	v_add_f32_dpp v34, v34, v34 quad_perm:[1,0,3,2] row_mask:0xf bank_mask:0xf bound_ctrl:1
	s_nop 1
	v_add_f32_dpp v34, v34, v34 quad_perm:[2,3,0,1] row_mask:0xf bank_mask:0xf bound_ctrl:1
	s_nop 1
	v_add_f32_dpp v34, v34, v34 row_half_mirror row_mask:0xf bank_mask:0xf bound_ctrl:1
	s_nop 1
	v_add_f32_dpp v34, v34, v34 row_mirror row_mask:0xf bank_mask:0xf bound_ctrl:1
	s_nop 0
	v_readlane_b32 s11, v34, 16
	v_readlane_b32 s23, v34, 48
	v_readlane_b32 s0, v34, 0
	v_readlane_b32 s1, v34, 32
	v_mov_b32_e32 v34, s11
	v_mov_b32_e32 v35, s23
	v_pk_add_f32 v[34:35], s[0:1], v[34:35]
	s_mov_b32 s0, 0xf800000
	v_add_f32_e32 v34, v34, v35
	v_fmamk_f32 v34, v34, 0x3a800000, v83
	s_ashr_i32 s23, s22, 31
	v_mul_f32_e32 v35, 0x4f800000, v34
	v_cmp_gt_f32_e32 vcc, s0, v34
	s_lshl_b64 s[0:1], s[22:23], 11
	s_and_b32 s11, s10, 3
	v_cndmask_b32_e32 v36, v34, v35, vcc
	v_lshl_add_u64 v[34:35], v[54:55], 0, s[0:1]
	flat_load_dwordx2 v[68:69], v[34:35] nt
	flat_load_dwordx2 v[70:71], v[34:35] offset:512 nt
	flat_load_dwordx2 v[72:73], v[34:35] offset:1024 nt
	flat_load_dwordx2 v[74:75], v[34:35] offset:1536 nt
	v_sqrt_f32_e32 v37, v36
	s_mul_i32 s26, s11, 0x810
	s_add_i32 s26, s87, s26
	v_add_u32_e32 v39, -1, v37
	v_fma_f32 v45, -v39, v37, v36
	v_cmp_ge_f32_e64 s[22:23], 0, v45
	v_add_u32_e32 v45, 1, v37
	s_nop 0
	v_cndmask_b32_e64 v39, v37, v39, s[22:23]
	v_fma_f32 v37, -v45, v37, v36
	v_cmp_lt_f32_e64 s[22:23], 0, v37
	s_nop 1
	v_cndmask_b32_e64 v37, v39, v45, s[22:23]
	v_mul_f32_e32 v39, 0x37800000, v37
	v_cndmask_b32_e32 v37, v37, v39, vcc
	v_cmp_class_f32_e32 vcc, v36, v84
	s_add_i32 s22, s4, s8
	s_ashr_i32 s23, s22, 31
	v_cndmask_b32_e32 v36, v37, v36, vcc
	v_div_scale_f32 v37, s[0:1], v36, v36, 1.0
	v_rcp_f32_e32 v39, v37
	s_lshl_b64 s[0:1], s[22:23], 11
	v_fma_f32 v34, -v37, v39, 1.0
	v_fmac_f32_e32 v39, v34, v39
	v_div_scale_f32 v34, vcc, 1.0, v36, 1.0
	v_mul_f32_e32 v35, v34, v39
	v_fma_f32 v45, -v37, v35, v34
	v_fmac_f32_e32 v35, v45, v39
	v_fma_f32 v34, -v37, v35, v34
	v_div_fmas_f32 v34, v34, v39, v35
	v_div_fixup_f32 v34, v34, v36, 1.0
	v_mov_b32_e32 v45, v38
	v_pk_mul_f32 v[36:37], v[76:77], v[34:35] op_sel_hi:[1,0]
	v_pk_mul_f32 v[76:77], v[88:89], v[34:35] op_sel_hi:[1,0]
	v_pk_mul_f32 v[38:39], v[44:45], v[34:35] op_sel_hi:[1,0]
	v_mov_b32_e32 v44, v78
	v_pk_fma_f32 v[76:77], v[4:5], v[76:77], v[12:13]
	v_pk_fma_f32 v[36:37], v[2:3], v[36:37], v[10:11]
	v_pk_mul_f32 v[86:87], v[86:87], v[34:35] op_sel_hi:[1,0]
	v_pk_mul_f32 v[88:89], v[90:91], v[34:35] op_sel_hi:[1,0]
	v_pk_fma_f32 v[86:87], v[6:7], v[86:87], v[14:15]
	v_pk_fma_f32 v[88:89], v[8:9], v[88:89], v[16:17]
	v_pk_mul_f32 v[42:43], v[42:43], v[34:35] op_sel_hi:[1,0]
	v_pk_mul_f32 v[40:41], v[40:41], v[34:35] op_sel_hi:[1,0]
	v_pk_mul_f32 v[34:35], v[46:47], v[34:35] op_sel_hi:[1,0]
	v_lshl_add_u32 v48, v44, 3, s26
	v_cvt_pk_bf16_f32 v44, v36, v37
	v_cvt_pk_bf16_f32 v45, v76, v77
	v_lshl_add_u64 v[46:47], v[56:57], 0, s[0:1]
	v_pk_fma_f32 v[40:41], v[20:21], v[40:41], v[28:29]
	v_pk_fma_f32 v[42:43], v[18:19], v[42:43], v[26:27]
	flat_store_dwordx2 v[46:47], v[44:45]
	ds_write_b64 v48, v[44:45] offset:33024
	v_cvt_pk_bf16_f32 v44, v86, v87
	v_cvt_pk_bf16_f32 v45, v88, v89
	v_pk_fma_f32 v[34:35], v[24:25], v[34:35], v[32:33]
	v_pk_fma_f32 v[38:39], v[22:23], v[38:39], v[30:31]
	flat_store_dwordx2 v[46:47], v[44:45] offset:512
	ds_write_b64 v48, v[44:45] offset:33536
	v_cvt_pk_bf16_f32 v44, v42, v43
	v_cvt_pk_bf16_f32 v45, v40, v41
	flat_store_dwordx2 v[46:47], v[44:45] offset:1024
	ds_write_b64 v48, v[44:45] offset:34048
	v_cvt_pk_bf16_f32 v44, v38, v39
	v_cvt_pk_bf16_f32 v45, v34, v35
	flat_store_dwordx2 v[46:47], v[44:45] offset:1536
	ds_write_b64 v48, v[44:45] offset:34560
	v_med3_f32 v36, v36, s6, v85
	v_med3_f32 v37, v37, s6, v85
	v_mov_b32_e32 v44, 0
	v_cvt_pk_fp8_f32 v44, v36, v37
	v_med3_f32 v36, v76, s6, v85
	v_med3_f32 v37, v77, s6, v85
	v_med3_f32 v45, v86, s6, v85
	v_cvt_pk_fp8_f32 v44, v36, v37 op_sel:[0,0,1]
	v_med3_f32 v46, v87, s6, v85
	v_mov_b32_e32 v47, 0
	v_cvt_pk_fp8_f32 v47, v45, v46
	s_lshl_b64 s[0:1], s[22:23], 10
	v_lshl_add_u64 v[36:37], v[58:59], 0, s[0:1]
	flat_store_dword v[36:37], v44
	v_med3_f32 v44, v88, s6, v85
	v_med3_f32 v45, v89, s6, v85
	v_cvt_pk_fp8_f32 v47, v44, v45 op_sel:[0,0,1]
	v_med3_f32 v42, v42, s6, v85
	v_med3_f32 v43, v43, s6, v85
	v_mov_b32_e32 v44, 0
	v_cvt_pk_fp8_f32 v44, v42, v43
	v_med3_f32 v38, v38, s6, v85
	v_med3_f32 v39, v39, s6, v85
	v_mov_b32_e32 v42, 0
	v_cvt_pk_fp8_f32 v42, v38, v39
	v_med3_f32 v34, v34, s6, v85
	v_med3_f32 v35, v35, s6, v85
	v_med3_f32 v40, v40, s6, v85
	v_med3_f32 v41, v41, s6, v85
	v_cvt_pk_fp8_f32 v42, v34, v35 op_sel:[0,0,1]
	v_cvt_pk_fp8_f32 v44, v40, v41 op_sel:[0,0,1]
	s_cmp_lg_u32 s11, 3
	flat_store_dword v[36:37], v47 offset:256
	flat_store_dword v[36:37], v44 offset:512
	flat_store_dword v[36:37], v42 offset:768
	s_cbranch_scc1 .LBB0_1809
	v_mov_b32_e32 v76, v78
	s_nop 0
	v_and_b32_e32 v34, 3, v76
	v_mul_u32_u24_e32 v34, 0x810, v34
	v_and_b32_e32 v35, -16, v76
	v_add3_u32 v77, s87, v34, v35
	v_and_b32_e32 v34, 15, v76
	v_mul_u32_u24_e32 v34, 0x810, v34
	v_add3_u32 v94, 0, v34, v35
	ds_read_b128 v[34:37], v77 offset:33024
	ds_read_b128 v[38:41], v94
	s_waitcnt lgkmcnt(0)
	v_mfma_f32_16x16x32_bf16 v[34:37], v[34:37], v[38:41], 0
	ds_read_b128 v[38:41], v77 offset:33088
	ds_read_b128 v[42:45], v94 offset:64
	v_cmp_gt_i32_e32 vcc, 16, v76
	s_waitcnt lgkmcnt(0)
	v_mfma_f32_16x16x32_bf16 v[38:41], v[38:41], v[42:45], 0
	ds_read_b128 v[42:45], v77 offset:33152
	ds_read_b128 v[46:49], v94 offset:128
	s_waitcnt lgkmcnt(0)
	v_mfma_f32_16x16x32_bf16 v[42:45], v[42:45], v[46:49], 0
	ds_read_b128 v[46:49], v77 offset:33216
	ds_read_b128 v[86:89], v94 offset:192
	s_waitcnt lgkmcnt(0)
	v_mfma_f32_16x16x32_bf16 v[46:49], v[46:49], v[86:89], 0
	ds_read_b128 v[86:89], v77 offset:33280
	ds_read_b128 v[90:93], v94 offset:256
	s_waitcnt lgkmcnt(0)
	v_mfma_f32_16x16x32_bf16 v[34:37], v[86:89], v[90:93], v[34:37]
	ds_read_b128 v[86:89], v77 offset:33344
	ds_read_b128 v[90:93], v94 offset:320
	s_waitcnt lgkmcnt(0)
	v_mfma_f32_16x16x32_bf16 v[38:41], v[86:89], v[90:93], v[38:41]
	ds_read_b128 v[86:89], v77 offset:33408
	ds_read_b128 v[90:93], v94 offset:384
	s_waitcnt lgkmcnt(0)
	v_mfma_f32_16x16x32_bf16 v[42:45], v[86:89], v[90:93], v[42:45]
	ds_read_b128 v[86:89], v77 offset:33472
	ds_read_b128 v[90:93], v94 offset:448
	s_waitcnt lgkmcnt(0)
	v_mfma_f32_16x16x32_bf16 v[46:49], v[86:89], v[90:93], v[46:49]
	ds_read_b128 v[86:89], v77 offset:33536
	ds_read_b128 v[90:93], v94 offset:512
	s_waitcnt lgkmcnt(0)
	v_mfma_f32_16x16x32_bf16 v[34:37], v[86:89], v[90:93], v[34:37]
	ds_read_b128 v[86:89], v77 offset:33600
	ds_read_b128 v[90:93], v94 offset:576
	s_waitcnt lgkmcnt(0)
	v_mfma_f32_16x16x32_bf16 v[38:41], v[86:89], v[90:93], v[38:41]
	ds_read_b128 v[86:89], v77 offset:33664
	ds_read_b128 v[90:93], v94 offset:640
	s_waitcnt lgkmcnt(0)
	v_mfma_f32_16x16x32_bf16 v[42:45], v[86:89], v[90:93], v[42:45]
	ds_read_b128 v[86:89], v77 offset:33728
	ds_read_b128 v[90:93], v94 offset:704
	s_waitcnt lgkmcnt(0)
	v_mfma_f32_16x16x32_bf16 v[46:49], v[86:89], v[90:93], v[46:49]
	ds_read_b128 v[86:89], v77 offset:33792
	ds_read_b128 v[90:93], v94 offset:768
	s_waitcnt lgkmcnt(0)
	v_mfma_f32_16x16x32_bf16 v[34:37], v[86:89], v[90:93], v[34:37]
	ds_read_b128 v[86:89], v77 offset:33856
	ds_read_b128 v[90:93], v94 offset:832
	s_waitcnt lgkmcnt(0)
	v_mfma_f32_16x16x32_bf16 v[38:41], v[86:89], v[90:93], v[38:41]
	ds_read_b128 v[86:89], v77 offset:33920
	ds_read_b128 v[90:93], v94 offset:896
	s_waitcnt lgkmcnt(0)
	v_mfma_f32_16x16x32_bf16 v[42:45], v[86:89], v[90:93], v[42:45]
	ds_read_b128 v[86:89], v77 offset:33984
	ds_read_b128 v[90:93], v94 offset:960
	s_waitcnt lgkmcnt(0)
	v_mfma_f32_16x16x32_bf16 v[46:49], v[86:89], v[90:93], v[46:49]
	ds_read_b128 v[86:89], v77 offset:34048
	ds_read_b128 v[90:93], v94 offset:1024
	s_waitcnt lgkmcnt(0)
	v_mfma_f32_16x16x32_bf16 v[34:37], v[86:89], v[90:93], v[34:37]
	ds_read_b128 v[86:89], v77 offset:34112
	ds_read_b128 v[90:93], v94 offset:1088
	s_waitcnt lgkmcnt(0)
	v_mfma_f32_16x16x32_bf16 v[38:41], v[86:89], v[90:93], v[38:41]
	ds_read_b128 v[86:89], v77 offset:34176
	ds_read_b128 v[90:93], v94 offset:1152
	s_waitcnt lgkmcnt(0)
	v_mfma_f32_16x16x32_bf16 v[42:45], v[86:89], v[90:93], v[42:45]
	ds_read_b128 v[86:89], v77 offset:34240
	ds_read_b128 v[90:93], v94 offset:1216
	s_waitcnt lgkmcnt(0)
	v_mfma_f32_16x16x32_bf16 v[46:49], v[86:89], v[90:93], v[46:49]
	ds_read_b128 v[86:89], v77 offset:34304
	ds_read_b128 v[90:93], v94 offset:1280
	s_waitcnt lgkmcnt(0)
	v_mfma_f32_16x16x32_bf16 v[34:37], v[86:89], v[90:93], v[34:37]
	ds_read_b128 v[86:89], v77 offset:34368
	ds_read_b128 v[90:93], v94 offset:1344
	s_waitcnt lgkmcnt(0)
	v_mfma_f32_16x16x32_bf16 v[38:41], v[86:89], v[90:93], v[38:41]
	ds_read_b128 v[86:89], v77 offset:34432
	ds_read_b128 v[90:93], v94 offset:1408
	s_waitcnt lgkmcnt(0)
	v_mfma_f32_16x16x32_bf16 v[42:45], v[86:89], v[90:93], v[42:45]
	ds_read_b128 v[86:89], v77 offset:34496
	ds_read_b128 v[90:93], v94 offset:1472
	s_waitcnt lgkmcnt(0)
	v_mfma_f32_16x16x32_bf16 v[46:49], v[86:89], v[90:93], v[46:49]
	ds_read_b128 v[86:89], v77 offset:34560
	ds_read_b128 v[90:93], v94 offset:1536
	s_waitcnt lgkmcnt(0)
	v_mfma_f32_16x16x32_bf16 v[34:37], v[86:89], v[90:93], v[34:37]
	ds_read_b128 v[86:89], v77 offset:34624
	ds_read_b128 v[90:93], v94 offset:1600
	s_waitcnt lgkmcnt(0)
	v_mfma_f32_16x16x32_bf16 v[38:41], v[86:89], v[90:93], v[38:41]
	ds_read_b128 v[86:89], v77 offset:34688
	ds_read_b128 v[90:93], v94 offset:1664
	s_waitcnt lgkmcnt(0)
	v_mfma_f32_16x16x32_bf16 v[42:45], v[86:89], v[90:93], v[42:45]
	ds_read_b128 v[86:89], v77 offset:34752
	ds_read_b128 v[90:93], v94 offset:1728
	s_waitcnt lgkmcnt(0)
	v_mfma_f32_16x16x32_bf16 v[46:49], v[86:89], v[90:93], v[46:49]
	ds_read_b128 v[86:89], v77 offset:34816
	ds_read_b128 v[90:93], v94 offset:1792
	s_waitcnt lgkmcnt(0)
	v_mfma_f32_16x16x32_bf16 v[34:37], v[86:89], v[90:93], v[34:37]
	ds_read_b128 v[86:89], v77 offset:34880
	ds_read_b128 v[90:93], v94 offset:1856
	s_waitcnt lgkmcnt(0)
	v_mfma_f32_16x16x32_bf16 v[38:41], v[86:89], v[90:93], v[38:41]
	ds_read_b128 v[86:89], v77 offset:34944
	ds_read_b128 v[90:93], v94 offset:1920
	s_waitcnt lgkmcnt(0)
	v_mfma_f32_16x16x32_bf16 v[42:45], v[86:89], v[90:93], v[42:45]
	ds_read_b128 v[86:89], v77 offset:35008
	ds_read_b128 v[90:93], v94 offset:1984
	s_nop 1
	v_pk_add_f32 v[34:35], v[34:35], v[38:39]
	v_ashrrev_i32_e32 v77, 31, v76
	s_waitcnt lgkmcnt(0)
	v_mfma_f32_16x16x32_bf16 v[46:49], v[86:89], v[90:93], v[46:49]
	s_nop 7
	v_pk_add_f32 v[38:39], v[42:43], v[46:47]
	s_nop 0
	v_pk_add_f32 v[38:39], v[34:35], v[38:39]
	v_lshlrev_b64 v[34:35], 13, v[76:77]
	v_lshl_add_u64 v[34:35], s[30:31], 0, v[34:35]
	v_mov_b32_dpp v42, v38 quad_perm:[1,0,3,2] row_mask:0xf bank_mask:0xf bound_ctrl:1
	v_max_f32_e32 v42, v42, v42
	v_max_f32_e32 v42, v38, v42
	s_nop 1
	v_mov_b32_dpp v43, v42 quad_perm:[2,3,0,1] row_mask:0xf bank_mask:0xf bound_ctrl:1
	v_max_f32_e32 v43, v43, v43
	v_max_f32_e32 v42, v42, v43
	s_nop 1
	v_mov_b32_dpp v43, v42 row_half_mirror row_mask:0xf bank_mask:0xf bound_ctrl:1
	v_max_f32_e32 v43, v43, v43
	v_max_f32_e32 v42, v42, v43
	s_nop 1
	v_mov_b32_dpp v43, v42 row_mirror row_mask:0xf bank_mask:0xf bound_ctrl:1
	v_max_f32_e32 v43, v43, v43
	v_max_f32_e32 v42, v42, v43
	v_sub_f32_e32 v38, v38, v42
	v_mul_f32_e32 v38, 0x3fb8aa3b, v38
	v_exp_f32_e32 v38, v38
	s_nop 1
	v_add_f32_dpp v42, v38, v38 quad_perm:[1,0,3,2] row_mask:0xf bank_mask:0xf bound_ctrl:1
	s_nop 1
	v_add_f32_dpp v42, v42, v42 quad_perm:[2,3,0,1] row_mask:0xf bank_mask:0xf bound_ctrl:1
	s_nop 1
	v_add_f32_dpp v42, v42, v42 row_half_mirror row_mask:0xf bank_mask:0xf bound_ctrl:1
	s_nop 1
	v_mov_b32_dpp v43, v42 row_mirror row_mask:0xf bank_mask:0xf bound_ctrl:1
	s_and_saveexec_b64 s[34:35], vcc
	s_cbranch_execz .LBB0_1813
	v_add_f32_e32 v42, v42, v43
	v_rcp_f32_e32 v42, v42
	s_sub_i32 s11, s22, 24
	s_ashr_i32 s0, s11, 11
	s_ashr_i32 s1, s0, 31
	s_and_b32 s11, s11, 0x7ff
	s_lshl_b64 s[0:1], s[0:1], 17
	v_mul_f32_e32 v38, v38, v42
	v_lshl_add_u64 v[42:43], v[34:35], 0, s[0:1]
	s_lshl_b32 s26, s11, 2
	v_lshl_add_u64 v[42:43], v[42:43], 0, s[26:27]
	flat_store_dword v[42:43], v38

.LBB0_2166:
	s_or_b64 exec, exec, s[12:13]
	s_waitcnt lgkmcnt(0)
	s_barrier
	s_load_dwordx8 s[16:23], s[84:85], 0xd8
	s_load_dwordx4 s[8:11], s[84:85], 0xf8
	s_load_dwordx2 s[0:1], s[84:85], 0x108
	v_mov_b32_e32 v45, v0
	v_mov_b32_e32 v35, 0
	v_and_b32_e32 v74, 63, v45
	s_waitcnt lgkmcnt(0)
	s_mov_b32 s6, s0
	s_mov_b32 s0, s10
	s_add_u32 s24, s6, 0x3e00000
	s_addc_u32 s25, s1, 0
	v_lshlrev_b32_e32 v34, 4, v74
	v_lshl_add_u64 v[2:3], s[22:23], 0, v[34:35]
	s_mov_b64 s[4:5], 0x5000
	s_movk_i32 s0, 0x5000
	s_add_u32 s22, s6, 0x3900000
	v_lshl_add_u64 v[26:27], v[2:3], 0, s[4:5]
	v_add_co_u32_e32 v2, vcc, s0, v2
	s_addc_u32 s23, s1, 0
	v_lshl_add_u64 v[6:7], s[8:9], 0, v[34:35]
	v_addc_co_u32_e32 v3, vcc, 0, v3, vcc
	s_add_u32 s14, s6, 0xa100000
	s_mov_b32 s7, s1
	v_lshl_add_u64 v[30:31], v[6:7], 0, s[4:5]
	v_add_co_u32_e32 v6, vcc, s0, v6
	s_addc_u32 s15, s1, 0
	v_readlane_b32 s0, v253, 36
	v_readlane_b32 s1, v253, 37
	s_add_u32 s0, s14, s0
	s_addc_u32 s1, s15, s1
	v_readlane_b32 s4, v253, 38
	v_readlane_b32 s5, v253, 39
	s_add_u32 s4, s14, s4
	s_addc_u32 s5, s15, s5
	v_lshlrev_b32_e32 v34, 3, v74
	v_addc_co_u32_e32 v7, vcc, 0, v7, vcc
	v_lshl_add_u64 v[42:43], s[0:1], 0, v[34:35]
	v_lshl_add_u64 v[46:47], s[4:5], 0, v[34:35]
	global_load_dwordx4 v[2:5], v[2:3], off nt
	s_nop 0
	global_load_dwordx4 v[6:9], v[6:7], off nt
	s_nop 0
	global_load_dwordx4 v[10:13], v[26:27], off offset:1024
	global_load_dwordx4 v[14:17], v[30:31], off offset:1024
	global_load_dwordx4 v[18:21], v[26:27], off offset:2048
	global_load_dwordx4 v[22:25], v[30:31], off offset:2048
	s_nop 0
	global_load_dwordx4 v[26:29], v[26:27], off offset:3072
	s_nop 0
	global_load_dwordx4 v[30:33], v[30:31], off offset:3072
	v_cmp_gt_u32_e64 s[12:13], 16, v74
	flat_load_dwordx2 v[62:63], v[42:43] nt
	flat_load_dwordx2 v[36:37], v[46:47] nt
	flat_load_dwordx2 v[64:65], v[42:43] offset:512 nt
	flat_load_dwordx2 v[38:39], v[46:47] offset:512 nt
	flat_load_dwordx2 v[60:61], v[42:43] offset:1024 nt
	flat_load_dwordx2 v[40:41], v[46:47] offset:1024 nt
	flat_load_dwordx2 v[58:59], v[42:43] offset:1536 nt
	s_nop 0
	flat_load_dwordx2 v[42:43], v[46:47] offset:1536 nt
	v_mov_b32_e32 v75, -1
	v_lshlrev_b32_e32 v44, 11, v74
	v_mov_b32_e32 v82, v35
	v_mov_b32_e32 v81, -1
	s_and_saveexec_b64 s[26:27], s[12:13]
	s_cbranch_execz .LBB0_2168
	v_readlane_b32 s0, v253, 34
	v_readlane_b32 s1, v253, 35
	s_mov_b32 s4, s0
	s_ashr_i32 s0, s0, 11
	s_ashr_i32 s1, s0, 31
	s_lshl_b64 s[0:1], s[0:1], 15
	s_and_b32 s4, s4, 0x7ff
	s_or_b32 s0, s0, s4
	s_ashr_i32 s4, s68, 11
	s_ashr_i32 s5, s4, 31
	s_lshl_b64 s[4:5], s[4:5], 15
	s_and_b32 s8, s68, 0x7ff
	s_or_b32 s4, s4, s8
	v_or_b32_e32 v46, s4, v44
	v_mov_b32_e32 v47, s5
	v_lshl_add_u64 v[48:49], v[46:47], 1, s[24:25]
	v_lshl_add_u64 v[46:47], v[46:47], 2, s[22:23]
	flat_load_sshort v81, v[48:49]
	flat_load_dword v82, v[46:47] nt
	v_or_b32_e32 v46, s0, v44
	v_mov_b32_e32 v47, s1
	v_lshl_add_u64 v[48:49], v[46:47], 1, s[24:25]
	v_lshl_add_u64 v[46:47], v[46:47], 2, s[22:23]
	flat_load_sshort v75, v[48:49]
	flat_load_dword v35, v[46:47] nt

.LBB0_2171:
	s_add_i32 s28, s30, s94
	s_cmp_gt_i32 s28, 0xffff
	v_mov_b32_e32 v80, v35
	s_cbranch_scc1 .LBB0_2175
	s_ashr_i32 s29, s28, 31
	s_lshl_b64 s[0:1], s[28:29], 11
	v_lshl_add_u64 v[50:51], v[48:49], 0, s[0:1]
	flat_load_dwordx2 v[56:57], v[50:51] nt
	flat_load_dwordx2 v[54:55], v[50:51] offset:512 nt
	flat_load_dwordx2 v[52:53], v[50:51] offset:1024 nt
	s_nop 0
	flat_load_dwordx2 v[50:51], v[50:51] offset:1536 nt
	v_mov_b32_e32 v79, v75
	v_mov_b32_e32 v80, v35
	s_and_saveexec_b64 s[14:15], s[12:13]
	s_cbranch_execz .LBB0_2174
	s_ashr_i32 s0, s28, 11
	s_ashr_i32 s1, s0, 31
	s_lshl_b64 s[0:1], s[0:1], 15
	v_or_b32_e32 v34, s0, v44
	s_and_b32 s0, s28, 0x7ff
	v_mov_b32_e32 v67, s1
	v_or_b32_e32 v66, s0, v34
	v_lshl_add_u64 v[68:69], v[66:67], 1, s[24:25]
	v_lshl_add_u64 v[66:67], v[66:67], 2, s[22:23]
	flat_load_sshort v79, v[68:69]
	flat_load_dword v80, v[66:67] nt

.LBB0_2177:
	s_add_u32 s10, s36, -1
	s_addc_u32 s11, s37, -1
	s_lshl_b32 s9, s9, 5
	s_and_b64 vcc, s[10:11], s[36:37]
	s_add_i32 s10, s9, s8
	s_ashr_i32 s11, s10, 31
	s_ashr_i32 s35, s34, 31
	s_lshl_b64 s[10:11], s[10:11], 18
	s_lshl_b64 s[34:35], s[34:35], 10
	s_add_u32 s9, s4, s10
	s_addc_u32 s11, s5, s11
	s_add_u32 s10, s9, s34
	s_addc_u32 s11, s11, s35
	s_lshl_b32 s1, s1, 5
	s_add_i32 s34, s1, s8
	s_ashr_i32 s35, s34, 31
	s_ashr_i32 s15, s14, 31
	v_lshlrev_b32_e32 v46, 2, v74
	s_lshl_b64 s[34:35], s[34:35], 18
	s_lshl_b64 s[14:15], s[14:15], 10
	v_lshl_add_u64 v[84:85], s[10:11], 0, v[46:47]
	s_add_u32 s1, s4, s34
	flat_load_dword v83, v[84:85] nt
	s_addc_u32 s9, s5, s35
	s_add_u32 s14, s1, s14
	s_addc_u32 s15, s9, s15
	v_lshl_add_u64 v[86:87], s[14:15], 0, v[46:47]
	flat_load_dword v90, v[86:87] nt
	flat_load_dword v92, v[84:85] offset:256 nt
	flat_load_dword v93, v[86:87] offset:256 nt
	flat_load_dword v94, v[84:85] offset:512 nt
	flat_load_dword v95, v[86:87] offset:512 nt
	flat_load_dword v96, v[84:85] offset:768 nt
	flat_load_dword v97, v[86:87] offset:768 nt
	v_mul_f32_e32 v46, s0, v78
	s_cmp_eq_u64 vcc, 0
	s_waitcnt vmcnt(0) lgkmcnt(0)
	v_cvt_pk_f32_fp8_e32 v[88:89], v90
	v_cvt_pk_f32_fp8_sdwa v[90:91], v90 src0_sel:WORD_1
	v_cvt_pk_f32_fp8_e32 v[84:85], v83
	v_cvt_pk_f32_fp8_sdwa v[86:87], v83 src0_sel:WORD_1
	v_pk_mul_f32 v[88:89], v[34:35], v[88:89] op_sel_hi:[0,1]
	v_pk_mul_f32 v[90:91], v[34:35], v[90:91] op_sel_hi:[0,1]
	v_pk_fma_f32 v[84:85], v[46:47], v[84:85], v[88:89] op_sel_hi:[0,1,1]
	v_pk_fma_f32 v[86:87], v[46:47], v[86:87], v[90:91] op_sel_hi:[0,1,1]
	v_cvt_pk_f32_fp8_e32 v[88:89], v93
	v_cvt_pk_f32_fp8_sdwa v[90:91], v93 src0_sel:WORD_1
	v_pk_add_f32 v[68:69], v[68:69], v[86:87]
	v_pk_add_f32 v[70:71], v[70:71], v[84:85]
	v_cvt_pk_f32_fp8_e32 v[84:85], v92
	v_cvt_pk_f32_fp8_sdwa v[86:87], v92 src0_sel:WORD_1
	v_pk_mul_f32 v[90:91], v[34:35], v[90:91] op_sel_hi:[0,1]
	v_pk_mul_f32 v[88:89], v[34:35], v[88:89] op_sel_hi:[0,1]
	v_pk_fma_f32 v[84:85], v[46:47], v[84:85], v[88:89] op_sel_hi:[0,1,1]
	v_pk_fma_f32 v[86:87], v[46:47], v[86:87], v[90:91] op_sel_hi:[0,1,1]
	v_cvt_pk_f32_fp8_e32 v[88:89], v95
	v_cvt_pk_f32_fp8_sdwa v[90:91], v95 src0_sel:WORD_1
	v_pk_add_f32 v[62:63], v[62:63], v[86:87]
	v_pk_add_f32 v[66:67], v[66:67], v[84:85]
	v_cvt_pk_f32_fp8_e32 v[84:85], v94
	v_cvt_pk_f32_fp8_sdwa v[86:87], v94 src0_sel:WORD_1
	v_pk_mul_f32 v[90:91], v[34:35], v[90:91] op_sel_hi:[0,1]
	v_pk_mul_f32 v[88:89], v[34:35], v[88:89] op_sel_hi:[0,1]
	v_pk_fma_f32 v[84:85], v[46:47], v[84:85], v[88:89] op_sel_hi:[0,1,1]
	v_pk_fma_f32 v[86:87], v[46:47], v[86:87], v[90:91] op_sel_hi:[0,1,1]
	v_cvt_pk_f32_fp8_e32 v[88:89], v97
	v_cvt_pk_f32_fp8_sdwa v[90:91], v97 src0_sel:WORD_1
	v_pk_add_f32 v[60:61], v[60:61], v[86:87]
	v_pk_add_f32 v[64:65], v[64:65], v[84:85]
	v_cvt_pk_f32_fp8_e32 v[84:85], v96
	v_cvt_pk_f32_fp8_sdwa v[86:87], v96 src0_sel:WORD_1
	v_pk_mul_f32 v[90:91], v[34:35], v[90:91] op_sel_hi:[0,1]
	v_pk_mul_f32 v[88:89], v[34:35], v[88:89] op_sel_hi:[0,1]
	v_pk_fma_f32 v[84:85], v[46:47], v[84:85], v[88:89] op_sel_hi:[0,1,1]
	v_pk_fma_f32 v[86:87], v[46:47], v[86:87], v[90:91] op_sel_hi:[0,1,1]
	v_pk_add_f32 v[72:73], v[72:73], v[86:87]
	v_pk_add_f32 v[58:59], v[58:59], v[84:85]
	s_cbranch_scc1 .LBB0_2170

.LBB0_2253:
	s_lshl_b32 s0, s8, 8
	s_add_i32 s20, s0, s97
	s_ashr_i32 s21, s20, 31
	v_mad_i64_i32 v[14:15], s[0:1], s20, v73, v[46:47]
	s_lshl_b64 s[0:1], s[20:21], 7
	global_load_dwordx4 v[2:5], v[34:35], off
	global_load_dwordx4 v[6:9], v[36:37], off
	global_load_dwordx4 v[10:13], v[38:39], off offset:512
	flat_load_dwordx2 v[32:33], v[14:15] nt
	flat_load_dwordx2 v[30:31], v[14:15] offset:512 nt
	flat_load_dwordx2 v[62:63], v[14:15] offset:1024 nt
	v_lshl_add_u64 v[14:15], v[40:41], 0, s[0:1]
	v_lshl_add_u64 v[16:17], v[42:43], 0, s[0:1]
	flat_load_dwordx4 v[22:25], v[14:15]
	flat_load_dwordx4 v[26:29], v[16:17]
	s_mov_b32 s9, 0
	s_branch .LBB0_2255

.LBB0_2255:
	s_mov_b32 s21, s9
	s_add_i32 s9, s9, 8
	s_cmpk_eq_i32 s21, 0xf8
	s_cselect_b32 s0, s21, s9
	s_add_i32 s0, s0, s20
	s_ashr_i32 s1, s0, 31
	v_mad_i64_i32 v[14:15], s[18:19], s0, v73, v[46:47]
	s_lshl_b64 s[0:1], s[0:1], 7
	s_waitcnt vmcnt(0) lgkmcnt(0)
	v_and_b32_e32 v81, 0xffff0000, v33
	v_and_b32_e32 v80, 0xffff0000, v32
	flat_load_dwordx2 v[58:59], v[14:15] nt
	flat_load_dwordx2 v[56:57], v[14:15] offset:512 nt
	flat_load_dwordx2 v[54:55], v[14:15] offset:1024 nt
	v_lshl_add_u64 v[14:15], v[40:41], 0, s[0:1]
	v_lshl_add_u64 v[18:19], v[42:43], 0, s[0:1]
	v_lshlrev_b32_e32 v71, 16, v33
	v_lshlrev_b32_e32 v70, 16, v32
	v_pk_mul_f32 v[32:33], v[80:81], v[80:81]
	flat_load_dwordx4 v[14:17], v[14:15]
	v_pk_fma_f32 v[32:33], v[70:71], v[70:71], v[32:33]
	flat_load_dwordx4 v[18:21], v[18:19]
	v_and_b32_e32 v67, 0xffff0000, v31
	v_and_b32_e32 v66, 0xffff0000, v30
	v_add_f32_e32 v68, v32, v33
	v_lshlrev_b32_e32 v65, 16, v31
	v_lshlrev_b32_e32 v64, 16, v30
	v_pk_mul_f32 v[32:33], v[66:67], v[66:67]
	v_lshlrev_b32_e32 v60, 16, v62
	v_and_b32_e32 v61, 0xffff0000, v62
	v_lshlrev_b32_e32 v62, 16, v63
	v_and_b32_e32 v63, 0xffff0000, v63
	v_pk_fma_f32 v[32:33], v[64:65], v[64:65], v[32:33]
	v_mov_b32_e32 v30, v64
	v_add_f32_e32 v64, v32, v33
	v_mul_f32_e32 v32, v61, v61
	v_mul_f32_e32 v33, v63, v63
	v_fmac_f32_e32 v32, v60, v60
	v_fmac_f32_e32 v33, v62, v62
	v_mov_b32_e32 v31, v66
	v_add_f32_e32 v66, v32, v33
	v_cndmask_b32_e64 v32, 0, v64, s[12:13]
	v_add_f32_e32 v32, v68, v32
	v_mov_b32_e32 v82, v70
	v_mov_b32_e32 v83, v80
	v_add_f32_dpp v32, v32, v32 quad_perm:[1,0,3,2] row_mask:0xf bank_mask:0xf bound_ctrl:1
	v_mov_b32_e32 v80, v71
	s_add_i32 s22, s4, s21
	v_add_f32_dpp v32, v32, v32 quad_perm:[2,3,0,1] row_mask:0xf bank_mask:0xf bound_ctrl:1
	s_ashr_i32 s23, s22, 31
	s_nop 0
	v_add_f32_dpp v32, v32, v32 row_half_mirror row_mask:0xf bank_mask:0xf bound_ctrl:1
	s_nop 1
	v_add_f32_dpp v32, v32, v32 row_mirror row_mask:0xf bank_mask:0xf bound_ctrl:1
	s_nop 0
	v_readlane_b32 s18, v32, 16
	v_readlane_b32 s19, v32, 48
	v_readlane_b32 s0, v32, 0
	v_readlane_b32 s1, v32, 32
	v_mov_b32_e32 v32, s18
	v_mov_b32_e32 v33, s19
	v_pk_add_f32 v[32:33], s[0:1], v[32:33]
	s_nop 0
	v_add_f32_e32 v32, v32, v33
	v_cndmask_b32_e64 v33, 0, v64, s[10:11]
	v_cndmask_b32_e64 v64, 0, v66, s[12:13]
	v_add_f32_e32 v33, v33, v64
	v_fmamk_f32 v32, v32, 0x3b2aaaab, v74
	v_cmp_gt_f32_e32 vcc, s6, v32
	v_add_f32_dpp v33, v33, v33 quad_perm:[1,0,3,2] row_mask:0xf bank_mask:0xf bound_ctrl:1
	s_nop 1
	v_add_f32_dpp v33, v33, v33 quad_perm:[2,3,0,1] row_mask:0xf bank_mask:0xf bound_ctrl:1
	s_nop 1
	v_add_f32_dpp v33, v33, v33 row_half_mirror row_mask:0xf bank_mask:0xf bound_ctrl:1
	s_nop 1
	v_add_f32_dpp v33, v33, v33 row_mirror row_mask:0xf bank_mask:0xf bound_ctrl:1
	s_nop 0
	v_readlane_b32 s1, v33, 16
	v_readlane_b32 s0, v33, 0
	s_nop 0
	v_mov_b32_e32 v64, s1
	v_readlane_b32 s1, v33, 48
	v_add_f32_e32 v64, s0, v64
	v_readlane_b32 s0, v33, 32
	v_mov_b32_e32 v33, s1
	s_nop 0
	v_add_f32_e32 v33, s0, v33
	v_add_f32_e32 v33, v64, v33
	v_mul_f32_e32 v64, 0x4f800000, v32
	v_cndmask_b32_e32 v32, v32, v64, vcc
	v_sqrt_f32_e32 v64, v32
	s_nop 0
	v_add_u32_e32 v66, -1, v64
	v_fma_f32 v68, -v66, v64, v32
	v_cmp_ge_f32_e64 s[18:19], 0, v68
	v_add_u32_e32 v68, 1, v64
	s_nop 0
	v_cndmask_b32_e64 v66, v64, v66, s[18:19]
	v_fma_f32 v64, -v68, v64, v32
	v_cmp_lt_f32_e64 s[18:19], 0, v64
	s_nop 1
	v_cndmask_b32_e64 v64, v66, v68, s[18:19]
	v_mul_f32_e32 v66, 0x37800000, v64
	v_cndmask_b32_e32 v64, v64, v66, vcc
	v_cmp_class_f32_e32 vcc, v32, v75
	s_nop 1
	v_cndmask_b32_e32 v32, v64, v32, vcc
	v_div_scale_f32 v64, s[0:1], v32, v32, 1.0
	v_rcp_f32_e32 v66, v64
	s_nop 0
	v_fma_f32 v68, -v64, v66, 1.0
	v_fmac_f32_e32 v66, v68, v66
	v_div_scale_f32 v68, vcc, 1.0, v32, 1.0
	v_mul_f32_e32 v69, v68, v66
	v_fma_f32 v79, -v64, v69, v68
	v_fmac_f32_e32 v69, v79, v66
	v_fma_f32 v64, -v64, v69, v68
	v_div_fmas_f32 v64, v64, v66, v69
	v_div_fixup_f32 v68, v64, v32, 1.0
	v_fmamk_f32 v32, v33, 0x3b800000, v74
	v_cmp_gt_f32_e32 vcc, s6, v32
	v_mul_f32_e32 v33, 0x4f800000, v32
	s_nop 0
	v_cndmask_b32_e32 v32, v32, v33, vcc
	v_sqrt_f32_e32 v33, v32
	s_nop 0
	v_add_u32_e32 v64, -1, v33
	v_fma_f32 v66, -v64, v33, v32
	v_cmp_ge_f32_e64 s[18:19], 0, v66
	v_add_u32_e32 v66, 1, v33
	s_nop 0
	v_cndmask_b32_e64 v64, v33, v64, s[18:19]
	v_fma_f32 v33, -v66, v33, v32
	v_cmp_lt_f32_e64 s[18:19], 0, v33
	s_nop 1
	v_cndmask_b32_e64 v33, v64, v66, s[18:19]
	v_mul_f32_e32 v64, 0x37800000, v33
	v_cndmask_b32_e32 v33, v33, v64, vcc
	v_cmp_class_f32_e32 vcc, v32, v75
	s_nop 1
	v_cndmask_b32_e32 v32, v33, v32, vcc
	v_div_scale_f32 v33, s[0:1], v32, v32, 1.0
	v_rcp_f32_e32 v64, v33
	s_nop 0
	v_fma_f32 v66, -v33, v64, 1.0
	v_fmac_f32_e32 v64, v66, v64
	v_div_scale_f32 v66, vcc, 1.0, v32, 1.0
	v_mul_f32_e32 v69, v66, v64
	v_fma_f32 v79, -v33, v69, v66
	v_fmac_f32_e32 v69, v79, v64
	v_fma_f32 v33, -v33, v69, v66
	v_pk_mul_f32 v[82:83], v[82:83], v[68:69] op_sel_hi:[1,0]
	v_pk_mul_f32 v[70:71], v[80:81], v[68:69] op_sel_hi:[1,0]
	v_div_fmas_f32 v33, v33, v64, v69
	v_pk_mul_f32 v[70:71], v[4:5], v[70:71]
	v_pk_mul_f32 v[80:81], v[2:3], v[82:83]
	v_div_fixup_f32 v32, v33, v32, 1.0
	v_cvt_pk_bf16_f32 v80, v80, v81
	v_cvt_pk_bf16_f32 v81, v70, v71
	v_mad_i64_i32 v[70:71], s[0:1], s22, v76, v[48:49]
	flat_store_dwordx2 v[70:71], v[80:81]
	s_and_saveexec_b64 s[0:1], s[10:11]
	s_xor_b64 s[18:19], exec, s[0:1]
	s_cbranch_execz .LBB0_2257
	v_mov_b32_e32 v66, v65
	v_pk_mul_f32 v[64:65], v[66:67], v[32:33] op_sel_hi:[1,0]
	v_pk_mul_f32 v[30:31], v[30:31], v[32:33] op_sel_hi:[1,0]
	v_pk_mul_f32 v[32:33], v[8:9], v[64:65]
	v_pk_mul_f32 v[30:31], v[6:7], v[30:31]
	s_lshl_b64 s[0:1], s[22:23], 9
	v_cvt_pk_bf16_f32 v30, v30, v31
	v_cvt_pk_bf16_f32 v31, v32, v33
	v_lshl_add_u64 v[32:33], v[44:45], 0, s[0:1]
	flat_store_dwordx2 v[32:33], v[30:31]

.LBB0_2495:
	ds_read_b128 v[130:133], v168
	ds_read_b128 v[134:137], v168 offset:1024
	ds_read_b128 v[138:141], v168 offset:2048
	ds_read_b128 v[142:145], v168 offset:3072
	s_add_u32 s0, s36, 0xfffc0080
	s_addc_u32 s1, s37, -1
	s_cmp_eq_u32 s69, 12
	s_cselect_b32 s41, s61, s1
	s_cselect_b32 s40, s62, s0
	s_cselect_b32 s39, s63, s67
	s_cselect_b32 s38, s64, s65
	s_mov_b32 m0, s51
	v_lshl_add_u64 v[164:165], s[36:37], 0, v[162:163]
	ds_read_b128 v[146:149], v169
	ds_read_b128 v[172:175], v169 offset:1024
	ds_read_b128 v[176:179], v169 offset:2048
	ds_read_b128 v[180:183], v169 offset:3072
	ds_read_b128 v[184:187], v169 offset:4096
	ds_read_b128 v[188:191], v169 offset:5120
	ds_read_b128 v[192:195], v169 offset:6144
	ds_read_b128 v[196:199], v169 offset:7168
	global_load_lds_dwordx4 v[164:165], off
	v_lshl_add_u64 v[164:165], s[36:37], 0, v[160:161]
	s_mov_b32 m0, s52
	s_nop 0
	global_load_lds_dwordx4 v[164:165], off
	s_waitcnt lgkmcnt(8)
	s_waitcnt vmcnt(10)
	s_barrier
	s_waitcnt lgkmcnt(0)
	s_setprio 1
	s_waitcnt lgkmcnt(0)
	v_mfma_f32_16x16x32_bf16 v[126:129], v[130:133], v[146:149], v[126:129]
	v_mfma_f32_16x16x32_bf16 v[122:125], v[138:141], v[146:149], v[122:125]
	v_mfma_f32_16x16x32_bf16 v[118:121], v[130:133], v[176:179], v[118:121]
	v_mfma_f32_16x16x32_bf16 v[110:113], v[138:141], v[176:179], v[110:113]
	v_mfma_f32_16x16x32_bf16 v[98:101], v[130:133], v[184:187], v[98:101]
	v_mfma_f32_16x16x32_bf16 v[90:93], v[138:141], v[184:187], v[90:93]
	v_mfma_f32_16x16x32_bf16 v[82:85], v[130:133], v[192:195], v[82:85]
	v_mfma_f32_16x16x32_bf16 v[74:77], v[138:141], v[192:195], v[74:77]
	v_mfma_f32_16x16x32_bf16 v[126:129], v[134:137], v[172:175], v[126:129]
	v_mfma_f32_16x16x32_bf16 v[122:125], v[142:145], v[172:175], v[122:125]
	v_mfma_f32_16x16x32_bf16 v[118:121], v[134:137], v[180:183], v[118:121]
	v_mfma_f32_16x16x32_bf16 v[110:113], v[142:145], v[180:183], v[110:113]
	v_mfma_f32_16x16x32_bf16 v[98:101], v[134:137], v[188:191], v[98:101]
	v_mfma_f32_16x16x32_bf16 v[90:93], v[142:145], v[188:191], v[90:93]
	v_mfma_f32_16x16x32_bf16 v[82:85], v[134:137], v[196:199], v[82:85]
	v_mfma_f32_16x16x32_bf16 v[74:77], v[142:145], v[196:199], v[74:77]
	s_setprio 0
	s_barrier
	s_mov_b32 m0, s53
	v_lshl_add_u64 v[164:165], s[38:39], 0, v[156:157]
	ds_read_b128 v[200:203], v170
	ds_read_b128 v[204:207], v170 offset:1024
	ds_read_b128 v[208:211], v170 offset:2048
	ds_read_b128 v[212:215], v170 offset:3072
	global_load_lds_dwordx4 v[164:165], off
	v_lshl_add_u64 v[216:217], s[38:39], 0, v[152:153]
	s_mov_b32 m0, s54
	s_nop 0
	global_load_lds_dwordx4 v[216:217], off
	s_waitcnt vmcnt(10)
	s_barrier
	s_waitcnt lgkmcnt(0)
	s_setprio 1
	s_waitcnt lgkmcnt(0)
	v_mfma_f32_16x16x32_bf16 v[114:117], v[200:203], v[146:149], v[114:117]
	v_mfma_f32_16x16x32_bf16 v[106:109], v[208:211], v[146:149], v[106:109]
	v_mfma_f32_16x16x32_bf16 v[102:105], v[200:203], v[176:179], v[102:105]
	v_mfma_f32_16x16x32_bf16 v[94:97], v[208:211], v[176:179], v[94:97]
	v_mfma_f32_16x16x32_bf16 v[86:89], v[200:203], v[184:187], v[86:89]
	v_mfma_f32_16x16x32_bf16 v[78:81], v[208:211], v[184:187], v[78:81]
	v_mfma_f32_16x16x32_bf16 v[70:73], v[200:203], v[192:195], v[70:73]
	v_mfma_f32_16x16x32_bf16 v[66:69], v[208:211], v[192:195], v[66:69]
	v_mfma_f32_16x16x32_bf16 v[114:117], v[204:207], v[172:175], v[114:117]
	v_mfma_f32_16x16x32_bf16 v[106:109], v[212:215], v[172:175], v[106:109]
	v_mfma_f32_16x16x32_bf16 v[102:105], v[204:207], v[180:183], v[102:105]
	v_mfma_f32_16x16x32_bf16 v[94:97], v[212:215], v[180:183], v[94:97]
	v_mfma_f32_16x16x32_bf16 v[86:89], v[204:207], v[188:191], v[86:89]
	v_mfma_f32_16x16x32_bf16 v[78:81], v[212:215], v[188:191], v[78:81]
	v_mfma_f32_16x16x32_bf16 v[70:73], v[204:207], v[196:199], v[70:73]
	v_mfma_f32_16x16x32_bf16 v[66:69], v[212:215], v[196:199], v[66:69]
	s_setprio 0
	s_mov_b32 m0, s9
	v_lshl_add_u64 v[218:219], s[40:41], 0, v[158:159]
	s_barrier
	ds_read_b128 v[146:149], v169 offset:16384
	ds_read_b128 v[172:175], v169 offset:17408
	ds_read_b128 v[176:179], v169 offset:18432
	ds_read_b128 v[180:183], v169 offset:19456
	ds_read_b128 v[184:187], v169 offset:20480
	ds_read_b128 v[188:191], v169 offset:21504
	ds_read_b128 v[192:195], v169 offset:22528
	ds_read_b128 v[196:199], v169 offset:23552
	global_load_lds_dwordx4 v[218:219], off
	v_lshl_add_u64 v[220:221], s[40:41], 0, v[154:155]
	s_mov_b32 m0, s29
	s_nop 0
	global_load_lds_dwordx4 v[220:221], off
	s_waitcnt vmcnt(10)
	s_barrier
	s_waitcnt lgkmcnt(0)
	s_setprio 1
	s_waitcnt lgkmcnt(0)
	v_mfma_f32_16x16x32_bf16 v[62:65], v[130:133], v[146:149], v[62:65]
	v_mfma_f32_16x16x32_bf16 v[58:61], v[138:141], v[146:149], v[58:61]
	v_mfma_f32_16x16x32_bf16 v[50:53], v[130:133], v[176:179], v[50:53]
	v_mfma_f32_16x16x32_bf16 v[42:45], v[138:141], v[176:179], v[42:45]
	v_mfma_f32_16x16x32_bf16 v[34:37], v[130:133], v[184:187], v[34:37]
	v_mfma_f32_16x16x32_bf16 v[26:29], v[138:141], v[184:187], v[26:29]
	v_mfma_f32_16x16x32_bf16 v[18:21], v[130:133], v[192:195], v[18:21]
	v_mfma_f32_16x16x32_bf16 v[10:13], v[138:141], v[192:195], v[10:13]
	v_mfma_f32_16x16x32_bf16 v[62:65], v[134:137], v[172:175], v[62:65]
	v_mfma_f32_16x16x32_bf16 v[58:61], v[142:145], v[172:175], v[58:61]
	v_mfma_f32_16x16x32_bf16 v[50:53], v[134:137], v[180:183], v[50:53]
	v_mfma_f32_16x16x32_bf16 v[42:45], v[142:145], v[180:183], v[42:45]
	v_mfma_f32_16x16x32_bf16 v[34:37], v[134:137], v[188:191], v[34:37]
	v_mfma_f32_16x16x32_bf16 v[26:29], v[142:145], v[188:191], v[26:29]
	v_mfma_f32_16x16x32_bf16 v[18:21], v[134:137], v[196:199], v[18:21]
	v_mfma_f32_16x16x32_bf16 v[10:13], v[142:145], v[196:199], v[10:13]
	s_setprio 0
	s_barrier
	s_add_u32 s0, s38, 0x40000
	s_addc_u32 s1, s39, 0
	s_mov_b32 m0, s55
	v_lshl_add_u64 v[130:131], s[0:1], 0, v[156:157]
	global_load_lds_dwordx4 v[130:131], off
	v_lshl_add_u64 v[130:131], s[0:1], 0, v[152:153]
	s_add_i32 m0, s55, 0x2000
	s_nop 0
	global_load_lds_dwordx4 v[130:131], off
	s_waitcnt vmcnt(10)
	s_barrier
	s_setprio 1
	v_mfma_f32_16x16x32_bf16 v[54:57], v[200:203], v[146:149], v[54:57]
	v_mfma_f32_16x16x32_bf16 v[46:49], v[208:211], v[146:149], v[46:49]
	v_mfma_f32_16x16x32_bf16 v[38:41], v[200:203], v[176:179], v[38:41]
	v_mfma_f32_16x16x32_bf16 v[30:33], v[208:211], v[176:179], v[30:33]
	v_mfma_f32_16x16x32_bf16 v[22:25], v[200:203], v[184:187], v[22:25]
	v_mfma_f32_16x16x32_bf16 v[14:17], v[208:211], v[184:187], v[14:17]
	v_mfma_f32_16x16x32_bf16 v[6:9], v[200:203], v[192:195], v[6:9]
	v_mfma_f32_16x16x32_bf16 v[2:5], v[208:211], v[192:195], v[2:5]
	v_mfma_f32_16x16x32_bf16 v[54:57], v[204:207], v[172:175], v[54:57]
	v_mfma_f32_16x16x32_bf16 v[46:49], v[212:215], v[172:175], v[46:49]
	v_mfma_f32_16x16x32_bf16 v[38:41], v[204:207], v[180:183], v[38:41]
	v_mfma_f32_16x16x32_bf16 v[30:33], v[212:215], v[180:183], v[30:33]
	v_mfma_f32_16x16x32_bf16 v[22:25], v[204:207], v[188:191], v[22:25]
	v_mfma_f32_16x16x32_bf16 v[14:17], v[212:215], v[188:191], v[14:17]
	v_mfma_f32_16x16x32_bf16 v[6:9], v[204:207], v[196:199], v[6:9]
	v_mfma_f32_16x16x32_bf16 v[2:5], v[212:215], v[196:199], v[2:5]
	s_setprio 0
	s_add_i32 s70, 0, 0x18000
	v_add_u32_e32 v142, s70, v167
	s_barrier
	ds_read_b128 v[130:133], v142
	ds_read_b128 v[134:137], v142 offset:1024
	ds_read_b128 v[138:141], v142 offset:2048
	ds_read_b128 v[142:145], v142 offset:3072
	s_add_u32 s0, s40, 0x40000
	s_addc_u32 s1, s41, 0
	s_mov_b32 m0, s42
	v_lshl_add_u64 v[200:201], s[0:1], 0, v[158:159]
	ds_read_b128 v[146:149], v169 offset:32768
	ds_read_b128 v[172:175], v169 offset:33792
	ds_read_b128 v[176:179], v169 offset:34816
	ds_read_b128 v[180:183], v169 offset:35840
	ds_read_b128 v[184:187], v169 offset:36864
	ds_read_b128 v[188:191], v169 offset:37888
	ds_read_b128 v[192:195], v169 offset:38912
	ds_read_b128 v[196:199], v169 offset:39936
	global_load_lds_dwordx4 v[200:201], off
	v_lshl_add_u64 v[200:201], s[0:1], 0, v[154:155]
	s_mov_b32 m0, s43
	s_nop 0
	global_load_lds_dwordx4 v[200:201], off
	s_waitcnt lgkmcnt(8)
	s_waitcnt vmcnt(10)
	s_barrier
	s_waitcnt lgkmcnt(0)
	s_setprio 1
	s_waitcnt lgkmcnt(0)
	v_mfma_f32_16x16x32_bf16 v[126:129], v[130:133], v[146:149], v[126:129]
	v_mfma_f32_16x16x32_bf16 v[122:125], v[138:141], v[146:149], v[122:125]
	v_mfma_f32_16x16x32_bf16 v[118:121], v[130:133], v[176:179], v[118:121]
	v_mfma_f32_16x16x32_bf16 v[110:113], v[138:141], v[176:179], v[110:113]
	v_mfma_f32_16x16x32_bf16 v[98:101], v[130:133], v[184:187], v[98:101]
	v_mfma_f32_16x16x32_bf16 v[90:93], v[138:141], v[184:187], v[90:93]
	v_mfma_f32_16x16x32_bf16 v[82:85], v[130:133], v[192:195], v[82:85]
	v_mfma_f32_16x16x32_bf16 v[74:77], v[138:141], v[192:195], v[74:77]
	v_mfma_f32_16x16x32_bf16 v[126:129], v[134:137], v[172:175], v[126:129]
	v_mfma_f32_16x16x32_bf16 v[122:125], v[142:145], v[172:175], v[122:125]
	v_mfma_f32_16x16x32_bf16 v[118:121], v[134:137], v[180:183], v[118:121]
	v_mfma_f32_16x16x32_bf16 v[110:113], v[142:145], v[180:183], v[110:113]
	v_mfma_f32_16x16x32_bf16 v[98:101], v[134:137], v[188:191], v[98:101]
	v_mfma_f32_16x16x32_bf16 v[90:93], v[142:145], v[188:191], v[90:93]
	v_mfma_f32_16x16x32_bf16 v[82:85], v[134:137], v[196:199], v[82:85]
	v_mfma_f32_16x16x32_bf16 v[74:77], v[142:145], v[196:199], v[74:77]
	s_setprio 0
	s_barrier
	s_add_i32 s40, 0, 0x1c000
	s_add_i32 s0, s70, s8
	v_add_u32_e32 v171, s40, v167
	v_lshl_add_u64 v[164:165], v[164:165], 0, s[26:27]
	s_mov_b32 m0, s0
	ds_read_b128 v[200:203], v171
	ds_read_b128 v[204:207], v171 offset:1024
	ds_read_b128 v[208:211], v171 offset:2048
	ds_read_b128 v[212:215], v171 offset:3072
	global_load_lds_dwordx4 v[164:165], off
	v_lshl_add_u64 v[164:165], v[216:217], 0, s[26:27]
	s_add_i32 m0, s0, 0x2000
	s_nop 0
	global_load_lds_dwordx4 v[164:165], off
	s_waitcnt vmcnt(10)
	s_barrier
	s_waitcnt lgkmcnt(0)
	s_setprio 1
	s_waitcnt lgkmcnt(0)
	v_mfma_f32_16x16x32_bf16 v[114:117], v[200:203], v[146:149], v[114:117]
	v_mfma_f32_16x16x32_bf16 v[106:109], v[208:211], v[146:149], v[106:109]
	v_mfma_f32_16x16x32_bf16 v[102:105], v[200:203], v[176:179], v[102:105]
	v_mfma_f32_16x16x32_bf16 v[94:97], v[208:211], v[176:179], v[94:97]
	v_mfma_f32_16x16x32_bf16 v[86:89], v[200:203], v[184:187], v[86:89]
	v_mfma_f32_16x16x32_bf16 v[78:81], v[208:211], v[184:187], v[78:81]
	v_mfma_f32_16x16x32_bf16 v[70:73], v[200:203], v[192:195], v[70:73]
	v_mfma_f32_16x16x32_bf16 v[66:69], v[208:211], v[192:195], v[66:69]
	v_mfma_f32_16x16x32_bf16 v[114:117], v[204:207], v[172:175], v[114:117]
	v_mfma_f32_16x16x32_bf16 v[106:109], v[212:215], v[172:175], v[106:109]
	v_mfma_f32_16x16x32_bf16 v[102:105], v[204:207], v[180:183], v[102:105]
	v_mfma_f32_16x16x32_bf16 v[94:97], v[212:215], v[180:183], v[94:97]
	v_mfma_f32_16x16x32_bf16 v[86:89], v[204:207], v[188:191], v[86:89]
	v_mfma_f32_16x16x32_bf16 v[78:81], v[212:215], v[188:191], v[78:81]
	v_mfma_f32_16x16x32_bf16 v[70:73], v[204:207], v[196:199], v[70:73]
	v_mfma_f32_16x16x32_bf16 v[66:69], v[212:215], v[196:199], v[66:69]
	s_setprio 0
	s_mov_b32 m0, s49
	v_lshl_add_u64 v[164:165], v[218:219], 0, s[26:27]
	s_barrier
	ds_read_b128 v[146:149], v169 offset:49152
	ds_read_b128 v[172:175], v169 offset:50176
	ds_read_b128 v[176:179], v169 offset:51200
	ds_read_b128 v[180:183], v169 offset:52224
	ds_read_b128 v[184:187], v169 offset:53248
	ds_read_b128 v[188:191], v169 offset:54272
	ds_read_b128 v[192:195], v169 offset:55296
	ds_read_b128 v[196:199], v169 offset:56320
	global_load_lds_dwordx4 v[164:165], off
	v_lshl_add_u64 v[164:165], v[220:221], 0, s[26:27]
	s_mov_b32 m0, s50
	s_nop 0
	global_load_lds_dwordx4 v[164:165], off
	s_waitcnt vmcnt(10)
	s_barrier
	s_waitcnt lgkmcnt(0)
	s_setprio 1
	s_waitcnt lgkmcnt(0)
	v_mfma_f32_16x16x32_bf16 v[62:65], v[130:133], v[146:149], v[62:65]
	v_mfma_f32_16x16x32_bf16 v[58:61], v[138:141], v[146:149], v[58:61]
	v_mfma_f32_16x16x32_bf16 v[50:53], v[130:133], v[176:179], v[50:53]
	v_mfma_f32_16x16x32_bf16 v[42:45], v[138:141], v[176:179], v[42:45]
	v_mfma_f32_16x16x32_bf16 v[34:37], v[130:133], v[184:187], v[34:37]
	v_mfma_f32_16x16x32_bf16 v[26:29], v[138:141], v[184:187], v[26:29]
	v_mfma_f32_16x16x32_bf16 v[18:21], v[130:133], v[192:195], v[18:21]
	v_mfma_f32_16x16x32_bf16 v[10:13], v[138:141], v[192:195], v[10:13]
	v_mfma_f32_16x16x32_bf16 v[62:65], v[134:137], v[172:175], v[62:65]
	v_mfma_f32_16x16x32_bf16 v[58:61], v[142:145], v[172:175], v[58:61]
	v_mfma_f32_16x16x32_bf16 v[50:53], v[134:137], v[180:183], v[50:53]
	v_mfma_f32_16x16x32_bf16 v[42:45], v[142:145], v[180:183], v[42:45]
	v_mfma_f32_16x16x32_bf16 v[34:37], v[134:137], v[188:191], v[34:37]
	v_mfma_f32_16x16x32_bf16 v[26:29], v[142:145], v[188:191], v[26:29]
	v_mfma_f32_16x16x32_bf16 v[18:21], v[134:137], v[196:199], v[18:21]
	v_mfma_f32_16x16x32_bf16 v[10:13], v[142:145], v[196:199], v[10:13]
	s_setprio 0
	s_barrier
	s_add_u32 s0, s38, 0x40080
	s_addc_u32 s1, s39, 0
	s_add_i32 s38, s40, s8
	v_lshl_add_u64 v[130:131], s[0:1], 0, v[156:157]
	s_mov_b32 m0, s38
	s_nop 0
	global_load_lds_dwordx4 v[130:131], off
	v_lshl_add_u64 v[130:131], s[0:1], 0, v[152:153]
	s_add_i32 m0, s38, 0x2000
	s_nop 0
	global_load_lds_dwordx4 v[130:131], off
	s_waitcnt vmcnt(10)
	s_barrier
	s_setprio 1
	v_mfma_f32_16x16x32_bf16 v[54:57], v[200:203], v[146:149], v[54:57]
	v_mfma_f32_16x16x32_bf16 v[46:49], v[208:211], v[146:149], v[46:49]
	v_mfma_f32_16x16x32_bf16 v[38:41], v[200:203], v[176:179], v[38:41]
	v_mfma_f32_16x16x32_bf16 v[30:33], v[208:211], v[176:179], v[30:33]
	v_mfma_f32_16x16x32_bf16 v[22:25], v[200:203], v[184:187], v[22:25]
	v_mfma_f32_16x16x32_bf16 v[14:17], v[208:211], v[184:187], v[14:17]
	v_mfma_f32_16x16x32_bf16 v[6:9], v[200:203], v[192:195], v[6:9]
	v_mfma_f32_16x16x32_bf16 v[2:5], v[208:211], v[192:195], v[2:5]
	v_mfma_f32_16x16x32_bf16 v[54:57], v[204:207], v[172:175], v[54:57]
	v_mfma_f32_16x16x32_bf16 v[46:49], v[212:215], v[172:175], v[46:49]
	v_mfma_f32_16x16x32_bf16 v[38:41], v[204:207], v[180:183], v[38:41]
	v_mfma_f32_16x16x32_bf16 v[30:33], v[212:215], v[180:183], v[30:33]
	v_mfma_f32_16x16x32_bf16 v[22:25], v[204:207], v[188:191], v[22:25]
	v_mfma_f32_16x16x32_bf16 v[14:17], v[212:215], v[188:191], v[14:17]
	v_mfma_f32_16x16x32_bf16 v[6:9], v[204:207], v[196:199], v[6:9]
	v_mfma_f32_16x16x32_bf16 v[2:5], v[212:215], v[196:199], v[2:5]
	s_setprio 0
	s_add_i32 s69, s69, 2
	s_add_u32 s65, s65, 0x100
	s_addc_u32 s67, s67, 0
	s_add_u32 s36, s36, 0x100
	s_addc_u32 s37, s37, 0
	s_cmp_gt_u32 s69, 13
	s_barrier
	s_cbranch_scc0 .LBB0_2495
	s_lshl_b32 s0, s59, 8
	v_mov_b32_e32 v130, v151
	v_mov_b32_e32 v131, v166
	s_or_b32 s0, s0, s46
	s_mov_b32 s59, s58
	v_lshl_add_u32 v164, v131, 3, s0
	s_lshl_b32 s0, s60, 8
	s_add_i32 s0, s0, s45
	v_add_u32_e32 v171, s0, v130
	v_mov_b32_e32 v130, v171
	v_ashrrev_i32_e32 v165, 31, v164
	v_ashrrev_i32_e32 v131, 31, v130
	v_lshlrev_b64 v[130:131], 10, v[130:131]
	v_lshl_add_u64 v[130:131], v[130:131], 0, v[164:165]
	v_lshlrev_b64 v[184:185], 1, v[130:131]
	v_lshl_add_u64 v[130:131], s[10:11], 0, v[184:185]
	flat_load_dwordx4 v[172:175], v[130:131] nt
	flat_load_dwordx4 v[176:179], v[130:131] offset:256 nt
	v_add_co_u32_e32 v132, vcc, s48, v130
	s_mov_b32 s60, s57
	s_nop 0
	v_addc_co_u32_e32 v133, vcc, 0, v131, vcc
	flat_load_dwordx4 v[180:183], v[132:133] nt
	flat_load_dwordx4 v[146:149], v[132:133] offset:256 nt
	v_add_co_u32_e32 v132, vcc, s44, v130
	s_waitcnt vmcnt(0) lgkmcnt(0)
	v_lshlrev_b32_e32 v186, 16, v172
	v_addc_co_u32_e32 v133, vcc, 0, v131, vcc
	flat_load_dwordx4 v[142:145], v[132:133] nt
	flat_load_dwordx4 v[138:141], v[132:133] offset:256 nt
	v_add_co_u32_e32 v130, vcc, s47, v130
	v_and_b32_e32 v187, 0xffff0000, v172
	s_nop 0
	v_addc_co_u32_e32 v131, vcc, 0, v131, vcc
	flat_load_dwordx4 v[134:137], v[130:131] nt
	s_nop 0
	flat_load_dwordx4 v[130:133], v[130:131] offset:256 nt
	v_lshlrev_b32_e32 v172, 16, v173
	v_and_b32_e32 v173, 0xffff0000, v173
	v_lshlrev_b32_e32 v188, 16, v174
	v_and_b32_e32 v189, 0xffff0000, v174
	v_lshlrev_b32_e32 v174, 16, v175
	v_and_b32_e32 v175, 0xffff0000, v175
	v_pk_fma_f32 v[128:129], v[172:173], s[28:29], v[128:129] op_sel_hi:[1,0,1]
	v_pk_fma_f32 v[126:127], v[186:187], s[28:29], v[126:127] op_sel_hi:[1,0,1]
	v_pk_fma_f32 v[172:173], v[174:175], s[28:29], v[124:125] op_sel_hi:[1,0,1]
	v_pk_fma_f32 v[122:123], v[188:189], s[28:29], v[122:123] op_sel_hi:[1,0,1]
	v_cvt_pk_bf16_f32 v124, v126, v127
	v_cvt_pk_bf16_f32 v125, v128, v129
	v_cvt_pk_bf16_f32 v126, v122, v123
	v_cvt_pk_bf16_f32 v127, v172, v173
	v_lshl_add_u64 v[122:123], s[16:17], 0, v[184:185]
	flat_store_dwordx4 v[122:123], v[124:127]
	v_lshlrev_b32_e32 v128, 16, v178
	v_and_b32_e32 v129, 0xffff0000, v178
	v_lshlrev_b32_e32 v124, 16, v176
	v_and_b32_e32 v125, 0xffff0000, v176
	v_lshlrev_b32_e32 v126, 16, v177
	v_and_b32_e32 v127, 0xffff0000, v177
	v_lshlrev_b32_e32 v172, 16, v179
	v_and_b32_e32 v173, 0xffff0000, v179
	v_pk_fma_f32 v[116:117], v[126:127], s[28:29], v[116:117] op_sel_hi:[1,0,1]
	v_pk_fma_f32 v[114:115], v[124:125], s[28:29], v[114:115] op_sel_hi:[1,0,1]
	v_pk_fma_f32 v[124:125], v[172:173], s[28:29], v[108:109] op_sel_hi:[1,0,1]
	v_pk_fma_f32 v[108:109], v[128:129], s[28:29], v[106:107] op_sel_hi:[1,0,1]
	v_cvt_pk_bf16_f32 v106, v114, v115
	v_cvt_pk_bf16_f32 v107, v116, v117
	v_cvt_pk_bf16_f32 v108, v108, v109
	v_cvt_pk_bf16_f32 v109, v124, v125
	flat_store_dwordx4 v[122:123], v[106:109] offset:256
	v_lshlrev_b32_e32 v114, 16, v182
	v_and_b32_e32 v115, 0xffff0000, v182
	v_lshlrev_b32_e32 v106, 16, v180
	v_and_b32_e32 v107, 0xffff0000, v180
	v_lshlrev_b32_e32 v108, 16, v181
	v_and_b32_e32 v109, 0xffff0000, v181
	v_lshlrev_b32_e32 v116, 16, v183
	v_and_b32_e32 v117, 0xffff0000, v183
	v_pk_fma_f32 v[108:109], v[108:109], s[28:29], v[120:121] op_sel_hi:[1,0,1]
	v_pk_fma_f32 v[106:107], v[106:107], s[28:29], v[118:119] op_sel_hi:[1,0,1]
	v_pk_fma_f32 v[110:111], v[114:115], s[28:29], v[110:111] op_sel_hi:[1,0,1]
	v_pk_fma_f32 v[112:113], v[116:117], s[28:29], v[112:113] op_sel_hi:[1,0,1]
	v_cvt_pk_bf16_f32 v106, v106, v107
	v_cvt_pk_bf16_f32 v107, v108, v109
	v_cvt_pk_bf16_f32 v108, v110, v111
	v_add_co_u32_e32 v110, vcc, s48, v122
	v_cvt_pk_bf16_f32 v109, v112, v113
	s_nop 0
	v_addc_co_u32_e32 v111, vcc, 0, v123, vcc
	flat_store_dwordx4 v[110:111], v[106:109]
	v_lshlrev_b32_e32 v112, 16, v148
	v_and_b32_e32 v113, 0xffff0000, v148
	v_lshlrev_b32_e32 v106, 16, v146
	v_and_b32_e32 v107, 0xffff0000, v146
	v_lshlrev_b32_e32 v108, 16, v147
	v_and_b32_e32 v109, 0xffff0000, v147
	v_lshlrev_b32_e32 v114, 16, v149
	v_and_b32_e32 v115, 0xffff0000, v149
	v_pk_fma_f32 v[104:105], v[108:109], s[28:29], v[104:105] op_sel_hi:[1,0,1]
	v_pk_fma_f32 v[102:103], v[106:107], s[28:29], v[102:103] op_sel_hi:[1,0,1]
	v_pk_fma_f32 v[106:107], v[114:115], s[28:29], v[96:97] op_sel_hi:[1,0,1]
	v_pk_fma_f32 v[96:97], v[112:113], s[28:29], v[94:95] op_sel_hi:[1,0,1]
	v_cvt_pk_bf16_f32 v94, v102, v103
	v_cvt_pk_bf16_f32 v95, v104, v105
	v_cvt_pk_bf16_f32 v96, v96, v97
	v_cvt_pk_bf16_f32 v97, v106, v107
	flat_store_dwordx4 v[110:111], v[94:97] offset:256
	s_waitcnt vmcnt(0) lgkmcnt(0)
	v_lshlrev_b32_e32 v102, 16, v144
	v_lshlrev_b32_e32 v94, 16, v142
	v_and_b32_e32 v95, 0xffff0000, v142
	v_lshlrev_b32_e32 v96, 16, v143
	v_and_b32_e32 v97, 0xffff0000, v143
	v_and_b32_e32 v103, 0xffff0000, v144
	v_lshlrev_b32_e32 v104, 16, v145
	v_and_b32_e32 v105, 0xffff0000, v145
	v_pk_fma_f32 v[94:95], v[94:95], s[28:29], v[98:99] op_sel_hi:[1,0,1]
	v_pk_fma_f32 v[96:97], v[96:97], s[28:29], v[100:101] op_sel_hi:[1,0,1]
	v_pk_fma_f32 v[98:99], v[104:105], s[28:29], v[92:93] op_sel_hi:[1,0,1]
	v_pk_fma_f32 v[92:93], v[102:103], s[28:29], v[90:91] op_sel_hi:[1,0,1]
	v_cvt_pk_bf16_f32 v90, v94, v95
	v_add_co_u32_e32 v94, vcc, s44, v122
	v_cvt_pk_bf16_f32 v91, v96, v97
	v_cvt_pk_bf16_f32 v92, v92, v93
	v_cvt_pk_bf16_f32 v93, v98, v99
	v_addc_co_u32_e32 v95, vcc, 0, v123, vcc
	flat_store_dwordx4 v[94:95], v[90:93]
	v_lshlrev_b32_e32 v96, 16, v140
	v_and_b32_e32 v97, 0xffff0000, v140
	v_lshlrev_b32_e32 v90, 16, v138
	v_and_b32_e32 v91, 0xffff0000, v138
	v_lshlrev_b32_e32 v92, 16, v139
	v_and_b32_e32 v93, 0xffff0000, v139
	v_lshlrev_b32_e32 v98, 16, v141
	v_and_b32_e32 v99, 0xffff0000, v141
	v_pk_fma_f32 v[88:89], v[92:93], s[28:29], v[88:89] op_sel_hi:[1,0,1]
	v_pk_fma_f32 v[86:87], v[90:91], s[28:29], v[86:87] op_sel_hi:[1,0,1]
	v_pk_fma_f32 v[90:91], v[98:99], s[28:29], v[80:81] op_sel_hi:[1,0,1]
	v_pk_fma_f32 v[80:81], v[96:97], s[28:29], v[78:79] op_sel_hi:[1,0,1]
	v_cvt_pk_bf16_f32 v78, v86, v87
	v_cvt_pk_bf16_f32 v79, v88, v89
	v_cvt_pk_bf16_f32 v80, v80, v81
	v_cvt_pk_bf16_f32 v81, v90, v91
	flat_store_dwordx4 v[94:95], v[78:81] offset:256
	v_lshlrev_b32_e32 v86, 16, v136
	v_and_b32_e32 v87, 0xffff0000, v136
	v_lshlrev_b32_e32 v78, 16, v134
	v_and_b32_e32 v79, 0xffff0000, v134
	v_lshlrev_b32_e32 v80, 16, v135
	v_and_b32_e32 v81, 0xffff0000, v135
	v_lshlrev_b32_e32 v88, 16, v137
	v_and_b32_e32 v89, 0xffff0000, v137
	v_pk_fma_f32 v[78:79], v[78:79], s[28:29], v[82:83] op_sel_hi:[1,0,1]
	v_pk_fma_f32 v[80:81], v[80:81], s[28:29], v[84:85] op_sel_hi:[1,0,1]
	v_pk_fma_f32 v[82:83], v[88:89], s[28:29], v[76:77] op_sel_hi:[1,0,1]
	v_pk_fma_f32 v[76:77], v[86:87], s[28:29], v[74:75] op_sel_hi:[1,0,1]
	v_cvt_pk_bf16_f32 v74, v78, v79
	v_add_co_u32_e32 v78, vcc, s47, v122
	v_cvt_pk_bf16_f32 v75, v80, v81
	v_cvt_pk_bf16_f32 v76, v76, v77
	v_cvt_pk_bf16_f32 v77, v82, v83
	v_addc_co_u32_e32 v79, vcc, 0, v123, vcc
	flat_store_dwordx4 v[78:79], v[74:77]
	v_lshlrev_b32_e32 v80, 16, v132
	v_and_b32_e32 v81, 0xffff0000, v132
	v_lshlrev_b32_e32 v74, 16, v130
	v_and_b32_e32 v75, 0xffff0000, v130
	v_lshlrev_b32_e32 v76, 16, v131
	v_and_b32_e32 v77, 0xffff0000, v131
	v_lshlrev_b32_e32 v82, 16, v133
	v_and_b32_e32 v83, 0xffff0000, v133
	v_pk_fma_f32 v[72:73], v[76:77], s[28:29], v[72:73] op_sel_hi:[1,0,1]
	v_pk_fma_f32 v[70:71], v[74:75], s[28:29], v[70:71] op_sel_hi:[1,0,1]
	v_pk_fma_f32 v[74:75], v[82:83], s[28:29], v[68:69] op_sel_hi:[1,0,1]
	v_pk_fma_f32 v[68:69], v[80:81], s[28:29], v[66:67] op_sel_hi:[1,0,1]
	v_cvt_pk_bf16_f32 v66, v70, v71
	v_cvt_pk_bf16_f32 v67, v72, v73
	v_cvt_pk_bf16_f32 v68, v68, v69
	v_cvt_pk_bf16_f32 v69, v74, v75
	flat_store_dwordx4 v[78:79], v[66:69] offset:256
	s_nop 1
	v_add_u32_e32 v66, 0x80, v171
	s_nop 0
	v_ashrrev_i32_e32 v67, 31, v66
	v_lshlrev_b64 v[66:67], 10, v[66:67]
	v_lshl_add_u64 v[66:67], v[66:67], 0, v[164:165]
	v_lshlrev_b64 v[98:99], 1, v[66:67]
	v_lshl_add_u64 v[90:91], s[10:11], 0, v[98:99]
	flat_load_dwordx4 v[66:69], v[90:91] nt
	flat_load_dwordx4 v[70:73], v[90:91] offset:256 nt
	v_add_co_u32_e32 v78, vcc, s48, v90
	s_waitcnt vmcnt(0) lgkmcnt(0)
	v_lshlrev_b32_e32 v100, 16, v66
	v_addc_co_u32_e32 v79, vcc, 0, v91, vcc
	flat_load_dwordx4 v[74:77], v[78:79] nt
	s_nop 0
	flat_load_dwordx4 v[78:81], v[78:79] offset:256 nt
	v_add_co_u32_e32 v86, vcc, s44, v90
	v_and_b32_e32 v101, 0xffff0000, v66
	s_nop 0
	v_addc_co_u32_e32 v87, vcc, 0, v91, vcc
	flat_load_dwordx4 v[82:85], v[86:87] nt
	s_nop 0
	flat_load_dwordx4 v[86:89], v[86:87] offset:256 nt
	v_add_co_u32_e32 v94, vcc, s47, v90
	v_lshlrev_b32_e32 v66, 16, v67
	s_nop 0
	v_addc_co_u32_e32 v95, vcc, 0, v91, vcc
	flat_load_dwordx4 v[90:93], v[94:95] nt
	s_nop 0
	flat_load_dwordx4 v[94:97], v[94:95] offset:256 nt
	v_and_b32_e32 v67, 0xffff0000, v67
	v_lshlrev_b32_e32 v102, 16, v68
	v_and_b32_e32 v103, 0xffff0000, v68
	v_lshlrev_b32_e32 v68, 16, v69
	v_and_b32_e32 v69, 0xffff0000, v69
	v_pk_fma_f32 v[64:65], v[66:67], s[28:29], v[64:65] op_sel_hi:[1,0,1]
	v_pk_fma_f32 v[62:63], v[100:101], s[28:29], v[62:63] op_sel_hi:[1,0,1]
	v_pk_fma_f32 v[66:67], v[68:69], s[28:29], v[60:61] op_sel_hi:[1,0,1]
	v_pk_fma_f32 v[60:61], v[102:103], s[28:29], v[58:59] op_sel_hi:[1,0,1]
	v_cvt_pk_bf16_f32 v58, v62, v63
	v_cvt_pk_bf16_f32 v59, v64, v65
	v_cvt_pk_bf16_f32 v60, v60, v61
	v_cvt_pk_bf16_f32 v61, v66, v67
	v_lshl_add_u64 v[62:63], s[16:17], 0, v[98:99]
	flat_store_dwordx4 v[62:63], v[58:61]
	v_lshlrev_b32_e32 v64, 16, v72
	v_and_b32_e32 v65, 0xffff0000, v72
	v_lshlrev_b32_e32 v58, 16, v70
	v_and_b32_e32 v59, 0xffff0000, v70
	v_lshlrev_b32_e32 v60, 16, v71
	v_and_b32_e32 v61, 0xffff0000, v71
	v_lshlrev_b32_e32 v66, 16, v73
	v_and_b32_e32 v67, 0xffff0000, v73
	v_pk_fma_f32 v[56:57], v[60:61], s[28:29], v[56:57] op_sel_hi:[1,0,1]
	v_pk_fma_f32 v[54:55], v[58:59], s[28:29], v[54:55] op_sel_hi:[1,0,1]
	v_pk_fma_f32 v[58:59], v[66:67], s[28:29], v[48:49] op_sel_hi:[1,0,1]
	v_pk_fma_f32 v[48:49], v[64:65], s[28:29], v[46:47] op_sel_hi:[1,0,1]
	v_cvt_pk_bf16_f32 v46, v54, v55
	v_cvt_pk_bf16_f32 v47, v56, v57
	v_cvt_pk_bf16_f32 v48, v48, v49
	v_cvt_pk_bf16_f32 v49, v58, v59
	flat_store_dwordx4 v[62:63], v[46:49] offset:256
	s_waitcnt vmcnt(0) lgkmcnt(0)
	v_lshlrev_b32_e32 v54, 16, v76
	v_lshlrev_b32_e32 v46, 16, v74
	v_and_b32_e32 v47, 0xffff0000, v74
	v_lshlrev_b32_e32 v48, 16, v75
	v_and_b32_e32 v49, 0xffff0000, v75
	v_and_b32_e32 v55, 0xffff0000, v76
	v_lshlrev_b32_e32 v56, 16, v77
	v_and_b32_e32 v57, 0xffff0000, v77
	v_pk_fma_f32 v[46:47], v[46:47], s[28:29], v[50:51] op_sel_hi:[1,0,1]
	v_pk_fma_f32 v[48:49], v[48:49], s[28:29], v[52:53] op_sel_hi:[1,0,1]
	v_pk_fma_f32 v[50:51], v[56:57], s[28:29], v[44:45] op_sel_hi:[1,0,1]
	v_pk_fma_f32 v[44:45], v[54:55], s[28:29], v[42:43] op_sel_hi:[1,0,1]
	v_cvt_pk_bf16_f32 v42, v46, v47
	v_add_co_u32_e32 v46, vcc, s48, v62
	v_cvt_pk_bf16_f32 v43, v48, v49
	v_cvt_pk_bf16_f32 v44, v44, v45
	v_cvt_pk_bf16_f32 v45, v50, v51
	v_addc_co_u32_e32 v47, vcc, 0, v63, vcc
	flat_store_dwordx4 v[46:47], v[42:45]
	v_lshlrev_b32_e32 v48, 16, v80
	v_and_b32_e32 v49, 0xffff0000, v80
	v_lshlrev_b32_e32 v42, 16, v78
	v_and_b32_e32 v43, 0xffff0000, v78
	v_lshlrev_b32_e32 v44, 16, v79
	v_and_b32_e32 v45, 0xffff0000, v79
	v_lshlrev_b32_e32 v50, 16, v81
	v_and_b32_e32 v51, 0xffff0000, v81
	v_pk_fma_f32 v[40:41], v[44:45], s[28:29], v[40:41] op_sel_hi:[1,0,1]
	v_pk_fma_f32 v[38:39], v[42:43], s[28:29], v[38:39] op_sel_hi:[1,0,1]
	v_pk_fma_f32 v[42:43], v[50:51], s[28:29], v[32:33] op_sel_hi:[1,0,1]
	v_pk_fma_f32 v[32:33], v[48:49], s[28:29], v[30:31] op_sel_hi:[1,0,1]
	v_cvt_pk_bf16_f32 v30, v38, v39
	v_cvt_pk_bf16_f32 v31, v40, v41
	v_cvt_pk_bf16_f32 v32, v32, v33
	v_cvt_pk_bf16_f32 v33, v42, v43
	flat_store_dwordx4 v[46:47], v[30:33] offset:256
	v_lshlrev_b32_e32 v38, 16, v84
	v_and_b32_e32 v39, 0xffff0000, v84
	v_lshlrev_b32_e32 v30, 16, v82
	v_and_b32_e32 v31, 0xffff0000, v82
	v_lshlrev_b32_e32 v32, 16, v83
	v_and_b32_e32 v33, 0xffff0000, v83
	v_lshlrev_b32_e32 v40, 16, v85
	v_and_b32_e32 v41, 0xffff0000, v85
	v_pk_fma_f32 v[30:31], v[30:31], s[28:29], v[34:35] op_sel_hi:[1,0,1]
	v_pk_fma_f32 v[32:33], v[32:33], s[28:29], v[36:37] op_sel_hi:[1,0,1]
	v_pk_fma_f32 v[34:35], v[40:41], s[28:29], v[28:29] op_sel_hi:[1,0,1]
	v_pk_fma_f32 v[28:29], v[38:39], s[28:29], v[26:27] op_sel_hi:[1,0,1]
	v_cvt_pk_bf16_f32 v26, v30, v31
	v_add_co_u32_e32 v30, vcc, s44, v62
	v_cvt_pk_bf16_f32 v27, v32, v33
	v_cvt_pk_bf16_f32 v28, v28, v29
	v_cvt_pk_bf16_f32 v29, v34, v35
	v_addc_co_u32_e32 v31, vcc, 0, v63, vcc
	flat_store_dwordx4 v[30:31], v[26:29]
	v_lshlrev_b32_e32 v32, 16, v88
	v_and_b32_e32 v33, 0xffff0000, v88
	v_lshlrev_b32_e32 v26, 16, v86
	v_and_b32_e32 v27, 0xffff0000, v86
	v_lshlrev_b32_e32 v28, 16, v87
	v_and_b32_e32 v29, 0xffff0000, v87
	v_lshlrev_b32_e32 v34, 16, v89
	v_and_b32_e32 v35, 0xffff0000, v89
	v_pk_fma_f32 v[24:25], v[28:29], s[28:29], v[24:25] op_sel_hi:[1,0,1]
	v_pk_fma_f32 v[22:23], v[26:27], s[28:29], v[22:23] op_sel_hi:[1,0,1]
	v_pk_fma_f32 v[26:27], v[34:35], s[28:29], v[16:17] op_sel_hi:[1,0,1]
	v_pk_fma_f32 v[16:17], v[32:33], s[28:29], v[14:15] op_sel_hi:[1,0,1]
	v_cvt_pk_bf16_f32 v14, v22, v23
	v_cvt_pk_bf16_f32 v15, v24, v25
	v_cvt_pk_bf16_f32 v16, v16, v17
	v_cvt_pk_bf16_f32 v17, v26, v27
	flat_store_dwordx4 v[30:31], v[14:17] offset:256
	v_lshlrev_b32_e32 v22, 16, v92
	v_and_b32_e32 v23, 0xffff0000, v92
	v_lshlrev_b32_e32 v14, 16, v90
	v_and_b32_e32 v15, 0xffff0000, v90
	v_lshlrev_b32_e32 v16, 16, v91
	v_and_b32_e32 v17, 0xffff0000, v91
	v_lshlrev_b32_e32 v24, 16, v93
	v_and_b32_e32 v25, 0xffff0000, v93
	v_pk_fma_f32 v[14:15], v[14:15], s[28:29], v[18:19] op_sel_hi:[1,0,1]
	v_pk_fma_f32 v[16:17], v[16:17], s[28:29], v[20:21] op_sel_hi:[1,0,1]
	v_pk_fma_f32 v[18:19], v[24:25], s[28:29], v[12:13] op_sel_hi:[1,0,1]
	v_pk_fma_f32 v[12:13], v[22:23], s[28:29], v[10:11] op_sel_hi:[1,0,1]
	v_cvt_pk_bf16_f32 v10, v14, v15
	v_add_co_u32_e32 v14, vcc, s47, v62
	v_cvt_pk_bf16_f32 v11, v16, v17
	v_cvt_pk_bf16_f32 v12, v12, v13
	v_cvt_pk_bf16_f32 v13, v18, v19
	v_addc_co_u32_e32 v15, vcc, 0, v63, vcc
	flat_store_dwordx4 v[14:15], v[10:13]
	v_lshlrev_b32_e32 v16, 16, v96
	v_and_b32_e32 v17, 0xffff0000, v96
	v_lshlrev_b32_e32 v10, 16, v94
	v_and_b32_e32 v11, 0xffff0000, v94
	v_lshlrev_b32_e32 v12, 16, v95
	v_and_b32_e32 v13, 0xffff0000, v95
	v_lshlrev_b32_e32 v18, 16, v97
	v_and_b32_e32 v19, 0xffff0000, v97
	v_pk_fma_f32 v[8:9], v[12:13], s[28:29], v[8:9] op_sel_hi:[1,0,1]
	v_pk_fma_f32 v[6:7], v[10:11], s[28:29], v[6:7] op_sel_hi:[1,0,1]
	v_pk_fma_f32 v[10:11], v[18:19], s[28:29], v[4:5] op_sel_hi:[1,0,1]
	v_pk_fma_f32 v[4:5], v[16:17], s[28:29], v[2:3] op_sel_hi:[1,0,1]
	v_cvt_pk_bf16_f32 v2, v6, v7
	v_cvt_pk_bf16_f32 v3, v8, v9
	v_cvt_pk_bf16_f32 v4, v4, v5
	v_cvt_pk_bf16_f32 v5, v10, v11
	s_and_b64 vcc, exec, s[30:31]
	flat_store_dwordx4 v[14:15], v[2:5] offset:256
	s_cbranch_vccz .LBB0_2494
	s_waitcnt vmcnt(0)
	s_cmpk_gt_u32 s5, 0xff
	s_cbranch_scc1 .LBB0_2499
	s_barrier

.LBB0_2516:
	s_or_b64 exec, exec, s[18:19]
	s_lshl_b32 s0, s9, 8
	s_add_i32 s0, s0, s97
	s_ashr_i32 s1, s0, 31
	s_lshl_b64 s[18:19], s[0:1], 11
	v_lshl_add_u64 v[38:39], v[54:55], 0, s[18:19]
	s_mov_b64 s[18:19], 0x4000
	v_add_co_u32_e32 v44, vcc, 0x4000, v38
	s_waitcnt lgkmcnt(0)
	s_barrier
	global_load_dwordx4 v[2:5], v[50:51], off
	global_load_dwordx4 v[6:9], v[50:51], off offset:1024
	global_load_dwordx4 v[10:13], v[52:53], off
	global_load_dwordx4 v[14:17], v[52:53], off offset:1024
	global_load_dwordx4 v[18:21], v[50:51], off offset:2048
	global_load_dwordx4 v[22:25], v[50:51], off offset:3072
	global_load_dwordx4 v[26:29], v[52:53], off offset:2048
	global_load_dwordx4 v[30:33], v[52:53], off offset:3072
	v_lshl_add_u64 v[42:43], v[38:39], 0, s[18:19]
	v_addc_co_u32_e32 v45, vcc, 0, v39, vcc
	flat_load_dwordx2 v[36:37], v[38:39] nt
	flat_load_dwordx2 v[34:35], v[38:39] offset:512 nt
	flat_load_dwordx2 v[40:41], v[38:39] offset:1024 nt
	s_nop 0
	flat_load_dwordx2 v[38:39], v[38:39] offset:1536 nt
	s_nop 0
	flat_load_dwordx2 v[60:61], v[44:45] nt
	flat_load_dwordx2 v[62:63], v[42:43] offset:512 nt
	flat_load_dwordx2 v[64:65], v[42:43] offset:1024 nt
	flat_load_dwordx2 v[66:67], v[42:43] offset:1536 nt
	s_mov_b32 s28, 0
	s_add_i32 s29, s0, 16
	s_mov_b32 s30, 0
	s_branch .LBB0_2519

.LBB0_2519:
	s_waitcnt vmcnt(0) lgkmcnt(0)
	v_lshlrev_b32_e32 v77, 16, v37
	v_lshlrev_b32_e32 v76, 16, v36
	v_and_b32_e32 v37, 0xffff0000, v37
	v_and_b32_e32 v36, 0xffff0000, v36
	v_pk_add_f32 v[68:69], v[76:77], v[36:37]
	v_lshlrev_b32_e32 v87, 16, v35
	v_lshlrev_b32_e32 v86, 16, v34
	v_and_b32_e32 v35, 0xffff0000, v35
	v_and_b32_e32 v34, 0xffff0000, v34
	v_lshlrev_b32_e32 v46, 16, v39
	v_and_b32_e32 v48, 0xffff0000, v39
	v_add_f32_e32 v39, v68, v69
	v_pk_add_f32 v[68:69], v[86:87], v[34:35]
	v_lshlrev_b32_e32 v42, 16, v40
	v_and_b32_e32 v43, 0xffff0000, v40
	v_lshlrev_b32_e32 v40, 16, v41
	v_and_b32_e32 v41, 0xffff0000, v41
	v_pk_add_f32 v[68:69], v[68:69], v[68:69] op_sel_hi:[0,1]
	v_lshlrev_b32_e32 v44, 16, v38
	v_and_b32_e32 v38, 0xffff0000, v38
	v_add_f32_e32 v49, 0, v39
	v_add_f32_e32 v45, v42, v43
	v_add_f32_e32 v39, v40, v41
	v_mov_b32_e32 v47, v69
	v_pk_add_f32 v[70:71], v[44:45], v[38:39]
	v_pk_add_f32 v[68:69], v[46:47], v[48:49]
	s_min_u32 s0, s30, 29
	v_pk_add_f32 v[68:69], v[70:71], v[68:69]
	s_lshl_b32 s0, s0, 3
	v_add_f32_e32 v39, v68, v69
	s_add_i32 s18, s29, s0
	s_nop 0
	v_add_f32_dpp v39, v39, v39 quad_perm:[1,0,3,2] row_mask:0xf bank_mask:0xf bound_ctrl:1
	s_nop 1
	v_add_f32_dpp v39, v39, v39 quad_perm:[2,3,0,1] row_mask:0xf bank_mask:0xf bound_ctrl:1
	s_nop 1
	v_add_f32_dpp v39, v39, v39 row_half_mirror row_mask:0xf bank_mask:0xf bound_ctrl:1
	s_nop 1
	v_add_f32_dpp v39, v39, v39 row_mirror row_mask:0xf bank_mask:0xf bound_ctrl:1
	s_nop 0
	v_readlane_b32 s19, v39, 16
	v_readlane_b32 s22, v39, 48
	v_readlane_b32 s0, v39, 0
	v_readlane_b32 s1, v39, 32
	v_mov_b32_e32 v68, s19
	v_mov_b32_e32 v69, s22
	v_pk_add_f32 v[68:69], s[0:1], v[68:69]
	s_nop 0
	v_add_f32_e32 v39, v68, v69
	v_fmac_f32_e32 v36, 0xba800000, v39
	v_fmac_f32_e32 v37, 0xba800000, v39
	v_fmac_f32_e32 v77, 0xba800000, v39
	v_fmac_f32_e32 v76, 0xba800000, v39
	v_mov_b32_e32 v88, v77
	v_mov_b32_e32 v89, v37
	v_mov_b32_e32 v77, v36
	v_fmac_f32_e32 v34, 0xba800000, v39
	v_fmac_f32_e32 v35, 0xba800000, v39
	v_fmac_f32_e32 v87, 0xba800000, v39
	v_pk_mul_f32 v[68:69], v[88:89], v[88:89]
	v_pk_mul_f32 v[36:37], v[76:77], v[76:77]
	v_fmac_f32_e32 v86, 0xba800000, v39
	v_mov_b32_e32 v90, v87
	v_mov_b32_e32 v91, v35
	v_mov_b32_e32 v87, v34
	v_pk_mov_b32 v[70:71], v[36:37], v[68:69] op_sel:[1,0]
	v_mov_b32_e32 v37, v69
	v_pk_mul_f32 v[68:69], v[90:91], v[90:91]
	v_pk_mul_f32 v[34:35], v[86:87], v[86:87]
	v_pk_add_f32 v[36:37], v[70:71], v[36:37]
	v_pk_mov_b32 v[70:71], v[34:35], v[68:69] op_sel:[1,0]
	v_mov_b32_e32 v35, v69
	v_pk_add_f32 v[34:35], v[70:71], v[34:35]
	v_fmac_f32_e32 v42, 0xba800000, v39
	v_pk_add_f32 v[34:35], v[34:35], v[34:35] op_sel_hi:[0,1]
	v_fmac_f32_e32 v43, 0xba800000, v39
	v_fmac_f32_e32 v40, 0xba800000, v39
	v_mul_f32_e32 v34, v42, v42
	v_fmac_f32_e32 v41, 0xba800000, v39
	v_pk_fma_f32 v[68:69], v[42:43], v[42:43], v[34:35] op_sel_hi:[1,1,0]
	v_mul_f32_e32 v34, v40, v40
	v_pk_add_f32 v[36:37], v[36:37], v[36:37] op_sel_hi:[0,1]
	v_pk_fma_f32 v[70:71], v[40:41], v[40:41], v[34:35] op_sel_hi:[1,1,0]
	v_fmac_f32_e32 v48, 0xba800000, v39
	v_fmac_f32_e32 v46, 0xba800000, v39
	v_fmac_f32_e32 v38, 0xba800000, v39
	v_fmac_f32_e32 v44, 0xba800000, v39
	v_mul_f32_e32 v68, v44, v44
	v_mul_f32_e32 v70, v38, v38
	v_mul_f32_e32 v36, v46, v46
	v_mul_f32_e32 v34, v48, v48
	v_pk_add_f32 v[68:69], v[68:69], v[70:71]
	v_pk_add_f32 v[34:35], v[36:37], v[34:35]
	v_mov_b32_e32 v47, v48
	v_pk_add_f32 v[34:35], v[68:69], v[34:35]
	s_nop 0
	v_add_f32_e32 v34, v34, v35
	s_nop 1
	v_add_f32_dpp v34, v34, v34 quad_perm:[1,0,3,2] row_mask:0xf bank_mask:0xf bound_ctrl:1
	s_nop 1
	v_add_f32_dpp v34, v34, v34 quad_perm:[2,3,0,1] row_mask:0xf bank_mask:0xf bound_ctrl:1
	s_nop 1
	v_add_f32_dpp v34, v34, v34 row_half_mirror row_mask:0xf bank_mask:0xf bound_ctrl:1
	s_nop 1
	v_add_f32_dpp v34, v34, v34 row_mirror row_mask:0xf bank_mask:0xf bound_ctrl:1
	s_nop 0
	v_readlane_b32 s19, v34, 16
	v_readlane_b32 s22, v34, 48
	v_readlane_b32 s0, v34, 0
	v_readlane_b32 s1, v34, 32
	v_mov_b32_e32 v34, s19
	v_mov_b32_e32 v35, s22
	v_pk_add_f32 v[34:35], s[0:1], v[34:35]
	s_mov_b32 s0, 0xf800000
	v_add_f32_e32 v34, v34, v35
	v_fmamk_f32 v34, v34, 0x3a800000, v83
	s_ashr_i32 s19, s18, 31
	v_mul_f32_e32 v35, 0x4f800000, v34
	v_cmp_gt_f32_e32 vcc, s0, v34
	s_lshl_b64 s[0:1], s[18:19], 11
	s_and_b32 s22, s30, 3
	v_cndmask_b32_e32 v36, v34, v35, vcc
	v_lshl_add_u64 v[34:35], v[54:55], 0, s[0:1]
	flat_load_dwordx2 v[68:69], v[34:35] nt
	flat_load_dwordx2 v[70:71], v[34:35] offset:512 nt
	flat_load_dwordx2 v[72:73], v[34:35] offset:1024 nt
	flat_load_dwordx2 v[74:75], v[34:35] offset:1536 nt
	v_sqrt_f32_e32 v37, v36
	s_mul_i32 s26, s22, 0x810
	s_add_i32 s26, s87, s26
	v_add_u32_e32 v39, -1, v37
	v_fma_f32 v45, -v39, v37, v36
	v_cmp_ge_f32_e64 s[18:19], 0, v45
	v_add_u32_e32 v45, 1, v37
	s_nop 0
	v_cndmask_b32_e64 v39, v37, v39, s[18:19]
	v_fma_f32 v37, -v45, v37, v36
	v_cmp_lt_f32_e64 s[18:19], 0, v37
	s_nop 1
	v_cndmask_b32_e64 v37, v39, v45, s[18:19]
	v_mul_f32_e32 v39, 0x37800000, v37
	v_cndmask_b32_e32 v37, v37, v39, vcc
	v_cmp_class_f32_e32 vcc, v36, v84
	s_add_i32 s18, s4, s28
	s_ashr_i32 s19, s18, 31
	v_cndmask_b32_e32 v36, v37, v36, vcc
	v_div_scale_f32 v37, s[0:1], v36, v36, 1.0
	v_rcp_f32_e32 v39, v37
	s_lshl_b64 s[0:1], s[18:19], 11
	v_fma_f32 v34, -v37, v39, 1.0
	v_fmac_f32_e32 v39, v34, v39
	v_div_scale_f32 v34, vcc, 1.0, v36, 1.0
	v_mul_f32_e32 v35, v34, v39
	v_fma_f32 v45, -v37, v35, v34
	v_fmac_f32_e32 v35, v45, v39
	v_fma_f32 v34, -v37, v35, v34
	v_div_fmas_f32 v34, v34, v39, v35
	v_div_fixup_f32 v34, v34, v36, 1.0
	v_mov_b32_e32 v45, v38
	v_pk_mul_f32 v[36:37], v[76:77], v[34:35] op_sel_hi:[1,0]
	v_pk_mul_f32 v[76:77], v[88:89], v[34:35] op_sel_hi:[1,0]
	v_pk_mul_f32 v[38:39], v[44:45], v[34:35] op_sel_hi:[1,0]
	v_mov_b32_e32 v44, v78
	v_pk_fma_f32 v[76:77], v[4:5], v[76:77], v[12:13]
	v_pk_fma_f32 v[36:37], v[2:3], v[36:37], v[10:11]
	v_pk_mul_f32 v[86:87], v[86:87], v[34:35] op_sel_hi:[1,0]
	v_pk_mul_f32 v[88:89], v[90:91], v[34:35] op_sel_hi:[1,0]
	v_pk_fma_f32 v[86:87], v[6:7], v[86:87], v[14:15]
	v_pk_fma_f32 v[88:89], v[8:9], v[88:89], v[16:17]
	v_pk_mul_f32 v[42:43], v[42:43], v[34:35] op_sel_hi:[1,0]
	v_pk_mul_f32 v[40:41], v[40:41], v[34:35] op_sel_hi:[1,0]
	v_pk_mul_f32 v[34:35], v[46:47], v[34:35] op_sel_hi:[1,0]
	v_lshl_add_u32 v48, v44, 3, s26
	v_cvt_pk_bf16_f32 v44, v36, v37
	v_cvt_pk_bf16_f32 v45, v76, v77
	v_lshl_add_u64 v[46:47], v[56:57], 0, s[0:1]
	v_pk_fma_f32 v[40:41], v[20:21], v[40:41], v[28:29]
	v_pk_fma_f32 v[42:43], v[18:19], v[42:43], v[26:27]
	flat_store_dwordx2 v[46:47], v[44:45]
	ds_write_b64 v48, v[44:45] offset:33024
	v_cvt_pk_bf16_f32 v44, v86, v87
	v_cvt_pk_bf16_f32 v45, v88, v89
	v_pk_fma_f32 v[34:35], v[24:25], v[34:35], v[32:33]
	v_pk_fma_f32 v[38:39], v[22:23], v[38:39], v[30:31]
	flat_store_dwordx2 v[46:47], v[44:45] offset:512
	ds_write_b64 v48, v[44:45] offset:33536
	v_cvt_pk_bf16_f32 v44, v42, v43
	v_cvt_pk_bf16_f32 v45, v40, v41
	flat_store_dwordx2 v[46:47], v[44:45] offset:1024
	ds_write_b64 v48, v[44:45] offset:34048
	v_cvt_pk_bf16_f32 v44, v38, v39
	v_cvt_pk_bf16_f32 v45, v34, v35
	flat_store_dwordx2 v[46:47], v[44:45] offset:1536
	ds_write_b64 v48, v[44:45] offset:34560
	v_med3_f32 v36, v36, s8, v85
	v_med3_f32 v37, v37, s8, v85
	v_mov_b32_e32 v44, 0
	v_cvt_pk_fp8_f32 v44, v36, v37
	v_med3_f32 v36, v76, s8, v85
	v_med3_f32 v37, v77, s8, v85
	v_med3_f32 v45, v86, s8, v85
	v_cvt_pk_fp8_f32 v44, v36, v37 op_sel:[0,0,1]
	v_med3_f32 v46, v87, s8, v85
	v_mov_b32_e32 v47, 0
	v_cvt_pk_fp8_f32 v47, v45, v46
	s_lshl_b64 s[0:1], s[18:19], 10
	v_lshl_add_u64 v[36:37], v[58:59], 0, s[0:1]
	flat_store_dword v[36:37], v44
	v_med3_f32 v44, v88, s8, v85
	v_med3_f32 v45, v89, s8, v85
	v_cvt_pk_fp8_f32 v47, v44, v45 op_sel:[0,0,1]
	v_med3_f32 v42, v42, s8, v85
	v_med3_f32 v43, v43, s8, v85
	v_mov_b32_e32 v44, 0
	v_cvt_pk_fp8_f32 v44, v42, v43
	v_med3_f32 v38, v38, s8, v85
	v_med3_f32 v39, v39, s8, v85
	v_mov_b32_e32 v42, 0
	v_cvt_pk_fp8_f32 v42, v38, v39
	v_med3_f32 v34, v34, s8, v85
	v_med3_f32 v35, v35, s8, v85
	v_med3_f32 v40, v40, s8, v85
	v_med3_f32 v41, v41, s8, v85
	v_cvt_pk_fp8_f32 v42, v34, v35 op_sel:[0,0,1]
	v_cvt_pk_fp8_f32 v44, v40, v41 op_sel:[0,0,1]
	s_cmp_lg_u32 s22, 3
	flat_store_dword v[36:37], v47 offset:256
	flat_store_dword v[36:37], v44 offset:512
	flat_store_dword v[36:37], v42 offset:768
	s_cbranch_scc1 .LBB0_2518
	v_mov_b32_e32 v76, v78
	s_nop 0
	v_and_b32_e32 v34, 3, v76
	v_mul_u32_u24_e32 v34, 0x810, v34
	v_and_b32_e32 v35, -16, v76
	v_add3_u32 v77, s87, v34, v35
	v_and_b32_e32 v34, 15, v76
	v_mul_u32_u24_e32 v34, 0x810, v34
	v_add3_u32 v94, 0, v34, v35
	ds_read_b128 v[34:37], v77 offset:33024
	ds_read_b128 v[38:41], v94
	s_waitcnt lgkmcnt(0)
	v_mfma_f32_16x16x32_bf16 v[34:37], v[34:37], v[38:41], 0
	ds_read_b128 v[38:41], v77 offset:33088
	ds_read_b128 v[42:45], v94 offset:64
	v_cmp_gt_i32_e32 vcc, 16, v76
	s_waitcnt lgkmcnt(0)
	v_mfma_f32_16x16x32_bf16 v[38:41], v[38:41], v[42:45], 0
	ds_read_b128 v[42:45], v77 offset:33152
	ds_read_b128 v[46:49], v94 offset:128
	s_waitcnt lgkmcnt(0)
	v_mfma_f32_16x16x32_bf16 v[42:45], v[42:45], v[46:49], 0
	ds_read_b128 v[46:49], v77 offset:33216
	ds_read_b128 v[86:89], v94 offset:192
	s_waitcnt lgkmcnt(0)
	v_mfma_f32_16x16x32_bf16 v[46:49], v[46:49], v[86:89], 0
	ds_read_b128 v[86:89], v77 offset:33280
	ds_read_b128 v[90:93], v94 offset:256
	s_waitcnt lgkmcnt(0)
	v_mfma_f32_16x16x32_bf16 v[34:37], v[86:89], v[90:93], v[34:37]
	ds_read_b128 v[86:89], v77 offset:33344
	ds_read_b128 v[90:93], v94 offset:320
	s_waitcnt lgkmcnt(0)
	v_mfma_f32_16x16x32_bf16 v[38:41], v[86:89], v[90:93], v[38:41]
	ds_read_b128 v[86:89], v77 offset:33408
	ds_read_b128 v[90:93], v94 offset:384
	s_waitcnt lgkmcnt(0)
	v_mfma_f32_16x16x32_bf16 v[42:45], v[86:89], v[90:93], v[42:45]
	ds_read_b128 v[86:89], v77 offset:33472
	ds_read_b128 v[90:93], v94 offset:448
	s_waitcnt lgkmcnt(0)
	v_mfma_f32_16x16x32_bf16 v[46:49], v[86:89], v[90:93], v[46:49]
	ds_read_b128 v[86:89], v77 offset:33536
	ds_read_b128 v[90:93], v94 offset:512
	s_waitcnt lgkmcnt(0)
	v_mfma_f32_16x16x32_bf16 v[34:37], v[86:89], v[90:93], v[34:37]
	ds_read_b128 v[86:89], v77 offset:33600
	ds_read_b128 v[90:93], v94 offset:576
	s_waitcnt lgkmcnt(0)
	v_mfma_f32_16x16x32_bf16 v[38:41], v[86:89], v[90:93], v[38:41]
	ds_read_b128 v[86:89], v77 offset:33664
	ds_read_b128 v[90:93], v94 offset:640
	s_waitcnt lgkmcnt(0)
	v_mfma_f32_16x16x32_bf16 v[42:45], v[86:89], v[90:93], v[42:45]
	ds_read_b128 v[86:89], v77 offset:33728
	ds_read_b128 v[90:93], v94 offset:704
	s_waitcnt lgkmcnt(0)
	v_mfma_f32_16x16x32_bf16 v[46:49], v[86:89], v[90:93], v[46:49]
	ds_read_b128 v[86:89], v77 offset:33792
	ds_read_b128 v[90:93], v94 offset:768
	s_waitcnt lgkmcnt(0)
	v_mfma_f32_16x16x32_bf16 v[34:37], v[86:89], v[90:93], v[34:37]
	ds_read_b128 v[86:89], v77 offset:33856
	ds_read_b128 v[90:93], v94 offset:832
	s_waitcnt lgkmcnt(0)
	v_mfma_f32_16x16x32_bf16 v[38:41], v[86:89], v[90:93], v[38:41]
	ds_read_b128 v[86:89], v77 offset:33920
	ds_read_b128 v[90:93], v94 offset:896
	s_waitcnt lgkmcnt(0)
	v_mfma_f32_16x16x32_bf16 v[42:45], v[86:89], v[90:93], v[42:45]
	ds_read_b128 v[86:89], v77 offset:33984
	ds_read_b128 v[90:93], v94 offset:960
	s_waitcnt lgkmcnt(0)
	v_mfma_f32_16x16x32_bf16 v[46:49], v[86:89], v[90:93], v[46:49]
	ds_read_b128 v[86:89], v77 offset:34048
	ds_read_b128 v[90:93], v94 offset:1024
	s_waitcnt lgkmcnt(0)
	v_mfma_f32_16x16x32_bf16 v[34:37], v[86:89], v[90:93], v[34:37]
	ds_read_b128 v[86:89], v77 offset:34112
	ds_read_b128 v[90:93], v94 offset:1088
	s_waitcnt lgkmcnt(0)
	v_mfma_f32_16x16x32_bf16 v[38:41], v[86:89], v[90:93], v[38:41]
	ds_read_b128 v[86:89], v77 offset:34176
	ds_read_b128 v[90:93], v94 offset:1152
	s_waitcnt lgkmcnt(0)
	v_mfma_f32_16x16x32_bf16 v[42:45], v[86:89], v[90:93], v[42:45]
	ds_read_b128 v[86:89], v77 offset:34240
	ds_read_b128 v[90:93], v94 offset:1216
	s_waitcnt lgkmcnt(0)
	v_mfma_f32_16x16x32_bf16 v[46:49], v[86:89], v[90:93], v[46:49]
	ds_read_b128 v[86:89], v77 offset:34304
	ds_read_b128 v[90:93], v94 offset:1280
	s_waitcnt lgkmcnt(0)
	v_mfma_f32_16x16x32_bf16 v[34:37], v[86:89], v[90:93], v[34:37]
	ds_read_b128 v[86:89], v77 offset:34368
	ds_read_b128 v[90:93], v94 offset:1344
	s_waitcnt lgkmcnt(0)
	v_mfma_f32_16x16x32_bf16 v[38:41], v[86:89], v[90:93], v[38:41]
	ds_read_b128 v[86:89], v77 offset:34432
	ds_read_b128 v[90:93], v94 offset:1408
	s_waitcnt lgkmcnt(0)
	v_mfma_f32_16x16x32_bf16 v[42:45], v[86:89], v[90:93], v[42:45]
	ds_read_b128 v[86:89], v77 offset:34496
	ds_read_b128 v[90:93], v94 offset:1472
	s_waitcnt lgkmcnt(0)
	v_mfma_f32_16x16x32_bf16 v[46:49], v[86:89], v[90:93], v[46:49]
	ds_read_b128 v[86:89], v77 offset:34560
	ds_read_b128 v[90:93], v94 offset:1536
	s_waitcnt lgkmcnt(0)
	v_mfma_f32_16x16x32_bf16 v[34:37], v[86:89], v[90:93], v[34:37]
	ds_read_b128 v[86:89], v77 offset:34624
	ds_read_b128 v[90:93], v94 offset:1600
	s_waitcnt lgkmcnt(0)
	v_mfma_f32_16x16x32_bf16 v[38:41], v[86:89], v[90:93], v[38:41]
	ds_read_b128 v[86:89], v77 offset:34688
	ds_read_b128 v[90:93], v94 offset:1664
	s_waitcnt lgkmcnt(0)
	v_mfma_f32_16x16x32_bf16 v[42:45], v[86:89], v[90:93], v[42:45]
	ds_read_b128 v[86:89], v77 offset:34752
	ds_read_b128 v[90:93], v94 offset:1728
	s_waitcnt lgkmcnt(0)
	v_mfma_f32_16x16x32_bf16 v[46:49], v[86:89], v[90:93], v[46:49]
	ds_read_b128 v[86:89], v77 offset:34816
	ds_read_b128 v[90:93], v94 offset:1792
	s_waitcnt lgkmcnt(0)
	v_mfma_f32_16x16x32_bf16 v[34:37], v[86:89], v[90:93], v[34:37]
	ds_read_b128 v[86:89], v77 offset:34880
	ds_read_b128 v[90:93], v94 offset:1856
	s_waitcnt lgkmcnt(0)
	v_mfma_f32_16x16x32_bf16 v[38:41], v[86:89], v[90:93], v[38:41]
	ds_read_b128 v[86:89], v77 offset:34944
	ds_read_b128 v[90:93], v94 offset:1920
	s_waitcnt lgkmcnt(0)
	v_mfma_f32_16x16x32_bf16 v[42:45], v[86:89], v[90:93], v[42:45]
	ds_read_b128 v[86:89], v77 offset:35008
	ds_read_b128 v[90:93], v94 offset:1984
	s_nop 1
	v_pk_add_f32 v[34:35], v[34:35], v[38:39]
	v_ashrrev_i32_e32 v77, 31, v76
	s_waitcnt lgkmcnt(0)
	v_mfma_f32_16x16x32_bf16 v[46:49], v[86:89], v[90:93], v[46:49]
	s_nop 7
	v_pk_add_f32 v[38:39], v[42:43], v[46:47]
	s_nop 0
	v_pk_add_f32 v[38:39], v[34:35], v[38:39]
	v_lshlrev_b64 v[34:35], 13, v[76:77]
	v_lshl_add_u64 v[34:35], s[24:25], 0, v[34:35]
	v_mov_b32_dpp v42, v38 quad_perm:[1,0,3,2] row_mask:0xf bank_mask:0xf bound_ctrl:1
	v_max_f32_e32 v42, v42, v42
	v_max_f32_e32 v42, v38, v42
	s_nop 1
	v_mov_b32_dpp v43, v42 quad_perm:[2,3,0,1] row_mask:0xf bank_mask:0xf bound_ctrl:1
	v_max_f32_e32 v43, v43, v43
	v_max_f32_e32 v42, v42, v43
	s_nop 1
	v_mov_b32_dpp v43, v42 row_half_mirror row_mask:0xf bank_mask:0xf bound_ctrl:1
	v_max_f32_e32 v43, v43, v43
	v_max_f32_e32 v42, v42, v43
	s_nop 1
	v_mov_b32_dpp v43, v42 row_mirror row_mask:0xf bank_mask:0xf bound_ctrl:1
	v_max_f32_e32 v43, v43, v43
	v_max_f32_e32 v42, v42, v43
	v_sub_f32_e32 v38, v38, v42
	v_mul_f32_e32 v38, 0x3fb8aa3b, v38
	v_exp_f32_e32 v38, v38
	s_nop 1
	v_add_f32_dpp v42, v38, v38 quad_perm:[1,0,3,2] row_mask:0xf bank_mask:0xf bound_ctrl:1
	s_nop 1
	v_add_f32_dpp v42, v42, v42 quad_perm:[2,3,0,1] row_mask:0xf bank_mask:0xf bound_ctrl:1
	s_nop 1
	v_add_f32_dpp v42, v42, v42 row_half_mirror row_mask:0xf bank_mask:0xf bound_ctrl:1
	s_nop 1
	v_mov_b32_dpp v43, v42 row_mirror row_mask:0xf bank_mask:0xf bound_ctrl:1
	s_and_saveexec_b64 s[26:27], vcc
	s_cbranch_execz .LBB0_2522
	v_add_f32_e32 v42, v42, v43
	v_rcp_f32_e32 v42, v42
	s_sub_i32 s19, s18, 24
	s_ashr_i32 s0, s19, 11
	s_ashr_i32 s1, s0, 31
	s_and_b32 s19, s19, 0x7ff
	s_lshl_b64 s[0:1], s[0:1], 17
	v_mul_f32_e32 v38, v38, v42
	v_lshl_add_u64 v[42:43], v[34:35], 0, s[0:1]
	s_lshl_b32 s22, s19, 2
	v_lshl_add_u64 v[42:43], v[42:43], 0, s[22:23]
	flat_store_dword v[42:43], v38

.LBB0_2874:
	s_or_b64 exec, exec, s[2:3]
	s_waitcnt lgkmcnt(0)
	s_barrier
	s_load_dwordx8 s[12:19], s[84:85], 0xf0
	v_mov_b32_e32 v33, 0
	v_and_b32_e32 v44, 63, v0
	v_lshlrev_b32_e32 v32, 4, v44
	s_waitcnt lgkmcnt(0)
	s_mov_b32 s8, s18
	s_add_u32 s4, s8, 0x3e00000
	s_addc_u32 s5, s19, 0
	v_lshl_add_u64 v[0:1], s[12:13], 0, v[32:33]
	s_mov_b64 s[0:1], 0x7000
	v_lshl_add_u64 v[4:5], s[14:15], 0, v[32:33]
	v_lshl_add_u64 v[34:35], v[0:1], 0, s[0:1]
	v_lshl_add_u64 v[36:37], v[4:5], 0, s[0:1]
	s_movk_i32 s0, 0x7000
	s_add_u32 s6, s8, 0x3900000
	v_add_co_u32_e32 v0, vcc, s0, v0
	s_addc_u32 s7, s19, 0
	s_nop 0
	v_addc_co_u32_e32 v1, vcc, 0, v1, vcc
	s_add_u32 s10, s8, 0xa100000
	v_add_co_u32_e32 v38, vcc, s0, v4
	s_addc_u32 s11, s19, 0
	v_readlane_b32 s0, v253, 36
	v_readlane_b32 s1, v253, 37
	s_add_u32 s0, s10, s0
	s_addc_u32 s1, s11, s1
	v_readlane_b32 s12, v253, 38
	s_mov_b32 s2, s16
	v_addc_co_u32_e32 v39, vcc, 0, v5, vcc
	v_readlane_b32 s13, v253, 39
	s_add_u32 s12, s10, s12
	v_lshlrev_b32_e32 v32, 3, v44
	global_load_dwordx4 v[0:3], v[0:1], off
	s_nop 0
	global_load_dwordx4 v[4:7], v[38:39], off
	global_load_dwordx4 v[8:11], v[34:35], off offset:1024
	global_load_dwordx4 v[12:15], v[34:35], off offset:2048
	global_load_dwordx4 v[16:19], v[36:37], off offset:1024
	global_load_dwordx4 v[20:23], v[36:37], off offset:2048
	global_load_dwordx4 v[24:27], v[34:35], off offset:3072
	global_load_dwordx4 v[28:31], v[36:37], off offset:3072
	s_addc_u32 s13, s11, s13
	v_lshl_add_u64 v[38:39], s[0:1], 0, v[32:33]
	v_lshl_add_u64 v[46:47], s[12:13], 0, v[32:33]
	flat_load_dwordx2 v[64:65], v[38:39] nt
	flat_load_dwordx2 v[62:63], v[38:39] offset:512 nt
	flat_load_dwordx2 v[60:61], v[38:39] offset:1024 nt
	flat_load_dwordx2 v[58:59], v[38:39] offset:1536 nt
	flat_load_dwordx2 v[42:43], v[46:47] nt
	flat_load_dwordx2 v[40:41], v[46:47] offset:512 nt
	flat_load_dwordx2 v[36:37], v[46:47] offset:1024 nt
	flat_load_dwordx2 v[34:35], v[46:47] offset:1536 nt
	s_mov_b32 s14, s19
	v_cmp_gt_u32_e64 s[0:1], 16, v44
	v_mov_b32_e32 v39, -1
	v_lshlrev_b32_e32 v38, 11, v44
	v_mov_b32_e32 v80, v33
	v_mov_b32_e32 v79, -1
	s_and_saveexec_b64 s[12:13], s[0:1]
	s_cbranch_execz .LBB0_2876
	v_readlane_b32 s18, v253, 34
	s_ashr_i32 s20, s68, 11
	v_readlane_b32 s19, v253, 35
	s_mov_b32 s16, s18
	s_ashr_i32 s18, s18, 11
	s_ashr_i32 s21, s20, 31
	s_ashr_i32 s19, s18, 31
	s_lshl_b64 s[20:21], s[20:21], 15
	s_and_b32 s9, s68, 0x7ff
	s_lshl_b64 s[18:19], s[18:19], 15
	s_and_b32 s3, s16, 0x7ff
	s_or_b32 s9, s20, s9
	s_or_b32 s3, s18, s3
	v_or_b32_e32 v46, s9, v38
	v_mov_b32_e32 v47, s21
	v_lshl_add_u64 v[48:49], v[46:47], 1, s[4:5]
	v_or_b32_e32 v50, s3, v38
	v_mov_b32_e32 v51, s19
	v_lshl_add_u64 v[46:47], v[46:47], 2, s[6:7]
	v_lshl_add_u64 v[52:53], v[50:51], 1, s[4:5]
	v_lshl_add_u64 v[50:51], v[50:51], 2, s[6:7]
	flat_load_sshort v79, v[48:49]
	flat_load_dword v80, v[46:47] nt
	flat_load_sshort v39, v[52:53]
	flat_load_dword v33, v[50:51] nt

.LBB0_2879:
	s_add_i32 s10, s68, s94
	s_cmp_gt_i32 s10, 0xffff
	v_mov_b32_e32 v78, v33
	s_cbranch_scc1 .LBB0_2883
	s_ashr_i32 s11, s10, 31
	s_lshl_b64 s[2:3], s[10:11], 11
	v_lshl_add_u64 v[66:67], v[46:47], 0, s[2:3]
	flat_load_dwordx2 v[56:57], v[66:67] nt
	flat_load_dwordx2 v[54:55], v[66:67] offset:512 nt
	flat_load_dwordx2 v[52:53], v[66:67] offset:1024 nt
	flat_load_dwordx2 v[50:51], v[66:67] offset:1536 nt
	v_mov_b32_e32 v77, v39
	v_mov_b32_e32 v78, v33
	s_and_saveexec_b64 s[2:3], s[0:1]
	s_cbranch_execz .LBB0_2882
	s_ashr_i32 s12, s10, 11
	s_ashr_i32 s13, s12, 31
	s_lshl_b64 s[12:13], s[12:13], 15
	v_or_b32_e32 v32, s12, v38
	s_and_b32 s11, s10, 0x7ff
	v_mov_b32_e32 v67, s13
	v_or_b32_e32 v66, s11, v32
	v_lshl_add_u64 v[68:69], v[66:67], 1, s[4:5]
	v_lshl_add_u64 v[66:67], v[66:67], 2, s[6:7]
	flat_load_sshort v77, v[68:69]
	flat_load_dword v78, v[66:67] nt

.LBB0_2885:
	s_add_u32 s20, s14, -1
	s_addc_u32 s21, s15, -1
	s_lshl_b32 s13, s13, 5
	s_and_b64 vcc, s[20:21], s[14:15]
	s_add_i32 s14, s13, s11
	s_ashr_i32 s15, s14, 31
	s_ashr_i32 s13, s12, 31
	s_lshl_b64 s[14:15], s[14:15], 18
	s_lshl_b64 s[12:13], s[12:13], 10
	s_add_u32 s14, s9, s14
	s_addc_u32 s15, s16, s15
	s_add_u32 s12, s14, s12
	s_addc_u32 s13, s15, s13
	s_lshl_b32 s3, s3, 5
	s_add_i32 s14, s3, s11
	s_ashr_i32 s15, s14, 31
	s_ashr_i32 s3, s2, 31
	s_lshl_b64 s[14:15], s[14:15], 18
	s_lshl_b64 s[2:3], s[2:3], 10
	s_add_u32 s14, s9, s14
	s_addc_u32 s15, s16, s15
	s_add_u32 s2, s14, s2
	s_addc_u32 s3, s15, s3
	v_lshl_add_u64 v[82:83], s[12:13], 0, v[44:45]
	v_lshl_add_u64 v[84:85], s[2:3], 0, v[44:45]
	flat_load_dword v81, v[82:83] nt
	flat_load_dword v90, v[82:83] offset:256 nt
	flat_load_dword v94, v[82:83] offset:512 nt
	flat_load_dword v98, v[84:85] nt
	flat_load_dword v102, v[84:85] offset:256 nt
	flat_load_dword v106, v[84:85] offset:512 nt
	flat_load_dword v114, v[84:85] offset:768 nt
	flat_load_dword v110, v[82:83] offset:768 nt
	v_mul_f32_e32 v82, s18, v76
	s_cmp_eq_u64 vcc, 0
	s_waitcnt vmcnt(0) lgkmcnt(0)
	v_cvt_pk_f32_fp8_e32 v[96:97], v98
	v_cvt_pk_f32_fp8_sdwa v[98:99], v98 src0_sel:WORD_1
	v_cvt_pk_f32_fp8_e32 v[100:101], v102
	v_cvt_pk_f32_fp8_sdwa v[102:103], v102 src0_sel:WORD_1
	v_cvt_pk_f32_fp8_e32 v[104:105], v106
	v_cvt_pk_f32_fp8_sdwa v[106:107], v106 src0_sel:WORD_1
	v_cvt_pk_f32_fp8_e32 v[112:113], v114
	v_cvt_pk_f32_fp8_sdwa v[114:115], v114 src0_sel:WORD_1
	v_cvt_pk_f32_fp8_e32 v[84:85], v81
	v_cvt_pk_f32_fp8_sdwa v[86:87], v81 src0_sel:WORD_1
	v_cvt_pk_f32_fp8_e32 v[88:89], v90
	v_cvt_pk_f32_fp8_sdwa v[90:91], v90 src0_sel:WORD_1
	v_cvt_pk_f32_fp8_e32 v[92:93], v94
	v_cvt_pk_f32_fp8_sdwa v[94:95], v94 src0_sel:WORD_1
	v_cvt_pk_f32_fp8_e32 v[108:109], v110
	v_cvt_pk_f32_fp8_sdwa v[110:111], v110 src0_sel:WORD_1
	v_pk_mul_f32 v[98:99], v[32:33], v[98:99] op_sel_hi:[0,1]
	v_pk_mul_f32 v[96:97], v[32:33], v[96:97] op_sel_hi:[0,1]
	v_pk_mul_f32 v[102:103], v[32:33], v[102:103] op_sel_hi:[0,1]
	v_pk_mul_f32 v[100:101], v[32:33], v[100:101] op_sel_hi:[0,1]
	v_pk_mul_f32 v[106:107], v[32:33], v[106:107] op_sel_hi:[0,1]
	v_pk_mul_f32 v[104:105], v[32:33], v[104:105] op_sel_hi:[0,1]
	v_pk_mul_f32 v[114:115], v[32:33], v[114:115] op_sel_hi:[0,1]
	v_pk_mul_f32 v[112:113], v[32:33], v[112:113] op_sel_hi:[0,1]
	v_pk_fma_f32 v[84:85], v[82:83], v[84:85], v[96:97] op_sel_hi:[0,1,1]
	v_pk_fma_f32 v[86:87], v[82:83], v[86:87], v[98:99] op_sel_hi:[0,1,1]
	v_pk_fma_f32 v[88:89], v[82:83], v[88:89], v[100:101] op_sel_hi:[0,1,1]
	v_pk_fma_f32 v[90:91], v[82:83], v[90:91], v[102:103] op_sel_hi:[0,1,1]
	v_pk_fma_f32 v[92:93], v[82:83], v[92:93], v[104:105] op_sel_hi:[0,1,1]
	v_pk_fma_f32 v[94:95], v[82:83], v[94:95], v[106:107] op_sel_hi:[0,1,1]
	v_pk_fma_f32 v[96:97], v[82:83], v[108:109], v[112:113] op_sel_hi:[0,1,1]
	v_pk_fma_f32 v[82:83], v[82:83], v[110:111], v[114:115] op_sel_hi:[0,1,1]
	v_pk_add_f32 v[68:69], v[68:69], v[86:87]
	v_pk_add_f32 v[70:71], v[70:71], v[84:85]
	v_pk_add_f32 v[62:63], v[62:63], v[90:91]
	v_pk_add_f32 v[66:67], v[66:67], v[88:89]
	v_pk_add_f32 v[60:61], v[60:61], v[94:95]
	v_pk_add_f32 v[64:65], v[64:65], v[92:93]
	v_pk_add_f32 v[72:73], v[72:73], v[82:83]
	v_pk_add_f32 v[58:59], v[58:59], v[96:97]
	s_cbranch_scc1 .LBB0_2878
